# all 16-byte global stores made write-through (sc1) so the grid-barrier L2 writeback finds little dirty data
# baseline (speedup 1.0000x reference)
.LBB0_105:
	s_lshl_b32 s20, s10, 1
	s_lshl_b32 s21, s4, 1
	v_or_b32_e32 v4, s21, v40
	s_add_i32 s22, s20, 4
	s_add_i32 s23, s21, 4
	v_mov_b32_e32 v45, v5
	s_add_i32 s25, s21, 8
	v_lshlrev_b64 v[58:59], 12, v[4:5]
	v_or_b32_e32 v44, s22, v3
	v_or_b32_e32 v4, s23, v40
	v_mov_b32_e32 v43, v5
	v_or_b32_e32 v42, s20, v3
	s_add_i32 s27, s21, 12
	v_lshlrev_b64 v[44:45], 12, v[44:45]
	v_lshlrev_b64 v[60:61], 12, v[4:5]
	v_or_b32_e32 v4, s25, v40
	s_add_i32 s24, s20, 8
	s_add_i32 s26, s20, 12
	s_add_i32 s29, s21, 16
	v_lshlrev_b64 v[42:43], 12, v[42:43]
	v_lshl_add_u64 v[58:59], v[38:39], 0, v[58:59]
	v_lshl_add_u64 v[44:45], v[38:39], 0, v[44:45]
	v_lshlrev_b64 v[62:63], 12, v[4:5]
	v_or_b32_e32 v4, s27, v40
	v_mov_b32_e32 v47, v5
	v_mov_b32_e32 v49, v5
	s_add_i32 s31, s21, 20
	v_or_b32_e32 v46, s24, v3
	v_or_b32_e32 v48, s26, v3
	v_lshl_add_u64 v[42:43], v[38:39], 0, v[42:43]
	v_lshl_add_u64 v[60:61], v[38:39], 0, v[60:61]
	global_load_dword v41, v[58:59], off
	global_load_dword v71, v[42:43], off
	global_load_dword v82, v[60:61], off
	global_load_dword v83, v[44:45], off
	v_lshlrev_b64 v[44:45], 12, v[4:5]
	v_or_b32_e32 v4, s29, v40
	s_add_i32 s28, s20, 16
	s_add_i32 s30, s20, 20
	s_add_i32 s35, s21, 24
	v_lshlrev_b64 v[46:47], 12, v[46:47]
	v_lshlrev_b64 v[48:49], 12, v[48:49]
	v_lshl_add_u64 v[42:43], v[38:39], 0, v[62:63]
	v_lshl_add_u64 v[44:45], v[38:39], 0, v[44:45]
	v_lshlrev_b64 v[58:59], 12, v[4:5]
	v_or_b32_e32 v4, s31, v40
	v_mov_b32_e32 v51, v5
	v_mov_b32_e32 v53, v5
	s_add_i32 s34, s20, 24
	s_add_i32 s36, s20, 28
	s_add_i32 s37, s21, 28
	v_or_b32_e32 v50, s28, v3
	v_or_b32_e32 v52, s30, v3
	v_lshl_add_u64 v[46:47], v[38:39], 0, v[46:47]
	v_lshl_add_u64 v[48:49], v[38:39], 0, v[48:49]
	global_load_dword v84, v[42:43], off
	global_load_dword v85, v[46:47], off
	global_load_dword v86, v[44:45], off
	global_load_dword v87, v[48:49], off
	v_lshlrev_b64 v[44:45], 12, v[4:5]
	v_or_b32_e32 v4, s35, v40
	v_mov_b32_e32 v55, v5
	v_mov_b32_e32 v57, v5
	v_or_b32_e32 v54, s34, v3
	v_or_b32_e32 v56, s36, v3
	v_lshlrev_b64 v[50:51], 12, v[50:51]
	v_lshlrev_b64 v[52:53], 12, v[52:53]
	v_lshl_add_u64 v[42:43], v[38:39], 0, v[58:59]
	v_lshl_add_u64 v[44:45], v[38:39], 0, v[44:45]
	v_lshlrev_b64 v[46:47], 12, v[4:5]
	v_or_b32_e32 v4, s37, v40
	v_lshlrev_b64 v[54:55], 12, v[54:55]
	v_lshlrev_b64 v[56:57], 12, v[56:57]
	v_lshl_add_u64 v[50:51], v[38:39], 0, v[50:51]
	v_lshl_add_u64 v[52:53], v[38:39], 0, v[52:53]
	global_load_dword v88, v[42:43], off
	global_load_dword v89, v[50:51], off
	global_load_dword v90, v[44:45], off
	global_load_dword v91, v[52:53], off
	v_lshl_add_u64 v[42:43], v[38:39], 0, v[46:47]
	v_lshlrev_b64 v[44:45], 12, v[4:5]
	v_lshl_add_u64 v[54:55], v[38:39], 0, v[54:55]
	v_lshl_add_u64 v[56:57], v[38:39], 0, v[56:57]
	v_lshl_add_u64 v[44:45], v[38:39], 0, v[44:45]
	global_load_dword v4, v[42:43], off
	global_load_dword v92, v[54:55], off
	global_load_dword v93, v[44:45], off
	global_load_dword v94, v[56:57], off
	v_or_b32_e32 v44, s20, v1
	v_or_b32_e32 v42, s21, v0
	s_add_i32 s4, s4, 16
	s_add_i32 s10, s10, 16
	s_add_i32 s11, s11, -16
	v_mad_u64_u32 v[42:43], s[20:21], v42, s12, v[2:3]
	v_mad_u64_u32 v[44:45], s[20:21], v44, s12, v[2:3]
	v_or_b32_e32 v43, s22, v1
	v_or_b32_e32 v45, s23, v0
	v_or_b32_e32 v52, s24, v1
	v_or_b32_e32 v50, s25, v0
	v_or_b32_e32 v56, s26, v1
	v_or_b32_e32 v54, s27, v0
	v_or_b32_e32 v60, s28, v1
	v_or_b32_e32 v58, s29, v0
	v_or_b32_e32 v72, s30, v1
	v_or_b32_e32 v62, s31, v0
	v_or_b32_e32 v76, s34, v1
	v_or_b32_e32 v74, s35, v0
	v_or_b32_e32 v80, s36, v1
	v_or_b32_e32 v78, s37, v0
	s_cmp_lg_u32 s11, 0
	v_mad_u64_u32 v[46:47], s[20:21], v45, s12, v[2:3]
	v_mad_u64_u32 v[48:49], s[20:21], v43, s12, v[2:3]
	v_mad_u64_u32 v[50:51], s[20:21], v50, s12, v[2:3]
	v_mad_u64_u32 v[52:53], s[20:21], v52, s12, v[2:3]
	v_mad_u64_u32 v[54:55], s[20:21], v54, s12, v[2:3]
	v_mad_u64_u32 v[56:57], s[20:21], v56, s12, v[2:3]
	v_mad_u64_u32 v[58:59], s[20:21], v58, s12, v[2:3]
	v_mad_u64_u32 v[60:61], s[20:21], v60, s12, v[2:3]
	v_mad_u64_u32 v[62:63], s[20:21], v62, s12, v[2:3]
	v_mad_u64_u32 v[72:73], s[20:21], v72, s12, v[2:3]
	v_mad_u64_u32 v[74:75], s[20:21], v74, s12, v[2:3]
	v_mad_u64_u32 v[76:77], s[20:21], v76, s12, v[2:3]
	v_mad_u64_u32 v[78:79], s[20:21], v78, s12, v[2:3]
	v_mad_u64_u32 v[80:81], s[20:21], v80, s12, v[2:3]
	s_waitcnt vmcnt(15)
	ds_write_b32 v42, v41
	s_waitcnt vmcnt(14)
	ds_write_b32 v44, v71
	s_waitcnt vmcnt(13)
	ds_write_b32 v46, v82
	s_waitcnt vmcnt(12)
	ds_write_b32 v48, v83
	s_waitcnt vmcnt(11)
	ds_write_b32 v50, v84
	s_waitcnt vmcnt(10)
	ds_write_b32 v52, v85
	s_waitcnt vmcnt(9)
	ds_write_b32 v54, v86
	s_waitcnt vmcnt(8)
	ds_write_b32 v56, v87
	s_waitcnt vmcnt(7)
	ds_write_b32 v58, v88
	s_waitcnt vmcnt(6)
	ds_write_b32 v60, v89
	s_waitcnt vmcnt(5)
	ds_write_b32 v62, v90
	s_waitcnt vmcnt(4)
	ds_write_b32 v72, v91
	s_waitcnt vmcnt(3)
	ds_write_b32 v74, v4
	s_waitcnt vmcnt(2)
	ds_write_b32 v76, v92
	s_waitcnt vmcnt(1)
	ds_write_b32 v78, v93
	s_waitcnt vmcnt(0)
	ds_write_b32 v80, v94
	s_cbranch_scc1 .LBB0_105
	s_waitcnt lgkmcnt(0)
	ds_read2_b32 v[42:43], v66 offset0:33 offset1:41
	ds_read2_b32 v[44:45], v66 offset1:8
	ds_read2_b32 v[46:47], v66 offset0:66 offset1:74
	ds_read2_b32 v[48:49], v66 offset0:99 offset1:107
	ds_read2_b32 v[50:51], v66 offset0:132 offset1:140
	ds_read2_b32 v[52:53], v66 offset0:165 offset1:173
	ds_read2_b32 v[54:55], v66 offset0:198 offset1:206
	ds_read2_b32 v[56:57], v66 offset0:231 offset1:239
	v_or_b32_e32 v3, s0, v65
	s_lshl_b32 s4, s1, 1
	v_mul_u32_u24_e32 v3, 0xb00, v3
	v_lshl_add_u64 v[58:59], v[6:7], 0, s[4:5]
	v_lshlrev_b32_e32 v4, 1, v3
	s_waitcnt lgkmcnt(6)
	v_cvt_pk_bf16_f32 v38, v44, v42
	s_waitcnt lgkmcnt(4)
	v_cvt_pk_bf16_f32 v39, v46, v48
	s_waitcnt lgkmcnt(2)
	v_cvt_pk_bf16_f32 v40, v50, v52
	s_waitcnt lgkmcnt(0)
	v_cvt_pk_bf16_f32 v41, v54, v56
	v_lshl_add_u64 v[60:61], v[58:59], 0, v[4:5]
	global_store_dwordx4 v[60:61], v[38:41], off sc1
	v_or_b32_e32 v3, s0, v67
	v_mul_u32_u24_e32 v3, 0xb00, v3
	v_cvt_pk_bf16_f32 v38, v45, v43
	v_cvt_pk_bf16_f32 v39, v47, v49
	v_cvt_pk_bf16_f32 v40, v51, v53
	v_cvt_pk_bf16_f32 v41, v55, v57
	ds_read2_b32 v[44:45], v66 offset0:16 offset1:24
	ds_read2_b32 v[46:47], v66 offset0:49 offset1:57
	ds_read2_b32 v[48:49], v66 offset0:82 offset1:90
	ds_read2_b32 v[50:51], v66 offset0:115 offset1:123
	ds_read2_b32 v[52:53], v66 offset0:148 offset1:156
	ds_read2_b32 v[54:55], v66 offset0:181 offset1:189
	ds_read2_b32 v[56:57], v66 offset0:214 offset1:222
	ds_read2_b32 v[60:61], v66 offset0:247 offset1:255
	v_lshlrev_b32_e32 v4, 1, v3
	v_or_b32_e32 v3, s0, v68
	v_mul_u32_u24_e32 v3, 0xb00, v3
	v_lshl_add_u64 v[42:43], v[58:59], 0, v[4:5]
	v_lshlrev_b32_e32 v4, 1, v3
	v_or_b32_e32 v3, s0, v69
	v_mul_u32_u24_e32 v3, 0xb00, v3
	global_store_dwordx4 v[42:43], v[38:41], off sc1
	v_lshl_add_u64 v[42:43], v[58:59], 0, v[4:5]
	v_lshlrev_b32_e32 v4, 1, v3
	s_waitcnt lgkmcnt(6)
	v_cvt_pk_bf16_f32 v38, v44, v46
	s_waitcnt lgkmcnt(4)
	v_cvt_pk_bf16_f32 v39, v48, v50
	s_waitcnt lgkmcnt(2)
	v_cvt_pk_bf16_f32 v40, v52, v54
	s_waitcnt lgkmcnt(0)
	v_cvt_pk_bf16_f32 v41, v56, v60
	global_store_dwordx4 v[42:43], v[38:41], off sc1
	v_lshl_add_u64 v[42:43], v[58:59], 0, v[4:5]
	s_mov_b64 s[0:1], 0
	v_cvt_pk_bf16_f32 v38, v45, v47
	v_cvt_pk_bf16_f32 v39, v49, v51
	v_cvt_pk_bf16_f32 v40, v53, v55
	v_cvt_pk_bf16_f32 v41, v57, v61
	global_store_dwordx4 v[42:43], v[38:41], off sc1
	s_waitcnt lgkmcnt(0)

.LBB0_109:
	s_lshl_b32 s22, s4, 1
	s_lshl_b32 s23, s10, 1
	v_or_b32_e32 v40, s23, v4
	s_add_i32 s24, s22, 4
	s_add_i32 s25, s23, 4
	s_add_i32 s26, s22, 8
	s_add_i32 s27, s23, 8
	s_add_i32 s28, s22, 12
	s_add_i32 s29, s23, 12
	s_add_i32 s30, s22, 16
	s_add_i32 s31, s23, 16
	s_add_i32 s34, s22, 20
	s_add_i32 s35, s23, 20
	s_add_i32 s36, s22, 24
	s_add_i32 s37, s23, 24
	s_add_i32 s38, s22, 28
	s_add_i32 s39, s23, 28
	v_or_b32_e32 v42, s22, v3
	v_mad_u64_u32 v[40:41], s[20:21], v40, s13, v[38:39]
	v_or_b32_e32 v46, s24, v3
	v_or_b32_e32 v44, s25, v4
	v_or_b32_e32 v50, s26, v3
	v_or_b32_e32 v48, s27, v4
	v_or_b32_e32 v54, s28, v3
	v_or_b32_e32 v52, s29, v4
	v_or_b32_e32 v58, s30, v3
	v_or_b32_e32 v56, s31, v4
	v_or_b32_e32 v62, s34, v3
	v_or_b32_e32 v60, s35, v4
	v_or_b32_e32 v71, s36, v3
	v_or_b32_e32 v72, s37, v4
	v_or_b32_e32 v78, s38, v3
	v_or_b32_e32 v76, s39, v4
	v_mad_u64_u32 v[42:43], s[20:21], v42, s13, v[38:39]
	v_mad_u64_u32 v[44:45], s[20:21], v44, s13, v[38:39]
	v_mad_u64_u32 v[46:47], s[20:21], v46, s13, v[38:39]
	v_mad_u64_u32 v[48:49], s[20:21], v48, s13, v[38:39]
	v_mad_u64_u32 v[50:51], s[20:21], v50, s13, v[38:39]
	v_mad_u64_u32 v[52:53], s[20:21], v52, s13, v[38:39]
	v_mad_u64_u32 v[54:55], s[20:21], v54, s13, v[38:39]
	v_mad_u64_u32 v[56:57], s[20:21], v56, s13, v[38:39]
	v_mad_u64_u32 v[58:59], s[20:21], v58, s13, v[38:39]
	v_mad_u64_u32 v[60:61], s[20:21], v60, s13, v[38:39]
	v_mad_u64_u32 v[62:63], s[20:21], v62, s13, v[38:39]
	v_mad_u64_u32 v[72:73], s[20:21], v72, s13, v[38:39]
	v_mad_u64_u32 v[74:75], s[20:21], v71, s13, v[38:39]
	v_mad_u64_u32 v[76:77], s[20:21], v76, s13, v[38:39]
	v_mad_u64_u32 v[78:79], s[20:21], v78, s13, v[38:39]
	global_load_dword v71, v[40:41], off
	global_load_dword v80, v[42:43], off
	global_load_dword v81, v[44:45], off
	global_load_dword v82, v[46:47], off
	global_load_dword v83, v[48:49], off
	global_load_dword v84, v[50:51], off
	global_load_dword v85, v[52:53], off
	global_load_dword v86, v[54:55], off
	global_load_dword v87, v[56:57], off
	global_load_dword v88, v[58:59], off
	global_load_dword v89, v[60:61], off
	global_load_dword v90, v[62:63], off
	global_load_dword v91, v[72:73], off
	global_load_dword v92, v[74:75], off
	global_load_dword v93, v[76:77], off
	global_load_dword v94, v[78:79], off
	v_or_b32_e32 v42, s22, v1
	v_or_b32_e32 v40, s23, v0
	s_add_i32 s10, s10, 16
	s_add_i32 s4, s4, 16
	s_add_i32 s11, s11, -16
	v_mad_u64_u32 v[40:41], s[20:21], v40, s12, v[2:3]
	v_mad_u64_u32 v[42:43], s[20:21], v42, s12, v[2:3]
	v_or_b32_e32 v41, s24, v1
	v_or_b32_e32 v43, s25, v0
	v_or_b32_e32 v50, s26, v1
	v_or_b32_e32 v48, s27, v0
	v_or_b32_e32 v54, s28, v1
	v_or_b32_e32 v52, s29, v0
	v_or_b32_e32 v58, s30, v1
	v_or_b32_e32 v56, s31, v0
	v_or_b32_e32 v62, s34, v1
	v_or_b32_e32 v60, s35, v0
	v_or_b32_e32 v74, s36, v1
	v_or_b32_e32 v72, s37, v0
	v_or_b32_e32 v78, s38, v1
	v_or_b32_e32 v76, s39, v0
	s_cmp_lg_u32 s11, 0
	v_mad_u64_u32 v[44:45], s[20:21], v43, s12, v[2:3]
	v_mad_u64_u32 v[46:47], s[20:21], v41, s12, v[2:3]
	v_mad_u64_u32 v[48:49], s[20:21], v48, s12, v[2:3]
	v_mad_u64_u32 v[50:51], s[20:21], v50, s12, v[2:3]
	v_mad_u64_u32 v[52:53], s[20:21], v52, s12, v[2:3]
	v_mad_u64_u32 v[54:55], s[20:21], v54, s12, v[2:3]
	v_mad_u64_u32 v[56:57], s[20:21], v56, s12, v[2:3]
	v_mad_u64_u32 v[58:59], s[20:21], v58, s12, v[2:3]
	v_mad_u64_u32 v[60:61], s[20:21], v60, s12, v[2:3]
	v_mad_u64_u32 v[62:63], s[20:21], v62, s12, v[2:3]
	v_mad_u64_u32 v[72:73], s[20:21], v72, s12, v[2:3]
	v_mad_u64_u32 v[74:75], s[20:21], v74, s12, v[2:3]
	v_mad_u64_u32 v[76:77], s[20:21], v76, s12, v[2:3]
	v_mad_u64_u32 v[78:79], s[20:21], v78, s12, v[2:3]
	s_waitcnt vmcnt(15)
	ds_write_b32 v40, v71
	s_waitcnt vmcnt(14)
	ds_write_b32 v42, v80
	s_waitcnt vmcnt(13)
	ds_write_b32 v44, v81
	s_waitcnt vmcnt(12)
	ds_write_b32 v46, v82
	s_waitcnt vmcnt(11)
	ds_write_b32 v48, v83
	s_waitcnt vmcnt(10)
	ds_write_b32 v50, v84
	s_waitcnt vmcnt(9)
	ds_write_b32 v52, v85
	s_waitcnt vmcnt(8)
	ds_write_b32 v54, v86
	s_waitcnt vmcnt(7)
	ds_write_b32 v56, v87
	s_waitcnt vmcnt(6)
	ds_write_b32 v58, v88
	s_waitcnt vmcnt(5)
	ds_write_b32 v60, v89
	s_waitcnt vmcnt(4)
	ds_write_b32 v62, v90
	s_waitcnt vmcnt(3)
	ds_write_b32 v72, v91
	s_waitcnt vmcnt(2)
	ds_write_b32 v74, v92
	s_waitcnt vmcnt(1)
	ds_write_b32 v76, v93
	s_waitcnt vmcnt(0)
	ds_write_b32 v78, v94
	s_cbranch_scc1 .LBB0_109
	s_waitcnt lgkmcnt(0)
	ds_read2_b32 v[42:43], v66 offset0:33 offset1:41
	ds_read2_b32 v[44:45], v66 offset1:8
	ds_read2_b32 v[46:47], v66 offset0:66 offset1:74
	ds_read2_b32 v[48:49], v66 offset0:99 offset1:107
	ds_read2_b32 v[50:51], v66 offset0:132 offset1:140
	ds_read2_b32 v[52:53], v66 offset0:165 offset1:173
	ds_read2_b32 v[54:55], v66 offset0:198 offset1:206
	ds_read2_b32 v[56:57], v66 offset0:231 offset1:239
	s_and_b32 s1, 0xffff, s1
	s_and_b32 s0, 0xffff, s0
	s_lshl_b32 s4, s0, 1
	v_or_b32_e32 v3, s1, v65
	v_lshl_add_u64 v[58:59], v[8:9], 0, s[4:5]
	v_lshlrev_b32_e32 v4, 11, v3
	s_waitcnt lgkmcnt(6)
	v_cvt_pk_bf16_f32 v38, v44, v42
	s_waitcnt lgkmcnt(4)
	v_cvt_pk_bf16_f32 v39, v46, v48
	s_waitcnt lgkmcnt(2)
	v_cvt_pk_bf16_f32 v40, v50, v52
	s_waitcnt lgkmcnt(0)
	v_cvt_pk_bf16_f32 v41, v54, v56
	v_lshl_add_u64 v[60:61], v[58:59], 0, v[4:5]
	global_store_dwordx4 v[60:61], v[38:41], off sc1
	v_or_b32_e32 v3, s1, v67
	v_lshlrev_b32_e32 v4, 11, v3
	v_cvt_pk_bf16_f32 v38, v45, v43
	v_cvt_pk_bf16_f32 v39, v47, v49
	v_cvt_pk_bf16_f32 v40, v51, v53
	v_cvt_pk_bf16_f32 v41, v55, v57
	ds_read2_b32 v[44:45], v66 offset0:49 offset1:57
	ds_read2_b32 v[46:47], v66 offset0:16 offset1:24
	ds_read2_b32 v[48:49], v66 offset0:82 offset1:90
	ds_read2_b32 v[50:51], v66 offset0:115 offset1:123
	ds_read2_b32 v[52:53], v66 offset0:148 offset1:156
	ds_read2_b32 v[54:55], v66 offset0:181 offset1:189
	ds_read2_b32 v[56:57], v66 offset0:214 offset1:222
	ds_read2_b32 v[60:61], v66 offset0:247 offset1:255
	v_or_b32_e32 v3, s1, v68
	v_lshl_add_u64 v[42:43], v[58:59], 0, v[4:5]
	v_lshlrev_b32_e32 v4, 11, v3
	v_or_b32_e32 v3, s1, v69
	global_store_dwordx4 v[42:43], v[38:41], off sc1
	v_lshl_add_u64 v[42:43], v[58:59], 0, v[4:5]
	v_lshlrev_b32_e32 v4, 11, v3
	s_waitcnt lgkmcnt(6)
	v_cvt_pk_bf16_f32 v38, v46, v44
	s_waitcnt lgkmcnt(4)
	v_cvt_pk_bf16_f32 v39, v48, v50
	s_waitcnt lgkmcnt(2)
	v_cvt_pk_bf16_f32 v40, v52, v54
	s_waitcnt lgkmcnt(0)
	v_cvt_pk_bf16_f32 v41, v56, v60
	global_store_dwordx4 v[42:43], v[38:41], off sc1
	v_lshl_add_u64 v[42:43], v[58:59], 0, v[4:5]
	s_nop 0
	v_cvt_pk_bf16_f32 v38, v47, v45
	v_cvt_pk_bf16_f32 v39, v49, v51
	v_cvt_pk_bf16_f32 v40, v53, v55
	v_cvt_pk_bf16_f32 v41, v57, v61
	global_store_dwordx4 v[42:43], v[38:41], off sc1
	s_waitcnt lgkmcnt(0)

.LBB0_114:
	s_lshl_b32 s20, s10, 1
	s_lshl_b32 s21, s4, 1
	v_or_b32_e32 v4, s21, v40
	s_add_i32 s22, s20, 4
	s_add_i32 s23, s21, 4
	v_mov_b32_e32 v45, v5
	s_add_i32 s25, s21, 8
	v_lshlrev_b64 v[58:59], 12, v[4:5]
	v_or_b32_e32 v44, s22, v3
	v_or_b32_e32 v4, s23, v40
	v_mov_b32_e32 v43, v5
	v_or_b32_e32 v42, s20, v3
	s_add_i32 s27, s21, 12
	v_lshlrev_b64 v[44:45], 12, v[44:45]
	v_lshlrev_b64 v[60:61], 12, v[4:5]
	v_or_b32_e32 v4, s25, v40
	s_add_i32 s24, s20, 8
	s_add_i32 s26, s20, 12
	s_add_i32 s29, s21, 16
	v_lshlrev_b64 v[42:43], 12, v[42:43]
	v_lshl_add_u64 v[58:59], v[38:39], 0, v[58:59]
	v_lshl_add_u64 v[44:45], v[38:39], 0, v[44:45]
	v_lshlrev_b64 v[62:63], 12, v[4:5]
	v_or_b32_e32 v4, s27, v40
	v_mov_b32_e32 v47, v5
	v_mov_b32_e32 v49, v5
	s_add_i32 s31, s21, 20
	v_or_b32_e32 v46, s24, v3
	v_or_b32_e32 v48, s26, v3
	v_lshl_add_u64 v[42:43], v[38:39], 0, v[42:43]
	v_lshl_add_u64 v[60:61], v[38:39], 0, v[60:61]
	global_load_dword v41, v[58:59], off
	global_load_dword v71, v[42:43], off
	global_load_dword v82, v[60:61], off
	global_load_dword v83, v[44:45], off
	v_lshlrev_b64 v[44:45], 12, v[4:5]
	v_or_b32_e32 v4, s29, v40
	s_add_i32 s28, s20, 16
	s_add_i32 s30, s20, 20
	s_add_i32 s35, s21, 24
	v_lshlrev_b64 v[46:47], 12, v[46:47]
	v_lshlrev_b64 v[48:49], 12, v[48:49]
	v_lshl_add_u64 v[42:43], v[38:39], 0, v[62:63]
	v_lshl_add_u64 v[44:45], v[38:39], 0, v[44:45]
	v_lshlrev_b64 v[58:59], 12, v[4:5]
	v_or_b32_e32 v4, s31, v40
	v_mov_b32_e32 v51, v5
	v_mov_b32_e32 v53, v5
	s_add_i32 s34, s20, 24
	s_add_i32 s36, s20, 28
	s_add_i32 s37, s21, 28
	v_or_b32_e32 v50, s28, v3
	v_or_b32_e32 v52, s30, v3
	v_lshl_add_u64 v[46:47], v[38:39], 0, v[46:47]
	v_lshl_add_u64 v[48:49], v[38:39], 0, v[48:49]
	global_load_dword v84, v[42:43], off
	global_load_dword v85, v[46:47], off
	global_load_dword v86, v[44:45], off
	global_load_dword v87, v[48:49], off
	v_lshlrev_b64 v[44:45], 12, v[4:5]
	v_or_b32_e32 v4, s35, v40
	v_mov_b32_e32 v55, v5
	v_mov_b32_e32 v57, v5
	v_or_b32_e32 v54, s34, v3
	v_or_b32_e32 v56, s36, v3
	v_lshlrev_b64 v[50:51], 12, v[50:51]
	v_lshlrev_b64 v[52:53], 12, v[52:53]
	v_lshl_add_u64 v[42:43], v[38:39], 0, v[58:59]
	v_lshl_add_u64 v[44:45], v[38:39], 0, v[44:45]
	v_lshlrev_b64 v[46:47], 12, v[4:5]
	v_or_b32_e32 v4, s37, v40
	v_lshlrev_b64 v[54:55], 12, v[54:55]
	v_lshlrev_b64 v[56:57], 12, v[56:57]
	v_lshl_add_u64 v[50:51], v[38:39], 0, v[50:51]
	v_lshl_add_u64 v[52:53], v[38:39], 0, v[52:53]
	global_load_dword v88, v[42:43], off
	global_load_dword v89, v[50:51], off
	global_load_dword v90, v[44:45], off
	global_load_dword v91, v[52:53], off
	v_lshl_add_u64 v[42:43], v[38:39], 0, v[46:47]
	v_lshlrev_b64 v[44:45], 12, v[4:5]
	v_lshl_add_u64 v[54:55], v[38:39], 0, v[54:55]
	v_lshl_add_u64 v[56:57], v[38:39], 0, v[56:57]
	v_lshl_add_u64 v[44:45], v[38:39], 0, v[44:45]
	global_load_dword v4, v[42:43], off
	global_load_dword v92, v[54:55], off
	global_load_dword v93, v[44:45], off
	global_load_dword v94, v[56:57], off
	v_or_b32_e32 v44, s20, v1
	v_or_b32_e32 v42, s21, v0
	s_add_i32 s4, s4, 16
	s_add_i32 s10, s10, 16
	s_add_i32 s11, s11, -16
	v_mad_u64_u32 v[42:43], s[20:21], v42, s12, v[2:3]
	v_mad_u64_u32 v[44:45], s[20:21], v44, s12, v[2:3]
	v_or_b32_e32 v43, s22, v1
	v_or_b32_e32 v45, s23, v0
	v_or_b32_e32 v52, s24, v1
	v_or_b32_e32 v50, s25, v0
	v_or_b32_e32 v56, s26, v1
	v_or_b32_e32 v54, s27, v0
	v_or_b32_e32 v60, s28, v1
	v_or_b32_e32 v58, s29, v0
	v_or_b32_e32 v72, s30, v1
	v_or_b32_e32 v62, s31, v0
	v_or_b32_e32 v76, s34, v1
	v_or_b32_e32 v74, s35, v0
	v_or_b32_e32 v80, s36, v1
	v_or_b32_e32 v78, s37, v0
	s_cmp_lg_u32 s11, 0
	v_mad_u64_u32 v[46:47], s[20:21], v45, s12, v[2:3]
	v_mad_u64_u32 v[48:49], s[20:21], v43, s12, v[2:3]
	v_mad_u64_u32 v[50:51], s[20:21], v50, s12, v[2:3]
	v_mad_u64_u32 v[52:53], s[20:21], v52, s12, v[2:3]
	v_mad_u64_u32 v[54:55], s[20:21], v54, s12, v[2:3]
	v_mad_u64_u32 v[56:57], s[20:21], v56, s12, v[2:3]
	v_mad_u64_u32 v[58:59], s[20:21], v58, s12, v[2:3]
	v_mad_u64_u32 v[60:61], s[20:21], v60, s12, v[2:3]
	v_mad_u64_u32 v[62:63], s[20:21], v62, s12, v[2:3]
	v_mad_u64_u32 v[72:73], s[20:21], v72, s12, v[2:3]
	v_mad_u64_u32 v[74:75], s[20:21], v74, s12, v[2:3]
	v_mad_u64_u32 v[76:77], s[20:21], v76, s12, v[2:3]
	v_mad_u64_u32 v[78:79], s[20:21], v78, s12, v[2:3]
	v_mad_u64_u32 v[80:81], s[20:21], v80, s12, v[2:3]
	s_waitcnt vmcnt(15)
	ds_write_b32 v42, v41
	s_waitcnt vmcnt(14)
	ds_write_b32 v44, v71
	s_waitcnt vmcnt(13)
	ds_write_b32 v46, v82
	s_waitcnt vmcnt(12)
	ds_write_b32 v48, v83
	s_waitcnt vmcnt(11)
	ds_write_b32 v50, v84
	s_waitcnt vmcnt(10)
	ds_write_b32 v52, v85
	s_waitcnt vmcnt(9)
	ds_write_b32 v54, v86
	s_waitcnt vmcnt(8)
	ds_write_b32 v56, v87
	s_waitcnt vmcnt(7)
	ds_write_b32 v58, v88
	s_waitcnt vmcnt(6)
	ds_write_b32 v60, v89
	s_waitcnt vmcnt(5)
	ds_write_b32 v62, v90
	s_waitcnt vmcnt(4)
	ds_write_b32 v72, v91
	s_waitcnt vmcnt(3)
	ds_write_b32 v74, v4
	s_waitcnt vmcnt(2)
	ds_write_b32 v76, v92
	s_waitcnt vmcnt(1)
	ds_write_b32 v78, v93
	s_waitcnt vmcnt(0)
	ds_write_b32 v80, v94
	s_cbranch_scc1 .LBB0_114
	s_waitcnt lgkmcnt(0)
	ds_read2_b32 v[42:43], v66 offset0:33 offset1:41
	ds_read2_b32 v[44:45], v66 offset1:8
	ds_read2_b32 v[46:47], v66 offset0:66 offset1:74
	ds_read2_b32 v[48:49], v66 offset0:99 offset1:107
	ds_read2_b32 v[50:51], v66 offset0:132 offset1:140
	ds_read2_b32 v[52:53], v66 offset0:165 offset1:173
	ds_read2_b32 v[54:55], v66 offset0:198 offset1:206
	ds_read2_b32 v[56:57], v66 offset0:231 offset1:239
	s_lshl_b32 s4, s1, 1
	v_or_b32_e32 v3, s0, v65
	v_lshl_add_u64 v[58:59], v[10:11], 0, s[4:5]
	v_lshlrev_b32_e32 v4, 11, v3
	s_waitcnt lgkmcnt(6)
	v_cvt_pk_bf16_f32 v38, v44, v42
	s_waitcnt lgkmcnt(4)
	v_cvt_pk_bf16_f32 v39, v46, v48
	s_waitcnt lgkmcnt(2)
	v_cvt_pk_bf16_f32 v40, v50, v52
	s_waitcnt lgkmcnt(0)
	v_cvt_pk_bf16_f32 v41, v54, v56
	v_lshl_add_u64 v[60:61], v[58:59], 0, v[4:5]
	global_store_dwordx4 v[60:61], v[38:41], off sc1
	v_or_b32_e32 v3, s0, v67
	v_lshlrev_b32_e32 v4, 11, v3
	v_cvt_pk_bf16_f32 v38, v45, v43
	v_cvt_pk_bf16_f32 v39, v47, v49
	v_cvt_pk_bf16_f32 v40, v51, v53
	v_cvt_pk_bf16_f32 v41, v55, v57
	ds_read2_b32 v[44:45], v66 offset0:49 offset1:57
	ds_read2_b32 v[46:47], v66 offset0:16 offset1:24
	ds_read2_b32 v[48:49], v66 offset0:82 offset1:90
	ds_read2_b32 v[50:51], v66 offset0:115 offset1:123
	ds_read2_b32 v[52:53], v66 offset0:148 offset1:156
	ds_read2_b32 v[54:55], v66 offset0:181 offset1:189
	ds_read2_b32 v[56:57], v66 offset0:214 offset1:222
	ds_read2_b32 v[60:61], v66 offset0:247 offset1:255
	v_or_b32_e32 v3, s0, v68
	v_lshl_add_u64 v[42:43], v[58:59], 0, v[4:5]
	v_lshlrev_b32_e32 v4, 11, v3
	v_or_b32_e32 v3, s0, v69
	global_store_dwordx4 v[42:43], v[38:41], off sc1
	v_lshl_add_u64 v[42:43], v[58:59], 0, v[4:5]
	v_lshlrev_b32_e32 v4, 11, v3
	s_waitcnt lgkmcnt(6)
	v_cvt_pk_bf16_f32 v38, v46, v44
	s_waitcnt lgkmcnt(4)
	v_cvt_pk_bf16_f32 v39, v48, v50
	s_waitcnt lgkmcnt(2)
	v_cvt_pk_bf16_f32 v40, v52, v54
	s_waitcnt lgkmcnt(0)
	v_cvt_pk_bf16_f32 v41, v56, v60
	global_store_dwordx4 v[42:43], v[38:41], off sc1
	v_lshl_add_u64 v[42:43], v[58:59], 0, v[4:5]
	s_nop 0
	v_cvt_pk_bf16_f32 v38, v47, v45
	v_cvt_pk_bf16_f32 v39, v49, v51
	v_cvt_pk_bf16_f32 v40, v53, v55
	v_cvt_pk_bf16_f32 v41, v57, v61
	global_store_dwordx4 v[42:43], v[38:41], off sc1
	s_waitcnt lgkmcnt(0)

.LBB0_119:
	s_lshl_b32 s20, s10, 1
	s_lshl_b32 s21, s4, 1
	v_or_b32_e32 v4, s21, v40
	s_add_i32 s22, s20, 4
	s_add_i32 s23, s21, 4
	v_mov_b32_e32 v45, v5
	s_add_i32 s25, s21, 8
	v_lshlrev_b64 v[58:59], 12, v[4:5]
	v_or_b32_e32 v44, s22, v3
	v_or_b32_e32 v4, s23, v40
	v_mov_b32_e32 v43, v5
	v_or_b32_e32 v42, s20, v3
	s_add_i32 s27, s21, 12
	v_lshlrev_b64 v[44:45], 12, v[44:45]
	v_lshlrev_b64 v[60:61], 12, v[4:5]
	v_or_b32_e32 v4, s25, v40
	s_add_i32 s24, s20, 8
	s_add_i32 s26, s20, 12
	s_add_i32 s29, s21, 16
	v_lshlrev_b64 v[42:43], 12, v[42:43]
	v_lshl_add_u64 v[58:59], v[38:39], 0, v[58:59]
	v_lshl_add_u64 v[44:45], v[38:39], 0, v[44:45]
	v_lshlrev_b64 v[62:63], 12, v[4:5]
	v_or_b32_e32 v4, s27, v40
	v_mov_b32_e32 v47, v5
	v_mov_b32_e32 v49, v5
	s_add_i32 s31, s21, 20
	v_or_b32_e32 v46, s24, v3
	v_or_b32_e32 v48, s26, v3
	v_lshl_add_u64 v[42:43], v[38:39], 0, v[42:43]
	v_lshl_add_u64 v[60:61], v[38:39], 0, v[60:61]
	global_load_dword v41, v[58:59], off
	global_load_dword v71, v[42:43], off
	global_load_dword v82, v[60:61], off
	global_load_dword v83, v[44:45], off
	v_lshlrev_b64 v[44:45], 12, v[4:5]
	v_or_b32_e32 v4, s29, v40
	s_add_i32 s28, s20, 16
	s_add_i32 s30, s20, 20
	s_add_i32 s35, s21, 24
	v_lshlrev_b64 v[46:47], 12, v[46:47]
	v_lshlrev_b64 v[48:49], 12, v[48:49]
	v_lshl_add_u64 v[42:43], v[38:39], 0, v[62:63]
	v_lshl_add_u64 v[44:45], v[38:39], 0, v[44:45]
	v_lshlrev_b64 v[58:59], 12, v[4:5]
	v_or_b32_e32 v4, s31, v40
	v_mov_b32_e32 v51, v5
	v_mov_b32_e32 v53, v5
	s_add_i32 s34, s20, 24
	s_add_i32 s36, s20, 28
	s_add_i32 s37, s21, 28
	v_or_b32_e32 v50, s28, v3
	v_or_b32_e32 v52, s30, v3
	v_lshl_add_u64 v[46:47], v[38:39], 0, v[46:47]
	v_lshl_add_u64 v[48:49], v[38:39], 0, v[48:49]
	global_load_dword v84, v[42:43], off
	global_load_dword v85, v[46:47], off
	global_load_dword v86, v[44:45], off
	global_load_dword v87, v[48:49], off
	v_lshlrev_b64 v[44:45], 12, v[4:5]
	v_or_b32_e32 v4, s35, v40
	v_mov_b32_e32 v55, v5
	v_mov_b32_e32 v57, v5
	v_or_b32_e32 v54, s34, v3
	v_or_b32_e32 v56, s36, v3
	v_lshlrev_b64 v[50:51], 12, v[50:51]
	v_lshlrev_b64 v[52:53], 12, v[52:53]
	v_lshl_add_u64 v[42:43], v[38:39], 0, v[58:59]
	v_lshl_add_u64 v[44:45], v[38:39], 0, v[44:45]
	v_lshlrev_b64 v[46:47], 12, v[4:5]
	v_or_b32_e32 v4, s37, v40
	v_lshlrev_b64 v[54:55], 12, v[54:55]
	v_lshlrev_b64 v[56:57], 12, v[56:57]
	v_lshl_add_u64 v[50:51], v[38:39], 0, v[50:51]
	v_lshl_add_u64 v[52:53], v[38:39], 0, v[52:53]
	global_load_dword v88, v[42:43], off
	global_load_dword v89, v[50:51], off
	global_load_dword v90, v[44:45], off
	global_load_dword v91, v[52:53], off
	v_lshl_add_u64 v[42:43], v[38:39], 0, v[46:47]
	v_lshlrev_b64 v[44:45], 12, v[4:5]
	v_lshl_add_u64 v[54:55], v[38:39], 0, v[54:55]
	v_lshl_add_u64 v[56:57], v[38:39], 0, v[56:57]
	v_lshl_add_u64 v[44:45], v[38:39], 0, v[44:45]
	global_load_dword v4, v[42:43], off
	global_load_dword v92, v[54:55], off
	global_load_dword v93, v[44:45], off
	global_load_dword v94, v[56:57], off
	v_or_b32_e32 v44, s20, v1
	v_or_b32_e32 v42, s21, v0
	s_add_i32 s4, s4, 16
	s_add_i32 s10, s10, 16
	s_add_i32 s11, s11, -16
	v_mad_u64_u32 v[42:43], s[20:21], v42, s12, v[2:3]
	v_mad_u64_u32 v[44:45], s[20:21], v44, s12, v[2:3]
	v_or_b32_e32 v43, s22, v1
	v_or_b32_e32 v45, s23, v0
	v_or_b32_e32 v52, s24, v1
	v_or_b32_e32 v50, s25, v0
	v_or_b32_e32 v56, s26, v1
	v_or_b32_e32 v54, s27, v0
	v_or_b32_e32 v60, s28, v1
	v_or_b32_e32 v58, s29, v0
	v_or_b32_e32 v72, s30, v1
	v_or_b32_e32 v62, s31, v0
	v_or_b32_e32 v76, s34, v1
	v_or_b32_e32 v74, s35, v0
	v_or_b32_e32 v80, s36, v1
	v_or_b32_e32 v78, s37, v0
	s_cmp_lg_u32 s11, 0
	v_mad_u64_u32 v[46:47], s[20:21], v45, s12, v[2:3]
	v_mad_u64_u32 v[48:49], s[20:21], v43, s12, v[2:3]
	v_mad_u64_u32 v[50:51], s[20:21], v50, s12, v[2:3]
	v_mad_u64_u32 v[52:53], s[20:21], v52, s12, v[2:3]
	v_mad_u64_u32 v[54:55], s[20:21], v54, s12, v[2:3]
	v_mad_u64_u32 v[56:57], s[20:21], v56, s12, v[2:3]
	v_mad_u64_u32 v[58:59], s[20:21], v58, s12, v[2:3]
	v_mad_u64_u32 v[60:61], s[20:21], v60, s12, v[2:3]
	v_mad_u64_u32 v[62:63], s[20:21], v62, s12, v[2:3]
	v_mad_u64_u32 v[72:73], s[20:21], v72, s12, v[2:3]
	v_mad_u64_u32 v[74:75], s[20:21], v74, s12, v[2:3]
	v_mad_u64_u32 v[76:77], s[20:21], v76, s12, v[2:3]
	v_mad_u64_u32 v[78:79], s[20:21], v78, s12, v[2:3]
	v_mad_u64_u32 v[80:81], s[20:21], v80, s12, v[2:3]
	s_waitcnt vmcnt(15)
	ds_write_b32 v42, v41
	s_waitcnt vmcnt(14)
	ds_write_b32 v44, v71
	s_waitcnt vmcnt(13)
	ds_write_b32 v46, v82
	s_waitcnt vmcnt(12)
	ds_write_b32 v48, v83
	s_waitcnt vmcnt(11)
	ds_write_b32 v50, v84
	s_waitcnt vmcnt(10)
	ds_write_b32 v52, v85
	s_waitcnt vmcnt(9)
	ds_write_b32 v54, v86
	s_waitcnt vmcnt(8)
	ds_write_b32 v56, v87
	s_waitcnt vmcnt(7)
	ds_write_b32 v58, v88
	s_waitcnt vmcnt(6)
	ds_write_b32 v60, v89
	s_waitcnt vmcnt(5)
	ds_write_b32 v62, v90
	s_waitcnt vmcnt(4)
	ds_write_b32 v72, v91
	s_waitcnt vmcnt(3)
	ds_write_b32 v74, v4
	s_waitcnt vmcnt(2)
	ds_write_b32 v76, v92
	s_waitcnt vmcnt(1)
	ds_write_b32 v78, v93
	s_waitcnt vmcnt(0)
	ds_write_b32 v80, v94
	s_cbranch_scc1 .LBB0_119
	s_waitcnt lgkmcnt(0)
	ds_read2_b32 v[42:43], v66 offset0:33 offset1:41
	ds_read2_b32 v[44:45], v66 offset1:8
	ds_read2_b32 v[46:47], v66 offset0:66 offset1:74
	ds_read2_b32 v[48:49], v66 offset0:99 offset1:107
	ds_read2_b32 v[50:51], v66 offset0:132 offset1:140
	ds_read2_b32 v[52:53], v66 offset0:165 offset1:173
	ds_read2_b32 v[54:55], v66 offset0:198 offset1:206
	ds_read2_b32 v[56:57], v66 offset0:231 offset1:239
	s_lshl_b32 s4, s1, 1
	v_or_b32_e32 v3, s0, v65
	v_lshl_add_u64 v[58:59], v[12:13], 0, s[4:5]
	v_lshlrev_b32_e32 v4, 10, v3
	s_waitcnt lgkmcnt(6)
	v_cvt_pk_bf16_f32 v38, v44, v42
	s_waitcnt lgkmcnt(4)
	v_cvt_pk_bf16_f32 v39, v46, v48
	s_waitcnt lgkmcnt(2)
	v_cvt_pk_bf16_f32 v40, v50, v52
	s_waitcnt lgkmcnt(0)
	v_cvt_pk_bf16_f32 v41, v54, v56
	v_lshl_add_u64 v[60:61], v[58:59], 0, v[4:5]
	global_store_dwordx4 v[60:61], v[38:41], off sc1
	v_or_b32_e32 v3, s0, v67
	v_lshlrev_b32_e32 v4, 10, v3
	v_cvt_pk_bf16_f32 v38, v45, v43
	v_cvt_pk_bf16_f32 v39, v47, v49
	v_cvt_pk_bf16_f32 v40, v51, v53
	v_cvt_pk_bf16_f32 v41, v55, v57
	ds_read2_b32 v[44:45], v66 offset0:49 offset1:57
	ds_read2_b32 v[46:47], v66 offset0:16 offset1:24
	ds_read2_b32 v[48:49], v66 offset0:82 offset1:90
	ds_read2_b32 v[50:51], v66 offset0:115 offset1:123
	ds_read2_b32 v[52:53], v66 offset0:148 offset1:156
	ds_read2_b32 v[54:55], v66 offset0:181 offset1:189
	ds_read2_b32 v[56:57], v66 offset0:214 offset1:222
	ds_read2_b32 v[60:61], v66 offset0:247 offset1:255
	v_or_b32_e32 v3, s0, v68
	v_lshl_add_u64 v[42:43], v[58:59], 0, v[4:5]
	v_lshlrev_b32_e32 v4, 10, v3
	v_or_b32_e32 v3, s0, v69
	global_store_dwordx4 v[42:43], v[38:41], off sc1
	v_lshl_add_u64 v[42:43], v[58:59], 0, v[4:5]
	v_lshlrev_b32_e32 v4, 10, v3
	s_waitcnt lgkmcnt(6)
	v_cvt_pk_bf16_f32 v38, v46, v44
	s_waitcnt lgkmcnt(4)
	v_cvt_pk_bf16_f32 v39, v48, v50
	s_waitcnt lgkmcnt(2)
	v_cvt_pk_bf16_f32 v40, v52, v54
	s_waitcnt lgkmcnt(0)
	v_cvt_pk_bf16_f32 v41, v56, v60
	global_store_dwordx4 v[42:43], v[38:41], off sc1
	v_lshl_add_u64 v[42:43], v[58:59], 0, v[4:5]
	s_nop 0
	v_cvt_pk_bf16_f32 v38, v47, v45
	v_cvt_pk_bf16_f32 v39, v49, v51
	v_cvt_pk_bf16_f32 v40, v53, v55
	v_cvt_pk_bf16_f32 v41, v57, v61
	global_store_dwordx4 v[42:43], v[38:41], off sc1
	s_waitcnt lgkmcnt(0)

.LBB0_124:
	s_lshl_b32 s20, s10, 1
	s_lshl_b32 s21, s4, 1
	v_or_b32_e32 v4, s21, v40
	s_add_i32 s22, s20, 4
	s_add_i32 s23, s21, 4
	v_mov_b32_e32 v45, v5
	s_add_i32 s25, s21, 8
	v_lshlrev_b64 v[58:59], 12, v[4:5]
	v_or_b32_e32 v44, s22, v3
	v_or_b32_e32 v4, s23, v40
	v_mov_b32_e32 v43, v5
	v_or_b32_e32 v42, s20, v3
	s_add_i32 s27, s21, 12
	v_lshlrev_b64 v[44:45], 12, v[44:45]
	v_lshlrev_b64 v[60:61], 12, v[4:5]
	v_or_b32_e32 v4, s25, v40
	s_add_i32 s24, s20, 8
	s_add_i32 s26, s20, 12
	s_add_i32 s29, s21, 16
	v_lshlrev_b64 v[42:43], 12, v[42:43]
	v_lshl_add_u64 v[58:59], v[38:39], 0, v[58:59]
	v_lshl_add_u64 v[44:45], v[38:39], 0, v[44:45]
	v_lshlrev_b64 v[62:63], 12, v[4:5]
	v_or_b32_e32 v4, s27, v40
	v_mov_b32_e32 v47, v5
	v_mov_b32_e32 v49, v5
	s_add_i32 s31, s21, 20
	v_or_b32_e32 v46, s24, v3
	v_or_b32_e32 v48, s26, v3
	v_lshl_add_u64 v[42:43], v[38:39], 0, v[42:43]
	v_lshl_add_u64 v[60:61], v[38:39], 0, v[60:61]
	global_load_dword v41, v[58:59], off
	global_load_dword v71, v[42:43], off
	global_load_dword v82, v[60:61], off
	global_load_dword v83, v[44:45], off
	v_lshlrev_b64 v[44:45], 12, v[4:5]
	v_or_b32_e32 v4, s29, v40
	s_add_i32 s28, s20, 16
	s_add_i32 s30, s20, 20
	s_add_i32 s35, s21, 24
	v_lshlrev_b64 v[46:47], 12, v[46:47]
	v_lshlrev_b64 v[48:49], 12, v[48:49]
	v_lshl_add_u64 v[42:43], v[38:39], 0, v[62:63]
	v_lshl_add_u64 v[44:45], v[38:39], 0, v[44:45]
	v_lshlrev_b64 v[58:59], 12, v[4:5]
	v_or_b32_e32 v4, s31, v40
	v_mov_b32_e32 v51, v5
	v_mov_b32_e32 v53, v5
	s_add_i32 s34, s20, 24
	s_add_i32 s36, s20, 28
	s_add_i32 s37, s21, 28
	v_or_b32_e32 v50, s28, v3
	v_or_b32_e32 v52, s30, v3
	v_lshl_add_u64 v[46:47], v[38:39], 0, v[46:47]
	v_lshl_add_u64 v[48:49], v[38:39], 0, v[48:49]
	global_load_dword v84, v[42:43], off
	global_load_dword v85, v[46:47], off
	global_load_dword v86, v[44:45], off
	global_load_dword v87, v[48:49], off
	v_lshlrev_b64 v[44:45], 12, v[4:5]
	v_or_b32_e32 v4, s35, v40
	v_mov_b32_e32 v55, v5
	v_mov_b32_e32 v57, v5
	v_or_b32_e32 v54, s34, v3
	v_or_b32_e32 v56, s36, v3
	v_lshlrev_b64 v[50:51], 12, v[50:51]
	v_lshlrev_b64 v[52:53], 12, v[52:53]
	v_lshl_add_u64 v[42:43], v[38:39], 0, v[58:59]
	v_lshl_add_u64 v[44:45], v[38:39], 0, v[44:45]
	v_lshlrev_b64 v[46:47], 12, v[4:5]
	v_or_b32_e32 v4, s37, v40
	v_lshlrev_b64 v[54:55], 12, v[54:55]
	v_lshlrev_b64 v[56:57], 12, v[56:57]
	v_lshl_add_u64 v[50:51], v[38:39], 0, v[50:51]
	v_lshl_add_u64 v[52:53], v[38:39], 0, v[52:53]
	global_load_dword v88, v[42:43], off
	global_load_dword v89, v[50:51], off
	global_load_dword v90, v[44:45], off
	global_load_dword v91, v[52:53], off
	v_lshl_add_u64 v[42:43], v[38:39], 0, v[46:47]
	v_lshlrev_b64 v[44:45], 12, v[4:5]
	v_lshl_add_u64 v[54:55], v[38:39], 0, v[54:55]
	v_lshl_add_u64 v[56:57], v[38:39], 0, v[56:57]
	v_lshl_add_u64 v[44:45], v[38:39], 0, v[44:45]
	global_load_dword v4, v[42:43], off
	global_load_dword v92, v[54:55], off
	global_load_dword v93, v[44:45], off
	global_load_dword v94, v[56:57], off
	v_or_b32_e32 v44, s20, v1
	v_or_b32_e32 v42, s21, v0
	s_add_i32 s4, s4, 16
	s_add_i32 s10, s10, 16
	s_add_i32 s11, s11, -16
	v_mad_u64_u32 v[42:43], s[20:21], v42, s12, v[2:3]
	v_mad_u64_u32 v[44:45], s[20:21], v44, s12, v[2:3]
	v_or_b32_e32 v43, s22, v1
	v_or_b32_e32 v45, s23, v0
	v_or_b32_e32 v52, s24, v1
	v_or_b32_e32 v50, s25, v0
	v_or_b32_e32 v56, s26, v1
	v_or_b32_e32 v54, s27, v0
	v_or_b32_e32 v60, s28, v1
	v_or_b32_e32 v58, s29, v0
	v_or_b32_e32 v72, s30, v1
	v_or_b32_e32 v62, s31, v0
	v_or_b32_e32 v76, s34, v1
	v_or_b32_e32 v74, s35, v0
	v_or_b32_e32 v80, s36, v1
	v_or_b32_e32 v78, s37, v0
	s_cmp_lg_u32 s11, 0
	v_mad_u64_u32 v[46:47], s[20:21], v45, s12, v[2:3]
	v_mad_u64_u32 v[48:49], s[20:21], v43, s12, v[2:3]
	v_mad_u64_u32 v[50:51], s[20:21], v50, s12, v[2:3]
	v_mad_u64_u32 v[52:53], s[20:21], v52, s12, v[2:3]
	v_mad_u64_u32 v[54:55], s[20:21], v54, s12, v[2:3]
	v_mad_u64_u32 v[56:57], s[20:21], v56, s12, v[2:3]
	v_mad_u64_u32 v[58:59], s[20:21], v58, s12, v[2:3]
	v_mad_u64_u32 v[60:61], s[20:21], v60, s12, v[2:3]
	v_mad_u64_u32 v[62:63], s[20:21], v62, s12, v[2:3]
	v_mad_u64_u32 v[72:73], s[20:21], v72, s12, v[2:3]
	v_mad_u64_u32 v[74:75], s[20:21], v74, s12, v[2:3]
	v_mad_u64_u32 v[76:77], s[20:21], v76, s12, v[2:3]
	v_mad_u64_u32 v[78:79], s[20:21], v78, s12, v[2:3]
	v_mad_u64_u32 v[80:81], s[20:21], v80, s12, v[2:3]
	s_waitcnt vmcnt(15)
	ds_write_b32 v42, v41
	s_waitcnt vmcnt(14)
	ds_write_b32 v44, v71
	s_waitcnt vmcnt(13)
	ds_write_b32 v46, v82
	s_waitcnt vmcnt(12)
	ds_write_b32 v48, v83
	s_waitcnt vmcnt(11)
	ds_write_b32 v50, v84
	s_waitcnt vmcnt(10)
	ds_write_b32 v52, v85
	s_waitcnt vmcnt(9)
	ds_write_b32 v54, v86
	s_waitcnt vmcnt(8)
	ds_write_b32 v56, v87
	s_waitcnt vmcnt(7)
	ds_write_b32 v58, v88
	s_waitcnt vmcnt(6)
	ds_write_b32 v60, v89
	s_waitcnt vmcnt(5)
	ds_write_b32 v62, v90
	s_waitcnt vmcnt(4)
	ds_write_b32 v72, v91
	s_waitcnt vmcnt(3)
	ds_write_b32 v74, v4
	s_waitcnt vmcnt(2)
	ds_write_b32 v76, v92
	s_waitcnt vmcnt(1)
	ds_write_b32 v78, v93
	s_waitcnt vmcnt(0)
	ds_write_b32 v80, v94
	s_cbranch_scc1 .LBB0_124
	s_waitcnt lgkmcnt(0)
	ds_read2_b32 v[42:43], v66 offset0:33 offset1:41
	ds_read2_b32 v[44:45], v66 offset1:8
	ds_read2_b32 v[46:47], v66 offset0:66 offset1:74
	ds_read2_b32 v[48:49], v66 offset0:99 offset1:107
	ds_read2_b32 v[50:51], v66 offset0:132 offset1:140
	ds_read2_b32 v[52:53], v66 offset0:165 offset1:173
	ds_read2_b32 v[54:55], v66 offset0:198 offset1:206
	ds_read2_b32 v[56:57], v66 offset0:231 offset1:239
	s_lshl_b32 s4, s1, 1
	v_or_b32_e32 v3, s0, v65
	v_lshl_add_u64 v[58:59], v[14:15], 0, s[4:5]
	v_lshlrev_b32_e32 v4, 10, v3
	s_waitcnt lgkmcnt(6)
	v_cvt_pk_bf16_f32 v38, v44, v42
	s_waitcnt lgkmcnt(4)
	v_cvt_pk_bf16_f32 v39, v46, v48
	s_waitcnt lgkmcnt(2)
	v_cvt_pk_bf16_f32 v40, v50, v52
	s_waitcnt lgkmcnt(0)
	v_cvt_pk_bf16_f32 v41, v54, v56
	v_lshl_add_u64 v[60:61], v[58:59], 0, v[4:5]
	global_store_dwordx4 v[60:61], v[38:41], off sc1
	v_or_b32_e32 v3, s0, v67
	v_lshlrev_b32_e32 v4, 10, v3
	v_cvt_pk_bf16_f32 v38, v45, v43
	v_cvt_pk_bf16_f32 v39, v47, v49
	v_cvt_pk_bf16_f32 v40, v51, v53
	v_cvt_pk_bf16_f32 v41, v55, v57
	ds_read2_b32 v[44:45], v66 offset0:49 offset1:57
	ds_read2_b32 v[46:47], v66 offset0:16 offset1:24
	ds_read2_b32 v[48:49], v66 offset0:82 offset1:90
	ds_read2_b32 v[50:51], v66 offset0:115 offset1:123
	ds_read2_b32 v[52:53], v66 offset0:148 offset1:156
	ds_read2_b32 v[54:55], v66 offset0:181 offset1:189
	ds_read2_b32 v[56:57], v66 offset0:214 offset1:222
	ds_read2_b32 v[60:61], v66 offset0:247 offset1:255
	v_or_b32_e32 v3, s0, v68
	v_lshl_add_u64 v[42:43], v[58:59], 0, v[4:5]
	v_lshlrev_b32_e32 v4, 10, v3
	v_or_b32_e32 v3, s0, v69
	global_store_dwordx4 v[42:43], v[38:41], off sc1
	v_lshl_add_u64 v[42:43], v[58:59], 0, v[4:5]
	v_lshlrev_b32_e32 v4, 10, v3
	s_waitcnt lgkmcnt(6)
	v_cvt_pk_bf16_f32 v38, v46, v44
	s_waitcnt lgkmcnt(4)
	v_cvt_pk_bf16_f32 v39, v48, v50
	s_waitcnt lgkmcnt(2)
	v_cvt_pk_bf16_f32 v40, v52, v54
	s_waitcnt lgkmcnt(0)
	v_cvt_pk_bf16_f32 v41, v56, v60
	global_store_dwordx4 v[42:43], v[38:41], off sc1
	v_lshl_add_u64 v[42:43], v[58:59], 0, v[4:5]
	s_nop 0
	v_cvt_pk_bf16_f32 v38, v47, v45
	v_cvt_pk_bf16_f32 v39, v49, v51
	v_cvt_pk_bf16_f32 v40, v53, v55
	v_cvt_pk_bf16_f32 v41, v57, v61
	global_store_dwordx4 v[42:43], v[38:41], off sc1
	s_waitcnt lgkmcnt(0)

.LBB0_146:
	ds_read2_b32 v[50:51], v66 offset1:8
	ds_read2_b32 v[52:53], v66 offset0:33 offset1:41
	ds_read2_b32 v[54:55], v66 offset0:66 offset1:74
	ds_read2_b32 v[58:59], v66 offset0:99 offset1:107
	ds_read2_b32 v[60:61], v66 offset0:132 offset1:140
	ds_read2_b32 v[62:63], v66 offset0:165 offset1:173
	ds_read2_b32 v[72:73], v66 offset0:198 offset1:206
	ds_read2_b32 v[74:75], v66 offset0:231 offset1:239
	s_waitcnt lgkmcnt(7)
	v_mov_b32_e32 v46, v50
	s_waitcnt lgkmcnt(6)
	v_mov_b32_e32 v47, v52
	s_waitcnt lgkmcnt(5)
	v_mov_b32_e32 v48, v54
	s_waitcnt lgkmcnt(4)
	v_mov_b32_e32 v49, v58
	s_waitcnt vmcnt(0)
	v_pk_mul_f32 v[46:47], v[38:39], v[46:47]
	v_pk_mul_f32 v[48:49], v[40:41], v[48:49]
	s_lshl_b32 s4, s11, 1
	v_cvt_pk_bf16_f32 v46, v46, v47
	v_cvt_pk_bf16_f32 v47, v48, v49
	s_waitcnt lgkmcnt(3)
	v_mov_b32_e32 v48, v60
	s_waitcnt lgkmcnt(2)
	v_mov_b32_e32 v49, v62
	s_waitcnt lgkmcnt(1)
	v_mov_b32_e32 v76, v72
	s_waitcnt lgkmcnt(0)
	v_mov_b32_e32 v77, v74
	v_or_b32_e32 v3, s10, v65
	v_lshl_add_u64 v[56:57], v[16:17], 0, s[4:5]
	v_pk_mul_f32 v[48:49], v[42:43], v[48:49]
	v_pk_mul_f32 v[76:77], v[44:45], v[76:77]
	v_lshlrev_b32_e32 v4, 9, v3
	v_cvt_pk_bf16_f32 v48, v48, v49
	v_cvt_pk_bf16_f32 v49, v76, v77
	v_lshl_add_u64 v[76:77], v[56:57], 0, v[4:5]
	v_mov_b32_e32 v52, v51
	v_mov_b32_e32 v58, v55
	global_store_dwordx4 v[76:77], v[46:49], off sc1
	v_mov_b32_e32 v62, v61
	v_mov_b32_e32 v74, v73
	v_pk_mul_f32 v[46:47], v[38:39], v[52:53]
	v_pk_mul_f32 v[48:49], v[40:41], v[58:59]
	v_or_b32_e32 v3, s10, v67
	v_cvt_pk_bf16_f32 v46, v46, v47
	v_cvt_pk_bf16_f32 v47, v48, v49
	v_pk_mul_f32 v[48:49], v[42:43], v[62:63]
	v_pk_mul_f32 v[50:51], v[44:45], v[74:75]
	v_lshlrev_b32_e32 v4, 9, v3
	v_cvt_pk_bf16_f32 v48, v48, v49
	v_cvt_pk_bf16_f32 v49, v50, v51
	v_lshl_add_u64 v[54:55], v[56:57], 0, v[4:5]
	ds_read2_b32 v[50:51], v66 offset0:16 offset1:24
	ds_read2_b32 v[52:53], v66 offset0:49 offset1:57
	global_store_dwordx4 v[54:55], v[46:49], off sc1
	ds_read2_b32 v[54:55], v66 offset0:82 offset1:90
	ds_read2_b32 v[58:59], v66 offset0:115 offset1:123
	ds_read2_b32 v[60:61], v66 offset0:148 offset1:156
	ds_read2_b32 v[62:63], v66 offset0:181 offset1:189
	ds_read2_b32 v[72:73], v66 offset0:214 offset1:222
	ds_read2_b32 v[74:75], v66 offset0:247 offset1:255
	s_waitcnt lgkmcnt(7)
	v_mov_b32_e32 v46, v50
	s_waitcnt lgkmcnt(6)
	v_mov_b32_e32 v47, v52
	s_waitcnt lgkmcnt(5)
	v_mov_b32_e32 v48, v54
	s_waitcnt lgkmcnt(4)
	v_mov_b32_e32 v49, v58
	v_pk_mul_f32 v[46:47], v[38:39], v[46:47]
	v_pk_mul_f32 v[48:49], v[40:41], v[48:49]
	v_cvt_pk_bf16_f32 v46, v46, v47
	v_cvt_pk_bf16_f32 v47, v48, v49
	s_waitcnt lgkmcnt(3)
	v_mov_b32_e32 v48, v60
	s_waitcnt lgkmcnt(2)
	v_mov_b32_e32 v49, v62
	s_waitcnt lgkmcnt(1)
	v_mov_b32_e32 v76, v72
	s_waitcnt lgkmcnt(0)
	v_mov_b32_e32 v77, v74
	v_or_b32_e32 v3, s10, v68
	v_mov_b32_e32 v52, v51
	v_mov_b32_e32 v58, v55
	v_pk_mul_f32 v[48:49], v[42:43], v[48:49]
	v_pk_mul_f32 v[76:77], v[44:45], v[76:77]
	v_lshlrev_b32_e32 v4, 9, v3
	v_or_b32_e32 v3, s10, v69
	v_pk_mul_f32 v[38:39], v[38:39], v[52:53]
	v_pk_mul_f32 v[40:41], v[40:41], v[58:59]
	v_mov_b32_e32 v62, v61
	v_mov_b32_e32 v74, v73
	v_cvt_pk_bf16_f32 v48, v48, v49
	v_cvt_pk_bf16_f32 v49, v76, v77
	v_lshl_add_u64 v[76:77], v[56:57], 0, v[4:5]
	v_cvt_pk_bf16_f32 v38, v38, v39
	v_cvt_pk_bf16_f32 v39, v40, v41
	v_pk_mul_f32 v[40:41], v[42:43], v[62:63]
	v_pk_mul_f32 v[42:43], v[44:45], v[74:75]
	v_lshlrev_b32_e32 v4, 9, v3
	v_cvt_pk_bf16_f32 v40, v40, v41
	v_cvt_pk_bf16_f32 v41, v42, v43
	v_lshl_add_u64 v[42:43], v[56:57], 0, v[4:5]
	global_store_dwordx4 v[76:77], v[46:49], off sc1
	global_store_dwordx4 v[42:43], v[38:41], off sc1
	s_waitcnt lgkmcnt(0)

.LBB0_167:
	ds_read2_b32 v[62:63], v66 offset1:8
	ds_read2_b32 v[48:49], v66 offset0:16 offset1:33
	ds_read2_b32 v[72:73], v66 offset0:66 offset1:74
	ds_read2_b32 v[50:51], v66 offset0:82 offset1:99
	ds_read2_b32 v[74:75], v66 offset0:132 offset1:140
	s_waitcnt lgkmcnt(4)
	v_mov_b32_e32 v52, v62
	s_waitcnt lgkmcnt(3)
	v_mov_b32_e32 v53, v49
	s_waitcnt vmcnt(0)
	v_pk_mul_f32 v[52:53], v[38:39], v[52:53]
	v_or_b32_e32 v3, s10, v65
	v_cvt_pk_bf16_f32 v58, v52, v53
	s_waitcnt lgkmcnt(2)
	v_mov_b32_e32 v52, v72
	s_waitcnt lgkmcnt(1)
	v_mov_b32_e32 v53, v51
	v_pk_mul_f32 v[54:55], v[40:41], v[52:53]
	ds_read2_b32 v[52:53], v66 offset0:148 offset1:165
	v_cvt_pk_bf16_f32 v59, v54, v55
	ds_read2_b32 v[76:77], v66 offset0:198 offset1:206
	ds_read2_b32 v[54:55], v66 offset0:214 offset1:231
	v_mul_hi_u32 v4, v3, s15
	v_mul_u32_u24_e32 v4, 0x60, v4
	v_sub_u32_e32 v49, v3, v4
	s_waitcnt lgkmcnt(3)
	v_mov_b32_e32 v56, v74
	s_waitcnt lgkmcnt(2)
	v_mov_b32_e32 v57, v53
	v_lshlrev_b32_e32 v51, 1, v49
	v_pk_mul_f32 v[56:57], v[42:43], v[56:57]
	v_and_or_b32 v4, v51, 14, v4
	s_lshl_b32 s4, s11, 1
	v_cvt_pk_bf16_f32 v60, v56, v57
	s_waitcnt lgkmcnt(1)
	v_mov_b32_e32 v56, v76
	s_waitcnt lgkmcnt(0)
	v_mov_b32_e32 v57, v55
	v_add_u32_e32 v4, 64, v4
	v_cmp_lt_u32_e32 vcc, 63, v49
	v_lshl_add_u64 v[46:47], v[18:19], 0, s[4:5]
	v_pk_mul_f32 v[56:57], v[44:45], v[56:57]
	v_cndmask_b32_e32 v3, v3, v4, vcc
	v_cvt_pk_bf16_f32 v61, v56, v57
	v_mad_u64_u32 v[78:79], s[0:1], v3, s16, v[46:47]
	ds_read2_b32 v[56:57], v66 offset0:41 offset1:49
	global_store_dwordx4 v[78:79], v[58:61], off sc1
	ds_read2_b32 v[58:59], v66 offset0:107 offset1:115
	v_mov_b32_e32 v62, v73
	v_mov_b32_e32 v60, v63
	s_waitcnt lgkmcnt(1)
	v_mov_b32_e32 v61, v56
	v_pk_mul_f32 v[60:61], v[38:39], v[60:61]
	s_waitcnt lgkmcnt(0)
	v_mov_b32_e32 v63, v58
	v_pk_mul_f32 v[62:63], v[40:41], v[62:63]
	v_or_b32_e32 v3, s10, v67
	v_cvt_pk_bf16_f32 v72, v60, v61
	ds_read2_b32 v[60:61], v66 offset0:173 offset1:181
	v_cvt_pk_bf16_f32 v73, v62, v63
	ds_read2_b32 v[62:63], v66 offset0:239 offset1:247
	v_mul_hi_u32 v4, v3, s15
	v_mul_u32_u24_e32 v4, 0x60, v4
	v_sub_u32_e32 v49, v3, v4
	v_lshlrev_b32_e32 v51, 1, v49
	v_and_or_b32 v4, v51, 14, v4
	v_mov_b32_e32 v74, v75
	s_waitcnt lgkmcnt(1)
	v_mov_b32_e32 v75, v60
	v_mov_b32_e32 v76, v77
	s_waitcnt lgkmcnt(0)
	v_mov_b32_e32 v77, v62
	v_add_u32_e32 v4, 0x41, v4
	v_cmp_lt_u32_e32 vcc, 63, v49
	v_pk_mul_f32 v[74:75], v[42:43], v[74:75]
	v_pk_mul_f32 v[76:77], v[44:45], v[76:77]
	v_cndmask_b32_e32 v3, v3, v4, vcc
	v_cvt_pk_bf16_f32 v74, v74, v75
	v_cvt_pk_bf16_f32 v75, v76, v77
	v_mad_u64_u32 v[76:77], s[0:1], v3, s16, v[46:47]
	v_or_b32_e32 v3, s10, v68
	v_mul_hi_u32 v4, v3, s15
	v_mul_u32_u24_e32 v4, 0x60, v4
	v_sub_u32_e32 v4, v3, v4
	v_cmp_lt_u32_e32 vcc, 63, v4
	global_store_dwordx4 v[76:77], v[72:75], off sc1
	s_and_saveexec_b64 s[0:1], vcc
	v_subrev_u32_e32 v49, 64, v4
	v_and_b32_e32 v51, 0x7ffffff0, v49
	v_lshlrev_b32_e32 v49, 1, v49
	v_sub_u32_e32 v3, v3, v4
	v_and_b32_e32 v49, 14, v49
	v_add_u32_e32 v3, v3, v51
	v_add3_u32 v3, v3, v49, 64
	s_or_b64 exec, exec, s[0:1]
	v_mov_b32_e32 v49, v57
	v_mov_b32_e32 v51, v59
	v_pk_mul_f32 v[48:49], v[38:39], v[48:49]
	v_pk_mul_f32 v[50:51], v[40:41], v[50:51]
	v_mov_b32_e32 v53, v61
	v_mov_b32_e32 v55, v63
	v_cvt_pk_bf16_f32 v48, v48, v49
	v_cvt_pk_bf16_f32 v49, v50, v51
	v_pk_mul_f32 v[50:51], v[42:43], v[52:53]
	v_pk_mul_f32 v[52:53], v[44:45], v[54:55]
	v_cvt_pk_bf16_f32 v50, v50, v51
	v_cvt_pk_bf16_f32 v51, v52, v53
	v_mad_u64_u32 v[52:53], s[0:1], v3, s16, v[46:47]
	global_store_dwordx4 v[52:53], v[48:51], off sc1
	ds_read2_b32 v[54:55], v66 offset0:24 offset1:57
	ds_read2_b32 v[52:53], v66 offset0:90 offset1:123
	ds_read2_b32 v[50:51], v66 offset0:156 offset1:189
	ds_read2_b32 v[48:49], v66 offset0:222 offset1:255
	v_or_b32_e32 v3, s10, v69
	v_mul_hi_u32 v4, v3, s15
	v_mul_u32_u24_e32 v4, 0x60, v4
	v_sub_u32_e32 v4, v3, v4
	v_cmp_lt_u32_e32 vcc, 63, v4
	s_and_saveexec_b64 s[0:1], vcc
	v_subrev_u32_e32 v56, 64, v4
	v_and_b32_e32 v57, 0x7ffffff0, v56
	v_lshlrev_b32_e32 v56, 1, v56
	v_sub_u32_e32 v3, v3, v4
	v_and_b32_e32 v56, 14, v56
	v_add_u32_e32 v3, v3, v57
	v_add3_u32 v3, v3, v56, s17
	s_or_b64 exec, exec, s[0:1]
	s_waitcnt lgkmcnt(3)
	v_pk_mul_f32 v[38:39], v[38:39], v[54:55]
	s_waitcnt lgkmcnt(2)
	v_pk_mul_f32 v[40:41], v[40:41], v[52:53]
	v_cvt_pk_bf16_f32 v38, v38, v39
	v_cvt_pk_bf16_f32 v39, v40, v41
	s_waitcnt lgkmcnt(1)
	v_pk_mul_f32 v[40:41], v[42:43], v[50:51]
	s_waitcnt lgkmcnt(0)
	v_pk_mul_f32 v[42:43], v[44:45], v[48:49]
	v_cvt_pk_bf16_f32 v40, v40, v41
	v_cvt_pk_bf16_f32 v41, v42, v43
	v_mad_u64_u32 v[42:43], s[0:1], v3, s16, v[46:47]
	global_store_dwordx4 v[42:43], v[38:41], off sc1
	s_waitcnt lgkmcnt(0)

.LBB0_174:
	s_lshl_b32 s21, s1, 1
	s_lshl_b32 s24, s11, 1
	v_or_b32_e32 v40, s24, v4
	s_add_i32 s25, s21, 4
	s_add_i32 s26, s24, 4
	s_add_i32 s27, s21, 8
	s_add_i32 s28, s24, 8
	s_add_i32 s29, s21, 12
	s_add_i32 s30, s24, 12
	s_add_i32 s31, s21, 16
	s_add_i32 s34, s24, 16
	s_add_i32 s35, s21, 20
	s_add_i32 s36, s24, 20
	s_add_i32 s37, s21, 24
	s_add_i32 s38, s24, 24
	s_add_i32 s39, s21, 28
	s_add_i32 s40, s24, 28
	v_or_b32_e32 v42, s21, v3
	v_mad_i64_i32 v[40:41], s[22:23], v40, s18, v[38:39]
	v_or_b32_e32 v46, s25, v3
	v_or_b32_e32 v44, s26, v4
	v_or_b32_e32 v50, s27, v3
	v_or_b32_e32 v48, s28, v4
	v_or_b32_e32 v54, s29, v3
	v_or_b32_e32 v52, s30, v4
	v_or_b32_e32 v58, s31, v3
	v_or_b32_e32 v56, s34, v4
	v_or_b32_e32 v62, s35, v3
	v_or_b32_e32 v60, s36, v4
	v_or_b32_e32 v71, s37, v3
	v_or_b32_e32 v72, s38, v4
	v_or_b32_e32 v78, s39, v3
	v_or_b32_e32 v76, s40, v4
	v_mad_i64_i32 v[42:43], s[22:23], v42, s18, v[38:39]
	v_mad_i64_i32 v[44:45], s[22:23], v44, s18, v[38:39]
	v_mad_i64_i32 v[46:47], s[22:23], v46, s18, v[38:39]
	v_mad_i64_i32 v[48:49], s[22:23], v48, s18, v[38:39]
	v_mad_i64_i32 v[50:51], s[22:23], v50, s18, v[38:39]
	v_mad_i64_i32 v[52:53], s[22:23], v52, s18, v[38:39]
	v_mad_i64_i32 v[54:55], s[22:23], v54, s18, v[38:39]
	v_mad_i64_i32 v[56:57], s[22:23], v56, s18, v[38:39]
	v_mad_i64_i32 v[58:59], s[22:23], v58, s18, v[38:39]
	v_mad_i64_i32 v[60:61], s[22:23], v60, s18, v[38:39]
	v_mad_i64_i32 v[62:63], s[22:23], v62, s18, v[38:39]
	v_mad_i64_i32 v[72:73], s[22:23], v72, s18, v[38:39]
	v_mad_i64_i32 v[74:75], s[22:23], v71, s18, v[38:39]
	v_mad_i64_i32 v[76:77], s[22:23], v76, s18, v[38:39]
	v_mad_i64_i32 v[78:79], s[22:23], v78, s18, v[38:39]
	global_load_dword v71, v[40:41], off
	global_load_dword v80, v[42:43], off
	global_load_dword v81, v[44:45], off
	global_load_dword v82, v[46:47], off
	global_load_dword v83, v[48:49], off
	global_load_dword v84, v[50:51], off
	global_load_dword v85, v[52:53], off
	global_load_dword v86, v[54:55], off
	global_load_dword v87, v[56:57], off
	global_load_dword v88, v[58:59], off
	global_load_dword v89, v[60:61], off
	global_load_dword v90, v[62:63], off
	global_load_dword v91, v[72:73], off
	global_load_dword v92, v[74:75], off
	global_load_dword v93, v[76:77], off
	global_load_dword v94, v[78:79], off
	v_or_b32_e32 v42, s21, v1
	v_or_b32_e32 v40, s24, v0
	s_add_i32 s11, s11, 16
	s_add_i32 s1, s1, 16
	s_add_i32 s20, s20, -16
	v_mad_u64_u32 v[40:41], s[22:23], v40, s12, v[2:3]
	v_mad_u64_u32 v[42:43], s[22:23], v42, s12, v[2:3]
	v_or_b32_e32 v41, s25, v1
	v_or_b32_e32 v43, s26, v0
	v_or_b32_e32 v50, s27, v1
	v_or_b32_e32 v48, s28, v0
	v_or_b32_e32 v54, s29, v1
	v_or_b32_e32 v52, s30, v0
	v_or_b32_e32 v58, s31, v1
	v_or_b32_e32 v56, s34, v0
	v_or_b32_e32 v62, s35, v1
	v_or_b32_e32 v60, s36, v0
	v_or_b32_e32 v74, s37, v1
	v_or_b32_e32 v72, s38, v0
	v_or_b32_e32 v78, s39, v1
	v_or_b32_e32 v76, s40, v0
	s_cmp_lg_u32 s20, 0
	v_mad_u64_u32 v[44:45], s[22:23], v43, s12, v[2:3]
	v_mad_u64_u32 v[46:47], s[22:23], v41, s12, v[2:3]
	v_mad_u64_u32 v[48:49], s[22:23], v48, s12, v[2:3]
	v_mad_u64_u32 v[50:51], s[22:23], v50, s12, v[2:3]
	v_mad_u64_u32 v[52:53], s[22:23], v52, s12, v[2:3]
	v_mad_u64_u32 v[54:55], s[22:23], v54, s12, v[2:3]
	v_mad_u64_u32 v[56:57], s[22:23], v56, s12, v[2:3]
	v_mad_u64_u32 v[58:59], s[22:23], v58, s12, v[2:3]
	v_mad_u64_u32 v[60:61], s[22:23], v60, s12, v[2:3]
	v_mad_u64_u32 v[62:63], s[22:23], v62, s12, v[2:3]
	v_mad_u64_u32 v[72:73], s[22:23], v72, s12, v[2:3]
	v_mad_u64_u32 v[74:75], s[22:23], v74, s12, v[2:3]
	v_mad_u64_u32 v[76:77], s[22:23], v76, s12, v[2:3]
	v_mad_u64_u32 v[78:79], s[22:23], v78, s12, v[2:3]
	s_waitcnt vmcnt(15)
	ds_write_b32 v40, v71
	s_waitcnt vmcnt(14)
	ds_write_b32 v42, v80
	s_waitcnt vmcnt(13)
	ds_write_b32 v44, v81
	s_waitcnt vmcnt(12)
	ds_write_b32 v46, v82
	s_waitcnt vmcnt(11)
	ds_write_b32 v48, v83
	s_waitcnt vmcnt(10)
	ds_write_b32 v50, v84
	s_waitcnt vmcnt(9)
	ds_write_b32 v52, v85
	s_waitcnt vmcnt(8)
	ds_write_b32 v54, v86
	s_waitcnt vmcnt(7)
	ds_write_b32 v56, v87
	s_waitcnt vmcnt(6)
	ds_write_b32 v58, v88
	s_waitcnt vmcnt(5)
	ds_write_b32 v60, v89
	s_waitcnt vmcnt(4)
	ds_write_b32 v62, v90
	s_waitcnt vmcnt(3)
	ds_write_b32 v72, v91
	s_waitcnt vmcnt(2)
	ds_write_b32 v74, v92
	s_waitcnt vmcnt(1)
	ds_write_b32 v76, v93
	s_waitcnt vmcnt(0)
	ds_write_b32 v78, v94
	s_cbranch_scc1 .LBB0_174
	s_ashr_i32 s11, s10, 31
	s_cmp_eq_u32 s4, 20
	v_or_b32_e32 v3, s0, v65
	s_waitcnt lgkmcnt(0)
	s_cselect_b64 vcc, -1, 0
	v_lshlrev_b32_e32 v4, 1, v3
	s_and_b32 s1, s0, 0x280
	ds_read2_b32 v[44:45], v66 offset0:33 offset1:41
	ds_read2_b32 v[46:47], v66 offset1:8
	ds_read2_b32 v[48:49], v66 offset0:66 offset1:74
	ds_read2_b32 v[50:51], v66 offset0:99 offset1:107
	ds_read2_b32 v[52:53], v66 offset0:132 offset1:140
	ds_read2_b32 v[54:55], v66 offset0:165 offset1:173
	ds_read2_b32 v[56:57], v66 offset0:198 offset1:206
	ds_read2_b32 v[58:59], v66 offset0:231 offset1:239
	v_and_or_b32 v4, v4, 14, s1
	v_cndmask_b32_e32 v60, v3, v4, vcc
	v_or_b32_e32 v3, s0, v67
	v_lshlrev_b32_e32 v4, 1, v3
	v_ashrrev_i32_e32 v61, 31, v60
	v_and_b32_e32 v4, 14, v4
	v_lshl_add_u64 v[42:43], s[10:11], 1, v[20:21]
	v_lshlrev_b64 v[60:61], 11, v[60:61]
	v_or3_b32 v4, s1, v4, 1
	s_waitcnt lgkmcnt(6)
	v_cvt_pk_bf16_f32 v38, v46, v44
	s_waitcnt lgkmcnt(4)
	v_cvt_pk_bf16_f32 v39, v48, v50
	s_waitcnt lgkmcnt(2)
	v_cvt_pk_bf16_f32 v40, v52, v54
	s_waitcnt lgkmcnt(0)
	v_cvt_pk_bf16_f32 v41, v56, v58
	v_lshl_add_u64 v[60:61], v[42:43], 0, v[60:61]
	v_cndmask_b32_e32 v44, v3, v4, vcc
	global_store_dwordx4 v[60:61], v[38:41], off sc1
	v_or_b32_e32 v3, s0, v68
	v_lshlrev_b32_e32 v4, 1, v3
	v_cvt_pk_bf16_f32 v38, v47, v45
	v_ashrrev_i32_e32 v45, 31, v44
	v_lshlrev_b64 v[44:45], 11, v[44:45]
	v_cvt_pk_bf16_f32 v39, v49, v51
	v_cvt_pk_bf16_f32 v40, v53, v55
	v_cvt_pk_bf16_f32 v41, v57, v59
	v_lshl_add_u64 v[44:45], v[42:43], 0, v[44:45]
	ds_read2_b32 v[46:47], v66 offset0:49 offset1:57
	ds_read2_b32 v[48:49], v66 offset0:16 offset1:24
	ds_read2_b32 v[50:51], v66 offset0:82 offset1:90
	ds_read2_b32 v[52:53], v66 offset0:115 offset1:123
	ds_read2_b32 v[54:55], v66 offset0:148 offset1:156
	ds_read2_b32 v[56:57], v66 offset0:181 offset1:189
	ds_read2_b32 v[58:59], v66 offset0:214 offset1:222
	ds_read2_b32 v[60:61], v66 offset0:247 offset1:255
	global_store_dwordx4 v[44:45], v[38:41], off sc1
	v_bitop3_b32 v44, s0, v70, v68 bitop3:0xc8
	v_and_or_b32 v4, v4, 14, v44
	v_cndmask_b32_e32 v44, v3, v4, vcc
	v_ashrrev_i32_e32 v45, 31, v44
	v_lshlrev_b64 v[44:45], 11, v[44:45]
	v_or_b32_e32 v3, s0, v69
	s_waitcnt lgkmcnt(6)
	v_cvt_pk_bf16_f32 v38, v48, v46
	s_waitcnt lgkmcnt(4)
	v_cvt_pk_bf16_f32 v39, v50, v52
	s_waitcnt lgkmcnt(2)
	v_cvt_pk_bf16_f32 v40, v54, v56
	s_waitcnt lgkmcnt(0)
	v_cvt_pk_bf16_f32 v41, v58, v60
	v_lshl_add_u64 v[44:45], v[42:43], 0, v[44:45]
	v_lshlrev_b32_e32 v4, 1, v3
	global_store_dwordx4 v[44:45], v[38:41], off sc1
	v_and_b32_e32 v4, 14, v4
	s_nop 0
	v_bitop3_b32 v38, s0, v70, v69 bitop3:0xc8
	v_or3_b32 v4, v38, v4, 1
	v_cndmask_b32_e32 v44, v3, v4, vcc
	v_ashrrev_i32_e32 v45, 31, v44
	v_lshlrev_b64 v[44:45], 11, v[44:45]
	v_cvt_pk_bf16_f32 v38, v49, v47
	v_cvt_pk_bf16_f32 v39, v51, v53
	v_cvt_pk_bf16_f32 v40, v55, v57
	v_cvt_pk_bf16_f32 v41, v59, v61
	v_lshl_add_u64 v[42:43], v[42:43], 0, v[44:45]
	global_store_dwordx4 v[42:43], v[38:41], off sc1
	s_waitcnt lgkmcnt(0)
	s_branch .LBB0_95

.LBB0_178:
	v_add_u32_e32 v8, s0, v8
	v_cmp_lt_i32_e32 vcc, s1, v8
	global_store_dwordx4 v[6:7], v[0:3], off sc1
	s_or_b64 s[8:9], vcc, s[8:9]
	v_lshl_add_u64 v[6:7], v[6:7], 0, s[6:7]
	s_andn2_b64 exec, exec, s[8:9]
	s_cbranch_execnz .LBB0_178

.LBB0_259:
	s_lshl_b32 s15, s22, 8
	v_or_b32_e32 v160, s15, v155
	s_lshl_b32 s13, s24, 8
	v_ashrrev_i32_e32 v161, 31, v160
	v_add_u32_e32 v142, s13, v146
	v_lshl_add_u64 v[164:165], v[160:161], 1, s[10:11]
	v_mad_i64_i32 v[166:167], s[24:25], v142, s69, v[164:165]
	v_cvt_pk_bf16_f32 v160, v124, v125
	v_cvt_pk_bf16_f32 v161, v126, v127
	v_cvt_pk_bf16_f32 v162, v120, v121
	v_cvt_pk_bf16_f32 v163, v122, v123
	global_store_dwordx4 v[166:167], v[160:163], off sc1
	v_or_b32_e32 v143, 16, v142
	s_cmp_gt_i32 s22, 2
	v_cvt_pk_bf16_f32 v160, v68, v69
	v_cvt_pk_bf16_f32 v161, v70, v71
	v_cvt_pk_bf16_f32 v162, v60, v61
	v_cvt_pk_bf16_f32 v163, v62, v63
	global_store_dwordx4 v[166:167], v[160:163], off offset:256 sc1
	v_mad_i64_i32 v[166:167], s[24:25], v143, s69, v[164:165]
	s_nop 0
	v_cvt_pk_bf16_f32 v160, v116, v117
	v_cvt_pk_bf16_f32 v161, v118, v119
	v_cvt_pk_bf16_f32 v162, v112, v113
	v_cvt_pk_bf16_f32 v163, v114, v115
	global_store_dwordx4 v[166:167], v[160:163], off sc1
	v_or_b32_e32 v143, 32, v142
	s_nop 0
	v_cvt_pk_bf16_f32 v160, v52, v53
	v_cvt_pk_bf16_f32 v161, v54, v55
	v_cvt_pk_bf16_f32 v162, v48, v49
	v_cvt_pk_bf16_f32 v163, v50, v51
	global_store_dwordx4 v[166:167], v[160:163], off offset:256 sc1
	v_mad_i64_i32 v[166:167], s[24:25], v143, s69, v[164:165]
	s_nop 0
	v_cvt_pk_bf16_f32 v160, v108, v109
	v_cvt_pk_bf16_f32 v161, v110, v111
	v_cvt_pk_bf16_f32 v162, v104, v105
	v_cvt_pk_bf16_f32 v163, v106, v107
	global_store_dwordx4 v[166:167], v[160:163], off sc1
	v_or_b32_e32 v143, 48, v142
	s_nop 0
	v_cvt_pk_bf16_f32 v160, v44, v45
	v_cvt_pk_bf16_f32 v161, v46, v47
	v_cvt_pk_bf16_f32 v162, v40, v41
	v_cvt_pk_bf16_f32 v163, v42, v43
	global_store_dwordx4 v[166:167], v[160:163], off offset:256 sc1
	v_mad_i64_i32 v[166:167], s[24:25], v143, s69, v[164:165]
	s_nop 0
	v_cvt_pk_bf16_f32 v160, v100, v101
	v_cvt_pk_bf16_f32 v161, v102, v103
	v_cvt_pk_bf16_f32 v162, v96, v97
	v_cvt_pk_bf16_f32 v163, v98, v99
	global_store_dwordx4 v[166:167], v[160:163], off sc1
	v_add_u32_e32 v143, 0x80, v142
	s_nop 0
	v_cvt_pk_bf16_f32 v160, v36, v37
	v_cvt_pk_bf16_f32 v161, v38, v39
	v_cvt_pk_bf16_f32 v162, v32, v33
	v_cvt_pk_bf16_f32 v163, v34, v35
	global_store_dwordx4 v[166:167], v[160:163], off offset:256 sc1
	v_mad_i64_i32 v[166:167], s[24:25], v143, s69, v[164:165]
	s_nop 0
	v_cvt_pk_bf16_f32 v160, v92, v93
	v_cvt_pk_bf16_f32 v161, v94, v95
	v_cvt_pk_bf16_f32 v162, v88, v89
	v_cvt_pk_bf16_f32 v163, v90, v91
	global_store_dwordx4 v[166:167], v[160:163], off sc1
	v_add_u32_e32 v143, 0x90, v142
	s_nop 0
	v_cvt_pk_bf16_f32 v160, v28, v29
	v_cvt_pk_bf16_f32 v161, v30, v31
	v_cvt_pk_bf16_f32 v162, v24, v25
	v_cvt_pk_bf16_f32 v163, v26, v27
	global_store_dwordx4 v[166:167], v[160:163], off offset:256 sc1
	v_mad_i64_i32 v[166:167], s[24:25], v143, s69, v[164:165]
	s_nop 0
	v_cvt_pk_bf16_f32 v160, v84, v85
	v_cvt_pk_bf16_f32 v161, v86, v87
	v_cvt_pk_bf16_f32 v162, v80, v81
	v_cvt_pk_bf16_f32 v163, v82, v83
	global_store_dwordx4 v[166:167], v[160:163], off sc1
	v_add_u32_e32 v143, 0xa0, v142
	s_nop 0
	v_cvt_pk_bf16_f32 v160, v20, v21
	v_cvt_pk_bf16_f32 v161, v22, v23
	v_cvt_pk_bf16_f32 v162, v16, v17
	v_cvt_pk_bf16_f32 v163, v18, v19
	global_store_dwordx4 v[166:167], v[160:163], off offset:256 sc1
	v_mad_i64_i32 v[166:167], s[24:25], v143, s69, v[164:165]
	s_nop 0
	v_cvt_pk_bf16_f32 v160, v76, v77
	v_cvt_pk_bf16_f32 v161, v78, v79
	v_cvt_pk_bf16_f32 v162, v72, v73
	v_cvt_pk_bf16_f32 v163, v74, v75
	global_store_dwordx4 v[166:167], v[160:163], off sc1
	v_add_u32_e32 v143, 0xb0, v142
	v_mad_i64_i32 v[164:165], s[24:25], v143, s69, v[164:165]
	v_cvt_pk_bf16_f32 v160, v12, v13
	v_cvt_pk_bf16_f32 v161, v14, v15
	v_cvt_pk_bf16_f32 v162, v8, v9
	v_cvt_pk_bf16_f32 v163, v10, v11
	global_store_dwordx4 v[166:167], v[160:163], off offset:256 sc1
	s_nop 1
	v_cvt_pk_bf16_f32 v160, v64, v65
	v_cvt_pk_bf16_f32 v161, v66, v67
	v_cvt_pk_bf16_f32 v162, v56, v57
	v_cvt_pk_bf16_f32 v163, v58, v59
	global_store_dwordx4 v[164:165], v[160:163], off sc1
	s_nop 1
	v_cvt_pk_bf16_f32 v160, v4, v5
	v_cvt_pk_bf16_f32 v161, v6, v7
	v_cvt_pk_bf16_f32 v162, v0, v1
	v_cvt_pk_bf16_f32 v163, v2, v3
	global_store_dwordx4 v[164:165], v[160:163], off offset:256 sc1
	s_cbranch_scc1 .LBB0_294
	v_mul_f32_e32 v125, v125, v125
	v_fmac_f32_e32 v125, v124, v124
	v_mul_f32_e32 v124, v127, v127
	v_and_b32_e32 v160, 64, v159
	v_fmac_f32_e32 v124, v126, v126
	v_mul_f32_e32 v121, v121, v121
	v_xor_b32_e32 v143, 16, v159
	v_add_u32_e32 v161, 64, v160
	v_add_f32_e32 v124, v125, v124
	v_fmac_f32_e32 v121, v120, v120
	v_cmp_lt_i32_e32 vcc, v143, v161
	v_add_f32_e32 v120, v124, v121
	v_mul_f32_e32 v121, v123, v123
	v_cndmask_b32_e32 v143, v159, v143, vcc
	v_fmac_f32_e32 v121, v122, v122
	v_lshlrev_b32_e32 v160, 2, v143
	v_add_f32_e32 v121, v121, v120
	ds_bpermute_b32 v122, v160, v121
	v_xor_b32_e32 v120, 32, v159
	v_cmp_lt_i32_e32 vcc, v120, v161
	s_cmp_eq_u32 s22, 2
	v_ashrrev_i32_e32 v143, 31, v142
	v_cndmask_b32_e32 v120, v159, v120, vcc
	v_lshlrev_b32_e32 v120, 2, v120
	s_waitcnt lgkmcnt(0)
	v_add_f32_e32 v121, v121, v122
	ds_bpermute_b32 v122, v120, v121
	s_cselect_b32 s23, s50, s55
	s_cselect_b32 s22, s49, s54
	s_and_saveexec_b64 s[24:25], s[2:3]
	s_cbranch_execz .LBB0_262
	v_lshl_add_u64 v[124:125], v[142:143], 2, s[22:23]
	s_waitcnt lgkmcnt(0)
	v_add_f32_e32 v121, v121, v122
	global_atomic_add_f32 v[124:125], v121, off

.LBB0_525:
	s_andn2_b64 vcc, exec, s[0:1]
	s_cbranch_vccnz .LBB0_527
	v_mad_i64_i32 v[124:125], s[0:1], v124, s44, v[138:139]
	v_lshlrev_b64 v[124:125], 7, v[124:125]
	v_lshl_add_u64 v[124:125], v[142:143], 0, v[124:125]
	global_store_dwordx4 v[124:125], v[120:123], off sc1

.LBB0_529:
	s_andn2_b64 vcc, exec, s[0:1]
	s_cbranch_vccnz .LBB0_531
	v_mad_i64_i32 v[116:117], s[0:1], v116, s44, v[138:139]
	v_lshlrev_b64 v[116:117], 7, v[116:117]
	v_lshl_add_u64 v[116:117], v[142:143], 0, v[116:117]
	global_store_dwordx4 v[116:117], v[112:115], off sc1

.LBB0_537:
	s_andn2_b64 vcc, exec, s[0:1]
	s_cbranch_vccnz .LBB0_539
	v_mad_i64_i32 v[108:109], s[0:1], v108, s44, v[138:139]
	v_lshlrev_b64 v[108:109], 7, v[108:109]
	v_lshl_add_u64 v[108:109], v[142:143], 0, v[108:109]
	global_store_dwordx4 v[108:109], v[104:107], off sc1

.LBB0_541:
	s_andn2_b64 vcc, exec, s[0:1]
	s_cbranch_vccnz .LBB0_543
	v_mad_i64_i32 v[100:101], s[0:1], v100, s44, v[138:139]
	v_lshlrev_b64 v[100:101], 7, v[100:101]
	v_lshl_add_u64 v[100:101], v[142:143], 0, v[100:101]
	global_store_dwordx4 v[100:101], v[96:99], off sc1

.LBB0_549:
	s_andn2_b64 vcc, exec, s[0:1]
	s_cbranch_vccnz .LBB0_551
	v_mad_i64_i32 v[92:93], s[0:1], v92, s44, v[138:139]
	v_lshlrev_b64 v[92:93], 7, v[92:93]
	v_lshl_add_u64 v[92:93], v[142:143], 0, v[92:93]
	global_store_dwordx4 v[92:93], v[88:91], off sc1

.LBB0_553:
	s_andn2_b64 vcc, exec, s[0:1]
	s_cbranch_vccnz .LBB0_555
	v_mad_i64_i32 v[84:85], s[0:1], v84, s44, v[138:139]
	v_lshlrev_b64 v[84:85], 7, v[84:85]
	v_lshl_add_u64 v[84:85], v[142:143], 0, v[84:85]
	global_store_dwordx4 v[84:85], v[80:83], off sc1

.LBB0_561:
	s_andn2_b64 vcc, exec, s[0:1]
	s_cbranch_vccnz .LBB0_563
	v_mad_i64_i32 v[76:77], s[0:1], v76, s44, v[138:139]
	v_lshlrev_b64 v[76:77], 7, v[76:77]
	v_lshl_add_u64 v[76:77], v[142:143], 0, v[76:77]
	global_store_dwordx4 v[76:77], v[72:75], off sc1

.LBB0_565:
	s_andn2_b64 vcc, exec, s[0:1]
	s_cbranch_vccnz .LBB0_567
	v_mad_i64_i32 v[68:69], s[0:1], v68, s44, v[138:139]
	v_lshlrev_b64 v[68:69], 7, v[68:69]
	v_lshl_add_u64 v[68:69], v[142:143], 0, v[68:69]
	global_store_dwordx4 v[68:69], v[64:67], off sc1

.LBB0_573:
	s_andn2_b64 vcc, exec, s[0:1]
	s_cbranch_vccnz .LBB0_575
	v_mad_i64_i32 v[60:61], s[0:1], v60, s44, v[138:139]
	v_lshlrev_b64 v[60:61], 7, v[60:61]
	v_lshl_add_u64 v[60:61], v[142:143], 0, v[60:61]
	global_store_dwordx4 v[60:61], v[56:59], off sc1

.LBB0_577:
	s_andn2_b64 vcc, exec, s[0:1]
	s_cbranch_vccnz .LBB0_579
	v_mad_i64_i32 v[52:53], s[0:1], v52, s44, v[138:139]
	v_lshlrev_b64 v[52:53], 7, v[52:53]
	v_lshl_add_u64 v[52:53], v[142:143], 0, v[52:53]
	global_store_dwordx4 v[52:53], v[48:51], off sc1

.LBB0_585:
	s_andn2_b64 vcc, exec, s[0:1]
	s_cbranch_vccnz .LBB0_587
	v_mad_i64_i32 v[44:45], s[0:1], v44, s44, v[138:139]
	v_lshlrev_b64 v[44:45], 7, v[44:45]
	v_lshl_add_u64 v[44:45], v[142:143], 0, v[44:45]
	global_store_dwordx4 v[44:45], v[40:43], off sc1

.LBB0_589:
	s_andn2_b64 vcc, exec, s[0:1]
	s_cbranch_vccnz .LBB0_591
	v_mad_i64_i32 v[36:37], s[0:1], v36, s44, v[138:139]
	v_lshlrev_b64 v[36:37], 7, v[36:37]
	v_lshl_add_u64 v[36:37], v[142:143], 0, v[36:37]
	global_store_dwordx4 v[36:37], v[32:35], off sc1

.LBB0_597:
	s_andn2_b64 vcc, exec, s[0:1]
	s_cbranch_vccnz .LBB0_599
	v_mad_i64_i32 v[28:29], s[0:1], v28, s44, v[138:139]
	v_lshlrev_b64 v[28:29], 7, v[28:29]
	v_lshl_add_u64 v[28:29], v[142:143], 0, v[28:29]
	global_store_dwordx4 v[28:29], v[24:27], off sc1

.LBB0_601:
	s_andn2_b64 vcc, exec, s[0:1]
	s_cbranch_vccnz .LBB0_603
	v_mad_i64_i32 v[20:21], s[0:1], v20, s44, v[138:139]
	v_lshlrev_b64 v[20:21], 7, v[20:21]
	v_lshl_add_u64 v[20:21], v[142:143], 0, v[20:21]
	global_store_dwordx4 v[20:21], v[16:19], off sc1

.LBB0_609:
	s_andn2_b64 vcc, exec, s[0:1]
	s_cbranch_vccnz .LBB0_611
	v_mad_i64_i32 v[12:13], s[0:1], v12, s44, v[138:139]
	v_lshlrev_b64 v[12:13], 7, v[12:13]
	v_lshl_add_u64 v[12:13], v[142:143], 0, v[12:13]
	global_store_dwordx4 v[12:13], v[8:11], off sc1

.LBB0_615:
	v_mad_i64_i32 v[4:5], s[0:1], v4, s44, v[138:139]
	v_lshlrev_b64 v[4:5], 7, v[4:5]
	v_lshl_add_u64 v[4:5], v[142:143], 0, v[4:5]
	global_store_dwordx4 v[4:5], v[0:3], off sc1
	s_and_b64 vcc, exec, s[2:3]
	s_mov_b64 s[0:1], -1
	s_cbranch_vccnz .LBB0_510

.LBB0_664:
	v_add_u32_e32 v41, s0, v120
	v_add_u32_e32 v18, 0x1b800, v41
	v_add_u32_e32 v22, 0x1b840, v41
	ds_read_b128 v[18:21], v18
	ds_read_b128 v[22:25], v22
	v_add_u32_e32 v42, 0x1c100, v41
	v_add_u32_e32 v41, 0x1c140, v41
	ds_read_b128 v[42:45], v42
	ds_read_b128 v[46:49], v41
	s_waitcnt lgkmcnt(3)
	v_mfma_f32_16x16x32_bf16 v[26:29], v[0:3], v[18:21], 0
	s_addk_i32 s0, 0x1200
	s_cmpk_lg_i32 s0, 0x4800
	v_mfma_f32_16x16x32_bf16 v[18:21], v[8:11], v[18:21], 0
	s_waitcnt lgkmcnt(1)
	v_mfma_f32_16x16x32_bf16 v[50:53], v[0:3], v[42:45], 0
	v_mfma_f32_16x16x32_bf16 v[42:45], v[8:11], v[42:45], 0
	v_mfma_f32_16x16x32_bf16 v[26:29], v[4:7], v[22:25], v[26:29]
	v_mfma_f32_16x16x32_bf16 v[18:21], v[12:15], v[22:25], v[18:21]
	s_waitcnt lgkmcnt(0)
	v_mfma_f32_16x16x32_bf16 v[22:25], v[4:7], v[46:49], v[50:53]
	s_nop 4
	v_cvt_pk_bf16_f32 v26, v26, v27
	v_cvt_pk_bf16_f32 v27, v28, v29
	v_cvt_pk_bf16_f32 v28, v18, v19
	v_mfma_f32_16x16x32_bf16 v[42:45], v[12:15], v[46:49], v[42:45]
	v_cvt_pk_bf16_f32 v29, v20, v21
	v_cvt_pk_bf16_f32 v20, v22, v23
	v_cvt_pk_bf16_f32 v21, v24, v25
	s_nop 4
	v_cvt_pk_bf16_f32 v22, v42, v43
	v_cvt_pk_bf16_f32 v23, v44, v45
	v_permlane16_swap_b32_e32 v26, v28
	v_permlane16_swap_b32_e32 v27, v29
	s_nop 0
	v_permlane16_swap_b32_e32 v20, v22
	v_permlane16_swap_b32_e32 v21, v23
	global_store_dwordx4 v[16:17], v[26:29], off offset:-4096 sc1
	global_store_dwordx4 v[16:17], v[20:23], off sc1
	v_lshl_add_u64 v[16:17], v[16:17], 0, s[24:25]
	s_cbranch_scc1 .LBB0_664
	s_add_i32 s30, s30, s72
	s_cmpk_lt_i32 s30, 0x880
	s_barrier
	s_cbranch_scc1 .LBB0_647

.LBB0_724:
	s_and_b64 s[10:11], vcc, exec
	s_mov_b32 s12, 0x8000
	s_mov_b32 s18, 0xffff8000
	s_movk_i32 s14, 0x200
	s_mov_b32 s19, 0xfffffe00
	s_cmp_lg_u64 s[10:11], 0
	s_cselect_b32 s12, s12, s18
	s_cselect_b32 s13, 0, -1
	s_cselect_b32 s14, s14, s19
	s_cselect_b32 s15, 0, -1
	s_cselect_b32 s16, 0, 63
	s_mov_b32 s17, 0
	s_lshl_b32 s18, s16, 15
	s_mov_b32 s19, 0
	v_lshl_add_u64 v[34:35], v[8:9], 0, s[18:19]
	v_lshl_add_u64 v[38:39], v[10:11], 0, s[16:17]
	v_lshlrev_b64 v[38:39], 9, v[38:39]
	v_lshl_add_u64 v[38:39], v[38:39], 0, v[6:7]
	v_mov_b32_e32 v36, v34
	v_mov_b32_e32 v37, v35
	global_load_dwordx4 v[40:43], v[34:35], off
	global_load_dwordx4 v[104:107], v[38:39], off
	global_load_dwordx4 v[170:173], v[38:39], off offset:16
	v_lshl_add_u64 v[34:35], v[34:35], 0, s[12:13]
	v_lshl_add_u64 v[38:39], v[38:39], 0, s[14:15]
	global_load_dwordx4 v[44:47], v[34:35], off
	global_load_dwordx4 v[108:111], v[38:39], off
	global_load_dwordx4 v[174:177], v[38:39], off offset:16
	v_lshl_add_u64 v[34:35], v[34:35], 0, s[12:13]
	v_lshl_add_u64 v[38:39], v[38:39], 0, s[14:15]
	global_load_dwordx4 v[48:51], v[34:35], off
	global_load_dwordx4 v[112:115], v[38:39], off
	global_load_dwordx4 v[178:181], v[38:39], off offset:16
	v_lshl_add_u64 v[34:35], v[34:35], 0, s[12:13]
	v_lshl_add_u64 v[38:39], v[38:39], 0, s[14:15]
	global_load_dwordx4 v[52:55], v[34:35], off
	global_load_dwordx4 v[116:119], v[38:39], off
	global_load_dwordx4 v[186:189], v[38:39], off offset:16
	v_lshl_add_u64 v[34:35], v[34:35], 0, s[12:13]
	v_lshl_add_u64 v[38:39], v[38:39], 0, s[14:15]
	global_load_dwordx4 v[56:59], v[34:35], off
	global_load_dwordx4 v[120:123], v[38:39], off
	global_load_dwordx4 v[190:193], v[38:39], off offset:16
	v_lshl_add_u64 v[34:35], v[34:35], 0, s[12:13]
	v_lshl_add_u64 v[38:39], v[38:39], 0, s[14:15]
	global_load_dwordx4 v[60:63], v[34:35], off
	global_load_dwordx4 v[124:127], v[38:39], off
	global_load_dwordx4 v[194:197], v[38:39], off offset:16
	v_lshl_add_u64 v[34:35], v[34:35], 0, s[12:13]
	v_lshl_add_u64 v[38:39], v[38:39], 0, s[14:15]
	global_load_dwordx4 v[64:67], v[34:35], off
	global_load_dwordx4 v[128:131], v[38:39], off
	global_load_dwordx4 v[198:201], v[38:39], off offset:16
	v_lshl_add_u64 v[34:35], v[34:35], 0, s[12:13]
	v_lshl_add_u64 v[38:39], v[38:39], 0, s[14:15]
	global_load_dwordx4 v[68:71], v[34:35], off
	global_load_dwordx4 v[132:135], v[38:39], off
	global_load_dwordx4 v[202:205], v[38:39], off offset:16
	v_lshl_add_u64 v[34:35], v[34:35], 0, s[12:13]
	v_lshl_add_u64 v[38:39], v[38:39], 0, s[14:15]
	global_load_dwordx4 v[72:75], v[34:35], off
	global_load_dwordx4 v[136:139], v[38:39], off
	global_load_dwordx4 v[206:209], v[38:39], off offset:16
	v_lshl_add_u64 v[34:35], v[34:35], 0, s[12:13]
	v_lshl_add_u64 v[38:39], v[38:39], 0, s[14:15]
	s_waitcnt vmcnt(24)
	v_cvt_pk_bf16_f32 v0, v12, v13
	v_cvt_pk_bf16_f32 v1, v14, v15
	v_cvt_pk_bf16_f32 v2, v16, v17
	v_cvt_pk_bf16_f32 v3, v18, v19
	v_lshlrev_b32_e32 v26, 16, v40
	v_and_b32_e32 v27, 0xffff0000, v40
	v_lshlrev_b32_e32 v28, 16, v41
	v_and_b32_e32 v29, 0xffff0000, v41
	v_lshlrev_b32_e32 v30, 16, v42
	v_and_b32_e32 v31, 0xffff0000, v42
	v_lshlrev_b32_e32 v32, 16, v43
	v_and_b32_e32 v33, 0xffff0000, v43
	global_store_dwordx4 v[36:37], v[0:3], off sc1
	v_lshl_add_u64 v[36:37], v[36:37], 0, s[12:13]
	v_pk_fma_f32 v[12:13], v[12:13], v[104:105], v[26:27]
	v_pk_fma_f32 v[14:15], v[14:15], v[106:107], v[28:29]
	v_pk_fma_f32 v[16:17], v[16:17], v[170:171], v[30:31]
	v_pk_fma_f32 v[18:19], v[18:19], v[172:173], v[32:33]
	global_load_dwordx4 v[76:79], v[34:35], off
	global_load_dwordx4 v[140:143], v[38:39], off
	global_load_dwordx4 v[210:213], v[38:39], off offset:16
	v_lshl_add_u64 v[34:35], v[34:35], 0, s[12:13]
	v_lshl_add_u64 v[38:39], v[38:39], 0, s[14:15]
	s_waitcnt vmcnt(25)
	v_cvt_pk_bf16_f32 v22, v12, v13
	v_cvt_pk_bf16_f32 v23, v14, v15
	v_cvt_pk_bf16_f32 v24, v16, v17
	v_cvt_pk_bf16_f32 v25, v18, v19
	v_lshlrev_b32_e32 v26, 16, v44
	v_and_b32_e32 v27, 0xffff0000, v44
	v_lshlrev_b32_e32 v28, 16, v45
	v_and_b32_e32 v29, 0xffff0000, v45
	v_lshlrev_b32_e32 v30, 16, v46
	v_and_b32_e32 v31, 0xffff0000, v46
	v_lshlrev_b32_e32 v32, 16, v47
	v_and_b32_e32 v33, 0xffff0000, v47
	global_store_dwordx4 v[36:37], v[22:25], off sc1
	v_lshl_add_u64 v[36:37], v[36:37], 0, s[12:13]
	v_pk_fma_f32 v[12:13], v[12:13], v[108:109], v[26:27]
	v_pk_fma_f32 v[14:15], v[14:15], v[110:111], v[28:29]
	v_pk_fma_f32 v[16:17], v[16:17], v[174:175], v[30:31]
	v_pk_fma_f32 v[18:19], v[18:19], v[176:177], v[32:33]
	global_load_dwordx4 v[80:83], v[34:35], off
	global_load_dwordx4 v[146:149], v[38:39], off
	global_load_dwordx4 v[214:217], v[38:39], off offset:16
	v_lshl_add_u64 v[34:35], v[34:35], 0, s[12:13]
	v_lshl_add_u64 v[38:39], v[38:39], 0, s[14:15]
	s_waitcnt vmcnt(26)
	v_cvt_pk_bf16_f32 v0, v12, v13
	v_cvt_pk_bf16_f32 v1, v14, v15
	v_cvt_pk_bf16_f32 v2, v16, v17
	v_cvt_pk_bf16_f32 v3, v18, v19
	v_lshlrev_b32_e32 v26, 16, v48
	v_and_b32_e32 v27, 0xffff0000, v48
	v_lshlrev_b32_e32 v28, 16, v49
	v_and_b32_e32 v29, 0xffff0000, v49
	v_lshlrev_b32_e32 v30, 16, v50
	v_and_b32_e32 v31, 0xffff0000, v50
	v_lshlrev_b32_e32 v32, 16, v51
	v_and_b32_e32 v33, 0xffff0000, v51
	global_store_dwordx4 v[36:37], v[0:3], off sc1
	v_lshl_add_u64 v[36:37], v[36:37], 0, s[12:13]
	v_pk_fma_f32 v[12:13], v[12:13], v[112:113], v[26:27]
	v_pk_fma_f32 v[14:15], v[14:15], v[114:115], v[28:29]
	v_pk_fma_f32 v[16:17], v[16:17], v[178:179], v[30:31]
	v_pk_fma_f32 v[18:19], v[18:19], v[180:181], v[32:33]
	global_load_dwordx4 v[84:87], v[34:35], off
	global_load_dwordx4 v[150:153], v[38:39], off
	global_load_dwordx4 v[218:221], v[38:39], off offset:16
	v_lshl_add_u64 v[34:35], v[34:35], 0, s[12:13]
	v_lshl_add_u64 v[38:39], v[38:39], 0, s[14:15]
	s_waitcnt vmcnt(27)
	v_cvt_pk_bf16_f32 v22, v12, v13
	v_cvt_pk_bf16_f32 v23, v14, v15
	v_cvt_pk_bf16_f32 v24, v16, v17
	v_cvt_pk_bf16_f32 v25, v18, v19
	v_lshlrev_b32_e32 v26, 16, v52
	v_and_b32_e32 v27, 0xffff0000, v52
	v_lshlrev_b32_e32 v28, 16, v53
	v_and_b32_e32 v29, 0xffff0000, v53
	v_lshlrev_b32_e32 v30, 16, v54
	v_and_b32_e32 v31, 0xffff0000, v54
	v_lshlrev_b32_e32 v32, 16, v55
	v_and_b32_e32 v33, 0xffff0000, v55
	global_store_dwordx4 v[36:37], v[22:25], off sc1
	v_lshl_add_u64 v[36:37], v[36:37], 0, s[12:13]
	v_pk_fma_f32 v[12:13], v[12:13], v[116:117], v[26:27]
	v_pk_fma_f32 v[14:15], v[14:15], v[118:119], v[28:29]
	v_pk_fma_f32 v[16:17], v[16:17], v[186:187], v[30:31]
	v_pk_fma_f32 v[18:19], v[18:19], v[188:189], v[32:33]
	global_load_dwordx4 v[88:91], v[34:35], off
	global_load_dwordx4 v[154:157], v[38:39], off
	global_load_dwordx4 v[222:225], v[38:39], off offset:16
	v_lshl_add_u64 v[34:35], v[34:35], 0, s[12:13]
	v_lshl_add_u64 v[38:39], v[38:39], 0, s[14:15]
	s_waitcnt vmcnt(28)
	v_cvt_pk_bf16_f32 v0, v12, v13
	v_cvt_pk_bf16_f32 v1, v14, v15
	v_cvt_pk_bf16_f32 v2, v16, v17
	v_cvt_pk_bf16_f32 v3, v18, v19
	v_lshlrev_b32_e32 v26, 16, v56
	v_and_b32_e32 v27, 0xffff0000, v56
	v_lshlrev_b32_e32 v28, 16, v57
	v_and_b32_e32 v29, 0xffff0000, v57
	v_lshlrev_b32_e32 v30, 16, v58
	v_and_b32_e32 v31, 0xffff0000, v58
	v_lshlrev_b32_e32 v32, 16, v59
	v_and_b32_e32 v33, 0xffff0000, v59
	global_store_dwordx4 v[36:37], v[0:3], off sc1
	v_lshl_add_u64 v[36:37], v[36:37], 0, s[12:13]
	v_pk_fma_f32 v[12:13], v[12:13], v[120:121], v[26:27]
	v_pk_fma_f32 v[14:15], v[14:15], v[122:123], v[28:29]
	v_pk_fma_f32 v[16:17], v[16:17], v[190:191], v[30:31]
	v_pk_fma_f32 v[18:19], v[18:19], v[192:193], v[32:33]
	global_load_dwordx4 v[92:95], v[34:35], off
	global_load_dwordx4 v[158:161], v[38:39], off
	global_load_dwordx4 v[226:229], v[38:39], off offset:16
	v_lshl_add_u64 v[34:35], v[34:35], 0, s[12:13]
	v_lshl_add_u64 v[38:39], v[38:39], 0, s[14:15]
	s_waitcnt vmcnt(29)
	v_cvt_pk_bf16_f32 v22, v12, v13
	v_cvt_pk_bf16_f32 v23, v14, v15
	v_cvt_pk_bf16_f32 v24, v16, v17
	v_cvt_pk_bf16_f32 v25, v18, v19
	v_lshlrev_b32_e32 v26, 16, v60
	v_and_b32_e32 v27, 0xffff0000, v60
	v_lshlrev_b32_e32 v28, 16, v61
	v_and_b32_e32 v29, 0xffff0000, v61
	v_lshlrev_b32_e32 v30, 16, v62
	v_and_b32_e32 v31, 0xffff0000, v62
	v_lshlrev_b32_e32 v32, 16, v63
	v_and_b32_e32 v33, 0xffff0000, v63
	global_store_dwordx4 v[36:37], v[22:25], off sc1
	v_lshl_add_u64 v[36:37], v[36:37], 0, s[12:13]
	v_pk_fma_f32 v[12:13], v[12:13], v[124:125], v[26:27]
	v_pk_fma_f32 v[14:15], v[14:15], v[126:127], v[28:29]
	v_pk_fma_f32 v[16:17], v[16:17], v[194:195], v[30:31]
	v_pk_fma_f32 v[18:19], v[18:19], v[196:197], v[32:33]
	global_load_dwordx4 v[96:99], v[34:35], off
	global_load_dwordx4 v[162:165], v[38:39], off
	global_load_dwordx4 v[230:233], v[38:39], off offset:16
	v_lshl_add_u64 v[34:35], v[34:35], 0, s[12:13]
	v_lshl_add_u64 v[38:39], v[38:39], 0, s[14:15]
	s_waitcnt vmcnt(30)
	v_cvt_pk_bf16_f32 v0, v12, v13
	v_cvt_pk_bf16_f32 v1, v14, v15
	v_cvt_pk_bf16_f32 v2, v16, v17
	v_cvt_pk_bf16_f32 v3, v18, v19
	v_lshlrev_b32_e32 v26, 16, v64
	v_and_b32_e32 v27, 0xffff0000, v64
	v_lshlrev_b32_e32 v28, 16, v65
	v_and_b32_e32 v29, 0xffff0000, v65
	v_lshlrev_b32_e32 v30, 16, v66
	v_and_b32_e32 v31, 0xffff0000, v66
	v_lshlrev_b32_e32 v32, 16, v67
	v_and_b32_e32 v33, 0xffff0000, v67
	global_store_dwordx4 v[36:37], v[0:3], off sc1
	v_lshl_add_u64 v[36:37], v[36:37], 0, s[12:13]
	v_pk_fma_f32 v[12:13], v[12:13], v[128:129], v[26:27]
	v_pk_fma_f32 v[14:15], v[14:15], v[130:131], v[28:29]
	v_pk_fma_f32 v[16:17], v[16:17], v[198:199], v[30:31]
	v_pk_fma_f32 v[18:19], v[18:19], v[200:201], v[32:33]
	global_load_dwordx4 v[100:103], v[34:35], off
	global_load_dwordx4 v[166:169], v[38:39], off
	global_load_dwordx4 v[234:237], v[38:39], off offset:16
	v_lshl_add_u64 v[34:35], v[34:35], 0, s[12:13]
	v_lshl_add_u64 v[38:39], v[38:39], 0, s[14:15]
	s_waitcnt vmcnt(31)
	v_cvt_pk_bf16_f32 v22, v12, v13
	v_cvt_pk_bf16_f32 v23, v14, v15
	v_cvt_pk_bf16_f32 v24, v16, v17
	v_cvt_pk_bf16_f32 v25, v18, v19
	v_lshlrev_b32_e32 v26, 16, v68
	v_and_b32_e32 v27, 0xffff0000, v68
	v_lshlrev_b32_e32 v28, 16, v69
	v_and_b32_e32 v29, 0xffff0000, v69
	v_lshlrev_b32_e32 v30, 16, v70
	v_and_b32_e32 v31, 0xffff0000, v70
	v_lshlrev_b32_e32 v32, 16, v71
	v_and_b32_e32 v33, 0xffff0000, v71
	global_store_dwordx4 v[36:37], v[22:25], off sc1
	v_lshl_add_u64 v[36:37], v[36:37], 0, s[12:13]
	v_pk_fma_f32 v[12:13], v[12:13], v[132:133], v[26:27]
	v_pk_fma_f32 v[14:15], v[14:15], v[134:135], v[28:29]
	v_pk_fma_f32 v[16:17], v[16:17], v[202:203], v[30:31]
	v_pk_fma_f32 v[18:19], v[18:19], v[204:205], v[32:33]
	global_load_dwordx4 v[40:43], v[34:35], off
	global_load_dwordx4 v[104:107], v[38:39], off
	global_load_dwordx4 v[170:173], v[38:39], off offset:16
	v_lshl_add_u64 v[34:35], v[34:35], 0, s[12:13]
	v_lshl_add_u64 v[38:39], v[38:39], 0, s[14:15]
	s_waitcnt vmcnt(32)
	v_cvt_pk_bf16_f32 v0, v12, v13
	v_cvt_pk_bf16_f32 v1, v14, v15
	v_cvt_pk_bf16_f32 v2, v16, v17
	v_cvt_pk_bf16_f32 v3, v18, v19
	v_lshlrev_b32_e32 v26, 16, v72
	v_and_b32_e32 v27, 0xffff0000, v72
	v_lshlrev_b32_e32 v28, 16, v73
	v_and_b32_e32 v29, 0xffff0000, v73
	v_lshlrev_b32_e32 v30, 16, v74
	v_and_b32_e32 v31, 0xffff0000, v74
	v_lshlrev_b32_e32 v32, 16, v75
	v_and_b32_e32 v33, 0xffff0000, v75
	global_store_dwordx4 v[36:37], v[0:3], off sc1
	v_lshl_add_u64 v[36:37], v[36:37], 0, s[12:13]
	v_pk_fma_f32 v[12:13], v[12:13], v[136:137], v[26:27]
	v_pk_fma_f32 v[14:15], v[14:15], v[138:139], v[28:29]
	v_pk_fma_f32 v[16:17], v[16:17], v[206:207], v[30:31]
	v_pk_fma_f32 v[18:19], v[18:19], v[208:209], v[32:33]
	global_load_dwordx4 v[44:47], v[34:35], off
	global_load_dwordx4 v[108:111], v[38:39], off
	global_load_dwordx4 v[174:177], v[38:39], off offset:16
	v_lshl_add_u64 v[34:35], v[34:35], 0, s[12:13]
	v_lshl_add_u64 v[38:39], v[38:39], 0, s[14:15]
	s_waitcnt vmcnt(32)
	v_cvt_pk_bf16_f32 v22, v12, v13
	v_cvt_pk_bf16_f32 v23, v14, v15
	v_cvt_pk_bf16_f32 v24, v16, v17
	v_cvt_pk_bf16_f32 v25, v18, v19
	v_lshlrev_b32_e32 v26, 16, v76
	v_and_b32_e32 v27, 0xffff0000, v76
	v_lshlrev_b32_e32 v28, 16, v77
	v_and_b32_e32 v29, 0xffff0000, v77
	v_lshlrev_b32_e32 v30, 16, v78
	v_and_b32_e32 v31, 0xffff0000, v78
	v_lshlrev_b32_e32 v32, 16, v79
	v_and_b32_e32 v33, 0xffff0000, v79
	global_store_dwordx4 v[36:37], v[22:25], off sc1
	v_lshl_add_u64 v[36:37], v[36:37], 0, s[12:13]
	v_pk_fma_f32 v[12:13], v[12:13], v[140:141], v[26:27]
	v_pk_fma_f32 v[14:15], v[14:15], v[142:143], v[28:29]
	v_pk_fma_f32 v[16:17], v[16:17], v[210:211], v[30:31]
	v_pk_fma_f32 v[18:19], v[18:19], v[212:213], v[32:33]
	global_load_dwordx4 v[48:51], v[34:35], off
	global_load_dwordx4 v[112:115], v[38:39], off
	global_load_dwordx4 v[178:181], v[38:39], off offset:16
	v_lshl_add_u64 v[34:35], v[34:35], 0, s[12:13]
	v_lshl_add_u64 v[38:39], v[38:39], 0, s[14:15]
	s_waitcnt vmcnt(32)
	v_cvt_pk_bf16_f32 v0, v12, v13
	v_cvt_pk_bf16_f32 v1, v14, v15
	v_cvt_pk_bf16_f32 v2, v16, v17
	v_cvt_pk_bf16_f32 v3, v18, v19
	v_lshlrev_b32_e32 v26, 16, v80
	v_and_b32_e32 v27, 0xffff0000, v80
	v_lshlrev_b32_e32 v28, 16, v81
	v_and_b32_e32 v29, 0xffff0000, v81
	v_lshlrev_b32_e32 v30, 16, v82
	v_and_b32_e32 v31, 0xffff0000, v82
	v_lshlrev_b32_e32 v32, 16, v83
	v_and_b32_e32 v33, 0xffff0000, v83
	global_store_dwordx4 v[36:37], v[0:3], off sc1
	v_lshl_add_u64 v[36:37], v[36:37], 0, s[12:13]
	v_pk_fma_f32 v[12:13], v[12:13], v[146:147], v[26:27]
	v_pk_fma_f32 v[14:15], v[14:15], v[148:149], v[28:29]
	v_pk_fma_f32 v[16:17], v[16:17], v[214:215], v[30:31]
	v_pk_fma_f32 v[18:19], v[18:19], v[216:217], v[32:33]
	global_load_dwordx4 v[52:55], v[34:35], off
	global_load_dwordx4 v[116:119], v[38:39], off
	global_load_dwordx4 v[186:189], v[38:39], off offset:16
	v_lshl_add_u64 v[34:35], v[34:35], 0, s[12:13]
	v_lshl_add_u64 v[38:39], v[38:39], 0, s[14:15]
	s_waitcnt vmcnt(32)
	v_cvt_pk_bf16_f32 v22, v12, v13
	v_cvt_pk_bf16_f32 v23, v14, v15
	v_cvt_pk_bf16_f32 v24, v16, v17
	v_cvt_pk_bf16_f32 v25, v18, v19
	v_lshlrev_b32_e32 v26, 16, v84
	v_and_b32_e32 v27, 0xffff0000, v84
	v_lshlrev_b32_e32 v28, 16, v85
	v_and_b32_e32 v29, 0xffff0000, v85
	v_lshlrev_b32_e32 v30, 16, v86
	v_and_b32_e32 v31, 0xffff0000, v86
	v_lshlrev_b32_e32 v32, 16, v87
	v_and_b32_e32 v33, 0xffff0000, v87
	global_store_dwordx4 v[36:37], v[22:25], off sc1
	v_lshl_add_u64 v[36:37], v[36:37], 0, s[12:13]
	v_pk_fma_f32 v[12:13], v[12:13], v[150:151], v[26:27]
	v_pk_fma_f32 v[14:15], v[14:15], v[152:153], v[28:29]
	v_pk_fma_f32 v[16:17], v[16:17], v[218:219], v[30:31]
	v_pk_fma_f32 v[18:19], v[18:19], v[220:221], v[32:33]
	global_load_dwordx4 v[56:59], v[34:35], off
	global_load_dwordx4 v[120:123], v[38:39], off
	global_load_dwordx4 v[190:193], v[38:39], off offset:16
	v_lshl_add_u64 v[34:35], v[34:35], 0, s[12:13]
	v_lshl_add_u64 v[38:39], v[38:39], 0, s[14:15]
	s_waitcnt vmcnt(32)
	v_cvt_pk_bf16_f32 v0, v12, v13
	v_cvt_pk_bf16_f32 v1, v14, v15
	v_cvt_pk_bf16_f32 v2, v16, v17
	v_cvt_pk_bf16_f32 v3, v18, v19
	v_lshlrev_b32_e32 v26, 16, v88
	v_and_b32_e32 v27, 0xffff0000, v88
	v_lshlrev_b32_e32 v28, 16, v89
	v_and_b32_e32 v29, 0xffff0000, v89
	v_lshlrev_b32_e32 v30, 16, v90
	v_and_b32_e32 v31, 0xffff0000, v90
	v_lshlrev_b32_e32 v32, 16, v91
	v_and_b32_e32 v33, 0xffff0000, v91
	global_store_dwordx4 v[36:37], v[0:3], off sc1
	v_lshl_add_u64 v[36:37], v[36:37], 0, s[12:13]
	v_pk_fma_f32 v[12:13], v[12:13], v[154:155], v[26:27]
	v_pk_fma_f32 v[14:15], v[14:15], v[156:157], v[28:29]
	v_pk_fma_f32 v[16:17], v[16:17], v[222:223], v[30:31]
	v_pk_fma_f32 v[18:19], v[18:19], v[224:225], v[32:33]
	global_load_dwordx4 v[60:63], v[34:35], off
	global_load_dwordx4 v[124:127], v[38:39], off
	global_load_dwordx4 v[194:197], v[38:39], off offset:16
	v_lshl_add_u64 v[34:35], v[34:35], 0, s[12:13]
	v_lshl_add_u64 v[38:39], v[38:39], 0, s[14:15]
	s_waitcnt vmcnt(32)
	v_cvt_pk_bf16_f32 v22, v12, v13
	v_cvt_pk_bf16_f32 v23, v14, v15
	v_cvt_pk_bf16_f32 v24, v16, v17
	v_cvt_pk_bf16_f32 v25, v18, v19
	v_lshlrev_b32_e32 v26, 16, v92
	v_and_b32_e32 v27, 0xffff0000, v92
	v_lshlrev_b32_e32 v28, 16, v93
	v_and_b32_e32 v29, 0xffff0000, v93
	v_lshlrev_b32_e32 v30, 16, v94
	v_and_b32_e32 v31, 0xffff0000, v94
	v_lshlrev_b32_e32 v32, 16, v95
	v_and_b32_e32 v33, 0xffff0000, v95
	global_store_dwordx4 v[36:37], v[22:25], off sc1
	v_lshl_add_u64 v[36:37], v[36:37], 0, s[12:13]
	v_pk_fma_f32 v[12:13], v[12:13], v[158:159], v[26:27]
	v_pk_fma_f32 v[14:15], v[14:15], v[160:161], v[28:29]
	v_pk_fma_f32 v[16:17], v[16:17], v[226:227], v[30:31]
	v_pk_fma_f32 v[18:19], v[18:19], v[228:229], v[32:33]
	global_load_dwordx4 v[64:67], v[34:35], off
	global_load_dwordx4 v[128:131], v[38:39], off
	global_load_dwordx4 v[198:201], v[38:39], off offset:16
	v_lshl_add_u64 v[34:35], v[34:35], 0, s[12:13]
	v_lshl_add_u64 v[38:39], v[38:39], 0, s[14:15]
	s_waitcnt vmcnt(32)
	v_cvt_pk_bf16_f32 v0, v12, v13
	v_cvt_pk_bf16_f32 v1, v14, v15
	v_cvt_pk_bf16_f32 v2, v16, v17
	v_cvt_pk_bf16_f32 v3, v18, v19
	v_lshlrev_b32_e32 v26, 16, v96
	v_and_b32_e32 v27, 0xffff0000, v96
	v_lshlrev_b32_e32 v28, 16, v97
	v_and_b32_e32 v29, 0xffff0000, v97
	v_lshlrev_b32_e32 v30, 16, v98
	v_and_b32_e32 v31, 0xffff0000, v98
	v_lshlrev_b32_e32 v32, 16, v99
	v_and_b32_e32 v33, 0xffff0000, v99
	global_store_dwordx4 v[36:37], v[0:3], off sc1
	v_lshl_add_u64 v[36:37], v[36:37], 0, s[12:13]
	v_pk_fma_f32 v[12:13], v[12:13], v[162:163], v[26:27]
	v_pk_fma_f32 v[14:15], v[14:15], v[164:165], v[28:29]
	v_pk_fma_f32 v[16:17], v[16:17], v[230:231], v[30:31]
	v_pk_fma_f32 v[18:19], v[18:19], v[232:233], v[32:33]
	global_load_dwordx4 v[68:71], v[34:35], off
	global_load_dwordx4 v[132:135], v[38:39], off
	global_load_dwordx4 v[202:205], v[38:39], off offset:16
	v_lshl_add_u64 v[34:35], v[34:35], 0, s[12:13]
	v_lshl_add_u64 v[38:39], v[38:39], 0, s[14:15]
	s_waitcnt vmcnt(32)
	v_cvt_pk_bf16_f32 v22, v12, v13
	v_cvt_pk_bf16_f32 v23, v14, v15
	v_cvt_pk_bf16_f32 v24, v16, v17
	v_cvt_pk_bf16_f32 v25, v18, v19
	v_lshlrev_b32_e32 v26, 16, v100
	v_and_b32_e32 v27, 0xffff0000, v100
	v_lshlrev_b32_e32 v28, 16, v101
	v_and_b32_e32 v29, 0xffff0000, v101
	v_lshlrev_b32_e32 v30, 16, v102
	v_and_b32_e32 v31, 0xffff0000, v102
	v_lshlrev_b32_e32 v32, 16, v103
	v_and_b32_e32 v33, 0xffff0000, v103
	global_store_dwordx4 v[36:37], v[22:25], off sc1
	v_lshl_add_u64 v[36:37], v[36:37], 0, s[12:13]
	v_pk_fma_f32 v[12:13], v[12:13], v[166:167], v[26:27]
	v_pk_fma_f32 v[14:15], v[14:15], v[168:169], v[28:29]
	v_pk_fma_f32 v[16:17], v[16:17], v[234:235], v[30:31]
	v_pk_fma_f32 v[18:19], v[18:19], v[236:237], v[32:33]
	global_load_dwordx4 v[72:75], v[34:35], off
	global_load_dwordx4 v[136:139], v[38:39], off
	global_load_dwordx4 v[206:209], v[38:39], off offset:16
	v_lshl_add_u64 v[34:35], v[34:35], 0, s[12:13]
	v_lshl_add_u64 v[38:39], v[38:39], 0, s[14:15]
	s_waitcnt vmcnt(32)
	v_cvt_pk_bf16_f32 v0, v12, v13
	v_cvt_pk_bf16_f32 v1, v14, v15
	v_cvt_pk_bf16_f32 v2, v16, v17
	v_cvt_pk_bf16_f32 v3, v18, v19
	v_lshlrev_b32_e32 v26, 16, v40
	v_and_b32_e32 v27, 0xffff0000, v40
	v_lshlrev_b32_e32 v28, 16, v41
	v_and_b32_e32 v29, 0xffff0000, v41
	v_lshlrev_b32_e32 v30, 16, v42
	v_and_b32_e32 v31, 0xffff0000, v42
	v_lshlrev_b32_e32 v32, 16, v43
	v_and_b32_e32 v33, 0xffff0000, v43
	global_store_dwordx4 v[36:37], v[0:3], off sc1
	v_lshl_add_u64 v[36:37], v[36:37], 0, s[12:13]
	v_pk_fma_f32 v[12:13], v[12:13], v[104:105], v[26:27]
	v_pk_fma_f32 v[14:15], v[14:15], v[106:107], v[28:29]
	v_pk_fma_f32 v[16:17], v[16:17], v[170:171], v[30:31]
	v_pk_fma_f32 v[18:19], v[18:19], v[172:173], v[32:33]
	global_load_dwordx4 v[76:79], v[34:35], off
	global_load_dwordx4 v[140:143], v[38:39], off
	global_load_dwordx4 v[210:213], v[38:39], off offset:16
	v_lshl_add_u64 v[34:35], v[34:35], 0, s[12:13]
	v_lshl_add_u64 v[38:39], v[38:39], 0, s[14:15]
	s_waitcnt vmcnt(32)
	v_cvt_pk_bf16_f32 v22, v12, v13
	v_cvt_pk_bf16_f32 v23, v14, v15
	v_cvt_pk_bf16_f32 v24, v16, v17
	v_cvt_pk_bf16_f32 v25, v18, v19
	v_lshlrev_b32_e32 v26, 16, v44
	v_and_b32_e32 v27, 0xffff0000, v44
	v_lshlrev_b32_e32 v28, 16, v45
	v_and_b32_e32 v29, 0xffff0000, v45
	v_lshlrev_b32_e32 v30, 16, v46
	v_and_b32_e32 v31, 0xffff0000, v46
	v_lshlrev_b32_e32 v32, 16, v47
	v_and_b32_e32 v33, 0xffff0000, v47
	global_store_dwordx4 v[36:37], v[22:25], off sc1
	v_lshl_add_u64 v[36:37], v[36:37], 0, s[12:13]
	v_pk_fma_f32 v[12:13], v[12:13], v[108:109], v[26:27]
	v_pk_fma_f32 v[14:15], v[14:15], v[110:111], v[28:29]
	v_pk_fma_f32 v[16:17], v[16:17], v[174:175], v[30:31]
	v_pk_fma_f32 v[18:19], v[18:19], v[176:177], v[32:33]
	global_load_dwordx4 v[80:83], v[34:35], off
	global_load_dwordx4 v[146:149], v[38:39], off
	global_load_dwordx4 v[214:217], v[38:39], off offset:16
	v_lshl_add_u64 v[34:35], v[34:35], 0, s[12:13]
	v_lshl_add_u64 v[38:39], v[38:39], 0, s[14:15]
	s_waitcnt vmcnt(32)
	v_cvt_pk_bf16_f32 v0, v12, v13
	v_cvt_pk_bf16_f32 v1, v14, v15
	v_cvt_pk_bf16_f32 v2, v16, v17
	v_cvt_pk_bf16_f32 v3, v18, v19
	v_lshlrev_b32_e32 v26, 16, v48
	v_and_b32_e32 v27, 0xffff0000, v48
	v_lshlrev_b32_e32 v28, 16, v49
	v_and_b32_e32 v29, 0xffff0000, v49
	v_lshlrev_b32_e32 v30, 16, v50
	v_and_b32_e32 v31, 0xffff0000, v50
	v_lshlrev_b32_e32 v32, 16, v51
	v_and_b32_e32 v33, 0xffff0000, v51
	global_store_dwordx4 v[36:37], v[0:3], off sc1
	v_lshl_add_u64 v[36:37], v[36:37], 0, s[12:13]
	v_pk_fma_f32 v[12:13], v[12:13], v[112:113], v[26:27]
	v_pk_fma_f32 v[14:15], v[14:15], v[114:115], v[28:29]
	v_pk_fma_f32 v[16:17], v[16:17], v[178:179], v[30:31]
	v_pk_fma_f32 v[18:19], v[18:19], v[180:181], v[32:33]
	global_load_dwordx4 v[84:87], v[34:35], off
	global_load_dwordx4 v[150:153], v[38:39], off
	global_load_dwordx4 v[218:221], v[38:39], off offset:16
	v_lshl_add_u64 v[34:35], v[34:35], 0, s[12:13]
	v_lshl_add_u64 v[38:39], v[38:39], 0, s[14:15]
	s_waitcnt vmcnt(32)
	v_cvt_pk_bf16_f32 v22, v12, v13
	v_cvt_pk_bf16_f32 v23, v14, v15
	v_cvt_pk_bf16_f32 v24, v16, v17
	v_cvt_pk_bf16_f32 v25, v18, v19
	v_lshlrev_b32_e32 v26, 16, v52
	v_and_b32_e32 v27, 0xffff0000, v52
	v_lshlrev_b32_e32 v28, 16, v53
	v_and_b32_e32 v29, 0xffff0000, v53
	v_lshlrev_b32_e32 v30, 16, v54
	v_and_b32_e32 v31, 0xffff0000, v54
	v_lshlrev_b32_e32 v32, 16, v55
	v_and_b32_e32 v33, 0xffff0000, v55
	global_store_dwordx4 v[36:37], v[22:25], off sc1
	v_lshl_add_u64 v[36:37], v[36:37], 0, s[12:13]
	v_pk_fma_f32 v[12:13], v[12:13], v[116:117], v[26:27]
	v_pk_fma_f32 v[14:15], v[14:15], v[118:119], v[28:29]
	v_pk_fma_f32 v[16:17], v[16:17], v[186:187], v[30:31]
	v_pk_fma_f32 v[18:19], v[18:19], v[188:189], v[32:33]
	global_load_dwordx4 v[88:91], v[34:35], off
	global_load_dwordx4 v[154:157], v[38:39], off
	global_load_dwordx4 v[222:225], v[38:39], off offset:16
	v_lshl_add_u64 v[34:35], v[34:35], 0, s[12:13]
	v_lshl_add_u64 v[38:39], v[38:39], 0, s[14:15]
	s_waitcnt vmcnt(32)
	v_cvt_pk_bf16_f32 v0, v12, v13
	v_cvt_pk_bf16_f32 v1, v14, v15
	v_cvt_pk_bf16_f32 v2, v16, v17
	v_cvt_pk_bf16_f32 v3, v18, v19
	v_lshlrev_b32_e32 v26, 16, v56
	v_and_b32_e32 v27, 0xffff0000, v56
	v_lshlrev_b32_e32 v28, 16, v57
	v_and_b32_e32 v29, 0xffff0000, v57
	v_lshlrev_b32_e32 v30, 16, v58
	v_and_b32_e32 v31, 0xffff0000, v58
	v_lshlrev_b32_e32 v32, 16, v59
	v_and_b32_e32 v33, 0xffff0000, v59
	global_store_dwordx4 v[36:37], v[0:3], off sc1
	v_lshl_add_u64 v[36:37], v[36:37], 0, s[12:13]
	v_pk_fma_f32 v[12:13], v[12:13], v[120:121], v[26:27]
	v_pk_fma_f32 v[14:15], v[14:15], v[122:123], v[28:29]
	v_pk_fma_f32 v[16:17], v[16:17], v[190:191], v[30:31]
	v_pk_fma_f32 v[18:19], v[18:19], v[192:193], v[32:33]
	global_load_dwordx4 v[92:95], v[34:35], off
	global_load_dwordx4 v[158:161], v[38:39], off
	global_load_dwordx4 v[226:229], v[38:39], off offset:16
	v_lshl_add_u64 v[34:35], v[34:35], 0, s[12:13]
	v_lshl_add_u64 v[38:39], v[38:39], 0, s[14:15]
	s_waitcnt vmcnt(32)
	v_cvt_pk_bf16_f32 v22, v12, v13
	v_cvt_pk_bf16_f32 v23, v14, v15
	v_cvt_pk_bf16_f32 v24, v16, v17
	v_cvt_pk_bf16_f32 v25, v18, v19
	v_lshlrev_b32_e32 v26, 16, v60
	v_and_b32_e32 v27, 0xffff0000, v60
	v_lshlrev_b32_e32 v28, 16, v61
	v_and_b32_e32 v29, 0xffff0000, v61
	v_lshlrev_b32_e32 v30, 16, v62
	v_and_b32_e32 v31, 0xffff0000, v62
	v_lshlrev_b32_e32 v32, 16, v63
	v_and_b32_e32 v33, 0xffff0000, v63
	global_store_dwordx4 v[36:37], v[22:25], off sc1
	v_lshl_add_u64 v[36:37], v[36:37], 0, s[12:13]
	v_pk_fma_f32 v[12:13], v[12:13], v[124:125], v[26:27]
	v_pk_fma_f32 v[14:15], v[14:15], v[126:127], v[28:29]
	v_pk_fma_f32 v[16:17], v[16:17], v[194:195], v[30:31]
	v_pk_fma_f32 v[18:19], v[18:19], v[196:197], v[32:33]
	global_load_dwordx4 v[96:99], v[34:35], off
	global_load_dwordx4 v[162:165], v[38:39], off
	global_load_dwordx4 v[230:233], v[38:39], off offset:16
	v_lshl_add_u64 v[34:35], v[34:35], 0, s[12:13]
	v_lshl_add_u64 v[38:39], v[38:39], 0, s[14:15]
	s_waitcnt vmcnt(32)
	v_cvt_pk_bf16_f32 v0, v12, v13
	v_cvt_pk_bf16_f32 v1, v14, v15
	v_cvt_pk_bf16_f32 v2, v16, v17
	v_cvt_pk_bf16_f32 v3, v18, v19
	v_lshlrev_b32_e32 v26, 16, v64
	v_and_b32_e32 v27, 0xffff0000, v64
	v_lshlrev_b32_e32 v28, 16, v65
	v_and_b32_e32 v29, 0xffff0000, v65
	v_lshlrev_b32_e32 v30, 16, v66
	v_and_b32_e32 v31, 0xffff0000, v66
	v_lshlrev_b32_e32 v32, 16, v67
	v_and_b32_e32 v33, 0xffff0000, v67
	global_store_dwordx4 v[36:37], v[0:3], off sc1
	v_lshl_add_u64 v[36:37], v[36:37], 0, s[12:13]
	v_pk_fma_f32 v[12:13], v[12:13], v[128:129], v[26:27]
	v_pk_fma_f32 v[14:15], v[14:15], v[130:131], v[28:29]
	v_pk_fma_f32 v[16:17], v[16:17], v[198:199], v[30:31]
	v_pk_fma_f32 v[18:19], v[18:19], v[200:201], v[32:33]
	global_load_dwordx4 v[100:103], v[34:35], off
	global_load_dwordx4 v[166:169], v[38:39], off
	global_load_dwordx4 v[234:237], v[38:39], off offset:16
	v_lshl_add_u64 v[34:35], v[34:35], 0, s[12:13]
	v_lshl_add_u64 v[38:39], v[38:39], 0, s[14:15]
	s_waitcnt vmcnt(32)
	v_cvt_pk_bf16_f32 v22, v12, v13
	v_cvt_pk_bf16_f32 v23, v14, v15
	v_cvt_pk_bf16_f32 v24, v16, v17
	v_cvt_pk_bf16_f32 v25, v18, v19
	v_lshlrev_b32_e32 v26, 16, v68
	v_and_b32_e32 v27, 0xffff0000, v68
	v_lshlrev_b32_e32 v28, 16, v69
	v_and_b32_e32 v29, 0xffff0000, v69
	v_lshlrev_b32_e32 v30, 16, v70
	v_and_b32_e32 v31, 0xffff0000, v70
	v_lshlrev_b32_e32 v32, 16, v71
	v_and_b32_e32 v33, 0xffff0000, v71
	global_store_dwordx4 v[36:37], v[22:25], off sc1
	v_lshl_add_u64 v[36:37], v[36:37], 0, s[12:13]
	v_pk_fma_f32 v[12:13], v[12:13], v[132:133], v[26:27]
	v_pk_fma_f32 v[14:15], v[14:15], v[134:135], v[28:29]
	v_pk_fma_f32 v[16:17], v[16:17], v[202:203], v[30:31]
	v_pk_fma_f32 v[18:19], v[18:19], v[204:205], v[32:33]
	global_load_dwordx4 v[40:43], v[34:35], off
	global_load_dwordx4 v[104:107], v[38:39], off
	global_load_dwordx4 v[170:173], v[38:39], off offset:16
	v_lshl_add_u64 v[34:35], v[34:35], 0, s[12:13]
	v_lshl_add_u64 v[38:39], v[38:39], 0, s[14:15]
	s_waitcnt vmcnt(32)
	v_cvt_pk_bf16_f32 v0, v12, v13
	v_cvt_pk_bf16_f32 v1, v14, v15
	v_cvt_pk_bf16_f32 v2, v16, v17
	v_cvt_pk_bf16_f32 v3, v18, v19
	v_lshlrev_b32_e32 v26, 16, v72
	v_and_b32_e32 v27, 0xffff0000, v72
	v_lshlrev_b32_e32 v28, 16, v73
	v_and_b32_e32 v29, 0xffff0000, v73
	v_lshlrev_b32_e32 v30, 16, v74
	v_and_b32_e32 v31, 0xffff0000, v74
	v_lshlrev_b32_e32 v32, 16, v75
	v_and_b32_e32 v33, 0xffff0000, v75
	global_store_dwordx4 v[36:37], v[0:3], off sc1
	v_lshl_add_u64 v[36:37], v[36:37], 0, s[12:13]
	v_pk_fma_f32 v[12:13], v[12:13], v[136:137], v[26:27]
	v_pk_fma_f32 v[14:15], v[14:15], v[138:139], v[28:29]
	v_pk_fma_f32 v[16:17], v[16:17], v[206:207], v[30:31]
	v_pk_fma_f32 v[18:19], v[18:19], v[208:209], v[32:33]
	global_load_dwordx4 v[44:47], v[34:35], off
	global_load_dwordx4 v[108:111], v[38:39], off
	global_load_dwordx4 v[174:177], v[38:39], off offset:16
	v_lshl_add_u64 v[34:35], v[34:35], 0, s[12:13]
	v_lshl_add_u64 v[38:39], v[38:39], 0, s[14:15]
	s_waitcnt vmcnt(32)
	v_cvt_pk_bf16_f32 v22, v12, v13
	v_cvt_pk_bf16_f32 v23, v14, v15
	v_cvt_pk_bf16_f32 v24, v16, v17
	v_cvt_pk_bf16_f32 v25, v18, v19
	v_lshlrev_b32_e32 v26, 16, v76
	v_and_b32_e32 v27, 0xffff0000, v76
	v_lshlrev_b32_e32 v28, 16, v77
	v_and_b32_e32 v29, 0xffff0000, v77
	v_lshlrev_b32_e32 v30, 16, v78
	v_and_b32_e32 v31, 0xffff0000, v78
	v_lshlrev_b32_e32 v32, 16, v79
	v_and_b32_e32 v33, 0xffff0000, v79
	global_store_dwordx4 v[36:37], v[22:25], off sc1
	v_lshl_add_u64 v[36:37], v[36:37], 0, s[12:13]
	v_pk_fma_f32 v[12:13], v[12:13], v[140:141], v[26:27]
	v_pk_fma_f32 v[14:15], v[14:15], v[142:143], v[28:29]
	v_pk_fma_f32 v[16:17], v[16:17], v[210:211], v[30:31]
	v_pk_fma_f32 v[18:19], v[18:19], v[212:213], v[32:33]
	global_load_dwordx4 v[48:51], v[34:35], off
	global_load_dwordx4 v[112:115], v[38:39], off
	global_load_dwordx4 v[178:181], v[38:39], off offset:16
	v_lshl_add_u64 v[34:35], v[34:35], 0, s[12:13]
	v_lshl_add_u64 v[38:39], v[38:39], 0, s[14:15]
	s_waitcnt vmcnt(32)
	v_cvt_pk_bf16_f32 v0, v12, v13
	v_cvt_pk_bf16_f32 v1, v14, v15
	v_cvt_pk_bf16_f32 v2, v16, v17
	v_cvt_pk_bf16_f32 v3, v18, v19
	v_lshlrev_b32_e32 v26, 16, v80
	v_and_b32_e32 v27, 0xffff0000, v80
	v_lshlrev_b32_e32 v28, 16, v81
	v_and_b32_e32 v29, 0xffff0000, v81
	v_lshlrev_b32_e32 v30, 16, v82
	v_and_b32_e32 v31, 0xffff0000, v82
	v_lshlrev_b32_e32 v32, 16, v83
	v_and_b32_e32 v33, 0xffff0000, v83
	global_store_dwordx4 v[36:37], v[0:3], off sc1
	v_lshl_add_u64 v[36:37], v[36:37], 0, s[12:13]
	v_pk_fma_f32 v[12:13], v[12:13], v[146:147], v[26:27]
	v_pk_fma_f32 v[14:15], v[14:15], v[148:149], v[28:29]
	v_pk_fma_f32 v[16:17], v[16:17], v[214:215], v[30:31]
	v_pk_fma_f32 v[18:19], v[18:19], v[216:217], v[32:33]
	global_load_dwordx4 v[52:55], v[34:35], off
	global_load_dwordx4 v[116:119], v[38:39], off
	global_load_dwordx4 v[186:189], v[38:39], off offset:16
	v_lshl_add_u64 v[34:35], v[34:35], 0, s[12:13]
	v_lshl_add_u64 v[38:39], v[38:39], 0, s[14:15]
	s_waitcnt vmcnt(32)
	v_cvt_pk_bf16_f32 v22, v12, v13
	v_cvt_pk_bf16_f32 v23, v14, v15
	v_cvt_pk_bf16_f32 v24, v16, v17
	v_cvt_pk_bf16_f32 v25, v18, v19
	v_lshlrev_b32_e32 v26, 16, v84
	v_and_b32_e32 v27, 0xffff0000, v84
	v_lshlrev_b32_e32 v28, 16, v85
	v_and_b32_e32 v29, 0xffff0000, v85
	v_lshlrev_b32_e32 v30, 16, v86
	v_and_b32_e32 v31, 0xffff0000, v86
	v_lshlrev_b32_e32 v32, 16, v87
	v_and_b32_e32 v33, 0xffff0000, v87
	global_store_dwordx4 v[36:37], v[22:25], off sc1
	v_lshl_add_u64 v[36:37], v[36:37], 0, s[12:13]
	v_pk_fma_f32 v[12:13], v[12:13], v[150:151], v[26:27]
	v_pk_fma_f32 v[14:15], v[14:15], v[152:153], v[28:29]
	v_pk_fma_f32 v[16:17], v[16:17], v[218:219], v[30:31]
	v_pk_fma_f32 v[18:19], v[18:19], v[220:221], v[32:33]
	global_load_dwordx4 v[56:59], v[34:35], off
	global_load_dwordx4 v[120:123], v[38:39], off
	global_load_dwordx4 v[190:193], v[38:39], off offset:16
	v_lshl_add_u64 v[34:35], v[34:35], 0, s[12:13]
	v_lshl_add_u64 v[38:39], v[38:39], 0, s[14:15]
	s_waitcnt vmcnt(32)
	v_cvt_pk_bf16_f32 v0, v12, v13
	v_cvt_pk_bf16_f32 v1, v14, v15
	v_cvt_pk_bf16_f32 v2, v16, v17
	v_cvt_pk_bf16_f32 v3, v18, v19
	v_lshlrev_b32_e32 v26, 16, v88
	v_and_b32_e32 v27, 0xffff0000, v88
	v_lshlrev_b32_e32 v28, 16, v89
	v_and_b32_e32 v29, 0xffff0000, v89
	v_lshlrev_b32_e32 v30, 16, v90
	v_and_b32_e32 v31, 0xffff0000, v90
	v_lshlrev_b32_e32 v32, 16, v91
	v_and_b32_e32 v33, 0xffff0000, v91
	global_store_dwordx4 v[36:37], v[0:3], off sc1
	v_lshl_add_u64 v[36:37], v[36:37], 0, s[12:13]
	v_pk_fma_f32 v[12:13], v[12:13], v[154:155], v[26:27]
	v_pk_fma_f32 v[14:15], v[14:15], v[156:157], v[28:29]
	v_pk_fma_f32 v[16:17], v[16:17], v[222:223], v[30:31]
	v_pk_fma_f32 v[18:19], v[18:19], v[224:225], v[32:33]
	global_load_dwordx4 v[60:63], v[34:35], off
	global_load_dwordx4 v[124:127], v[38:39], off
	global_load_dwordx4 v[194:197], v[38:39], off offset:16
	v_lshl_add_u64 v[34:35], v[34:35], 0, s[12:13]
	v_lshl_add_u64 v[38:39], v[38:39], 0, s[14:15]
	s_waitcnt vmcnt(32)
	v_cvt_pk_bf16_f32 v22, v12, v13
	v_cvt_pk_bf16_f32 v23, v14, v15
	v_cvt_pk_bf16_f32 v24, v16, v17
	v_cvt_pk_bf16_f32 v25, v18, v19
	v_lshlrev_b32_e32 v26, 16, v92
	v_and_b32_e32 v27, 0xffff0000, v92
	v_lshlrev_b32_e32 v28, 16, v93
	v_and_b32_e32 v29, 0xffff0000, v93
	v_lshlrev_b32_e32 v30, 16, v94
	v_and_b32_e32 v31, 0xffff0000, v94
	v_lshlrev_b32_e32 v32, 16, v95
	v_and_b32_e32 v33, 0xffff0000, v95
	global_store_dwordx4 v[36:37], v[22:25], off sc1
	v_lshl_add_u64 v[36:37], v[36:37], 0, s[12:13]
	v_pk_fma_f32 v[12:13], v[12:13], v[158:159], v[26:27]
	v_pk_fma_f32 v[14:15], v[14:15], v[160:161], v[28:29]
	v_pk_fma_f32 v[16:17], v[16:17], v[226:227], v[30:31]
	v_pk_fma_f32 v[18:19], v[18:19], v[228:229], v[32:33]
	global_load_dwordx4 v[64:67], v[34:35], off
	global_load_dwordx4 v[128:131], v[38:39], off
	global_load_dwordx4 v[198:201], v[38:39], off offset:16
	v_lshl_add_u64 v[34:35], v[34:35], 0, s[12:13]
	v_lshl_add_u64 v[38:39], v[38:39], 0, s[14:15]
	s_waitcnt vmcnt(32)
	v_cvt_pk_bf16_f32 v0, v12, v13
	v_cvt_pk_bf16_f32 v1, v14, v15
	v_cvt_pk_bf16_f32 v2, v16, v17
	v_cvt_pk_bf16_f32 v3, v18, v19
	v_lshlrev_b32_e32 v26, 16, v96
	v_and_b32_e32 v27, 0xffff0000, v96
	v_lshlrev_b32_e32 v28, 16, v97
	v_and_b32_e32 v29, 0xffff0000, v97
	v_lshlrev_b32_e32 v30, 16, v98
	v_and_b32_e32 v31, 0xffff0000, v98
	v_lshlrev_b32_e32 v32, 16, v99
	v_and_b32_e32 v33, 0xffff0000, v99
	global_store_dwordx4 v[36:37], v[0:3], off sc1
	v_lshl_add_u64 v[36:37], v[36:37], 0, s[12:13]
	v_pk_fma_f32 v[12:13], v[12:13], v[162:163], v[26:27]
	v_pk_fma_f32 v[14:15], v[14:15], v[164:165], v[28:29]
	v_pk_fma_f32 v[16:17], v[16:17], v[230:231], v[30:31]
	v_pk_fma_f32 v[18:19], v[18:19], v[232:233], v[32:33]
	global_load_dwordx4 v[68:71], v[34:35], off
	global_load_dwordx4 v[132:135], v[38:39], off
	global_load_dwordx4 v[202:205], v[38:39], off offset:16
	v_lshl_add_u64 v[34:35], v[34:35], 0, s[12:13]
	v_lshl_add_u64 v[38:39], v[38:39], 0, s[14:15]
	s_waitcnt vmcnt(32)
	v_cvt_pk_bf16_f32 v22, v12, v13
	v_cvt_pk_bf16_f32 v23, v14, v15
	v_cvt_pk_bf16_f32 v24, v16, v17
	v_cvt_pk_bf16_f32 v25, v18, v19
	v_lshlrev_b32_e32 v26, 16, v100
	v_and_b32_e32 v27, 0xffff0000, v100
	v_lshlrev_b32_e32 v28, 16, v101
	v_and_b32_e32 v29, 0xffff0000, v101
	v_lshlrev_b32_e32 v30, 16, v102
	v_and_b32_e32 v31, 0xffff0000, v102
	v_lshlrev_b32_e32 v32, 16, v103
	v_and_b32_e32 v33, 0xffff0000, v103
	global_store_dwordx4 v[36:37], v[22:25], off sc1
	v_lshl_add_u64 v[36:37], v[36:37], 0, s[12:13]
	v_pk_fma_f32 v[12:13], v[12:13], v[166:167], v[26:27]
	v_pk_fma_f32 v[14:15], v[14:15], v[168:169], v[28:29]
	v_pk_fma_f32 v[16:17], v[16:17], v[234:235], v[30:31]
	v_pk_fma_f32 v[18:19], v[18:19], v[236:237], v[32:33]
	global_load_dwordx4 v[72:75], v[34:35], off
	global_load_dwordx4 v[136:139], v[38:39], off
	global_load_dwordx4 v[206:209], v[38:39], off offset:16
	v_lshl_add_u64 v[34:35], v[34:35], 0, s[12:13]
	v_lshl_add_u64 v[38:39], v[38:39], 0, s[14:15]
	s_waitcnt vmcnt(32)
	v_cvt_pk_bf16_f32 v0, v12, v13
	v_cvt_pk_bf16_f32 v1, v14, v15
	v_cvt_pk_bf16_f32 v2, v16, v17
	v_cvt_pk_bf16_f32 v3, v18, v19
	v_lshlrev_b32_e32 v26, 16, v40
	v_and_b32_e32 v27, 0xffff0000, v40
	v_lshlrev_b32_e32 v28, 16, v41
	v_and_b32_e32 v29, 0xffff0000, v41
	v_lshlrev_b32_e32 v30, 16, v42
	v_and_b32_e32 v31, 0xffff0000, v42
	v_lshlrev_b32_e32 v32, 16, v43
	v_and_b32_e32 v33, 0xffff0000, v43
	global_store_dwordx4 v[36:37], v[0:3], off sc1
	v_lshl_add_u64 v[36:37], v[36:37], 0, s[12:13]
	v_pk_fma_f32 v[12:13], v[12:13], v[104:105], v[26:27]
	v_pk_fma_f32 v[14:15], v[14:15], v[106:107], v[28:29]
	v_pk_fma_f32 v[16:17], v[16:17], v[170:171], v[30:31]
	v_pk_fma_f32 v[18:19], v[18:19], v[172:173], v[32:33]
	global_load_dwordx4 v[76:79], v[34:35], off
	global_load_dwordx4 v[140:143], v[38:39], off
	global_load_dwordx4 v[210:213], v[38:39], off offset:16
	v_lshl_add_u64 v[34:35], v[34:35], 0, s[12:13]
	v_lshl_add_u64 v[38:39], v[38:39], 0, s[14:15]
	s_waitcnt vmcnt(32)
	v_cvt_pk_bf16_f32 v22, v12, v13
	v_cvt_pk_bf16_f32 v23, v14, v15
	v_cvt_pk_bf16_f32 v24, v16, v17
	v_cvt_pk_bf16_f32 v25, v18, v19
	v_lshlrev_b32_e32 v26, 16, v44
	v_and_b32_e32 v27, 0xffff0000, v44
	v_lshlrev_b32_e32 v28, 16, v45
	v_and_b32_e32 v29, 0xffff0000, v45
	v_lshlrev_b32_e32 v30, 16, v46
	v_and_b32_e32 v31, 0xffff0000, v46
	v_lshlrev_b32_e32 v32, 16, v47
	v_and_b32_e32 v33, 0xffff0000, v47
	global_store_dwordx4 v[36:37], v[22:25], off sc1
	v_lshl_add_u64 v[36:37], v[36:37], 0, s[12:13]
	v_pk_fma_f32 v[12:13], v[12:13], v[108:109], v[26:27]
	v_pk_fma_f32 v[14:15], v[14:15], v[110:111], v[28:29]
	v_pk_fma_f32 v[16:17], v[16:17], v[174:175], v[30:31]
	v_pk_fma_f32 v[18:19], v[18:19], v[176:177], v[32:33]
	global_load_dwordx4 v[80:83], v[34:35], off
	global_load_dwordx4 v[146:149], v[38:39], off
	global_load_dwordx4 v[214:217], v[38:39], off offset:16
	v_lshl_add_u64 v[34:35], v[34:35], 0, s[12:13]
	v_lshl_add_u64 v[38:39], v[38:39], 0, s[14:15]
	s_waitcnt vmcnt(32)
	v_cvt_pk_bf16_f32 v0, v12, v13
	v_cvt_pk_bf16_f32 v1, v14, v15
	v_cvt_pk_bf16_f32 v2, v16, v17
	v_cvt_pk_bf16_f32 v3, v18, v19
	v_lshlrev_b32_e32 v26, 16, v48
	v_and_b32_e32 v27, 0xffff0000, v48
	v_lshlrev_b32_e32 v28, 16, v49
	v_and_b32_e32 v29, 0xffff0000, v49
	v_lshlrev_b32_e32 v30, 16, v50
	v_and_b32_e32 v31, 0xffff0000, v50
	v_lshlrev_b32_e32 v32, 16, v51
	v_and_b32_e32 v33, 0xffff0000, v51
	global_store_dwordx4 v[36:37], v[0:3], off sc1
	v_lshl_add_u64 v[36:37], v[36:37], 0, s[12:13]
	v_pk_fma_f32 v[12:13], v[12:13], v[112:113], v[26:27]
	v_pk_fma_f32 v[14:15], v[14:15], v[114:115], v[28:29]
	v_pk_fma_f32 v[16:17], v[16:17], v[178:179], v[30:31]
	v_pk_fma_f32 v[18:19], v[18:19], v[180:181], v[32:33]
	global_load_dwordx4 v[84:87], v[34:35], off
	global_load_dwordx4 v[150:153], v[38:39], off
	global_load_dwordx4 v[218:221], v[38:39], off offset:16
	v_lshl_add_u64 v[34:35], v[34:35], 0, s[12:13]
	v_lshl_add_u64 v[38:39], v[38:39], 0, s[14:15]
	s_waitcnt vmcnt(32)
	v_cvt_pk_bf16_f32 v22, v12, v13
	v_cvt_pk_bf16_f32 v23, v14, v15
	v_cvt_pk_bf16_f32 v24, v16, v17
	v_cvt_pk_bf16_f32 v25, v18, v19
	v_lshlrev_b32_e32 v26, 16, v52
	v_and_b32_e32 v27, 0xffff0000, v52
	v_lshlrev_b32_e32 v28, 16, v53
	v_and_b32_e32 v29, 0xffff0000, v53
	v_lshlrev_b32_e32 v30, 16, v54
	v_and_b32_e32 v31, 0xffff0000, v54
	v_lshlrev_b32_e32 v32, 16, v55
	v_and_b32_e32 v33, 0xffff0000, v55
	global_store_dwordx4 v[36:37], v[22:25], off sc1
	v_lshl_add_u64 v[36:37], v[36:37], 0, s[12:13]
	v_pk_fma_f32 v[12:13], v[12:13], v[116:117], v[26:27]
	v_pk_fma_f32 v[14:15], v[14:15], v[118:119], v[28:29]
	v_pk_fma_f32 v[16:17], v[16:17], v[186:187], v[30:31]
	v_pk_fma_f32 v[18:19], v[18:19], v[188:189], v[32:33]
	global_load_dwordx4 v[88:91], v[34:35], off
	global_load_dwordx4 v[154:157], v[38:39], off
	global_load_dwordx4 v[222:225], v[38:39], off offset:16
	v_lshl_add_u64 v[34:35], v[34:35], 0, s[12:13]
	v_lshl_add_u64 v[38:39], v[38:39], 0, s[14:15]
	s_waitcnt vmcnt(32)
	v_cvt_pk_bf16_f32 v0, v12, v13
	v_cvt_pk_bf16_f32 v1, v14, v15
	v_cvt_pk_bf16_f32 v2, v16, v17
	v_cvt_pk_bf16_f32 v3, v18, v19
	v_lshlrev_b32_e32 v26, 16, v56
	v_and_b32_e32 v27, 0xffff0000, v56
	v_lshlrev_b32_e32 v28, 16, v57
	v_and_b32_e32 v29, 0xffff0000, v57
	v_lshlrev_b32_e32 v30, 16, v58
	v_and_b32_e32 v31, 0xffff0000, v58
	v_lshlrev_b32_e32 v32, 16, v59
	v_and_b32_e32 v33, 0xffff0000, v59
	global_store_dwordx4 v[36:37], v[0:3], off sc1
	v_lshl_add_u64 v[36:37], v[36:37], 0, s[12:13]
	v_pk_fma_f32 v[12:13], v[12:13], v[120:121], v[26:27]
	v_pk_fma_f32 v[14:15], v[14:15], v[122:123], v[28:29]
	v_pk_fma_f32 v[16:17], v[16:17], v[190:191], v[30:31]
	v_pk_fma_f32 v[18:19], v[18:19], v[192:193], v[32:33]
	global_load_dwordx4 v[92:95], v[34:35], off
	global_load_dwordx4 v[158:161], v[38:39], off
	global_load_dwordx4 v[226:229], v[38:39], off offset:16
	v_lshl_add_u64 v[34:35], v[34:35], 0, s[12:13]
	v_lshl_add_u64 v[38:39], v[38:39], 0, s[14:15]
	s_waitcnt vmcnt(32)
	v_cvt_pk_bf16_f32 v22, v12, v13
	v_cvt_pk_bf16_f32 v23, v14, v15
	v_cvt_pk_bf16_f32 v24, v16, v17
	v_cvt_pk_bf16_f32 v25, v18, v19
	v_lshlrev_b32_e32 v26, 16, v60
	v_and_b32_e32 v27, 0xffff0000, v60
	v_lshlrev_b32_e32 v28, 16, v61
	v_and_b32_e32 v29, 0xffff0000, v61
	v_lshlrev_b32_e32 v30, 16, v62
	v_and_b32_e32 v31, 0xffff0000, v62
	v_lshlrev_b32_e32 v32, 16, v63
	v_and_b32_e32 v33, 0xffff0000, v63
	global_store_dwordx4 v[36:37], v[22:25], off sc1
	v_lshl_add_u64 v[36:37], v[36:37], 0, s[12:13]
	v_pk_fma_f32 v[12:13], v[12:13], v[124:125], v[26:27]
	v_pk_fma_f32 v[14:15], v[14:15], v[126:127], v[28:29]
	v_pk_fma_f32 v[16:17], v[16:17], v[194:195], v[30:31]
	v_pk_fma_f32 v[18:19], v[18:19], v[196:197], v[32:33]
	global_load_dwordx4 v[96:99], v[34:35], off
	global_load_dwordx4 v[162:165], v[38:39], off
	global_load_dwordx4 v[230:233], v[38:39], off offset:16
	v_lshl_add_u64 v[34:35], v[34:35], 0, s[12:13]
	v_lshl_add_u64 v[38:39], v[38:39], 0, s[14:15]
	s_waitcnt vmcnt(32)
	v_cvt_pk_bf16_f32 v0, v12, v13
	v_cvt_pk_bf16_f32 v1, v14, v15
	v_cvt_pk_bf16_f32 v2, v16, v17
	v_cvt_pk_bf16_f32 v3, v18, v19
	v_lshlrev_b32_e32 v26, 16, v64
	v_and_b32_e32 v27, 0xffff0000, v64
	v_lshlrev_b32_e32 v28, 16, v65
	v_and_b32_e32 v29, 0xffff0000, v65
	v_lshlrev_b32_e32 v30, 16, v66
	v_and_b32_e32 v31, 0xffff0000, v66
	v_lshlrev_b32_e32 v32, 16, v67
	v_and_b32_e32 v33, 0xffff0000, v67
	global_store_dwordx4 v[36:37], v[0:3], off sc1
	v_lshl_add_u64 v[36:37], v[36:37], 0, s[12:13]
	v_pk_fma_f32 v[12:13], v[12:13], v[128:129], v[26:27]
	v_pk_fma_f32 v[14:15], v[14:15], v[130:131], v[28:29]
	v_pk_fma_f32 v[16:17], v[16:17], v[198:199], v[30:31]
	v_pk_fma_f32 v[18:19], v[18:19], v[200:201], v[32:33]
	global_load_dwordx4 v[100:103], v[34:35], off
	global_load_dwordx4 v[166:169], v[38:39], off
	global_load_dwordx4 v[234:237], v[38:39], off offset:16
	v_lshl_add_u64 v[34:35], v[34:35], 0, s[12:13]
	v_lshl_add_u64 v[38:39], v[38:39], 0, s[14:15]
	s_waitcnt vmcnt(32)
	v_cvt_pk_bf16_f32 v22, v12, v13
	v_cvt_pk_bf16_f32 v23, v14, v15
	v_cvt_pk_bf16_f32 v24, v16, v17
	v_cvt_pk_bf16_f32 v25, v18, v19
	v_lshlrev_b32_e32 v26, 16, v68
	v_and_b32_e32 v27, 0xffff0000, v68
	v_lshlrev_b32_e32 v28, 16, v69
	v_and_b32_e32 v29, 0xffff0000, v69
	v_lshlrev_b32_e32 v30, 16, v70
	v_and_b32_e32 v31, 0xffff0000, v70
	v_lshlrev_b32_e32 v32, 16, v71
	v_and_b32_e32 v33, 0xffff0000, v71
	global_store_dwordx4 v[36:37], v[22:25], off sc1
	v_lshl_add_u64 v[36:37], v[36:37], 0, s[12:13]
	v_pk_fma_f32 v[12:13], v[12:13], v[132:133], v[26:27]
	v_pk_fma_f32 v[14:15], v[14:15], v[134:135], v[28:29]
	v_pk_fma_f32 v[16:17], v[16:17], v[202:203], v[30:31]
	v_pk_fma_f32 v[18:19], v[18:19], v[204:205], v[32:33]
	global_load_dwordx4 v[40:43], v[34:35], off
	global_load_dwordx4 v[104:107], v[38:39], off
	global_load_dwordx4 v[170:173], v[38:39], off offset:16
	v_lshl_add_u64 v[34:35], v[34:35], 0, s[12:13]
	v_lshl_add_u64 v[38:39], v[38:39], 0, s[14:15]
	s_waitcnt vmcnt(32)
	v_cvt_pk_bf16_f32 v0, v12, v13
	v_cvt_pk_bf16_f32 v1, v14, v15
	v_cvt_pk_bf16_f32 v2, v16, v17
	v_cvt_pk_bf16_f32 v3, v18, v19
	v_lshlrev_b32_e32 v26, 16, v72
	v_and_b32_e32 v27, 0xffff0000, v72
	v_lshlrev_b32_e32 v28, 16, v73
	v_and_b32_e32 v29, 0xffff0000, v73
	v_lshlrev_b32_e32 v30, 16, v74
	v_and_b32_e32 v31, 0xffff0000, v74
	v_lshlrev_b32_e32 v32, 16, v75
	v_and_b32_e32 v33, 0xffff0000, v75
	global_store_dwordx4 v[36:37], v[0:3], off sc1
	v_lshl_add_u64 v[36:37], v[36:37], 0, s[12:13]
	v_pk_fma_f32 v[12:13], v[12:13], v[136:137], v[26:27]
	v_pk_fma_f32 v[14:15], v[14:15], v[138:139], v[28:29]
	v_pk_fma_f32 v[16:17], v[16:17], v[206:207], v[30:31]
	v_pk_fma_f32 v[18:19], v[18:19], v[208:209], v[32:33]
	global_load_dwordx4 v[44:47], v[34:35], off
	global_load_dwordx4 v[108:111], v[38:39], off
	global_load_dwordx4 v[174:177], v[38:39], off offset:16
	v_lshl_add_u64 v[34:35], v[34:35], 0, s[12:13]
	v_lshl_add_u64 v[38:39], v[38:39], 0, s[14:15]
	s_waitcnt vmcnt(32)
	v_cvt_pk_bf16_f32 v22, v12, v13
	v_cvt_pk_bf16_f32 v23, v14, v15
	v_cvt_pk_bf16_f32 v24, v16, v17
	v_cvt_pk_bf16_f32 v25, v18, v19
	v_lshlrev_b32_e32 v26, 16, v76
	v_and_b32_e32 v27, 0xffff0000, v76
	v_lshlrev_b32_e32 v28, 16, v77
	v_and_b32_e32 v29, 0xffff0000, v77
	v_lshlrev_b32_e32 v30, 16, v78
	v_and_b32_e32 v31, 0xffff0000, v78
	v_lshlrev_b32_e32 v32, 16, v79
	v_and_b32_e32 v33, 0xffff0000, v79
	global_store_dwordx4 v[36:37], v[22:25], off sc1
	v_lshl_add_u64 v[36:37], v[36:37], 0, s[12:13]
	v_pk_fma_f32 v[12:13], v[12:13], v[140:141], v[26:27]
	v_pk_fma_f32 v[14:15], v[14:15], v[142:143], v[28:29]
	v_pk_fma_f32 v[16:17], v[16:17], v[210:211], v[30:31]
	v_pk_fma_f32 v[18:19], v[18:19], v[212:213], v[32:33]
	global_load_dwordx4 v[48:51], v[34:35], off
	global_load_dwordx4 v[112:115], v[38:39], off
	global_load_dwordx4 v[178:181], v[38:39], off offset:16
	v_lshl_add_u64 v[34:35], v[34:35], 0, s[12:13]
	v_lshl_add_u64 v[38:39], v[38:39], 0, s[14:15]
	s_waitcnt vmcnt(32)
	v_cvt_pk_bf16_f32 v0, v12, v13
	v_cvt_pk_bf16_f32 v1, v14, v15
	v_cvt_pk_bf16_f32 v2, v16, v17
	v_cvt_pk_bf16_f32 v3, v18, v19
	v_lshlrev_b32_e32 v26, 16, v80
	v_and_b32_e32 v27, 0xffff0000, v80
	v_lshlrev_b32_e32 v28, 16, v81
	v_and_b32_e32 v29, 0xffff0000, v81
	v_lshlrev_b32_e32 v30, 16, v82
	v_and_b32_e32 v31, 0xffff0000, v82
	v_lshlrev_b32_e32 v32, 16, v83
	v_and_b32_e32 v33, 0xffff0000, v83
	global_store_dwordx4 v[36:37], v[0:3], off sc1
	v_lshl_add_u64 v[36:37], v[36:37], 0, s[12:13]
	v_pk_fma_f32 v[12:13], v[12:13], v[146:147], v[26:27]
	v_pk_fma_f32 v[14:15], v[14:15], v[148:149], v[28:29]
	v_pk_fma_f32 v[16:17], v[16:17], v[214:215], v[30:31]
	v_pk_fma_f32 v[18:19], v[18:19], v[216:217], v[32:33]
	global_load_dwordx4 v[52:55], v[34:35], off
	global_load_dwordx4 v[116:119], v[38:39], off
	global_load_dwordx4 v[186:189], v[38:39], off offset:16
	v_lshl_add_u64 v[34:35], v[34:35], 0, s[12:13]
	v_lshl_add_u64 v[38:39], v[38:39], 0, s[14:15]
	s_waitcnt vmcnt(32)
	v_cvt_pk_bf16_f32 v22, v12, v13
	v_cvt_pk_bf16_f32 v23, v14, v15
	v_cvt_pk_bf16_f32 v24, v16, v17
	v_cvt_pk_bf16_f32 v25, v18, v19
	v_lshlrev_b32_e32 v26, 16, v84
	v_and_b32_e32 v27, 0xffff0000, v84
	v_lshlrev_b32_e32 v28, 16, v85
	v_and_b32_e32 v29, 0xffff0000, v85
	v_lshlrev_b32_e32 v30, 16, v86
	v_and_b32_e32 v31, 0xffff0000, v86
	v_lshlrev_b32_e32 v32, 16, v87
	v_and_b32_e32 v33, 0xffff0000, v87
	global_store_dwordx4 v[36:37], v[22:25], off sc1
	v_lshl_add_u64 v[36:37], v[36:37], 0, s[12:13]
	v_pk_fma_f32 v[12:13], v[12:13], v[150:151], v[26:27]
	v_pk_fma_f32 v[14:15], v[14:15], v[152:153], v[28:29]
	v_pk_fma_f32 v[16:17], v[16:17], v[218:219], v[30:31]
	v_pk_fma_f32 v[18:19], v[18:19], v[220:221], v[32:33]
	global_load_dwordx4 v[56:59], v[34:35], off
	global_load_dwordx4 v[120:123], v[38:39], off
	global_load_dwordx4 v[190:193], v[38:39], off offset:16
	v_lshl_add_u64 v[34:35], v[34:35], 0, s[12:13]
	v_lshl_add_u64 v[38:39], v[38:39], 0, s[14:15]
	s_waitcnt vmcnt(32)
	v_cvt_pk_bf16_f32 v0, v12, v13
	v_cvt_pk_bf16_f32 v1, v14, v15
	v_cvt_pk_bf16_f32 v2, v16, v17
	v_cvt_pk_bf16_f32 v3, v18, v19
	v_lshlrev_b32_e32 v26, 16, v88
	v_and_b32_e32 v27, 0xffff0000, v88
	v_lshlrev_b32_e32 v28, 16, v89
	v_and_b32_e32 v29, 0xffff0000, v89
	v_lshlrev_b32_e32 v30, 16, v90
	v_and_b32_e32 v31, 0xffff0000, v90
	v_lshlrev_b32_e32 v32, 16, v91
	v_and_b32_e32 v33, 0xffff0000, v91
	global_store_dwordx4 v[36:37], v[0:3], off sc1
	v_lshl_add_u64 v[36:37], v[36:37], 0, s[12:13]
	v_pk_fma_f32 v[12:13], v[12:13], v[154:155], v[26:27]
	v_pk_fma_f32 v[14:15], v[14:15], v[156:157], v[28:29]
	v_pk_fma_f32 v[16:17], v[16:17], v[222:223], v[30:31]
	v_pk_fma_f32 v[18:19], v[18:19], v[224:225], v[32:33]
	global_load_dwordx4 v[60:63], v[34:35], off
	global_load_dwordx4 v[124:127], v[38:39], off
	global_load_dwordx4 v[194:197], v[38:39], off offset:16
	v_lshl_add_u64 v[34:35], v[34:35], 0, s[12:13]
	v_lshl_add_u64 v[38:39], v[38:39], 0, s[14:15]
	s_waitcnt vmcnt(32)
	v_cvt_pk_bf16_f32 v22, v12, v13
	v_cvt_pk_bf16_f32 v23, v14, v15
	v_cvt_pk_bf16_f32 v24, v16, v17
	v_cvt_pk_bf16_f32 v25, v18, v19
	v_lshlrev_b32_e32 v26, 16, v92
	v_and_b32_e32 v27, 0xffff0000, v92
	v_lshlrev_b32_e32 v28, 16, v93
	v_and_b32_e32 v29, 0xffff0000, v93
	v_lshlrev_b32_e32 v30, 16, v94
	v_and_b32_e32 v31, 0xffff0000, v94
	v_lshlrev_b32_e32 v32, 16, v95
	v_and_b32_e32 v33, 0xffff0000, v95
	global_store_dwordx4 v[36:37], v[22:25], off sc1
	v_lshl_add_u64 v[36:37], v[36:37], 0, s[12:13]
	v_pk_fma_f32 v[12:13], v[12:13], v[158:159], v[26:27]
	v_pk_fma_f32 v[14:15], v[14:15], v[160:161], v[28:29]
	v_pk_fma_f32 v[16:17], v[16:17], v[226:227], v[30:31]
	v_pk_fma_f32 v[18:19], v[18:19], v[228:229], v[32:33]
	global_load_dwordx4 v[64:67], v[34:35], off
	global_load_dwordx4 v[128:131], v[38:39], off
	global_load_dwordx4 v[198:201], v[38:39], off offset:16
	v_lshl_add_u64 v[34:35], v[34:35], 0, s[12:13]
	v_lshl_add_u64 v[38:39], v[38:39], 0, s[14:15]
	s_waitcnt vmcnt(32)
	v_cvt_pk_bf16_f32 v0, v12, v13
	v_cvt_pk_bf16_f32 v1, v14, v15
	v_cvt_pk_bf16_f32 v2, v16, v17
	v_cvt_pk_bf16_f32 v3, v18, v19
	v_lshlrev_b32_e32 v26, 16, v96
	v_and_b32_e32 v27, 0xffff0000, v96
	v_lshlrev_b32_e32 v28, 16, v97
	v_and_b32_e32 v29, 0xffff0000, v97
	v_lshlrev_b32_e32 v30, 16, v98
	v_and_b32_e32 v31, 0xffff0000, v98
	v_lshlrev_b32_e32 v32, 16, v99
	v_and_b32_e32 v33, 0xffff0000, v99
	global_store_dwordx4 v[36:37], v[0:3], off sc1
	v_lshl_add_u64 v[36:37], v[36:37], 0, s[12:13]
	v_pk_fma_f32 v[12:13], v[12:13], v[162:163], v[26:27]
	v_pk_fma_f32 v[14:15], v[14:15], v[164:165], v[28:29]
	v_pk_fma_f32 v[16:17], v[16:17], v[230:231], v[30:31]
	v_pk_fma_f32 v[18:19], v[18:19], v[232:233], v[32:33]
	global_load_dwordx4 v[68:71], v[34:35], off
	global_load_dwordx4 v[132:135], v[38:39], off
	global_load_dwordx4 v[202:205], v[38:39], off offset:16
	v_lshl_add_u64 v[34:35], v[34:35], 0, s[12:13]
	v_lshl_add_u64 v[38:39], v[38:39], 0, s[14:15]
	s_waitcnt vmcnt(32)
	v_cvt_pk_bf16_f32 v22, v12, v13
	v_cvt_pk_bf16_f32 v23, v14, v15
	v_cvt_pk_bf16_f32 v24, v16, v17
	v_cvt_pk_bf16_f32 v25, v18, v19
	v_lshlrev_b32_e32 v26, 16, v100
	v_and_b32_e32 v27, 0xffff0000, v100
	v_lshlrev_b32_e32 v28, 16, v101
	v_and_b32_e32 v29, 0xffff0000, v101
	v_lshlrev_b32_e32 v30, 16, v102
	v_and_b32_e32 v31, 0xffff0000, v102
	v_lshlrev_b32_e32 v32, 16, v103
	v_and_b32_e32 v33, 0xffff0000, v103
	global_store_dwordx4 v[36:37], v[22:25], off sc1
	v_lshl_add_u64 v[36:37], v[36:37], 0, s[12:13]
	v_pk_fma_f32 v[12:13], v[12:13], v[166:167], v[26:27]
	v_pk_fma_f32 v[14:15], v[14:15], v[168:169], v[28:29]
	v_pk_fma_f32 v[16:17], v[16:17], v[234:235], v[30:31]
	v_pk_fma_f32 v[18:19], v[18:19], v[236:237], v[32:33]
	global_load_dwordx4 v[72:75], v[34:35], off
	global_load_dwordx4 v[136:139], v[38:39], off
	global_load_dwordx4 v[206:209], v[38:39], off offset:16
	v_lshl_add_u64 v[34:35], v[34:35], 0, s[12:13]
	v_lshl_add_u64 v[38:39], v[38:39], 0, s[14:15]
	s_waitcnt vmcnt(32)
	v_cvt_pk_bf16_f32 v0, v12, v13
	v_cvt_pk_bf16_f32 v1, v14, v15
	v_cvt_pk_bf16_f32 v2, v16, v17
	v_cvt_pk_bf16_f32 v3, v18, v19
	v_lshlrev_b32_e32 v26, 16, v40
	v_and_b32_e32 v27, 0xffff0000, v40
	v_lshlrev_b32_e32 v28, 16, v41
	v_and_b32_e32 v29, 0xffff0000, v41
	v_lshlrev_b32_e32 v30, 16, v42
	v_and_b32_e32 v31, 0xffff0000, v42
	v_lshlrev_b32_e32 v32, 16, v43
	v_and_b32_e32 v33, 0xffff0000, v43
	global_store_dwordx4 v[36:37], v[0:3], off sc1
	v_lshl_add_u64 v[36:37], v[36:37], 0, s[12:13]
	v_pk_fma_f32 v[12:13], v[12:13], v[104:105], v[26:27]
	v_pk_fma_f32 v[14:15], v[14:15], v[106:107], v[28:29]
	v_pk_fma_f32 v[16:17], v[16:17], v[170:171], v[30:31]
	v_pk_fma_f32 v[18:19], v[18:19], v[172:173], v[32:33]
	global_load_dwordx4 v[76:79], v[34:35], off
	global_load_dwordx4 v[140:143], v[38:39], off
	global_load_dwordx4 v[210:213], v[38:39], off offset:16
	v_lshl_add_u64 v[34:35], v[34:35], 0, s[12:13]
	v_lshl_add_u64 v[38:39], v[38:39], 0, s[14:15]
	s_waitcnt vmcnt(32)
	v_cvt_pk_bf16_f32 v22, v12, v13
	v_cvt_pk_bf16_f32 v23, v14, v15
	v_cvt_pk_bf16_f32 v24, v16, v17
	v_cvt_pk_bf16_f32 v25, v18, v19
	v_lshlrev_b32_e32 v26, 16, v44
	v_and_b32_e32 v27, 0xffff0000, v44
	v_lshlrev_b32_e32 v28, 16, v45
	v_and_b32_e32 v29, 0xffff0000, v45
	v_lshlrev_b32_e32 v30, 16, v46
	v_and_b32_e32 v31, 0xffff0000, v46
	v_lshlrev_b32_e32 v32, 16, v47
	v_and_b32_e32 v33, 0xffff0000, v47
	global_store_dwordx4 v[36:37], v[22:25], off sc1
	v_lshl_add_u64 v[36:37], v[36:37], 0, s[12:13]
	v_pk_fma_f32 v[12:13], v[12:13], v[108:109], v[26:27]
	v_pk_fma_f32 v[14:15], v[14:15], v[110:111], v[28:29]
	v_pk_fma_f32 v[16:17], v[16:17], v[174:175], v[30:31]
	v_pk_fma_f32 v[18:19], v[18:19], v[176:177], v[32:33]
	global_load_dwordx4 v[80:83], v[34:35], off
	global_load_dwordx4 v[146:149], v[38:39], off
	global_load_dwordx4 v[214:217], v[38:39], off offset:16
	v_lshl_add_u64 v[34:35], v[34:35], 0, s[12:13]
	v_lshl_add_u64 v[38:39], v[38:39], 0, s[14:15]
	s_waitcnt vmcnt(32)
	v_cvt_pk_bf16_f32 v0, v12, v13
	v_cvt_pk_bf16_f32 v1, v14, v15
	v_cvt_pk_bf16_f32 v2, v16, v17
	v_cvt_pk_bf16_f32 v3, v18, v19
	v_lshlrev_b32_e32 v26, 16, v48
	v_and_b32_e32 v27, 0xffff0000, v48
	v_lshlrev_b32_e32 v28, 16, v49
	v_and_b32_e32 v29, 0xffff0000, v49
	v_lshlrev_b32_e32 v30, 16, v50
	v_and_b32_e32 v31, 0xffff0000, v50
	v_lshlrev_b32_e32 v32, 16, v51
	v_and_b32_e32 v33, 0xffff0000, v51
	global_store_dwordx4 v[36:37], v[0:3], off sc1
	v_lshl_add_u64 v[36:37], v[36:37], 0, s[12:13]
	v_pk_fma_f32 v[12:13], v[12:13], v[112:113], v[26:27]
	v_pk_fma_f32 v[14:15], v[14:15], v[114:115], v[28:29]
	v_pk_fma_f32 v[16:17], v[16:17], v[178:179], v[30:31]
	v_pk_fma_f32 v[18:19], v[18:19], v[180:181], v[32:33]
	global_load_dwordx4 v[84:87], v[34:35], off
	global_load_dwordx4 v[150:153], v[38:39], off
	global_load_dwordx4 v[218:221], v[38:39], off offset:16
	v_lshl_add_u64 v[34:35], v[34:35], 0, s[12:13]
	v_lshl_add_u64 v[38:39], v[38:39], 0, s[14:15]
	s_waitcnt vmcnt(32)
	v_cvt_pk_bf16_f32 v22, v12, v13
	v_cvt_pk_bf16_f32 v23, v14, v15
	v_cvt_pk_bf16_f32 v24, v16, v17
	v_cvt_pk_bf16_f32 v25, v18, v19
	v_lshlrev_b32_e32 v26, 16, v52
	v_and_b32_e32 v27, 0xffff0000, v52
	v_lshlrev_b32_e32 v28, 16, v53
	v_and_b32_e32 v29, 0xffff0000, v53
	v_lshlrev_b32_e32 v30, 16, v54
	v_and_b32_e32 v31, 0xffff0000, v54
	v_lshlrev_b32_e32 v32, 16, v55
	v_and_b32_e32 v33, 0xffff0000, v55
	global_store_dwordx4 v[36:37], v[22:25], off sc1
	v_lshl_add_u64 v[36:37], v[36:37], 0, s[12:13]
	v_pk_fma_f32 v[12:13], v[12:13], v[116:117], v[26:27]
	v_pk_fma_f32 v[14:15], v[14:15], v[118:119], v[28:29]
	v_pk_fma_f32 v[16:17], v[16:17], v[186:187], v[30:31]
	v_pk_fma_f32 v[18:19], v[18:19], v[188:189], v[32:33]
	global_load_dwordx4 v[88:91], v[34:35], off
	global_load_dwordx4 v[154:157], v[38:39], off
	global_load_dwordx4 v[222:225], v[38:39], off offset:16
	v_lshl_add_u64 v[34:35], v[34:35], 0, s[12:13]
	v_lshl_add_u64 v[38:39], v[38:39], 0, s[14:15]
	s_waitcnt vmcnt(32)
	v_cvt_pk_bf16_f32 v0, v12, v13
	v_cvt_pk_bf16_f32 v1, v14, v15
	v_cvt_pk_bf16_f32 v2, v16, v17
	v_cvt_pk_bf16_f32 v3, v18, v19
	v_lshlrev_b32_e32 v26, 16, v56
	v_and_b32_e32 v27, 0xffff0000, v56
	v_lshlrev_b32_e32 v28, 16, v57
	v_and_b32_e32 v29, 0xffff0000, v57
	v_lshlrev_b32_e32 v30, 16, v58
	v_and_b32_e32 v31, 0xffff0000, v58
	v_lshlrev_b32_e32 v32, 16, v59
	v_and_b32_e32 v33, 0xffff0000, v59
	global_store_dwordx4 v[36:37], v[0:3], off sc1
	v_lshl_add_u64 v[36:37], v[36:37], 0, s[12:13]
	v_pk_fma_f32 v[12:13], v[12:13], v[120:121], v[26:27]
	v_pk_fma_f32 v[14:15], v[14:15], v[122:123], v[28:29]
	v_pk_fma_f32 v[16:17], v[16:17], v[190:191], v[30:31]
	v_pk_fma_f32 v[18:19], v[18:19], v[192:193], v[32:33]
	global_load_dwordx4 v[92:95], v[34:35], off
	global_load_dwordx4 v[158:161], v[38:39], off
	global_load_dwordx4 v[226:229], v[38:39], off offset:16
	v_lshl_add_u64 v[34:35], v[34:35], 0, s[12:13]
	v_lshl_add_u64 v[38:39], v[38:39], 0, s[14:15]
	s_waitcnt vmcnt(32)
	v_cvt_pk_bf16_f32 v22, v12, v13
	v_cvt_pk_bf16_f32 v23, v14, v15
	v_cvt_pk_bf16_f32 v24, v16, v17
	v_cvt_pk_bf16_f32 v25, v18, v19
	v_lshlrev_b32_e32 v26, 16, v60
	v_and_b32_e32 v27, 0xffff0000, v60
	v_lshlrev_b32_e32 v28, 16, v61
	v_and_b32_e32 v29, 0xffff0000, v61
	v_lshlrev_b32_e32 v30, 16, v62
	v_and_b32_e32 v31, 0xffff0000, v62
	v_lshlrev_b32_e32 v32, 16, v63
	v_and_b32_e32 v33, 0xffff0000, v63
	global_store_dwordx4 v[36:37], v[22:25], off sc1
	v_lshl_add_u64 v[36:37], v[36:37], 0, s[12:13]
	v_pk_fma_f32 v[12:13], v[12:13], v[124:125], v[26:27]
	v_pk_fma_f32 v[14:15], v[14:15], v[126:127], v[28:29]
	v_pk_fma_f32 v[16:17], v[16:17], v[194:195], v[30:31]
	v_pk_fma_f32 v[18:19], v[18:19], v[196:197], v[32:33]
	global_load_dwordx4 v[96:99], v[34:35], off
	global_load_dwordx4 v[162:165], v[38:39], off
	global_load_dwordx4 v[230:233], v[38:39], off offset:16
	v_lshl_add_u64 v[34:35], v[34:35], 0, s[12:13]
	v_lshl_add_u64 v[38:39], v[38:39], 0, s[14:15]
	s_waitcnt vmcnt(32)
	v_cvt_pk_bf16_f32 v0, v12, v13
	v_cvt_pk_bf16_f32 v1, v14, v15
	v_cvt_pk_bf16_f32 v2, v16, v17
	v_cvt_pk_bf16_f32 v3, v18, v19
	v_lshlrev_b32_e32 v26, 16, v64
	v_and_b32_e32 v27, 0xffff0000, v64
	v_lshlrev_b32_e32 v28, 16, v65
	v_and_b32_e32 v29, 0xffff0000, v65
	v_lshlrev_b32_e32 v30, 16, v66
	v_and_b32_e32 v31, 0xffff0000, v66
	v_lshlrev_b32_e32 v32, 16, v67
	v_and_b32_e32 v33, 0xffff0000, v67
	global_store_dwordx4 v[36:37], v[0:3], off sc1
	v_lshl_add_u64 v[36:37], v[36:37], 0, s[12:13]
	v_pk_fma_f32 v[12:13], v[12:13], v[128:129], v[26:27]
	v_pk_fma_f32 v[14:15], v[14:15], v[130:131], v[28:29]
	v_pk_fma_f32 v[16:17], v[16:17], v[198:199], v[30:31]
	v_pk_fma_f32 v[18:19], v[18:19], v[200:201], v[32:33]
	global_load_dwordx4 v[100:103], v[34:35], off
	global_load_dwordx4 v[166:169], v[38:39], off
	global_load_dwordx4 v[234:237], v[38:39], off offset:16
	v_lshl_add_u64 v[34:35], v[34:35], 0, s[12:13]
	v_lshl_add_u64 v[38:39], v[38:39], 0, s[14:15]
	s_waitcnt vmcnt(32)
	v_cvt_pk_bf16_f32 v22, v12, v13
	v_cvt_pk_bf16_f32 v23, v14, v15
	v_cvt_pk_bf16_f32 v24, v16, v17
	v_cvt_pk_bf16_f32 v25, v18, v19
	v_lshlrev_b32_e32 v26, 16, v68
	v_and_b32_e32 v27, 0xffff0000, v68
	v_lshlrev_b32_e32 v28, 16, v69
	v_and_b32_e32 v29, 0xffff0000, v69
	v_lshlrev_b32_e32 v30, 16, v70
	v_and_b32_e32 v31, 0xffff0000, v70
	v_lshlrev_b32_e32 v32, 16, v71
	v_and_b32_e32 v33, 0xffff0000, v71
	global_store_dwordx4 v[36:37], v[22:25], off sc1
	v_lshl_add_u64 v[36:37], v[36:37], 0, s[12:13]
	v_pk_fma_f32 v[12:13], v[12:13], v[132:133], v[26:27]
	v_pk_fma_f32 v[14:15], v[14:15], v[134:135], v[28:29]
	v_pk_fma_f32 v[16:17], v[16:17], v[202:203], v[30:31]
	v_pk_fma_f32 v[18:19], v[18:19], v[204:205], v[32:33]
	s_waitcnt vmcnt(29)
	v_cvt_pk_bf16_f32 v0, v12, v13
	v_cvt_pk_bf16_f32 v1, v14, v15
	v_cvt_pk_bf16_f32 v2, v16, v17
	v_cvt_pk_bf16_f32 v3, v18, v19
	v_lshlrev_b32_e32 v26, 16, v72
	v_and_b32_e32 v27, 0xffff0000, v72
	v_lshlrev_b32_e32 v28, 16, v73
	v_and_b32_e32 v29, 0xffff0000, v73
	v_lshlrev_b32_e32 v30, 16, v74
	v_and_b32_e32 v31, 0xffff0000, v74
	v_lshlrev_b32_e32 v32, 16, v75
	v_and_b32_e32 v33, 0xffff0000, v75
	global_store_dwordx4 v[36:37], v[0:3], off sc1
	v_lshl_add_u64 v[36:37], v[36:37], 0, s[12:13]
	v_pk_fma_f32 v[12:13], v[12:13], v[136:137], v[26:27]
	v_pk_fma_f32 v[14:15], v[14:15], v[138:139], v[28:29]
	v_pk_fma_f32 v[16:17], v[16:17], v[206:207], v[30:31]
	v_pk_fma_f32 v[18:19], v[18:19], v[208:209], v[32:33]
	s_waitcnt vmcnt(26)
	v_cvt_pk_bf16_f32 v22, v12, v13
	v_cvt_pk_bf16_f32 v23, v14, v15
	v_cvt_pk_bf16_f32 v24, v16, v17
	v_cvt_pk_bf16_f32 v25, v18, v19
	v_lshlrev_b32_e32 v26, 16, v76
	v_and_b32_e32 v27, 0xffff0000, v76
	v_lshlrev_b32_e32 v28, 16, v77
	v_and_b32_e32 v29, 0xffff0000, v77
	v_lshlrev_b32_e32 v30, 16, v78
	v_and_b32_e32 v31, 0xffff0000, v78
	v_lshlrev_b32_e32 v32, 16, v79
	v_and_b32_e32 v33, 0xffff0000, v79
	global_store_dwordx4 v[36:37], v[22:25], off sc1
	v_lshl_add_u64 v[36:37], v[36:37], 0, s[12:13]
	v_pk_fma_f32 v[12:13], v[12:13], v[140:141], v[26:27]
	v_pk_fma_f32 v[14:15], v[14:15], v[142:143], v[28:29]
	v_pk_fma_f32 v[16:17], v[16:17], v[210:211], v[30:31]
	v_pk_fma_f32 v[18:19], v[18:19], v[212:213], v[32:33]
	s_waitcnt vmcnt(23)
	v_cvt_pk_bf16_f32 v0, v12, v13
	v_cvt_pk_bf16_f32 v1, v14, v15
	v_cvt_pk_bf16_f32 v2, v16, v17
	v_cvt_pk_bf16_f32 v3, v18, v19
	v_lshlrev_b32_e32 v26, 16, v80
	v_and_b32_e32 v27, 0xffff0000, v80
	v_lshlrev_b32_e32 v28, 16, v81
	v_and_b32_e32 v29, 0xffff0000, v81
	v_lshlrev_b32_e32 v30, 16, v82
	v_and_b32_e32 v31, 0xffff0000, v82
	v_lshlrev_b32_e32 v32, 16, v83
	v_and_b32_e32 v33, 0xffff0000, v83
	global_store_dwordx4 v[36:37], v[0:3], off sc1
	v_lshl_add_u64 v[36:37], v[36:37], 0, s[12:13]
	v_pk_fma_f32 v[12:13], v[12:13], v[146:147], v[26:27]
	v_pk_fma_f32 v[14:15], v[14:15], v[148:149], v[28:29]
	v_pk_fma_f32 v[16:17], v[16:17], v[214:215], v[30:31]
	v_pk_fma_f32 v[18:19], v[18:19], v[216:217], v[32:33]
	s_waitcnt vmcnt(20)
	v_cvt_pk_bf16_f32 v22, v12, v13
	v_cvt_pk_bf16_f32 v23, v14, v15
	v_cvt_pk_bf16_f32 v24, v16, v17
	v_cvt_pk_bf16_f32 v25, v18, v19
	v_lshlrev_b32_e32 v26, 16, v84
	v_and_b32_e32 v27, 0xffff0000, v84
	v_lshlrev_b32_e32 v28, 16, v85
	v_and_b32_e32 v29, 0xffff0000, v85
	v_lshlrev_b32_e32 v30, 16, v86
	v_and_b32_e32 v31, 0xffff0000, v86
	v_lshlrev_b32_e32 v32, 16, v87
	v_and_b32_e32 v33, 0xffff0000, v87
	global_store_dwordx4 v[36:37], v[22:25], off sc1
	v_lshl_add_u64 v[36:37], v[36:37], 0, s[12:13]
	v_pk_fma_f32 v[12:13], v[12:13], v[150:151], v[26:27]
	v_pk_fma_f32 v[14:15], v[14:15], v[152:153], v[28:29]
	v_pk_fma_f32 v[16:17], v[16:17], v[218:219], v[30:31]
	v_pk_fma_f32 v[18:19], v[18:19], v[220:221], v[32:33]
	s_waitcnt vmcnt(17)
	v_cvt_pk_bf16_f32 v0, v12, v13
	v_cvt_pk_bf16_f32 v1, v14, v15
	v_cvt_pk_bf16_f32 v2, v16, v17
	v_cvt_pk_bf16_f32 v3, v18, v19
	v_lshlrev_b32_e32 v26, 16, v88
	v_and_b32_e32 v27, 0xffff0000, v88
	v_lshlrev_b32_e32 v28, 16, v89
	v_and_b32_e32 v29, 0xffff0000, v89
	v_lshlrev_b32_e32 v30, 16, v90
	v_and_b32_e32 v31, 0xffff0000, v90
	v_lshlrev_b32_e32 v32, 16, v91
	v_and_b32_e32 v33, 0xffff0000, v91
	global_store_dwordx4 v[36:37], v[0:3], off sc1
	v_lshl_add_u64 v[36:37], v[36:37], 0, s[12:13]
	v_pk_fma_f32 v[12:13], v[12:13], v[154:155], v[26:27]
	v_pk_fma_f32 v[14:15], v[14:15], v[156:157], v[28:29]
	v_pk_fma_f32 v[16:17], v[16:17], v[222:223], v[30:31]
	v_pk_fma_f32 v[18:19], v[18:19], v[224:225], v[32:33]
	s_waitcnt vmcnt(14)
	v_cvt_pk_bf16_f32 v22, v12, v13
	v_cvt_pk_bf16_f32 v23, v14, v15
	v_cvt_pk_bf16_f32 v24, v16, v17
	v_cvt_pk_bf16_f32 v25, v18, v19
	v_lshlrev_b32_e32 v26, 16, v92
	v_and_b32_e32 v27, 0xffff0000, v92
	v_lshlrev_b32_e32 v28, 16, v93
	v_and_b32_e32 v29, 0xffff0000, v93
	v_lshlrev_b32_e32 v30, 16, v94
	v_and_b32_e32 v31, 0xffff0000, v94
	v_lshlrev_b32_e32 v32, 16, v95
	v_and_b32_e32 v33, 0xffff0000, v95
	global_store_dwordx4 v[36:37], v[22:25], off sc1
	v_lshl_add_u64 v[36:37], v[36:37], 0, s[12:13]
	v_pk_fma_f32 v[12:13], v[12:13], v[158:159], v[26:27]
	v_pk_fma_f32 v[14:15], v[14:15], v[160:161], v[28:29]
	v_pk_fma_f32 v[16:17], v[16:17], v[226:227], v[30:31]
	v_pk_fma_f32 v[18:19], v[18:19], v[228:229], v[32:33]
	s_waitcnt vmcnt(11)
	v_cvt_pk_bf16_f32 v0, v12, v13
	v_cvt_pk_bf16_f32 v1, v14, v15
	v_cvt_pk_bf16_f32 v2, v16, v17
	v_cvt_pk_bf16_f32 v3, v18, v19
	v_lshlrev_b32_e32 v26, 16, v96
	v_and_b32_e32 v27, 0xffff0000, v96
	v_lshlrev_b32_e32 v28, 16, v97
	v_and_b32_e32 v29, 0xffff0000, v97
	v_lshlrev_b32_e32 v30, 16, v98
	v_and_b32_e32 v31, 0xffff0000, v98
	v_lshlrev_b32_e32 v32, 16, v99
	v_and_b32_e32 v33, 0xffff0000, v99
	global_store_dwordx4 v[36:37], v[0:3], off sc1
	v_lshl_add_u64 v[36:37], v[36:37], 0, s[12:13]
	v_pk_fma_f32 v[12:13], v[12:13], v[162:163], v[26:27]
	v_pk_fma_f32 v[14:15], v[14:15], v[164:165], v[28:29]
	v_pk_fma_f32 v[16:17], v[16:17], v[230:231], v[30:31]
	v_pk_fma_f32 v[18:19], v[18:19], v[232:233], v[32:33]
	s_waitcnt vmcnt(8)
	v_cvt_pk_bf16_f32 v22, v12, v13
	v_cvt_pk_bf16_f32 v23, v14, v15
	v_cvt_pk_bf16_f32 v24, v16, v17
	v_cvt_pk_bf16_f32 v25, v18, v19
	v_lshlrev_b32_e32 v26, 16, v100
	v_and_b32_e32 v27, 0xffff0000, v100
	v_lshlrev_b32_e32 v28, 16, v101
	v_and_b32_e32 v29, 0xffff0000, v101
	v_lshlrev_b32_e32 v30, 16, v102
	v_and_b32_e32 v31, 0xffff0000, v102
	v_lshlrev_b32_e32 v32, 16, v103
	v_and_b32_e32 v33, 0xffff0000, v103
	global_store_dwordx4 v[36:37], v[22:25], off sc1
	v_lshl_add_u64 v[36:37], v[36:37], 0, s[12:13]
	v_pk_fma_f32 v[12:13], v[12:13], v[166:167], v[26:27]
	v_pk_fma_f32 v[14:15], v[14:15], v[168:169], v[28:29]
	v_pk_fma_f32 v[16:17], v[16:17], v[234:235], v[30:31]
	v_pk_fma_f32 v[18:19], v[18:19], v[236:237], v[32:33]
	v_add_u32_e32 v20, s8, v20
	v_cmp_lt_i32_e32 vcc, s9, v20
	s_or_b64 s[6:7], vcc, s[6:7]
	s_andn2_b64 exec, exec, s[6:7]
	s_cbranch_execnz .LBB0_723

.LBB0_730:
	v_and_b32_e32 v33, 64, v187
	v_xor_b32_e32 v32, 32, v187
	v_add_u32_e32 v33, 64, v33
	v_cmp_lt_i32_e32 vcc, v32, v33
	v_mov_b32_e32 v161, v97
	s_add_i32 s36, s36, s72
	v_cndmask_b32_e32 v32, v187, v32, vcc
	v_lshlrev_b32_e32 v32, 2, v32
	ds_bpermute_b32 v32, v32, v157
	s_cmpk_lt_i32 s36, 0x400
	s_waitcnt lgkmcnt(0)
	v_add_f32_e32 v32, v157, v32
	v_div_scale_f32 v33, s[0:1], v32, v32, 1.0
	v_rcp_f32_e32 v34, v33
	v_div_scale_f32 v35, vcc, 1.0, v32, 1.0
	v_fma_f32 v36, -v33, v34, 1.0
	v_fmac_f32_e32 v34, v36, v34
	v_mul_f32_e32 v36, v35, v34
	v_fma_f32 v37, -v33, v36, v35
	v_fmac_f32_e32 v36, v37, v34
	v_fma_f32 v33, -v33, v36, v35
	v_div_fmas_f32 v33, v33, v34, v36
	v_div_fixup_f32 v32, v33, v32, 1.0
	v_mul_u32_u24_e32 v36, 0x90, v137
	v_add_u32_e32 v36, v36, v160
	v_add_u32_e32 v36, 0x1ae00, v36
	v_and_b32_e32 v38, 31, v187
	v_lshrrev_b32_e32 v39, 3, v187
	v_sub_u32_e32 v40, v39, v38
	v_add_u32_e32 v37, v137, v40
	v_mul_u32_u24_e32 v37, 0x90, v37
	v_and_b32_e32 v41, 7, v187
	v_lshlrev_b32_e32 v41, 4, v41
	v_add_u32_e32 v37, v37, v41
	v_add_u32_e32 v37, 0x1ae00, v37
	v_lshl_add_u32 v38, v40, 10, v41
	v_ashrrev_i32_e32 v39, 31, v38
	v_lshl_add_u64 v[34:35], v[166:167], 0, v[38:39]
	v_pk_mul_f32 v[0:1], v[0:1], v[32:33] op_sel_hi:[1,0]
	v_pk_mul_f32 v[2:3], v[2:3], v[32:33] op_sel_hi:[1,0]
	v_cvt_pk_bf16_f32 v0, v0, v1
	v_cvt_pk_bf16_f32 v1, v2, v3
	ds_write_b64 v36, v[0:1]
	v_pk_mul_f32 v[4:5], v[4:5], v[32:33] op_sel_hi:[1,0]
	v_pk_mul_f32 v[6:7], v[6:7], v[32:33] op_sel_hi:[1,0]
	v_cvt_pk_bf16_f32 v4, v4, v5
	v_cvt_pk_bf16_f32 v5, v6, v7
	ds_write_b64 v36, v[4:5] offset:16
	v_pk_mul_f32 v[8:9], v[8:9], v[32:33] op_sel_hi:[1,0]
	v_pk_mul_f32 v[10:11], v[10:11], v[32:33] op_sel_hi:[1,0]
	v_cvt_pk_bf16_f32 v8, v8, v9
	v_cvt_pk_bf16_f32 v9, v10, v11
	ds_write_b64 v36, v[8:9] offset:32
	v_pk_mul_f32 v[12:13], v[12:13], v[32:33] op_sel_hi:[1,0]
	v_pk_mul_f32 v[14:15], v[14:15], v[32:33] op_sel_hi:[1,0]
	v_cvt_pk_bf16_f32 v12, v12, v13
	v_cvt_pk_bf16_f32 v13, v14, v15
	ds_write_b64 v36, v[12:13] offset:48
	v_pk_mul_f32 v[16:17], v[16:17], v[32:33] op_sel_hi:[1,0]
	v_pk_mul_f32 v[18:19], v[18:19], v[32:33] op_sel_hi:[1,0]
	v_cvt_pk_bf16_f32 v16, v16, v17
	v_cvt_pk_bf16_f32 v17, v18, v19
	ds_write_b64 v36, v[16:17] offset:64
	v_pk_mul_f32 v[20:21], v[20:21], v[32:33] op_sel_hi:[1,0]
	v_pk_mul_f32 v[22:23], v[22:23], v[32:33] op_sel_hi:[1,0]
	v_cvt_pk_bf16_f32 v20, v20, v21
	v_cvt_pk_bf16_f32 v21, v22, v23
	ds_write_b64 v36, v[20:21] offset:80
	v_pk_mul_f32 v[24:25], v[24:25], v[32:33] op_sel_hi:[1,0]
	v_pk_mul_f32 v[26:27], v[26:27], v[32:33] op_sel_hi:[1,0]
	v_cvt_pk_bf16_f32 v24, v24, v25
	v_cvt_pk_bf16_f32 v25, v26, v27
	ds_write_b64 v36, v[24:25] offset:96
	v_pk_mul_f32 v[28:29], v[28:29], v[32:33] op_sel_hi:[1,0]
	v_pk_mul_f32 v[30:31], v[30:31], v[32:33] op_sel_hi:[1,0]
	v_cvt_pk_bf16_f32 v28, v28, v29
	v_cvt_pk_bf16_f32 v29, v30, v31
	ds_write_b64 v36, v[28:29] offset:112
	s_waitcnt lgkmcnt(0)
	ds_read_b128 v[0:3], v37
	ds_read_b128 v[4:7], v37 offset:1152
	ds_read_b128 v[8:11], v37 offset:2304
	ds_read_b128 v[12:15], v37 offset:3456
	s_mov_b64 s[8:9], 0x2000
	s_waitcnt lgkmcnt(3)
	global_store_dwordx4 v[34:35], v[0:3], off sc1
	v_lshl_add_u64 v[34:35], v[34:35], 0, s[8:9]
	s_waitcnt lgkmcnt(2)
	global_store_dwordx4 v[34:35], v[4:7], off sc1
	v_lshl_add_u64 v[34:35], v[34:35], 0, s[8:9]
	s_waitcnt lgkmcnt(1)
	global_store_dwordx4 v[34:35], v[8:11], off sc1
	v_lshl_add_u64 v[34:35], v[34:35], 0, s[8:9]
	s_waitcnt lgkmcnt(0)
	global_store_dwordx4 v[34:35], v[12:15], off sc1
	s_cbranch_scc0 .LBB0_762

.LBB0_852:
	s_lshl_b32 s21, s0, 8
	v_lshl_or_b32 v130, s1, 8, v165
	v_add_u32_e32 v156, s21, v160
	v_mov_b64_e32 v[158:159], s[18:19]
	v_ashrrev_i32_e32 v131, 31, v130
	v_mad_i64_i32 v[128:129], s[4:5], v156, s49, v[158:159]
	v_lshlrev_b64 v[154:155], 1, v[130:131]
	v_lshl_add_u64 v[128:129], v[128:129], 0, v[154:155]
	global_load_dwordx4 v[132:135], v[128:129], off
	v_ashrrev_i32_e32 v157, 31, v156
	global_load_dwordx4 v[128:131], v[128:129], off offset:256
	v_lshlrev_b64 v[170:171], 11, v[156:157]
	v_lshl_add_u64 v[170:171], s[16:17], 0, v[170:171]
	s_waitcnt vmcnt(0)
	v_lshlrev_b32_e32 v157, 16, v132
	v_and_b32_e32 v132, 0xffff0000, v132
	v_lshlrev_b32_e32 v169, 16, v133
	v_and_b32_e32 v133, 0xffff0000, v133
	v_mul_f32_e32 v157, 0xbfb8aa3b, v157
	v_mul_f32_e32 v173, 0xbfb8aa3b, v132
	v_mul_f32_e32 v174, 0xbfb8aa3b, v133
	v_exp_f32_e32 v132, v157
	v_exp_f32_e32 v133, v173
	v_lshlrev_b32_e32 v172, 16, v134
	v_mul_f32_e32 v169, 0xbfb8aa3b, v169
	v_mul_f32_e32 v175, 0xbfb8aa3b, v172
	v_exp_f32_e32 v172, v169
	v_exp_f32_e32 v173, v174
	v_and_b32_e32 v134, 0xffff0000, v134
	v_mul_f32_e32 v134, 0xbfb8aa3b, v134
	v_pk_add_f32 v[132:133], v[132:133], 1.0 op_sel_hi:[1,0]
	v_exp_f32_e32 v174, v175
	v_exp_f32_e32 v175, v134
	v_pk_add_f32 v[172:173], v[172:173], 1.0 op_sel_hi:[1,0]
	v_pk_add_f32 v[174:175], v[174:175], 1.0 op_sel_hi:[1,0]
	s_mov_b64 vcc, s[0:1]
	v_rcp_f32_e32 v133, v133
	s_mov_b64 vcc, s[4:5]
	v_rcp_f32_e32 v132, v132
	s_mov_b64 vcc, s[6:7]
	v_pk_mul_f32 v[132:133], v[124:125], v[132:133]
	v_rcp_f32_e32 v125, v173
	v_lshlrev_b32_e32 v134, 16, v135
	v_and_b32_e32 v135, 0xffff0000, v135
	v_rcp_f32_e32 v124, v172
	s_mov_b64 vcc, s[8:9]
	v_mul_f32_e32 v134, 0xbfb8aa3b, v134
	v_mul_f32_e32 v135, 0xbfb8aa3b, v135
	v_pk_mul_f32 v[126:127], v[126:127], v[124:125]
	v_exp_f32_e32 v134, v134
	v_exp_f32_e32 v135, v135
	v_rcp_f32_e32 v125, v175
	v_pk_add_f32 v[134:135], v[134:135], 1.0 op_sel_hi:[1,0]
	v_rcp_f32_e32 v124, v174
	s_nop 0
	v_pk_mul_f32 v[172:173], v[120:121], v[124:125]
	v_rcp_f32_e32 v121, v135
	s_nop 0
	v_rcp_f32_e32 v120, v134
	s_nop 0
	v_pk_mul_f32 v[134:135], v[122:123], v[120:121]
	v_lshlrev_b32_e32 v120, 16, v128
	v_mul_f32_e32 v120, 0xbfb8aa3b, v120
	v_exp_f32_e32 v122, v120
	v_and_b32_e32 v120, 0xffff0000, v128
	v_mul_f32_e32 v120, 0xbfb8aa3b, v120
	v_exp_f32_e32 v123, v120
	v_cvt_pk_bf16_f32 v121, v126, v127
	v_cvt_pk_bf16_f32 v120, v132, v133
	v_lshl_add_u64 v[124:125], v[170:171], 0, v[154:155]
	v_pk_add_f32 v[126:127], v[122:123], 1.0 op_sel_hi:[1,0]
	v_cvt_pk_bf16_f32 v122, v172, v173
	v_cvt_pk_bf16_f32 v123, v134, v135
	global_store_dwordx4 v[124:125], v[120:123], off sc1
	s_nop 1
	v_lshlrev_b32_e32 v122, 16, v129
	v_and_b32_e32 v123, 0xffff0000, v129
	v_rcp_f32_e32 v121, v127
	v_mul_f32_e32 v122, 0xbfb8aa3b, v122
	v_mul_f32_e32 v123, 0xbfb8aa3b, v123
	v_exp_f32_e32 v122, v122
	v_exp_f32_e32 v123, v123
	s_nop 0
	v_pk_add_f32 v[128:129], v[122:123], 1.0 op_sel_hi:[1,0]
	v_rcp_f32_e32 v120, v126
	s_nop 0
	v_pk_mul_f32 v[126:127], v[116:117], v[120:121]
	v_rcp_f32_e32 v129, v129
	v_lshlrev_b32_e32 v116, 16, v130
	v_mul_f32_e32 v116, 0xbfb8aa3b, v116
	v_exp_f32_e32 v132, v116
	v_add_u32_e32 v116, s21, v162
	v_mad_i64_i32 v[120:121], s[0:1], v116, s49, v[158:159]
	v_lshl_add_u64 v[134:135], v[120:121], 0, v[154:155]
	global_load_dwordx4 v[120:123], v[134:135], off
	v_and_b32_e32 v130, 0xffff0000, v130
	v_mul_f32_e32 v130, 0xbfb8aa3b, v130
	v_exp_f32_e32 v133, v130
	s_nop 0
	v_pk_add_f32 v[132:133], v[132:133], 1.0 op_sel_hi:[1,0]
	v_rcp_f32_e32 v128, v128
	s_nop 0
	v_pk_mul_f32 v[118:119], v[118:119], v[128:129]
	v_lshlrev_b32_e32 v130, 16, v131
	v_and_b32_e32 v131, 0xffff0000, v131
	v_mul_f32_e32 v130, 0xbfb8aa3b, v130
	v_mul_f32_e32 v131, 0xbfb8aa3b, v131
	v_exp_f32_e32 v130, v130
	v_exp_f32_e32 v131, v131
	v_rcp_f32_e32 v129, v133
	v_pk_add_f32 v[130:131], v[130:131], 1.0 op_sel_hi:[1,0]
	v_rcp_f32_e32 v128, v132
	s_nop 0
	v_pk_mul_f32 v[128:129], v[112:113], v[128:129]
	v_rcp_f32_e32 v113, v131
	s_nop 0
	v_rcp_f32_e32 v112, v130
	s_nop 0
	v_pk_mul_f32 v[130:131], v[114:115], v[112:113]
	global_load_dwordx4 v[112:115], v[134:135], off offset:256
	v_cvt_pk_bf16_f32 v126, v126, v127
	v_cvt_pk_bf16_f32 v127, v118, v119
	v_cvt_pk_bf16_f32 v128, v128, v129
	v_cvt_pk_bf16_f32 v129, v130, v131
	s_waitcnt vmcnt(1)
	v_lshlrev_b32_e32 v117, 16, v120
	v_mul_f32_e32 v117, 0xbfb8aa3b, v117
	v_exp_f32_e32 v118, v117
	v_and_b32_e32 v117, 0xffff0000, v120
	v_mul_f32_e32 v117, 0xbfb8aa3b, v117
	v_exp_f32_e32 v119, v117
	global_store_dwordx4 v[124:125], v[126:129], off offset:256 sc1
	v_ashrrev_i32_e32 v117, 31, v116
	v_lshlrev_b64 v[116:117], 11, v[116:117]
	v_pk_add_f32 v[118:119], v[118:119], 1.0 op_sel_hi:[1,0]
	v_lshl_add_u64 v[116:117], s[16:17], 0, v[116:117]
	s_nop 0
	v_rcp_f32_e32 v119, v119
	v_lshlrev_b32_e32 v120, 16, v121
	v_and_b32_e32 v121, 0xffff0000, v121
	v_mul_f32_e32 v120, 0xbfb8aa3b, v120
	v_mul_f32_e32 v121, 0xbfb8aa3b, v121
	v_exp_f32_e32 v120, v120
	v_exp_f32_e32 v121, v121
	s_nop 0
	v_pk_add_f32 v[120:121], v[120:121], 1.0 op_sel_hi:[1,0]
	v_rcp_f32_e32 v118, v118
	s_nop 0
	v_pk_mul_f32 v[118:119], v[108:109], v[118:119]
	v_lshlrev_b32_e32 v124, 16, v122
	v_and_b32_e32 v122, 0xffff0000, v122
	v_mul_f32_e32 v124, 0xbfb8aa3b, v124
	v_mul_f32_e32 v122, 0xbfb8aa3b, v122
	v_exp_f32_e32 v124, v124
	v_exp_f32_e32 v125, v122
	v_rcp_f32_e32 v109, v121
	v_pk_add_f32 v[124:125], v[124:125], 1.0 op_sel_hi:[1,0]
	v_rcp_f32_e32 v108, v120
	s_nop 0
	v_pk_mul_f32 v[110:111], v[110:111], v[108:109]
	v_lshlrev_b32_e32 v120, 16, v123
	v_and_b32_e32 v121, 0xffff0000, v123
	v_mul_f32_e32 v120, 0xbfb8aa3b, v120
	v_mul_f32_e32 v121, 0xbfb8aa3b, v121
	v_exp_f32_e32 v120, v120
	v_exp_f32_e32 v121, v121
	v_rcp_f32_e32 v109, v125
	v_pk_add_f32 v[120:121], v[120:121], 1.0 op_sel_hi:[1,0]
	v_rcp_f32_e32 v108, v124
	s_nop 0
	v_pk_mul_f32 v[122:123], v[104:105], v[108:109]
	v_rcp_f32_e32 v105, v121
	s_nop 0
	v_rcp_f32_e32 v104, v120
	s_nop 0
	v_pk_mul_f32 v[120:121], v[106:107], v[104:105]
	s_waitcnt vmcnt(1)
	v_lshlrev_b32_e32 v104, 16, v112
	v_mul_f32_e32 v104, 0xbfb8aa3b, v104
	v_exp_f32_e32 v106, v104
	v_and_b32_e32 v104, 0xffff0000, v112
	v_mul_f32_e32 v104, 0xbfb8aa3b, v104
	v_exp_f32_e32 v107, v104
	v_cvt_pk_bf16_f32 v105, v110, v111
	v_lshl_add_u64 v[108:109], v[116:117], 0, v[154:155]
	v_cvt_pk_bf16_f32 v104, v118, v119
	v_pk_add_f32 v[110:111], v[106:107], 1.0 op_sel_hi:[1,0]
	v_cvt_pk_bf16_f32 v106, v122, v123
	v_cvt_pk_bf16_f32 v107, v120, v121
	global_store_dwordx4 v[108:109], v[104:107], off sc1
	s_nop 1
	v_lshlrev_b32_e32 v106, 16, v113
	v_and_b32_e32 v107, 0xffff0000, v113
	v_rcp_f32_e32 v105, v111
	v_mul_f32_e32 v106, 0xbfb8aa3b, v106
	v_mul_f32_e32 v107, 0xbfb8aa3b, v107
	v_exp_f32_e32 v106, v106
	v_exp_f32_e32 v107, v107
	s_nop 0
	v_pk_add_f32 v[112:113], v[106:107], 1.0 op_sel_hi:[1,0]
	v_rcp_f32_e32 v104, v110
	s_nop 0
	v_pk_mul_f32 v[110:111], v[100:101], v[104:105]
	v_rcp_f32_e32 v113, v113
	v_lshlrev_b32_e32 v100, 16, v114
	v_mul_f32_e32 v100, 0xbfb8aa3b, v100
	v_exp_f32_e32 v116, v100
	v_add_u32_e32 v100, s21, v163
	v_mad_i64_i32 v[104:105], s[0:1], v100, s49, v[158:159]
	v_lshl_add_u64 v[118:119], v[104:105], 0, v[154:155]
	global_load_dwordx4 v[104:107], v[118:119], off
	v_and_b32_e32 v114, 0xffff0000, v114
	v_mul_f32_e32 v114, 0xbfb8aa3b, v114
	v_exp_f32_e32 v117, v114
	s_nop 0
	v_pk_add_f32 v[116:117], v[116:117], 1.0 op_sel_hi:[1,0]
	v_rcp_f32_e32 v112, v112
	s_nop 0
	v_pk_mul_f32 v[102:103], v[102:103], v[112:113]
	v_lshlrev_b32_e32 v114, 16, v115
	v_and_b32_e32 v115, 0xffff0000, v115
	v_mul_f32_e32 v114, 0xbfb8aa3b, v114
	v_mul_f32_e32 v115, 0xbfb8aa3b, v115
	v_exp_f32_e32 v114, v114
	v_exp_f32_e32 v115, v115
	v_rcp_f32_e32 v113, v117
	v_pk_add_f32 v[114:115], v[114:115], 1.0 op_sel_hi:[1,0]
	v_rcp_f32_e32 v112, v116
	s_nop 0
	v_pk_mul_f32 v[112:113], v[96:97], v[112:113]
	v_rcp_f32_e32 v97, v115
	s_nop 0
	v_rcp_f32_e32 v96, v114
	s_nop 0
	v_pk_mul_f32 v[114:115], v[98:99], v[96:97]
	global_load_dwordx4 v[96:99], v[118:119], off offset:256
	v_cvt_pk_bf16_f32 v110, v110, v111
	v_cvt_pk_bf16_f32 v111, v102, v103
	v_cvt_pk_bf16_f32 v112, v112, v113
	v_cvt_pk_bf16_f32 v113, v114, v115
	s_waitcnt vmcnt(1)
	v_lshlrev_b32_e32 v101, 16, v104
	v_mul_f32_e32 v101, 0xbfb8aa3b, v101
	v_exp_f32_e32 v102, v101
	v_and_b32_e32 v101, 0xffff0000, v104
	v_mul_f32_e32 v101, 0xbfb8aa3b, v101
	v_exp_f32_e32 v103, v101
	global_store_dwordx4 v[108:109], v[110:113], off offset:256 sc1
	v_ashrrev_i32_e32 v101, 31, v100
	v_lshlrev_b64 v[100:101], 11, v[100:101]
	v_pk_add_f32 v[102:103], v[102:103], 1.0 op_sel_hi:[1,0]
	v_lshl_add_u64 v[100:101], s[16:17], 0, v[100:101]
	s_nop 0
	v_rcp_f32_e32 v103, v103
	v_lshlrev_b32_e32 v104, 16, v105
	v_and_b32_e32 v105, 0xffff0000, v105
	v_mul_f32_e32 v104, 0xbfb8aa3b, v104
	v_mul_f32_e32 v105, 0xbfb8aa3b, v105
	v_exp_f32_e32 v104, v104
	v_exp_f32_e32 v105, v105
	s_nop 0
	v_pk_add_f32 v[104:105], v[104:105], 1.0 op_sel_hi:[1,0]
	v_rcp_f32_e32 v102, v102
	s_nop 0
	v_pk_mul_f32 v[102:103], v[92:93], v[102:103]
	v_lshlrev_b32_e32 v108, 16, v106
	v_and_b32_e32 v106, 0xffff0000, v106
	v_mul_f32_e32 v108, 0xbfb8aa3b, v108
	v_mul_f32_e32 v106, 0xbfb8aa3b, v106
	v_exp_f32_e32 v108, v108
	v_exp_f32_e32 v109, v106
	v_rcp_f32_e32 v93, v105
	v_pk_add_f32 v[108:109], v[108:109], 1.0 op_sel_hi:[1,0]
	v_rcp_f32_e32 v92, v104
	s_nop 0
	v_pk_mul_f32 v[94:95], v[94:95], v[92:93]
	v_lshlrev_b32_e32 v104, 16, v107
	v_and_b32_e32 v105, 0xffff0000, v107
	v_mul_f32_e32 v104, 0xbfb8aa3b, v104
	v_mul_f32_e32 v105, 0xbfb8aa3b, v105
	v_exp_f32_e32 v104, v104
	v_exp_f32_e32 v105, v105
	v_rcp_f32_e32 v93, v109
	v_pk_add_f32 v[104:105], v[104:105], 1.0 op_sel_hi:[1,0]
	v_rcp_f32_e32 v92, v108
	s_nop 0
	v_pk_mul_f32 v[106:107], v[88:89], v[92:93]
	v_rcp_f32_e32 v89, v105
	s_nop 0
	v_rcp_f32_e32 v88, v104
	s_nop 0
	v_pk_mul_f32 v[104:105], v[90:91], v[88:89]
	s_waitcnt vmcnt(1)
	v_lshlrev_b32_e32 v88, 16, v96
	v_mul_f32_e32 v88, 0xbfb8aa3b, v88
	v_exp_f32_e32 v90, v88
	v_and_b32_e32 v88, 0xffff0000, v96
	v_mul_f32_e32 v88, 0xbfb8aa3b, v88
	v_exp_f32_e32 v91, v88
	v_cvt_pk_bf16_f32 v89, v94, v95
	v_lshl_add_u64 v[92:93], v[100:101], 0, v[154:155]
	v_cvt_pk_bf16_f32 v88, v102, v103
	v_pk_add_f32 v[94:95], v[90:91], 1.0 op_sel_hi:[1,0]
	v_cvt_pk_bf16_f32 v90, v106, v107
	v_cvt_pk_bf16_f32 v91, v104, v105
	global_store_dwordx4 v[92:93], v[88:91], off sc1
	s_nop 1
	v_lshlrev_b32_e32 v90, 16, v97
	v_and_b32_e32 v91, 0xffff0000, v97
	v_rcp_f32_e32 v89, v95
	v_mul_f32_e32 v90, 0xbfb8aa3b, v90
	v_mul_f32_e32 v91, 0xbfb8aa3b, v91
	v_exp_f32_e32 v90, v90
	v_exp_f32_e32 v91, v91
	s_nop 0
	v_pk_add_f32 v[96:97], v[90:91], 1.0 op_sel_hi:[1,0]
	v_rcp_f32_e32 v88, v94
	s_nop 0
	v_pk_mul_f32 v[94:95], v[84:85], v[88:89]
	v_rcp_f32_e32 v97, v97
	v_lshlrev_b32_e32 v84, 16, v98
	v_mul_f32_e32 v84, 0xbfb8aa3b, v84
	v_exp_f32_e32 v100, v84
	v_add_u32_e32 v84, s21, v164
	v_mad_i64_i32 v[88:89], s[0:1], v84, s49, v[158:159]
	v_lshl_add_u64 v[102:103], v[88:89], 0, v[154:155]
	global_load_dwordx4 v[88:91], v[102:103], off
	v_and_b32_e32 v98, 0xffff0000, v98
	v_mul_f32_e32 v98, 0xbfb8aa3b, v98
	v_exp_f32_e32 v101, v98
	s_nop 0
	v_pk_add_f32 v[100:101], v[100:101], 1.0 op_sel_hi:[1,0]
	v_rcp_f32_e32 v96, v96
	s_nop 0
	v_pk_mul_f32 v[86:87], v[86:87], v[96:97]
	v_lshlrev_b32_e32 v98, 16, v99
	v_and_b32_e32 v99, 0xffff0000, v99
	v_mul_f32_e32 v98, 0xbfb8aa3b, v98
	v_mul_f32_e32 v99, 0xbfb8aa3b, v99
	v_exp_f32_e32 v98, v98
	v_exp_f32_e32 v99, v99
	v_rcp_f32_e32 v97, v101
	v_pk_add_f32 v[98:99], v[98:99], 1.0 op_sel_hi:[1,0]
	v_rcp_f32_e32 v96, v100
	s_nop 0
	v_pk_mul_f32 v[96:97], v[80:81], v[96:97]
	v_rcp_f32_e32 v81, v99
	s_nop 0
	v_rcp_f32_e32 v80, v98
	s_nop 0
	v_pk_mul_f32 v[98:99], v[82:83], v[80:81]
	global_load_dwordx4 v[80:83], v[102:103], off offset:256
	v_cvt_pk_bf16_f32 v94, v94, v95
	v_cvt_pk_bf16_f32 v95, v86, v87
	v_cvt_pk_bf16_f32 v96, v96, v97
	v_cvt_pk_bf16_f32 v97, v98, v99
	s_waitcnt vmcnt(1)
	v_lshlrev_b32_e32 v85, 16, v88
	v_mul_f32_e32 v85, 0xbfb8aa3b, v85
	v_exp_f32_e32 v86, v85
	v_and_b32_e32 v85, 0xffff0000, v88
	v_mul_f32_e32 v85, 0xbfb8aa3b, v85
	v_exp_f32_e32 v87, v85
	global_store_dwordx4 v[92:93], v[94:97], off offset:256 sc1
	v_ashrrev_i32_e32 v85, 31, v84
	v_lshlrev_b64 v[84:85], 11, v[84:85]
	v_pk_add_f32 v[86:87], v[86:87], 1.0 op_sel_hi:[1,0]
	v_lshl_add_u64 v[84:85], s[16:17], 0, v[84:85]
	s_nop 0
	v_rcp_f32_e32 v87, v87
	v_lshlrev_b32_e32 v88, 16, v89
	v_and_b32_e32 v89, 0xffff0000, v89
	v_mul_f32_e32 v88, 0xbfb8aa3b, v88
	v_mul_f32_e32 v89, 0xbfb8aa3b, v89
	v_exp_f32_e32 v88, v88
	v_exp_f32_e32 v89, v89
	s_nop 0
	v_pk_add_f32 v[88:89], v[88:89], 1.0 op_sel_hi:[1,0]
	v_rcp_f32_e32 v86, v86
	s_nop 0
	v_pk_mul_f32 v[86:87], v[76:77], v[86:87]
	v_lshlrev_b32_e32 v92, 16, v90
	v_and_b32_e32 v90, 0xffff0000, v90
	v_mul_f32_e32 v92, 0xbfb8aa3b, v92
	v_mul_f32_e32 v90, 0xbfb8aa3b, v90
	v_exp_f32_e32 v92, v92
	v_exp_f32_e32 v93, v90
	v_rcp_f32_e32 v77, v89
	v_pk_add_f32 v[92:93], v[92:93], 1.0 op_sel_hi:[1,0]
	v_rcp_f32_e32 v76, v88
	s_nop 0
	v_pk_mul_f32 v[78:79], v[78:79], v[76:77]
	v_lshlrev_b32_e32 v88, 16, v91
	v_and_b32_e32 v89, 0xffff0000, v91
	v_mul_f32_e32 v88, 0xbfb8aa3b, v88
	v_mul_f32_e32 v89, 0xbfb8aa3b, v89
	v_exp_f32_e32 v88, v88
	v_exp_f32_e32 v89, v89
	v_rcp_f32_e32 v77, v93
	v_pk_add_f32 v[88:89], v[88:89], 1.0 op_sel_hi:[1,0]
	v_rcp_f32_e32 v76, v92
	s_nop 0
	v_pk_mul_f32 v[90:91], v[72:73], v[76:77]
	v_rcp_f32_e32 v73, v89
	s_nop 0
	v_rcp_f32_e32 v72, v88
	s_nop 0
	v_pk_mul_f32 v[88:89], v[74:75], v[72:73]
	s_waitcnt vmcnt(1)
	v_lshlrev_b32_e32 v72, 16, v80
	v_mul_f32_e32 v72, 0xbfb8aa3b, v72
	v_exp_f32_e32 v74, v72
	v_and_b32_e32 v72, 0xffff0000, v80
	v_mul_f32_e32 v72, 0xbfb8aa3b, v72
	v_exp_f32_e32 v75, v72
	v_cvt_pk_bf16_f32 v73, v78, v79
	v_lshl_add_u64 v[76:77], v[84:85], 0, v[154:155]
	v_cvt_pk_bf16_f32 v72, v86, v87
	v_pk_add_f32 v[78:79], v[74:75], 1.0 op_sel_hi:[1,0]
	v_cvt_pk_bf16_f32 v74, v90, v91
	v_cvt_pk_bf16_f32 v75, v88, v89
	global_store_dwordx4 v[76:77], v[72:75], off sc1
	s_nop 1
	v_lshlrev_b32_e32 v74, 16, v81
	v_and_b32_e32 v75, 0xffff0000, v81
	v_rcp_f32_e32 v73, v79
	v_mul_f32_e32 v74, 0xbfb8aa3b, v74
	v_mul_f32_e32 v75, 0xbfb8aa3b, v75
	v_exp_f32_e32 v74, v74
	v_exp_f32_e32 v75, v75
	s_nop 0
	v_pk_add_f32 v[80:81], v[74:75], 1.0 op_sel_hi:[1,0]
	v_rcp_f32_e32 v72, v78
	s_nop 0
	v_pk_mul_f32 v[78:79], v[68:69], v[72:73]
	v_rcp_f32_e32 v81, v81
	v_lshlrev_b32_e32 v68, 16, v82
	v_mul_f32_e32 v68, 0xbfb8aa3b, v68
	v_exp_f32_e32 v84, v68
	v_add_u32_e32 v68, 0x80, v156
	v_mad_i64_i32 v[72:73], s[0:1], v68, s49, v[158:159]
	v_lshl_add_u64 v[86:87], v[72:73], 0, v[154:155]
	global_load_dwordx4 v[72:75], v[86:87], off
	v_and_b32_e32 v82, 0xffff0000, v82
	v_mul_f32_e32 v82, 0xbfb8aa3b, v82
	v_exp_f32_e32 v85, v82
	s_nop 0
	v_pk_add_f32 v[84:85], v[84:85], 1.0 op_sel_hi:[1,0]
	v_rcp_f32_e32 v80, v80
	s_nop 0
	v_pk_mul_f32 v[70:71], v[70:71], v[80:81]
	v_lshlrev_b32_e32 v82, 16, v83
	v_and_b32_e32 v83, 0xffff0000, v83
	v_mul_f32_e32 v82, 0xbfb8aa3b, v82
	v_mul_f32_e32 v83, 0xbfb8aa3b, v83
	v_exp_f32_e32 v82, v82
	v_exp_f32_e32 v83, v83
	v_rcp_f32_e32 v81, v85
	v_pk_add_f32 v[82:83], v[82:83], 1.0 op_sel_hi:[1,0]
	v_rcp_f32_e32 v80, v84
	s_nop 0
	v_pk_mul_f32 v[80:81], v[64:65], v[80:81]
	v_rcp_f32_e32 v65, v83
	s_nop 0
	v_rcp_f32_e32 v64, v82
	s_nop 0
	v_pk_mul_f32 v[82:83], v[66:67], v[64:65]
	global_load_dwordx4 v[64:67], v[86:87], off offset:256
	v_cvt_pk_bf16_f32 v78, v78, v79
	v_cvt_pk_bf16_f32 v79, v70, v71
	v_cvt_pk_bf16_f32 v80, v80, v81
	v_cvt_pk_bf16_f32 v81, v82, v83
	s_waitcnt vmcnt(1)
	v_lshlrev_b32_e32 v69, 16, v72
	v_mul_f32_e32 v69, 0xbfb8aa3b, v69
	v_exp_f32_e32 v70, v69
	v_and_b32_e32 v69, 0xffff0000, v72
	v_mul_f32_e32 v69, 0xbfb8aa3b, v69
	v_exp_f32_e32 v71, v69
	global_store_dwordx4 v[76:77], v[78:81], off offset:256 sc1
	v_ashrrev_i32_e32 v69, 31, v68
	v_lshlrev_b64 v[68:69], 11, v[68:69]
	v_pk_add_f32 v[70:71], v[70:71], 1.0 op_sel_hi:[1,0]
	v_lshl_add_u64 v[68:69], s[16:17], 0, v[68:69]
	s_nop 0
	v_rcp_f32_e32 v71, v71
	v_lshlrev_b32_e32 v72, 16, v73
	v_and_b32_e32 v73, 0xffff0000, v73
	v_mul_f32_e32 v72, 0xbfb8aa3b, v72
	v_mul_f32_e32 v73, 0xbfb8aa3b, v73
	v_exp_f32_e32 v72, v72
	v_exp_f32_e32 v73, v73
	s_nop 0
	v_pk_add_f32 v[72:73], v[72:73], 1.0 op_sel_hi:[1,0]
	v_rcp_f32_e32 v70, v70
	s_nop 0
	v_pk_mul_f32 v[70:71], v[60:61], v[70:71]
	v_lshlrev_b32_e32 v76, 16, v74
	v_and_b32_e32 v74, 0xffff0000, v74
	v_mul_f32_e32 v76, 0xbfb8aa3b, v76
	v_mul_f32_e32 v74, 0xbfb8aa3b, v74
	v_exp_f32_e32 v76, v76
	v_exp_f32_e32 v77, v74
	v_rcp_f32_e32 v61, v73
	v_pk_add_f32 v[76:77], v[76:77], 1.0 op_sel_hi:[1,0]
	v_rcp_f32_e32 v60, v72
	s_nop 0
	v_pk_mul_f32 v[62:63], v[62:63], v[60:61]
	v_lshlrev_b32_e32 v72, 16, v75
	v_and_b32_e32 v73, 0xffff0000, v75
	v_mul_f32_e32 v72, 0xbfb8aa3b, v72
	v_mul_f32_e32 v73, 0xbfb8aa3b, v73
	v_exp_f32_e32 v72, v72
	v_exp_f32_e32 v73, v73
	v_rcp_f32_e32 v61, v77
	v_pk_add_f32 v[72:73], v[72:73], 1.0 op_sel_hi:[1,0]
	v_rcp_f32_e32 v60, v76
	s_nop 0
	v_pk_mul_f32 v[74:75], v[56:57], v[60:61]
	v_rcp_f32_e32 v57, v73
	s_nop 0
	v_rcp_f32_e32 v56, v72
	s_nop 0
	v_pk_mul_f32 v[72:73], v[58:59], v[56:57]
	s_waitcnt vmcnt(1)
	v_lshlrev_b32_e32 v56, 16, v64
	v_mul_f32_e32 v56, 0xbfb8aa3b, v56
	v_exp_f32_e32 v58, v56
	v_and_b32_e32 v56, 0xffff0000, v64
	v_mul_f32_e32 v56, 0xbfb8aa3b, v56
	v_exp_f32_e32 v59, v56
	v_cvt_pk_bf16_f32 v57, v62, v63
	v_lshl_add_u64 v[60:61], v[68:69], 0, v[154:155]
	v_cvt_pk_bf16_f32 v56, v70, v71
	v_pk_add_f32 v[62:63], v[58:59], 1.0 op_sel_hi:[1,0]
	v_cvt_pk_bf16_f32 v58, v74, v75
	v_cvt_pk_bf16_f32 v59, v72, v73
	global_store_dwordx4 v[60:61], v[56:59], off sc1
	s_nop 1
	v_lshlrev_b32_e32 v58, 16, v65
	v_and_b32_e32 v59, 0xffff0000, v65
	v_rcp_f32_e32 v57, v63
	v_mul_f32_e32 v58, 0xbfb8aa3b, v58
	v_mul_f32_e32 v59, 0xbfb8aa3b, v59
	v_exp_f32_e32 v58, v58
	v_exp_f32_e32 v59, v59
	s_nop 0
	v_pk_add_f32 v[64:65], v[58:59], 1.0 op_sel_hi:[1,0]
	v_rcp_f32_e32 v56, v62
	s_nop 0
	v_pk_mul_f32 v[62:63], v[52:53], v[56:57]
	v_rcp_f32_e32 v65, v65
	v_lshlrev_b32_e32 v52, 16, v66
	v_mul_f32_e32 v52, 0xbfb8aa3b, v52
	v_exp_f32_e32 v68, v52
	v_add_u32_e32 v52, 0x90, v156
	v_mad_i64_i32 v[56:57], s[0:1], v52, s49, v[158:159]
	v_lshl_add_u64 v[70:71], v[56:57], 0, v[154:155]
	global_load_dwordx4 v[56:59], v[70:71], off
	v_and_b32_e32 v66, 0xffff0000, v66
	v_mul_f32_e32 v66, 0xbfb8aa3b, v66
	v_exp_f32_e32 v69, v66
	s_nop 0
	v_pk_add_f32 v[68:69], v[68:69], 1.0 op_sel_hi:[1,0]
	v_rcp_f32_e32 v64, v64
	s_nop 0
	v_pk_mul_f32 v[54:55], v[54:55], v[64:65]
	v_lshlrev_b32_e32 v66, 16, v67
	v_and_b32_e32 v67, 0xffff0000, v67
	v_mul_f32_e32 v66, 0xbfb8aa3b, v66
	v_mul_f32_e32 v67, 0xbfb8aa3b, v67
	v_exp_f32_e32 v66, v66
	v_exp_f32_e32 v67, v67
	v_rcp_f32_e32 v65, v69
	v_pk_add_f32 v[66:67], v[66:67], 1.0 op_sel_hi:[1,0]
	v_rcp_f32_e32 v64, v68
	s_nop 0
	v_pk_mul_f32 v[64:65], v[48:49], v[64:65]
	v_rcp_f32_e32 v49, v67
	s_nop 0
	v_rcp_f32_e32 v48, v66
	s_nop 0
	v_pk_mul_f32 v[66:67], v[50:51], v[48:49]
	global_load_dwordx4 v[48:51], v[70:71], off offset:256
	v_cvt_pk_bf16_f32 v62, v62, v63
	v_cvt_pk_bf16_f32 v63, v54, v55
	v_cvt_pk_bf16_f32 v64, v64, v65
	v_cvt_pk_bf16_f32 v65, v66, v67
	s_waitcnt vmcnt(1)
	v_lshlrev_b32_e32 v53, 16, v56
	v_mul_f32_e32 v53, 0xbfb8aa3b, v53
	v_exp_f32_e32 v54, v53
	v_and_b32_e32 v53, 0xffff0000, v56
	v_mul_f32_e32 v53, 0xbfb8aa3b, v53
	v_exp_f32_e32 v55, v53
	global_store_dwordx4 v[60:61], v[62:65], off offset:256 sc1
	v_ashrrev_i32_e32 v53, 31, v52
	v_lshlrev_b64 v[52:53], 11, v[52:53]
	v_pk_add_f32 v[54:55], v[54:55], 1.0 op_sel_hi:[1,0]
	v_lshl_add_u64 v[52:53], s[16:17], 0, v[52:53]
	s_nop 0
	v_rcp_f32_e32 v55, v55
	v_lshlrev_b32_e32 v56, 16, v57
	v_and_b32_e32 v57, 0xffff0000, v57
	v_mul_f32_e32 v56, 0xbfb8aa3b, v56
	v_mul_f32_e32 v57, 0xbfb8aa3b, v57
	v_exp_f32_e32 v56, v56
	v_exp_f32_e32 v57, v57
	s_nop 0
	v_pk_add_f32 v[56:57], v[56:57], 1.0 op_sel_hi:[1,0]
	v_rcp_f32_e32 v54, v54
	s_nop 0
	v_pk_mul_f32 v[54:55], v[44:45], v[54:55]
	v_lshlrev_b32_e32 v60, 16, v58
	v_and_b32_e32 v58, 0xffff0000, v58
	v_mul_f32_e32 v60, 0xbfb8aa3b, v60
	v_mul_f32_e32 v58, 0xbfb8aa3b, v58
	v_exp_f32_e32 v60, v60
	v_exp_f32_e32 v61, v58
	v_rcp_f32_e32 v45, v57
	v_pk_add_f32 v[60:61], v[60:61], 1.0 op_sel_hi:[1,0]
	v_rcp_f32_e32 v44, v56
	s_nop 0
	v_pk_mul_f32 v[46:47], v[46:47], v[44:45]
	v_lshlrev_b32_e32 v56, 16, v59
	v_and_b32_e32 v57, 0xffff0000, v59
	v_mul_f32_e32 v56, 0xbfb8aa3b, v56
	v_mul_f32_e32 v57, 0xbfb8aa3b, v57
	v_exp_f32_e32 v56, v56
	v_exp_f32_e32 v57, v57
	v_rcp_f32_e32 v45, v61
	v_pk_add_f32 v[56:57], v[56:57], 1.0 op_sel_hi:[1,0]
	v_rcp_f32_e32 v44, v60
	s_nop 0
	v_pk_mul_f32 v[58:59], v[40:41], v[44:45]
	v_rcp_f32_e32 v41, v57
	s_nop 0
	v_rcp_f32_e32 v40, v56
	s_nop 0
	v_pk_mul_f32 v[56:57], v[42:43], v[40:41]
	s_waitcnt vmcnt(1)
	v_lshlrev_b32_e32 v40, 16, v48
	v_mul_f32_e32 v40, 0xbfb8aa3b, v40
	v_exp_f32_e32 v42, v40
	v_and_b32_e32 v40, 0xffff0000, v48
	v_mul_f32_e32 v40, 0xbfb8aa3b, v40
	v_exp_f32_e32 v43, v40
	v_cvt_pk_bf16_f32 v41, v46, v47
	v_lshl_add_u64 v[44:45], v[52:53], 0, v[154:155]
	v_cvt_pk_bf16_f32 v40, v54, v55
	v_pk_add_f32 v[46:47], v[42:43], 1.0 op_sel_hi:[1,0]
	v_cvt_pk_bf16_f32 v42, v58, v59
	v_cvt_pk_bf16_f32 v43, v56, v57
	global_store_dwordx4 v[44:45], v[40:43], off sc1
	s_nop 1
	v_lshlrev_b32_e32 v42, 16, v49
	v_and_b32_e32 v43, 0xffff0000, v49
	v_rcp_f32_e32 v41, v47
	v_mul_f32_e32 v42, 0xbfb8aa3b, v42
	v_mul_f32_e32 v43, 0xbfb8aa3b, v43
	v_exp_f32_e32 v42, v42
	v_exp_f32_e32 v43, v43
	s_nop 0
	v_pk_add_f32 v[48:49], v[42:43], 1.0 op_sel_hi:[1,0]
	v_rcp_f32_e32 v40, v46
	s_nop 0
	v_pk_mul_f32 v[46:47], v[36:37], v[40:41]
	v_rcp_f32_e32 v49, v49
	v_lshlrev_b32_e32 v36, 16, v50
	v_mul_f32_e32 v36, 0xbfb8aa3b, v36
	v_exp_f32_e32 v52, v36
	v_add_u32_e32 v36, 0xa0, v156
	v_mad_i64_i32 v[40:41], s[0:1], v36, s49, v[158:159]
	v_lshl_add_u64 v[54:55], v[40:41], 0, v[154:155]
	global_load_dwordx4 v[40:43], v[54:55], off
	v_and_b32_e32 v50, 0xffff0000, v50
	v_mul_f32_e32 v50, 0xbfb8aa3b, v50
	v_exp_f32_e32 v53, v50
	s_nop 0
	v_pk_add_f32 v[52:53], v[52:53], 1.0 op_sel_hi:[1,0]
	v_rcp_f32_e32 v48, v48
	s_nop 0
	v_pk_mul_f32 v[38:39], v[38:39], v[48:49]
	v_lshlrev_b32_e32 v50, 16, v51
	v_and_b32_e32 v51, 0xffff0000, v51
	v_mul_f32_e32 v50, 0xbfb8aa3b, v50
	v_mul_f32_e32 v51, 0xbfb8aa3b, v51
	v_exp_f32_e32 v50, v50
	v_exp_f32_e32 v51, v51
	v_rcp_f32_e32 v49, v53
	v_pk_add_f32 v[50:51], v[50:51], 1.0 op_sel_hi:[1,0]
	v_rcp_f32_e32 v48, v52
	s_nop 0
	v_pk_mul_f32 v[48:49], v[32:33], v[48:49]
	v_rcp_f32_e32 v33, v51
	s_nop 0
	v_rcp_f32_e32 v32, v50
	s_nop 0
	v_pk_mul_f32 v[50:51], v[34:35], v[32:33]
	global_load_dwordx4 v[32:35], v[54:55], off offset:256
	v_cvt_pk_bf16_f32 v46, v46, v47
	v_cvt_pk_bf16_f32 v47, v38, v39
	v_cvt_pk_bf16_f32 v48, v48, v49
	v_cvt_pk_bf16_f32 v49, v50, v51
	s_waitcnt vmcnt(1)
	v_lshlrev_b32_e32 v37, 16, v40
	v_mul_f32_e32 v37, 0xbfb8aa3b, v37
	v_exp_f32_e32 v38, v37
	v_and_b32_e32 v37, 0xffff0000, v40
	v_mul_f32_e32 v37, 0xbfb8aa3b, v37
	v_exp_f32_e32 v39, v37
	global_store_dwordx4 v[44:45], v[46:49], off offset:256 sc1
	v_ashrrev_i32_e32 v37, 31, v36
	v_lshlrev_b64 v[36:37], 11, v[36:37]
	v_pk_add_f32 v[38:39], v[38:39], 1.0 op_sel_hi:[1,0]
	v_lshl_add_u64 v[36:37], s[16:17], 0, v[36:37]
	s_nop 0
	v_rcp_f32_e32 v39, v39
	v_lshlrev_b32_e32 v40, 16, v41
	v_and_b32_e32 v41, 0xffff0000, v41
	v_mul_f32_e32 v40, 0xbfb8aa3b, v40
	v_mul_f32_e32 v41, 0xbfb8aa3b, v41
	v_exp_f32_e32 v40, v40
	v_exp_f32_e32 v41, v41
	s_nop 0
	v_pk_add_f32 v[40:41], v[40:41], 1.0 op_sel_hi:[1,0]
	v_rcp_f32_e32 v38, v38
	s_nop 0
	v_pk_mul_f32 v[38:39], v[28:29], v[38:39]
	v_lshlrev_b32_e32 v44, 16, v42
	v_and_b32_e32 v42, 0xffff0000, v42
	v_mul_f32_e32 v44, 0xbfb8aa3b, v44
	v_mul_f32_e32 v42, 0xbfb8aa3b, v42
	v_exp_f32_e32 v44, v44
	v_exp_f32_e32 v45, v42
	v_rcp_f32_e32 v29, v41
	v_pk_add_f32 v[44:45], v[44:45], 1.0 op_sel_hi:[1,0]
	v_rcp_f32_e32 v28, v40
	s_nop 0
	v_pk_mul_f32 v[30:31], v[30:31], v[28:29]
	v_lshlrev_b32_e32 v40, 16, v43
	v_and_b32_e32 v41, 0xffff0000, v43
	v_mul_f32_e32 v40, 0xbfb8aa3b, v40
	v_mul_f32_e32 v41, 0xbfb8aa3b, v41
	v_exp_f32_e32 v40, v40
	v_exp_f32_e32 v41, v41
	v_rcp_f32_e32 v29, v45
	v_pk_add_f32 v[40:41], v[40:41], 1.0 op_sel_hi:[1,0]
	v_rcp_f32_e32 v28, v44
	s_nop 0
	v_pk_mul_f32 v[42:43], v[24:25], v[28:29]
	v_rcp_f32_e32 v25, v41
	s_nop 0
	v_rcp_f32_e32 v24, v40
	s_nop 0
	v_pk_mul_f32 v[40:41], v[26:27], v[24:25]
	s_waitcnt vmcnt(1)
	v_lshlrev_b32_e32 v24, 16, v32
	v_mul_f32_e32 v24, 0xbfb8aa3b, v24
	v_exp_f32_e32 v26, v24
	v_and_b32_e32 v24, 0xffff0000, v32
	v_mul_f32_e32 v24, 0xbfb8aa3b, v24
	v_exp_f32_e32 v27, v24
	v_cvt_pk_bf16_f32 v25, v30, v31
	v_lshl_add_u64 v[28:29], v[36:37], 0, v[154:155]
	v_cvt_pk_bf16_f32 v24, v38, v39
	v_pk_add_f32 v[30:31], v[26:27], 1.0 op_sel_hi:[1,0]
	v_cvt_pk_bf16_f32 v26, v42, v43
	v_cvt_pk_bf16_f32 v27, v40, v41
	global_store_dwordx4 v[28:29], v[24:27], off sc1
	s_nop 1
	v_lshlrev_b32_e32 v26, 16, v33
	v_and_b32_e32 v27, 0xffff0000, v33
	v_rcp_f32_e32 v25, v31
	v_mul_f32_e32 v26, 0xbfb8aa3b, v26
	v_mul_f32_e32 v27, 0xbfb8aa3b, v27
	v_exp_f32_e32 v26, v26
	v_exp_f32_e32 v27, v27
	s_nop 0
	v_pk_add_f32 v[32:33], v[26:27], 1.0 op_sel_hi:[1,0]
	v_rcp_f32_e32 v24, v30
	s_nop 0
	v_pk_mul_f32 v[30:31], v[20:21], v[24:25]
	v_rcp_f32_e32 v33, v33
	v_lshlrev_b32_e32 v20, 16, v34
	v_mul_f32_e32 v20, 0xbfb8aa3b, v20
	v_exp_f32_e32 v36, v20
	v_add_u32_e32 v20, 0xb0, v156
	v_mad_i64_i32 v[24:25], s[0:1], v20, s49, v[158:159]
	v_lshl_add_u64 v[38:39], v[24:25], 0, v[154:155]
	global_load_dwordx4 v[24:27], v[38:39], off
	v_and_b32_e32 v34, 0xffff0000, v34
	v_mul_f32_e32 v34, 0xbfb8aa3b, v34
	v_exp_f32_e32 v37, v34
	s_nop 0
	v_pk_add_f32 v[36:37], v[36:37], 1.0 op_sel_hi:[1,0]
	v_rcp_f32_e32 v32, v32
	s_nop 0
	v_pk_mul_f32 v[22:23], v[22:23], v[32:33]
	v_lshlrev_b32_e32 v34, 16, v35
	v_and_b32_e32 v35, 0xffff0000, v35
	v_mul_f32_e32 v34, 0xbfb8aa3b, v34
	v_mul_f32_e32 v35, 0xbfb8aa3b, v35
	v_exp_f32_e32 v34, v34
	v_exp_f32_e32 v35, v35
	v_rcp_f32_e32 v33, v37
	v_pk_add_f32 v[34:35], v[34:35], 1.0 op_sel_hi:[1,0]
	v_rcp_f32_e32 v32, v36
	s_nop 0
	v_pk_mul_f32 v[32:33], v[16:17], v[32:33]
	v_rcp_f32_e32 v17, v35
	s_nop 0
	v_rcp_f32_e32 v16, v34
	s_nop 0
	v_pk_mul_f32 v[34:35], v[18:19], v[16:17]
	global_load_dwordx4 v[16:19], v[38:39], off offset:256
	v_cvt_pk_bf16_f32 v30, v30, v31
	v_cvt_pk_bf16_f32 v31, v22, v23
	v_cvt_pk_bf16_f32 v32, v32, v33
	v_cvt_pk_bf16_f32 v33, v34, v35
	s_waitcnt vmcnt(1)
	v_lshlrev_b32_e32 v21, 16, v24
	v_mul_f32_e32 v21, 0xbfb8aa3b, v21
	v_exp_f32_e32 v22, v21
	v_and_b32_e32 v21, 0xffff0000, v24
	v_mul_f32_e32 v21, 0xbfb8aa3b, v21
	v_exp_f32_e32 v23, v21
	global_store_dwordx4 v[28:29], v[30:33], off offset:256 sc1
	v_ashrrev_i32_e32 v21, 31, v20
	v_lshlrev_b64 v[20:21], 11, v[20:21]
	v_pk_add_f32 v[22:23], v[22:23], 1.0 op_sel_hi:[1,0]
	v_lshl_add_u64 v[20:21], s[16:17], 0, v[20:21]
	v_lshl_add_u64 v[20:21], v[20:21], 0, v[154:155]
	v_rcp_f32_e32 v23, v23
	v_lshlrev_b32_e32 v24, 16, v25
	v_and_b32_e32 v25, 0xffff0000, v25
	v_mul_f32_e32 v24, 0xbfb8aa3b, v24
	v_mul_f32_e32 v25, 0xbfb8aa3b, v25
	v_exp_f32_e32 v24, v24
	v_exp_f32_e32 v25, v25
	s_nop 0
	v_pk_add_f32 v[24:25], v[24:25], 1.0 op_sel_hi:[1,0]
	v_rcp_f32_e32 v22, v22
	s_nop 0
	v_pk_mul_f32 v[12:13], v[12:13], v[22:23]
	v_lshlrev_b32_e32 v28, 16, v26
	v_and_b32_e32 v26, 0xffff0000, v26
	v_mul_f32_e32 v28, 0xbfb8aa3b, v28
	v_mul_f32_e32 v26, 0xbfb8aa3b, v26
	v_exp_f32_e32 v28, v28
	v_exp_f32_e32 v29, v26
	v_rcp_f32_e32 v23, v25
	v_pk_add_f32 v[28:29], v[28:29], 1.0 op_sel_hi:[1,0]
	v_rcp_f32_e32 v22, v24
	s_nop 0
	v_pk_mul_f32 v[14:15], v[14:15], v[22:23]
	v_lshlrev_b32_e32 v24, 16, v27
	v_and_b32_e32 v25, 0xffff0000, v27
	v_mul_f32_e32 v24, 0xbfb8aa3b, v24
	v_mul_f32_e32 v25, 0xbfb8aa3b, v25
	v_rcp_f32_e32 v23, v29
	v_exp_f32_e32 v24, v24
	v_exp_f32_e32 v25, v25
	s_nop 0
	v_pk_add_f32 v[24:25], v[24:25], 1.0 op_sel_hi:[1,0]
	v_rcp_f32_e32 v22, v28
	s_nop 0
	v_pk_mul_f32 v[22:23], v[8:9], v[22:23]
	v_rcp_f32_e32 v9, v25
	s_nop 0
	v_rcp_f32_e32 v8, v24
	s_nop 0
	v_pk_mul_f32 v[24:25], v[10:11], v[8:9]
	s_waitcnt vmcnt(1)
	v_lshlrev_b32_e32 v8, 16, v16
	v_mul_f32_e32 v8, 0xbfb8aa3b, v8
	v_exp_f32_e32 v10, v8
	v_and_b32_e32 v8, 0xffff0000, v16
	v_mul_f32_e32 v8, 0xbfb8aa3b, v8
	v_exp_f32_e32 v11, v8
	v_cvt_pk_bf16_f32 v8, v12, v13
	v_cvt_pk_bf16_f32 v9, v14, v15
	v_pk_add_f32 v[12:13], v[10:11], 1.0 op_sel_hi:[1,0]
	s_nop 0
	v_cvt_pk_bf16_f32 v10, v22, v23
	v_cvt_pk_bf16_f32 v11, v24, v25
	global_store_dwordx4 v[20:21], v[8:11], off sc1
	s_nop 1
	v_lshlrev_b32_e32 v10, 16, v17
	v_and_b32_e32 v11, 0xffff0000, v17
	v_mul_f32_e32 v10, 0xbfb8aa3b, v10
	v_mul_f32_e32 v11, 0xbfb8aa3b, v11
	v_rcp_f32_e32 v9, v13
	v_exp_f32_e32 v10, v10
	v_exp_f32_e32 v11, v11
	s_nop 0
	v_pk_add_f32 v[10:11], v[10:11], 1.0 op_sel_hi:[1,0]
	v_rcp_f32_e32 v8, v12
	s_nop 0
	v_pk_mul_f32 v[4:5], v[4:5], v[8:9]
	v_lshlrev_b32_e32 v12, 16, v18
	v_and_b32_e32 v13, 0xffff0000, v18
	v_mul_f32_e32 v12, 0xbfb8aa3b, v12
	v_mul_f32_e32 v13, 0xbfb8aa3b, v13
	v_rcp_f32_e32 v9, v11
	v_exp_f32_e32 v12, v12
	v_exp_f32_e32 v13, v13
	s_nop 0
	v_pk_add_f32 v[12:13], v[12:13], 1.0 op_sel_hi:[1,0]
	v_rcp_f32_e32 v8, v10
	s_nop 0
	v_pk_mul_f32 v[6:7], v[6:7], v[8:9]
	v_lshlrev_b32_e32 v10, 16, v19
	v_and_b32_e32 v11, 0xffff0000, v19
	v_mul_f32_e32 v10, 0xbfb8aa3b, v10
	v_mul_f32_e32 v11, 0xbfb8aa3b, v11
	v_rcp_f32_e32 v9, v13
	v_exp_f32_e32 v10, v10
	v_exp_f32_e32 v11, v11
	s_nop 0
	v_pk_add_f32 v[10:11], v[10:11], 1.0 op_sel_hi:[1,0]
	v_rcp_f32_e32 v8, v12
	s_nop 0
	v_pk_mul_f32 v[8:9], v[0:1], v[8:9]
	v_rcp_f32_e32 v1, v11
	s_nop 0
	v_rcp_f32_e32 v0, v10
	s_nop 0
	v_pk_mul_f32 v[10:11], v[2:3], v[0:1]
	v_cvt_pk_bf16_f32 v0, v4, v5
	v_cvt_pk_bf16_f32 v1, v6, v7
	v_cvt_pk_bf16_f32 v2, v8, v9
	v_cvt_pk_bf16_f32 v3, v10, v11
	s_andn2_b64 vcc, exec, s[2:3]
	s_mov_b64 s[0:1], -1
	global_store_dwordx4 v[20:21], v[0:3], off offset:256 sc1
	s_cbranch_vccnz .LBB0_841
	s_andn2_b64 vcc, exec, s[10:11]
	s_cbranch_vccnz .LBB0_840
	s_barrier
	s_branch .LBB0_840

.LBB0_931:
	s_lshl_b32 s21, s0, 8
	v_lshl_or_b32 v130, s1, 8, v167
	v_add_u32_e32 v156, s21, v162
	v_mov_b64_e32 v[158:159], s[18:19]
	v_ashrrev_i32_e32 v131, 31, v130
	v_mad_i64_i32 v[128:129], s[4:5], v156, s51, v[158:159]
	v_lshlrev_b64 v[154:155], 1, v[130:131]
	v_lshl_add_u64 v[128:129], v[128:129], 0, v[154:155]
	global_load_dwordx4 v[172:175], v[128:129], off
	v_ashrrev_i32_e32 v157, 31, v156
	v_lshlrev_b64 v[130:131], 11, v[156:157]
	v_lshl_add_u64 v[130:131], s[16:17], 0, v[130:131]
	v_lshl_add_u64 v[160:161], v[130:131], 0, v[154:155]
	global_load_dwordx4 v[132:135], v[160:161], off
	global_load_dwordx4 v[176:179], v[128:129], off offset:256
	s_nop 0
	global_load_dwordx4 v[128:131], v[160:161], off offset:256
	s_waitcnt vmcnt(0)
	v_lshlrev_b32_e32 v157, 16, v172
	v_and_b32_e32 v171, 0xffff0000, v172
	v_lshlrev_b32_e32 v172, 16, v173
	v_and_b32_e32 v173, 0xffff0000, v173
	v_mul_f32_e32 v157, 0xbfb8aa3b, v157
	v_mul_f32_e32 v171, 0xbfb8aa3b, v171
	v_mul_f32_e32 v182, 0xbfb8aa3b, v172
	v_mul_f32_e32 v183, 0xbfb8aa3b, v173
	v_exp_f32_e32 v172, v157
	v_exp_f32_e32 v173, v171
	v_lshlrev_b32_e32 v180, 16, v174
	v_and_b32_e32 v174, 0xffff0000, v174
	v_lshlrev_b32_e32 v181, 16, v175
	v_and_b32_e32 v175, 0xffff0000, v175
	v_mul_f32_e32 v185, 0xbfb8aa3b, v174
	v_mul_f32_e32 v187, 0xbfb8aa3b, v175
	v_exp_f32_e32 v174, v182
	v_exp_f32_e32 v175, v183
	v_pk_add_f32 v[172:173], v[172:173], 1.0 op_sel_hi:[1,0]
	v_mul_f32_e32 v186, 0xbfb8aa3b, v181
	v_exp_f32_e32 v181, v185
	v_pk_add_f32 v[174:175], v[174:175], 1.0 op_sel_hi:[1,0]
	v_mul_f32_e32 v180, 0xbfb8aa3b, v180
	v_exp_f32_e32 v180, v180
	s_nop 0
	v_pk_add_f32 v[180:181], v[180:181], 1.0 op_sel_hi:[1,0]
	s_mov_b64 vcc, s[0:1]
	v_rcp_f32_e32 v173, v173
	s_mov_b64 vcc, s[4:5]
	v_exp_f32_e32 v182, v186
	v_exp_f32_e32 v183, v187
	v_lshlrev_b32_e32 v186, 16, v132
	v_and_b32_e32 v187, 0xffff0000, v132
	v_rcp_f32_e32 v172, v172
	s_mov_b64 vcc, s[6:7]
	v_pk_fma_f32 v[124:125], v[124:125], v[172:173], v[186:187]
	v_rcp_f32_e32 v173, v175
	v_lshlrev_b32_e32 v132, 16, v133
	v_rcp_f32_e32 v172, v174
	v_and_b32_e32 v133, 0xffff0000, v133
	v_pk_fma_f32 v[126:127], v[126:127], v[172:173], v[132:133]
	v_rcp_f32_e32 v133, v181
	v_pk_add_f32 v[172:173], v[182:183], 1.0 op_sel_hi:[1,0]
	v_rcp_f32_e32 v132, v180
	v_lshlrev_b32_e32 v174, 16, v134
	v_and_b32_e32 v175, 0xffff0000, v134
	v_pk_fma_f32 v[132:133], v[120:121], v[132:133], v[174:175]
	v_rcp_f32_e32 v121, v173
	s_nop 0
	v_rcp_f32_e32 v120, v172
	v_lshlrev_b32_e32 v134, 16, v135
	v_and_b32_e32 v135, 0xffff0000, v135
	v_pk_fma_f32 v[134:135], v[122:123], v[120:121], v[134:135]
	v_cvt_pk_bf16_f32 v120, v124, v125
	v_cvt_pk_bf16_f32 v121, v126, v127
	v_cvt_pk_bf16_f32 v122, v132, v133
	v_cvt_pk_bf16_f32 v123, v134, v135
	global_store_dwordx4 v[160:161], v[120:123], off sc1
	v_lshlrev_b32_e32 v126, 16, v179
	v_mul_f32_e32 v126, 0xbfb8aa3b, v126
	v_lshlrev_b32_e32 v120, 16, v176
	v_and_b32_e32 v121, 0xffff0000, v176
	v_mul_f32_e32 v120, 0xbfb8aa3b, v120
	v_mul_f32_e32 v121, 0xbfb8aa3b, v121
	v_exp_f32_e32 v120, v120
	v_exp_f32_e32 v121, v121
	v_exp_f32_e32 v132, v126
	v_lshlrev_b32_e32 v122, 16, v177
	v_and_b32_e32 v123, 0xffff0000, v177
	v_pk_add_f32 v[120:121], v[120:121], 1.0 op_sel_hi:[1,0]
	v_mul_f32_e32 v122, 0xbfb8aa3b, v122
	v_mul_f32_e32 v123, 0xbfb8aa3b, v123
	v_exp_f32_e32 v122, v122
	v_exp_f32_e32 v123, v123
	v_rcp_f32_e32 v121, v121
	v_lshlrev_b32_e32 v124, 16, v178
	v_pk_add_f32 v[134:135], v[122:123], 1.0 op_sel_hi:[1,0]
	v_rcp_f32_e32 v120, v120
	v_lshlrev_b32_e32 v122, 16, v128
	v_and_b32_e32 v123, 0xffff0000, v128
	v_pk_fma_f32 v[172:173], v[116:117], v[120:121], v[122:123]
	v_and_b32_e32 v125, 0xffff0000, v178
	v_mul_f32_e32 v124, 0xbfb8aa3b, v124
	v_mul_f32_e32 v125, 0xbfb8aa3b, v125
	v_rcp_f32_e32 v117, v135
	v_exp_f32_e32 v124, v124
	v_exp_f32_e32 v125, v125
	v_add_u32_e32 v128, s21, v164
	v_pk_add_f32 v[124:125], v[124:125], 1.0 op_sel_hi:[1,0]
	v_mad_i64_i32 v[120:121], s[0:1], v128, s51, v[158:159]
	v_lshl_add_u64 v[126:127], v[120:121], 0, v[154:155]
	global_load_dwordx4 v[120:123], v[126:127], off
	v_rcp_f32_e32 v116, v134
	v_lshlrev_b32_e32 v134, 16, v129
	v_and_b32_e32 v135, 0xffff0000, v129
	v_pk_fma_f32 v[134:135], v[118:119], v[116:117], v[134:135]
	v_and_b32_e32 v133, 0xffff0000, v179
	v_rcp_f32_e32 v117, v125
	v_mul_f32_e32 v133, 0xbfb8aa3b, v133
	v_exp_f32_e32 v133, v133
	s_nop 0
	v_pk_add_f32 v[132:133], v[132:133], 1.0 op_sel_hi:[1,0]
	v_rcp_f32_e32 v116, v124
	v_lshlrev_b32_e32 v118, 16, v130
	v_and_b32_e32 v119, 0xffff0000, v130
	v_pk_fma_f32 v[174:175], v[112:113], v[116:117], v[118:119]
	v_ashrrev_i32_e32 v129, 31, v128
	v_lshlrev_b64 v[112:113], 11, v[128:129]
	v_lshl_add_u64 v[112:113], s[16:17], 0, v[112:113]
	v_lshl_add_u64 v[124:125], v[112:113], 0, v[154:155]
	global_load_dwordx4 v[116:119], v[124:125], off
	v_rcp_f32_e32 v113, v133
	s_nop 0
	v_rcp_f32_e32 v112, v132
	v_lshlrev_b32_e32 v128, 16, v131
	v_and_b32_e32 v129, 0xffff0000, v131
	v_pk_fma_f32 v[128:129], v[114:115], v[112:113], v[128:129]
	v_cvt_pk_bf16_f32 v112, v172, v173
	v_cvt_pk_bf16_f32 v113, v134, v135
	v_cvt_pk_bf16_f32 v114, v174, v175
	v_cvt_pk_bf16_f32 v115, v128, v129
	global_store_dwordx4 v[160:161], v[112:115], off offset:256 sc1
	global_load_dwordx4 v[126:129], v[126:127], off offset:256
	s_waitcnt vmcnt(3)
	v_lshlrev_b32_e32 v112, 16, v120
	v_and_b32_e32 v113, 0xffff0000, v120
	v_mul_f32_e32 v112, 0xbfb8aa3b, v112
	v_mul_f32_e32 v113, 0xbfb8aa3b, v113
	v_exp_f32_e32 v112, v112
	v_exp_f32_e32 v113, v113
	v_lshlrev_b32_e32 v114, 16, v121
	v_and_b32_e32 v115, 0xffff0000, v121
	v_mul_f32_e32 v114, 0xbfb8aa3b, v114
	v_pk_add_f32 v[112:113], v[112:113], 1.0 op_sel_hi:[1,0]
	v_mul_f32_e32 v115, 0xbfb8aa3b, v115
	v_exp_f32_e32 v114, v114
	v_exp_f32_e32 v115, v115
	v_lshlrev_b32_e32 v120, 16, v122
	v_rcp_f32_e32 v131, v113
	v_and_b32_e32 v121, 0xffff0000, v122
	v_pk_add_f32 v[132:133], v[114:115], 1.0 op_sel_hi:[1,0]
	v_rcp_f32_e32 v130, v112
	global_load_dwordx4 v[112:115], v[124:125], off offset:256
	v_mul_f32_e32 v120, 0xbfb8aa3b, v120
	v_mul_f32_e32 v121, 0xbfb8aa3b, v121
	v_exp_f32_e32 v120, v120
	v_exp_f32_e32 v121, v121
	v_lshlrev_b32_e32 v122, 16, v123
	s_waitcnt vmcnt(3)
	v_lshlrev_b32_e32 v134, 16, v116
	v_and_b32_e32 v135, 0xffff0000, v116
	v_pk_fma_f32 v[108:109], v[108:109], v[130:131], v[134:135]
	v_rcp_f32_e32 v131, v133
	v_pk_add_f32 v[120:121], v[120:121], 1.0 op_sel_hi:[1,0]
	v_rcp_f32_e32 v130, v132
	v_lshlrev_b32_e32 v116, 16, v117
	v_and_b32_e32 v117, 0xffff0000, v117
	v_pk_fma_f32 v[110:111], v[110:111], v[130:131], v[116:117]
	v_rcp_f32_e32 v117, v121
	v_and_b32_e32 v123, 0xffff0000, v123
	v_mul_f32_e32 v122, 0xbfb8aa3b, v122
	v_mul_f32_e32 v123, 0xbfb8aa3b, v123
	v_exp_f32_e32 v122, v122
	v_exp_f32_e32 v123, v123
	v_rcp_f32_e32 v116, v120
	v_pk_add_f32 v[120:121], v[122:123], 1.0 op_sel_hi:[1,0]
	v_lshlrev_b32_e32 v122, 16, v118
	v_and_b32_e32 v123, 0xffff0000, v118
	v_pk_fma_f32 v[116:117], v[104:105], v[116:117], v[122:123]
	v_rcp_f32_e32 v105, v121
	s_nop 0
	v_rcp_f32_e32 v104, v120
	v_lshlrev_b32_e32 v118, 16, v119
	v_and_b32_e32 v119, 0xffff0000, v119
	v_pk_fma_f32 v[118:119], v[106:107], v[104:105], v[118:119]
	v_cvt_pk_bf16_f32 v104, v108, v109
	v_cvt_pk_bf16_f32 v105, v110, v111
	v_cvt_pk_bf16_f32 v106, v116, v117
	v_cvt_pk_bf16_f32 v107, v118, v119
	global_store_dwordx4 v[124:125], v[104:107], off sc1
	s_waitcnt vmcnt(2)
	v_lshlrev_b32_e32 v110, 16, v129
	v_mul_f32_e32 v110, 0xbfb8aa3b, v110
	v_lshlrev_b32_e32 v104, 16, v126
	v_and_b32_e32 v105, 0xffff0000, v126
	v_mul_f32_e32 v104, 0xbfb8aa3b, v104
	v_mul_f32_e32 v105, 0xbfb8aa3b, v105
	v_exp_f32_e32 v104, v104
	v_exp_f32_e32 v105, v105
	v_exp_f32_e32 v116, v110
	v_lshlrev_b32_e32 v106, 16, v127
	v_and_b32_e32 v107, 0xffff0000, v127
	v_pk_add_f32 v[104:105], v[104:105], 1.0 op_sel_hi:[1,0]
	v_mul_f32_e32 v106, 0xbfb8aa3b, v106
	v_mul_f32_e32 v107, 0xbfb8aa3b, v107
	v_exp_f32_e32 v106, v106
	v_exp_f32_e32 v107, v107
	v_rcp_f32_e32 v105, v105
	v_lshlrev_b32_e32 v108, 16, v128
	v_pk_add_f32 v[118:119], v[106:107], 1.0 op_sel_hi:[1,0]
	v_rcp_f32_e32 v104, v104
	s_waitcnt vmcnt(1)
	v_lshlrev_b32_e32 v106, 16, v112
	v_and_b32_e32 v107, 0xffff0000, v112
	v_pk_fma_f32 v[120:121], v[100:101], v[104:105], v[106:107]
	v_and_b32_e32 v109, 0xffff0000, v128
	v_mul_f32_e32 v108, 0xbfb8aa3b, v108
	v_mul_f32_e32 v109, 0xbfb8aa3b, v109
	v_rcp_f32_e32 v101, v119
	v_exp_f32_e32 v108, v108
	v_exp_f32_e32 v109, v109
	v_add_u32_e32 v112, s21, v165
	v_pk_add_f32 v[108:109], v[108:109], 1.0 op_sel_hi:[1,0]
	v_mad_i64_i32 v[104:105], s[0:1], v112, s51, v[158:159]
	v_lshl_add_u64 v[110:111], v[104:105], 0, v[154:155]
	global_load_dwordx4 v[104:107], v[110:111], off
	v_rcp_f32_e32 v100, v118
	v_lshlrev_b32_e32 v118, 16, v113
	v_and_b32_e32 v119, 0xffff0000, v113
	v_pk_fma_f32 v[118:119], v[102:103], v[100:101], v[118:119]
	v_and_b32_e32 v117, 0xffff0000, v129
	v_rcp_f32_e32 v101, v109
	v_mul_f32_e32 v117, 0xbfb8aa3b, v117
	v_exp_f32_e32 v117, v117
	s_nop 0
	v_pk_add_f32 v[116:117], v[116:117], 1.0 op_sel_hi:[1,0]
	v_rcp_f32_e32 v100, v108
	v_lshlrev_b32_e32 v102, 16, v114
	v_and_b32_e32 v103, 0xffff0000, v114
	v_pk_fma_f32 v[122:123], v[96:97], v[100:101], v[102:103]
	v_ashrrev_i32_e32 v113, 31, v112
	v_lshlrev_b64 v[96:97], 11, v[112:113]
	v_lshl_add_u64 v[96:97], s[16:17], 0, v[96:97]
	v_lshl_add_u64 v[108:109], v[96:97], 0, v[154:155]
	global_load_dwordx4 v[100:103], v[108:109], off
	v_rcp_f32_e32 v97, v117
	s_nop 0
	v_rcp_f32_e32 v96, v116
	v_lshlrev_b32_e32 v112, 16, v115
	v_and_b32_e32 v113, 0xffff0000, v115
	v_pk_fma_f32 v[112:113], v[98:99], v[96:97], v[112:113]
	v_cvt_pk_bf16_f32 v96, v120, v121
	v_cvt_pk_bf16_f32 v97, v118, v119
	v_cvt_pk_bf16_f32 v98, v122, v123
	v_cvt_pk_bf16_f32 v99, v112, v113
	global_store_dwordx4 v[124:125], v[96:99], off offset:256 sc1
	global_load_dwordx4 v[110:113], v[110:111], off offset:256
	s_waitcnt vmcnt(3)
	v_lshlrev_b32_e32 v96, 16, v104
	v_and_b32_e32 v97, 0xffff0000, v104
	v_mul_f32_e32 v96, 0xbfb8aa3b, v96
	v_mul_f32_e32 v97, 0xbfb8aa3b, v97
	v_exp_f32_e32 v96, v96
	v_exp_f32_e32 v97, v97
	v_lshlrev_b32_e32 v98, 16, v105
	v_and_b32_e32 v99, 0xffff0000, v105
	v_mul_f32_e32 v98, 0xbfb8aa3b, v98
	v_pk_add_f32 v[96:97], v[96:97], 1.0 op_sel_hi:[1,0]
	v_mul_f32_e32 v99, 0xbfb8aa3b, v99
	v_exp_f32_e32 v98, v98
	v_exp_f32_e32 v99, v99
	v_lshlrev_b32_e32 v104, 16, v106
	v_rcp_f32_e32 v115, v97
	v_and_b32_e32 v105, 0xffff0000, v106
	v_pk_add_f32 v[116:117], v[98:99], 1.0 op_sel_hi:[1,0]
	v_rcp_f32_e32 v114, v96
	global_load_dwordx4 v[96:99], v[108:109], off offset:256
	v_mul_f32_e32 v104, 0xbfb8aa3b, v104
	v_mul_f32_e32 v105, 0xbfb8aa3b, v105
	v_exp_f32_e32 v104, v104
	v_exp_f32_e32 v105, v105
	v_lshlrev_b32_e32 v106, 16, v107
	s_waitcnt vmcnt(3)
	v_lshlrev_b32_e32 v118, 16, v100
	v_and_b32_e32 v119, 0xffff0000, v100
	v_pk_fma_f32 v[92:93], v[92:93], v[114:115], v[118:119]
	v_rcp_f32_e32 v115, v117
	v_pk_add_f32 v[104:105], v[104:105], 1.0 op_sel_hi:[1,0]
	v_rcp_f32_e32 v114, v116
	v_lshlrev_b32_e32 v100, 16, v101
	v_and_b32_e32 v101, 0xffff0000, v101
	v_pk_fma_f32 v[94:95], v[94:95], v[114:115], v[100:101]
	v_rcp_f32_e32 v101, v105
	v_and_b32_e32 v107, 0xffff0000, v107
	v_mul_f32_e32 v106, 0xbfb8aa3b, v106
	v_mul_f32_e32 v107, 0xbfb8aa3b, v107
	v_exp_f32_e32 v106, v106
	v_exp_f32_e32 v107, v107
	v_rcp_f32_e32 v100, v104
	v_pk_add_f32 v[104:105], v[106:107], 1.0 op_sel_hi:[1,0]
	v_lshlrev_b32_e32 v106, 16, v102
	v_and_b32_e32 v107, 0xffff0000, v102
	v_pk_fma_f32 v[100:101], v[88:89], v[100:101], v[106:107]
	v_rcp_f32_e32 v89, v105
	s_nop 0
	v_rcp_f32_e32 v88, v104
	v_lshlrev_b32_e32 v102, 16, v103
	v_and_b32_e32 v103, 0xffff0000, v103
	v_pk_fma_f32 v[102:103], v[90:91], v[88:89], v[102:103]
	v_cvt_pk_bf16_f32 v88, v92, v93
	v_cvt_pk_bf16_f32 v89, v94, v95
	v_cvt_pk_bf16_f32 v90, v100, v101
	v_cvt_pk_bf16_f32 v91, v102, v103
	global_store_dwordx4 v[108:109], v[88:91], off sc1
	s_waitcnt vmcnt(2)
	v_lshlrev_b32_e32 v94, 16, v113
	v_mul_f32_e32 v94, 0xbfb8aa3b, v94
	v_lshlrev_b32_e32 v88, 16, v110
	v_and_b32_e32 v89, 0xffff0000, v110
	v_mul_f32_e32 v88, 0xbfb8aa3b, v88
	v_mul_f32_e32 v89, 0xbfb8aa3b, v89
	v_exp_f32_e32 v88, v88
	v_exp_f32_e32 v89, v89
	v_exp_f32_e32 v100, v94
	v_lshlrev_b32_e32 v90, 16, v111
	v_and_b32_e32 v91, 0xffff0000, v111
	v_pk_add_f32 v[88:89], v[88:89], 1.0 op_sel_hi:[1,0]
	v_mul_f32_e32 v90, 0xbfb8aa3b, v90
	v_mul_f32_e32 v91, 0xbfb8aa3b, v91
	v_exp_f32_e32 v90, v90
	v_exp_f32_e32 v91, v91
	v_rcp_f32_e32 v89, v89
	v_lshlrev_b32_e32 v92, 16, v112
	v_pk_add_f32 v[102:103], v[90:91], 1.0 op_sel_hi:[1,0]
	v_rcp_f32_e32 v88, v88
	s_waitcnt vmcnt(1)
	v_lshlrev_b32_e32 v90, 16, v96
	v_and_b32_e32 v91, 0xffff0000, v96
	v_pk_fma_f32 v[104:105], v[84:85], v[88:89], v[90:91]
	v_and_b32_e32 v93, 0xffff0000, v112
	v_mul_f32_e32 v92, 0xbfb8aa3b, v92
	v_mul_f32_e32 v93, 0xbfb8aa3b, v93
	v_rcp_f32_e32 v85, v103
	v_exp_f32_e32 v92, v92
	v_exp_f32_e32 v93, v93
	v_add_u32_e32 v96, s21, v166
	v_pk_add_f32 v[92:93], v[92:93], 1.0 op_sel_hi:[1,0]
	v_mad_i64_i32 v[88:89], s[0:1], v96, s51, v[158:159]
	v_lshl_add_u64 v[94:95], v[88:89], 0, v[154:155]
	global_load_dwordx4 v[88:91], v[94:95], off
	v_rcp_f32_e32 v84, v102
	v_lshlrev_b32_e32 v102, 16, v97
	v_and_b32_e32 v103, 0xffff0000, v97
	v_pk_fma_f32 v[102:103], v[86:87], v[84:85], v[102:103]
	v_and_b32_e32 v101, 0xffff0000, v113
	v_rcp_f32_e32 v85, v93
	v_mul_f32_e32 v101, 0xbfb8aa3b, v101
	v_exp_f32_e32 v101, v101
	s_nop 0
	v_pk_add_f32 v[100:101], v[100:101], 1.0 op_sel_hi:[1,0]
	v_rcp_f32_e32 v84, v92
	v_lshlrev_b32_e32 v86, 16, v98
	v_and_b32_e32 v87, 0xffff0000, v98
	v_pk_fma_f32 v[106:107], v[80:81], v[84:85], v[86:87]
	v_ashrrev_i32_e32 v97, 31, v96
	v_lshlrev_b64 v[80:81], 11, v[96:97]
	v_lshl_add_u64 v[80:81], s[16:17], 0, v[80:81]
	v_lshl_add_u64 v[92:93], v[80:81], 0, v[154:155]
	global_load_dwordx4 v[84:87], v[92:93], off
	v_rcp_f32_e32 v81, v101
	s_nop 0
	v_rcp_f32_e32 v80, v100
	v_lshlrev_b32_e32 v96, 16, v99
	v_and_b32_e32 v97, 0xffff0000, v99
	v_pk_fma_f32 v[96:97], v[82:83], v[80:81], v[96:97]
	v_cvt_pk_bf16_f32 v80, v104, v105
	v_cvt_pk_bf16_f32 v81, v102, v103
	v_cvt_pk_bf16_f32 v82, v106, v107
	v_cvt_pk_bf16_f32 v83, v96, v97
	global_store_dwordx4 v[108:109], v[80:83], off offset:256 sc1
	global_load_dwordx4 v[94:97], v[94:95], off offset:256
	s_waitcnt vmcnt(3)
	v_lshlrev_b32_e32 v80, 16, v88
	v_and_b32_e32 v81, 0xffff0000, v88
	v_mul_f32_e32 v80, 0xbfb8aa3b, v80
	v_mul_f32_e32 v81, 0xbfb8aa3b, v81
	v_exp_f32_e32 v80, v80
	v_exp_f32_e32 v81, v81
	v_lshlrev_b32_e32 v82, 16, v89
	v_and_b32_e32 v83, 0xffff0000, v89
	v_mul_f32_e32 v82, 0xbfb8aa3b, v82
	v_pk_add_f32 v[80:81], v[80:81], 1.0 op_sel_hi:[1,0]
	v_mul_f32_e32 v83, 0xbfb8aa3b, v83
	v_exp_f32_e32 v82, v82
	v_exp_f32_e32 v83, v83
	v_lshlrev_b32_e32 v88, 16, v90
	v_rcp_f32_e32 v99, v81
	v_and_b32_e32 v89, 0xffff0000, v90
	v_pk_add_f32 v[100:101], v[82:83], 1.0 op_sel_hi:[1,0]
	v_rcp_f32_e32 v98, v80
	global_load_dwordx4 v[80:83], v[92:93], off offset:256
	v_mul_f32_e32 v88, 0xbfb8aa3b, v88
	v_mul_f32_e32 v89, 0xbfb8aa3b, v89
	v_exp_f32_e32 v88, v88
	v_exp_f32_e32 v89, v89
	v_lshlrev_b32_e32 v90, 16, v91
	s_waitcnt vmcnt(3)
	v_lshlrev_b32_e32 v102, 16, v84
	v_and_b32_e32 v103, 0xffff0000, v84
	v_pk_fma_f32 v[76:77], v[76:77], v[98:99], v[102:103]
	v_rcp_f32_e32 v99, v101
	v_pk_add_f32 v[88:89], v[88:89], 1.0 op_sel_hi:[1,0]
	v_rcp_f32_e32 v98, v100
	v_lshlrev_b32_e32 v84, 16, v85
	v_and_b32_e32 v85, 0xffff0000, v85
	v_pk_fma_f32 v[78:79], v[78:79], v[98:99], v[84:85]
	v_rcp_f32_e32 v85, v89
	v_and_b32_e32 v91, 0xffff0000, v91
	v_mul_f32_e32 v90, 0xbfb8aa3b, v90
	v_mul_f32_e32 v91, 0xbfb8aa3b, v91
	v_exp_f32_e32 v90, v90
	v_exp_f32_e32 v91, v91
	v_rcp_f32_e32 v84, v88
	v_pk_add_f32 v[88:89], v[90:91], 1.0 op_sel_hi:[1,0]
	v_lshlrev_b32_e32 v90, 16, v86
	v_and_b32_e32 v91, 0xffff0000, v86
	v_pk_fma_f32 v[84:85], v[72:73], v[84:85], v[90:91]
	v_rcp_f32_e32 v73, v89
	s_nop 0
	v_rcp_f32_e32 v72, v88
	v_lshlrev_b32_e32 v86, 16, v87
	v_and_b32_e32 v87, 0xffff0000, v87
	v_pk_fma_f32 v[86:87], v[74:75], v[72:73], v[86:87]
	v_cvt_pk_bf16_f32 v72, v76, v77
	v_cvt_pk_bf16_f32 v73, v78, v79
	v_cvt_pk_bf16_f32 v74, v84, v85
	v_cvt_pk_bf16_f32 v75, v86, v87
	global_store_dwordx4 v[92:93], v[72:75], off sc1
	s_waitcnt vmcnt(2)
	v_lshlrev_b32_e32 v78, 16, v97
	v_mul_f32_e32 v78, 0xbfb8aa3b, v78
	v_lshlrev_b32_e32 v72, 16, v94
	v_and_b32_e32 v73, 0xffff0000, v94
	v_mul_f32_e32 v72, 0xbfb8aa3b, v72
	v_mul_f32_e32 v73, 0xbfb8aa3b, v73
	v_exp_f32_e32 v72, v72
	v_exp_f32_e32 v73, v73
	v_exp_f32_e32 v84, v78
	v_lshlrev_b32_e32 v74, 16, v95
	v_and_b32_e32 v75, 0xffff0000, v95
	v_pk_add_f32 v[72:73], v[72:73], 1.0 op_sel_hi:[1,0]
	v_mul_f32_e32 v74, 0xbfb8aa3b, v74
	v_mul_f32_e32 v75, 0xbfb8aa3b, v75
	v_exp_f32_e32 v74, v74
	v_exp_f32_e32 v75, v75
	v_rcp_f32_e32 v73, v73
	v_lshlrev_b32_e32 v76, 16, v96
	v_pk_add_f32 v[86:87], v[74:75], 1.0 op_sel_hi:[1,0]
	v_rcp_f32_e32 v72, v72
	s_waitcnt vmcnt(1)
	v_lshlrev_b32_e32 v74, 16, v80
	v_and_b32_e32 v75, 0xffff0000, v80
	v_pk_fma_f32 v[88:89], v[68:69], v[72:73], v[74:75]
	v_and_b32_e32 v77, 0xffff0000, v96
	v_mul_f32_e32 v76, 0xbfb8aa3b, v76
	v_mul_f32_e32 v77, 0xbfb8aa3b, v77
	v_rcp_f32_e32 v69, v87
	v_exp_f32_e32 v76, v76
	v_exp_f32_e32 v77, v77
	v_add_u32_e32 v80, 0x80, v156
	v_pk_add_f32 v[76:77], v[76:77], 1.0 op_sel_hi:[1,0]
	v_mad_i64_i32 v[72:73], s[0:1], v80, s51, v[158:159]
	v_lshl_add_u64 v[78:79], v[72:73], 0, v[154:155]
	global_load_dwordx4 v[72:75], v[78:79], off
	v_rcp_f32_e32 v68, v86
	v_lshlrev_b32_e32 v86, 16, v81
	v_and_b32_e32 v87, 0xffff0000, v81
	v_pk_fma_f32 v[86:87], v[70:71], v[68:69], v[86:87]
	v_and_b32_e32 v85, 0xffff0000, v97
	v_rcp_f32_e32 v69, v77
	v_mul_f32_e32 v85, 0xbfb8aa3b, v85
	v_exp_f32_e32 v85, v85
	s_nop 0
	v_pk_add_f32 v[84:85], v[84:85], 1.0 op_sel_hi:[1,0]
	v_rcp_f32_e32 v68, v76
	v_lshlrev_b32_e32 v70, 16, v82
	v_and_b32_e32 v71, 0xffff0000, v82
	v_pk_fma_f32 v[90:91], v[64:65], v[68:69], v[70:71]
	v_ashrrev_i32_e32 v81, 31, v80
	v_lshlrev_b64 v[64:65], 11, v[80:81]
	v_lshl_add_u64 v[64:65], s[16:17], 0, v[64:65]
	v_lshl_add_u64 v[76:77], v[64:65], 0, v[154:155]
	global_load_dwordx4 v[68:71], v[76:77], off
	v_rcp_f32_e32 v65, v85
	s_nop 0
	v_rcp_f32_e32 v64, v84
	v_lshlrev_b32_e32 v80, 16, v83
	v_and_b32_e32 v81, 0xffff0000, v83
	v_pk_fma_f32 v[80:81], v[66:67], v[64:65], v[80:81]
	v_cvt_pk_bf16_f32 v64, v88, v89
	v_cvt_pk_bf16_f32 v65, v86, v87
	v_cvt_pk_bf16_f32 v66, v90, v91
	v_cvt_pk_bf16_f32 v67, v80, v81
	global_store_dwordx4 v[92:93], v[64:67], off offset:256 sc1
	global_load_dwordx4 v[78:81], v[78:79], off offset:256
	s_waitcnt vmcnt(3)
	v_lshlrev_b32_e32 v64, 16, v72
	v_and_b32_e32 v65, 0xffff0000, v72
	v_mul_f32_e32 v64, 0xbfb8aa3b, v64
	v_mul_f32_e32 v65, 0xbfb8aa3b, v65
	v_exp_f32_e32 v64, v64
	v_exp_f32_e32 v65, v65
	v_lshlrev_b32_e32 v66, 16, v73
	v_and_b32_e32 v67, 0xffff0000, v73
	v_mul_f32_e32 v66, 0xbfb8aa3b, v66
	v_pk_add_f32 v[64:65], v[64:65], 1.0 op_sel_hi:[1,0]
	v_mul_f32_e32 v67, 0xbfb8aa3b, v67
	v_exp_f32_e32 v66, v66
	v_exp_f32_e32 v67, v67
	v_lshlrev_b32_e32 v72, 16, v74
	v_rcp_f32_e32 v83, v65
	v_and_b32_e32 v73, 0xffff0000, v74
	v_pk_add_f32 v[84:85], v[66:67], 1.0 op_sel_hi:[1,0]
	v_rcp_f32_e32 v82, v64
	global_load_dwordx4 v[64:67], v[76:77], off offset:256
	v_mul_f32_e32 v72, 0xbfb8aa3b, v72
	v_mul_f32_e32 v73, 0xbfb8aa3b, v73
	v_exp_f32_e32 v72, v72
	v_exp_f32_e32 v73, v73
	v_lshlrev_b32_e32 v74, 16, v75
	s_waitcnt vmcnt(3)
	v_lshlrev_b32_e32 v86, 16, v68
	v_and_b32_e32 v87, 0xffff0000, v68
	v_pk_fma_f32 v[60:61], v[60:61], v[82:83], v[86:87]
	v_rcp_f32_e32 v83, v85
	v_pk_add_f32 v[72:73], v[72:73], 1.0 op_sel_hi:[1,0]
	v_rcp_f32_e32 v82, v84
	v_lshlrev_b32_e32 v68, 16, v69
	v_and_b32_e32 v69, 0xffff0000, v69
	v_pk_fma_f32 v[62:63], v[62:63], v[82:83], v[68:69]
	v_rcp_f32_e32 v69, v73
	v_and_b32_e32 v75, 0xffff0000, v75
	v_mul_f32_e32 v74, 0xbfb8aa3b, v74
	v_mul_f32_e32 v75, 0xbfb8aa3b, v75
	v_exp_f32_e32 v74, v74
	v_exp_f32_e32 v75, v75
	v_rcp_f32_e32 v68, v72
	v_pk_add_f32 v[72:73], v[74:75], 1.0 op_sel_hi:[1,0]
	v_lshlrev_b32_e32 v74, 16, v70
	v_and_b32_e32 v75, 0xffff0000, v70
	v_pk_fma_f32 v[68:69], v[56:57], v[68:69], v[74:75]
	v_rcp_f32_e32 v57, v73
	s_nop 0
	v_rcp_f32_e32 v56, v72
	v_lshlrev_b32_e32 v70, 16, v71
	v_and_b32_e32 v71, 0xffff0000, v71
	v_pk_fma_f32 v[70:71], v[58:59], v[56:57], v[70:71]
	v_cvt_pk_bf16_f32 v56, v60, v61
	v_cvt_pk_bf16_f32 v57, v62, v63
	v_cvt_pk_bf16_f32 v58, v68, v69
	v_cvt_pk_bf16_f32 v59, v70, v71
	global_store_dwordx4 v[76:77], v[56:59], off sc1
	s_waitcnt vmcnt(2)
	v_lshlrev_b32_e32 v62, 16, v81
	v_mul_f32_e32 v62, 0xbfb8aa3b, v62
	v_lshlrev_b32_e32 v56, 16, v78
	v_and_b32_e32 v57, 0xffff0000, v78
	v_mul_f32_e32 v56, 0xbfb8aa3b, v56
	v_mul_f32_e32 v57, 0xbfb8aa3b, v57
	v_exp_f32_e32 v56, v56
	v_exp_f32_e32 v57, v57
	v_exp_f32_e32 v68, v62
	v_lshlrev_b32_e32 v58, 16, v79
	v_and_b32_e32 v59, 0xffff0000, v79
	v_pk_add_f32 v[56:57], v[56:57], 1.0 op_sel_hi:[1,0]
	v_mul_f32_e32 v58, 0xbfb8aa3b, v58
	v_mul_f32_e32 v59, 0xbfb8aa3b, v59
	v_exp_f32_e32 v58, v58
	v_exp_f32_e32 v59, v59
	v_rcp_f32_e32 v57, v57
	v_lshlrev_b32_e32 v60, 16, v80
	v_pk_add_f32 v[70:71], v[58:59], 1.0 op_sel_hi:[1,0]
	v_rcp_f32_e32 v56, v56
	s_waitcnt vmcnt(1)
	v_lshlrev_b32_e32 v58, 16, v64
	v_and_b32_e32 v59, 0xffff0000, v64
	v_pk_fma_f32 v[72:73], v[52:53], v[56:57], v[58:59]
	v_and_b32_e32 v61, 0xffff0000, v80
	v_mul_f32_e32 v60, 0xbfb8aa3b, v60
	v_mul_f32_e32 v61, 0xbfb8aa3b, v61
	v_rcp_f32_e32 v53, v71
	v_exp_f32_e32 v60, v60
	v_exp_f32_e32 v61, v61
	v_add_u32_e32 v64, 0x90, v156
	v_pk_add_f32 v[60:61], v[60:61], 1.0 op_sel_hi:[1,0]
	v_mad_i64_i32 v[56:57], s[0:1], v64, s51, v[158:159]
	v_lshl_add_u64 v[62:63], v[56:57], 0, v[154:155]
	global_load_dwordx4 v[56:59], v[62:63], off
	v_rcp_f32_e32 v52, v70
	v_lshlrev_b32_e32 v70, 16, v65
	v_and_b32_e32 v71, 0xffff0000, v65
	v_pk_fma_f32 v[70:71], v[54:55], v[52:53], v[70:71]
	v_and_b32_e32 v69, 0xffff0000, v81
	v_rcp_f32_e32 v53, v61
	v_mul_f32_e32 v69, 0xbfb8aa3b, v69
	v_exp_f32_e32 v69, v69
	s_nop 0
	v_pk_add_f32 v[68:69], v[68:69], 1.0 op_sel_hi:[1,0]
	v_rcp_f32_e32 v52, v60
	v_lshlrev_b32_e32 v54, 16, v66
	v_and_b32_e32 v55, 0xffff0000, v66
	v_pk_fma_f32 v[74:75], v[48:49], v[52:53], v[54:55]
	v_ashrrev_i32_e32 v65, 31, v64
	v_lshlrev_b64 v[48:49], 11, v[64:65]
	v_lshl_add_u64 v[48:49], s[16:17], 0, v[48:49]
	v_lshl_add_u64 v[60:61], v[48:49], 0, v[154:155]
	global_load_dwordx4 v[52:55], v[60:61], off
	v_rcp_f32_e32 v49, v69
	s_nop 0
	v_rcp_f32_e32 v48, v68
	v_lshlrev_b32_e32 v64, 16, v67
	v_and_b32_e32 v65, 0xffff0000, v67
	v_pk_fma_f32 v[64:65], v[50:51], v[48:49], v[64:65]
	v_cvt_pk_bf16_f32 v48, v72, v73
	v_cvt_pk_bf16_f32 v49, v70, v71
	v_cvt_pk_bf16_f32 v50, v74, v75
	v_cvt_pk_bf16_f32 v51, v64, v65
	global_store_dwordx4 v[76:77], v[48:51], off offset:256 sc1
	global_load_dwordx4 v[62:65], v[62:63], off offset:256
	s_waitcnt vmcnt(3)
	v_lshlrev_b32_e32 v48, 16, v56
	v_and_b32_e32 v49, 0xffff0000, v56
	v_mul_f32_e32 v48, 0xbfb8aa3b, v48
	v_mul_f32_e32 v49, 0xbfb8aa3b, v49
	v_exp_f32_e32 v48, v48
	v_exp_f32_e32 v49, v49
	v_lshlrev_b32_e32 v50, 16, v57
	v_and_b32_e32 v51, 0xffff0000, v57
	v_mul_f32_e32 v50, 0xbfb8aa3b, v50
	v_pk_add_f32 v[48:49], v[48:49], 1.0 op_sel_hi:[1,0]
	v_mul_f32_e32 v51, 0xbfb8aa3b, v51
	v_exp_f32_e32 v50, v50
	v_exp_f32_e32 v51, v51
	v_lshlrev_b32_e32 v56, 16, v58
	v_rcp_f32_e32 v67, v49
	v_and_b32_e32 v57, 0xffff0000, v58
	v_pk_add_f32 v[68:69], v[50:51], 1.0 op_sel_hi:[1,0]
	v_rcp_f32_e32 v66, v48
	global_load_dwordx4 v[48:51], v[60:61], off offset:256
	v_mul_f32_e32 v56, 0xbfb8aa3b, v56
	v_mul_f32_e32 v57, 0xbfb8aa3b, v57
	v_exp_f32_e32 v56, v56
	v_exp_f32_e32 v57, v57
	v_lshlrev_b32_e32 v58, 16, v59
	s_waitcnt vmcnt(3)
	v_lshlrev_b32_e32 v70, 16, v52
	v_and_b32_e32 v71, 0xffff0000, v52
	v_pk_fma_f32 v[44:45], v[44:45], v[66:67], v[70:71]
	v_rcp_f32_e32 v67, v69
	v_pk_add_f32 v[56:57], v[56:57], 1.0 op_sel_hi:[1,0]
	v_rcp_f32_e32 v66, v68
	v_lshlrev_b32_e32 v52, 16, v53
	v_and_b32_e32 v53, 0xffff0000, v53
	v_pk_fma_f32 v[46:47], v[46:47], v[66:67], v[52:53]
	v_rcp_f32_e32 v53, v57
	v_and_b32_e32 v59, 0xffff0000, v59
	v_mul_f32_e32 v58, 0xbfb8aa3b, v58
	v_mul_f32_e32 v59, 0xbfb8aa3b, v59
	v_exp_f32_e32 v58, v58
	v_exp_f32_e32 v59, v59
	v_rcp_f32_e32 v52, v56
	v_pk_add_f32 v[56:57], v[58:59], 1.0 op_sel_hi:[1,0]
	v_lshlrev_b32_e32 v58, 16, v54
	v_and_b32_e32 v59, 0xffff0000, v54
	v_pk_fma_f32 v[52:53], v[40:41], v[52:53], v[58:59]
	v_rcp_f32_e32 v41, v57
	s_nop 0
	v_rcp_f32_e32 v40, v56
	v_lshlrev_b32_e32 v54, 16, v55
	v_and_b32_e32 v55, 0xffff0000, v55
	v_pk_fma_f32 v[54:55], v[42:43], v[40:41], v[54:55]
	v_cvt_pk_bf16_f32 v40, v44, v45
	v_cvt_pk_bf16_f32 v41, v46, v47
	v_cvt_pk_bf16_f32 v42, v52, v53
	v_cvt_pk_bf16_f32 v43, v54, v55
	global_store_dwordx4 v[60:61], v[40:43], off sc1
	s_waitcnt vmcnt(2)
	v_lshlrev_b32_e32 v46, 16, v65
	v_mul_f32_e32 v46, 0xbfb8aa3b, v46
	v_lshlrev_b32_e32 v40, 16, v62
	v_and_b32_e32 v41, 0xffff0000, v62
	v_mul_f32_e32 v40, 0xbfb8aa3b, v40
	v_mul_f32_e32 v41, 0xbfb8aa3b, v41
	v_exp_f32_e32 v40, v40
	v_exp_f32_e32 v41, v41
	v_exp_f32_e32 v52, v46
	v_lshlrev_b32_e32 v42, 16, v63
	v_and_b32_e32 v43, 0xffff0000, v63
	v_pk_add_f32 v[40:41], v[40:41], 1.0 op_sel_hi:[1,0]
	v_mul_f32_e32 v42, 0xbfb8aa3b, v42
	v_mul_f32_e32 v43, 0xbfb8aa3b, v43
	v_exp_f32_e32 v42, v42
	v_exp_f32_e32 v43, v43
	v_rcp_f32_e32 v41, v41
	v_lshlrev_b32_e32 v44, 16, v64
	v_pk_add_f32 v[54:55], v[42:43], 1.0 op_sel_hi:[1,0]
	v_rcp_f32_e32 v40, v40
	s_waitcnt vmcnt(1)
	v_lshlrev_b32_e32 v42, 16, v48
	v_and_b32_e32 v43, 0xffff0000, v48
	v_pk_fma_f32 v[56:57], v[36:37], v[40:41], v[42:43]
	v_and_b32_e32 v45, 0xffff0000, v64
	v_mul_f32_e32 v44, 0xbfb8aa3b, v44
	v_mul_f32_e32 v45, 0xbfb8aa3b, v45
	v_rcp_f32_e32 v37, v55
	v_exp_f32_e32 v44, v44
	v_exp_f32_e32 v45, v45
	v_add_u32_e32 v48, 0xa0, v156
	v_pk_add_f32 v[44:45], v[44:45], 1.0 op_sel_hi:[1,0]
	v_mad_i64_i32 v[40:41], s[0:1], v48, s51, v[158:159]
	v_lshl_add_u64 v[46:47], v[40:41], 0, v[154:155]
	global_load_dwordx4 v[40:43], v[46:47], off
	v_rcp_f32_e32 v36, v54
	v_lshlrev_b32_e32 v54, 16, v49
	v_and_b32_e32 v55, 0xffff0000, v49
	v_pk_fma_f32 v[54:55], v[38:39], v[36:37], v[54:55]
	v_and_b32_e32 v53, 0xffff0000, v65
	v_rcp_f32_e32 v37, v45
	v_mul_f32_e32 v53, 0xbfb8aa3b, v53
	v_exp_f32_e32 v53, v53
	s_nop 0
	v_pk_add_f32 v[52:53], v[52:53], 1.0 op_sel_hi:[1,0]
	v_rcp_f32_e32 v36, v44
	v_lshlrev_b32_e32 v38, 16, v50
	v_and_b32_e32 v39, 0xffff0000, v50
	v_pk_fma_f32 v[58:59], v[32:33], v[36:37], v[38:39]
	v_ashrrev_i32_e32 v49, 31, v48
	v_lshlrev_b64 v[32:33], 11, v[48:49]
	v_lshl_add_u64 v[32:33], s[16:17], 0, v[32:33]
	v_lshl_add_u64 v[44:45], v[32:33], 0, v[154:155]
	global_load_dwordx4 v[36:39], v[44:45], off
	v_rcp_f32_e32 v33, v53
	s_nop 0
	v_rcp_f32_e32 v32, v52
	v_lshlrev_b32_e32 v48, 16, v51
	v_and_b32_e32 v49, 0xffff0000, v51
	v_pk_fma_f32 v[48:49], v[34:35], v[32:33], v[48:49]
	v_cvt_pk_bf16_f32 v32, v56, v57
	v_cvt_pk_bf16_f32 v33, v54, v55
	v_cvt_pk_bf16_f32 v34, v58, v59
	v_cvt_pk_bf16_f32 v35, v48, v49
	global_store_dwordx4 v[60:61], v[32:35], off offset:256 sc1
	global_load_dwordx4 v[46:49], v[46:47], off offset:256
	s_waitcnt vmcnt(3)
	v_lshlrev_b32_e32 v32, 16, v40
	v_and_b32_e32 v33, 0xffff0000, v40
	v_mul_f32_e32 v32, 0xbfb8aa3b, v32
	v_mul_f32_e32 v33, 0xbfb8aa3b, v33
	v_exp_f32_e32 v32, v32
	v_exp_f32_e32 v33, v33
	v_lshlrev_b32_e32 v34, 16, v41
	v_and_b32_e32 v35, 0xffff0000, v41
	v_mul_f32_e32 v34, 0xbfb8aa3b, v34
	v_pk_add_f32 v[32:33], v[32:33], 1.0 op_sel_hi:[1,0]
	v_mul_f32_e32 v35, 0xbfb8aa3b, v35
	v_exp_f32_e32 v34, v34
	v_exp_f32_e32 v35, v35
	v_lshlrev_b32_e32 v40, 16, v42
	v_rcp_f32_e32 v51, v33
	v_and_b32_e32 v41, 0xffff0000, v42
	v_pk_add_f32 v[52:53], v[34:35], 1.0 op_sel_hi:[1,0]
	v_rcp_f32_e32 v50, v32
	global_load_dwordx4 v[32:35], v[44:45], off offset:256
	v_mul_f32_e32 v40, 0xbfb8aa3b, v40
	v_mul_f32_e32 v41, 0xbfb8aa3b, v41
	v_exp_f32_e32 v40, v40
	v_exp_f32_e32 v41, v41
	v_lshlrev_b32_e32 v42, 16, v43
	s_waitcnt vmcnt(3)
	v_lshlrev_b32_e32 v54, 16, v36
	v_and_b32_e32 v55, 0xffff0000, v36
	v_pk_fma_f32 v[28:29], v[28:29], v[50:51], v[54:55]
	v_rcp_f32_e32 v51, v53
	v_pk_add_f32 v[40:41], v[40:41], 1.0 op_sel_hi:[1,0]
	v_rcp_f32_e32 v50, v52
	v_lshlrev_b32_e32 v36, 16, v37
	v_and_b32_e32 v37, 0xffff0000, v37
	v_pk_fma_f32 v[30:31], v[30:31], v[50:51], v[36:37]
	v_rcp_f32_e32 v37, v41
	v_and_b32_e32 v43, 0xffff0000, v43
	v_mul_f32_e32 v42, 0xbfb8aa3b, v42
	v_mul_f32_e32 v43, 0xbfb8aa3b, v43
	v_exp_f32_e32 v42, v42
	v_exp_f32_e32 v43, v43
	v_rcp_f32_e32 v36, v40
	v_pk_add_f32 v[40:41], v[42:43], 1.0 op_sel_hi:[1,0]
	v_lshlrev_b32_e32 v42, 16, v38
	v_and_b32_e32 v43, 0xffff0000, v38
	v_pk_fma_f32 v[36:37], v[24:25], v[36:37], v[42:43]
	v_rcp_f32_e32 v25, v41
	s_nop 0
	v_rcp_f32_e32 v24, v40
	v_lshlrev_b32_e32 v38, 16, v39
	v_and_b32_e32 v39, 0xffff0000, v39
	v_pk_fma_f32 v[38:39], v[26:27], v[24:25], v[38:39]
	v_cvt_pk_bf16_f32 v24, v28, v29
	v_cvt_pk_bf16_f32 v25, v30, v31
	v_cvt_pk_bf16_f32 v26, v36, v37
	v_cvt_pk_bf16_f32 v27, v38, v39
	global_store_dwordx4 v[44:45], v[24:27], off sc1
	s_waitcnt vmcnt(2)
	v_lshlrev_b32_e32 v30, 16, v49
	v_mul_f32_e32 v30, 0xbfb8aa3b, v30
	v_lshlrev_b32_e32 v24, 16, v46
	v_and_b32_e32 v25, 0xffff0000, v46
	v_mul_f32_e32 v24, 0xbfb8aa3b, v24
	v_mul_f32_e32 v25, 0xbfb8aa3b, v25
	v_exp_f32_e32 v24, v24
	v_exp_f32_e32 v25, v25
	v_exp_f32_e32 v36, v30
	v_lshlrev_b32_e32 v26, 16, v47
	v_and_b32_e32 v27, 0xffff0000, v47
	v_pk_add_f32 v[24:25], v[24:25], 1.0 op_sel_hi:[1,0]
	v_mul_f32_e32 v26, 0xbfb8aa3b, v26
	v_mul_f32_e32 v27, 0xbfb8aa3b, v27
	v_exp_f32_e32 v26, v26
	v_exp_f32_e32 v27, v27
	v_rcp_f32_e32 v25, v25
	v_lshlrev_b32_e32 v28, 16, v48
	v_pk_add_f32 v[38:39], v[26:27], 1.0 op_sel_hi:[1,0]
	v_rcp_f32_e32 v24, v24
	s_waitcnt vmcnt(1)
	v_lshlrev_b32_e32 v26, 16, v32
	v_and_b32_e32 v27, 0xffff0000, v32
	v_pk_fma_f32 v[40:41], v[20:21], v[24:25], v[26:27]
	v_and_b32_e32 v29, 0xffff0000, v48
	v_mul_f32_e32 v28, 0xbfb8aa3b, v28
	v_mul_f32_e32 v29, 0xbfb8aa3b, v29
	v_rcp_f32_e32 v21, v39
	v_exp_f32_e32 v28, v28
	v_exp_f32_e32 v29, v29
	v_add_u32_e32 v32, 0xb0, v156
	v_pk_add_f32 v[28:29], v[28:29], 1.0 op_sel_hi:[1,0]
	v_mad_i64_i32 v[24:25], s[0:1], v32, s51, v[158:159]
	v_lshl_add_u64 v[30:31], v[24:25], 0, v[154:155]
	global_load_dwordx4 v[24:27], v[30:31], off
	v_rcp_f32_e32 v20, v38
	v_lshlrev_b32_e32 v38, 16, v33
	v_and_b32_e32 v39, 0xffff0000, v33
	v_pk_fma_f32 v[38:39], v[22:23], v[20:21], v[38:39]
	v_and_b32_e32 v37, 0xffff0000, v49
	v_rcp_f32_e32 v21, v29
	v_mul_f32_e32 v37, 0xbfb8aa3b, v37
	v_exp_f32_e32 v37, v37
	s_nop 0
	v_pk_add_f32 v[36:37], v[36:37], 1.0 op_sel_hi:[1,0]
	v_rcp_f32_e32 v20, v28
	v_lshlrev_b32_e32 v22, 16, v34
	v_and_b32_e32 v23, 0xffff0000, v34
	v_pk_fma_f32 v[42:43], v[16:17], v[20:21], v[22:23]
	v_ashrrev_i32_e32 v33, 31, v32
	v_lshlrev_b64 v[16:17], 11, v[32:33]
	v_lshl_add_u64 v[16:17], s[16:17], 0, v[16:17]
	v_lshl_add_u64 v[28:29], v[16:17], 0, v[154:155]
	global_load_dwordx4 v[20:23], v[28:29], off
	v_rcp_f32_e32 v17, v37
	s_nop 0
	v_rcp_f32_e32 v16, v36
	v_lshlrev_b32_e32 v32, 16, v35
	v_and_b32_e32 v33, 0xffff0000, v35
	v_pk_fma_f32 v[32:33], v[18:19], v[16:17], v[32:33]
	v_cvt_pk_bf16_f32 v16, v40, v41
	v_cvt_pk_bf16_f32 v17, v38, v39
	v_cvt_pk_bf16_f32 v18, v42, v43
	v_cvt_pk_bf16_f32 v19, v32, v33
	global_store_dwordx4 v[44:45], v[16:19], off offset:256 sc1
	global_load_dwordx4 v[30:33], v[30:31], off offset:256
	s_waitcnt vmcnt(3)
	v_lshlrev_b32_e32 v16, 16, v24
	v_and_b32_e32 v17, 0xffff0000, v24
	v_mul_f32_e32 v16, 0xbfb8aa3b, v16
	v_mul_f32_e32 v17, 0xbfb8aa3b, v17
	v_exp_f32_e32 v16, v16
	v_exp_f32_e32 v17, v17
	v_lshlrev_b32_e32 v18, 16, v25
	v_and_b32_e32 v19, 0xffff0000, v25
	v_mul_f32_e32 v18, 0xbfb8aa3b, v18
	v_pk_add_f32 v[16:17], v[16:17], 1.0 op_sel_hi:[1,0]
	v_mul_f32_e32 v19, 0xbfb8aa3b, v19
	v_exp_f32_e32 v18, v18
	v_exp_f32_e32 v19, v19
	v_lshlrev_b32_e32 v24, 16, v26
	v_rcp_f32_e32 v35, v17
	v_and_b32_e32 v25, 0xffff0000, v26
	v_pk_add_f32 v[36:37], v[18:19], 1.0 op_sel_hi:[1,0]
	v_rcp_f32_e32 v34, v16
	global_load_dwordx4 v[16:19], v[28:29], off offset:256
	v_mul_f32_e32 v24, 0xbfb8aa3b, v24
	v_mul_f32_e32 v25, 0xbfb8aa3b, v25
	v_exp_f32_e32 v24, v24
	v_exp_f32_e32 v25, v25
	v_lshlrev_b32_e32 v26, 16, v27
	s_waitcnt vmcnt(3)
	v_lshlrev_b32_e32 v38, 16, v20
	v_and_b32_e32 v39, 0xffff0000, v20
	v_pk_fma_f32 v[12:13], v[12:13], v[34:35], v[38:39]
	v_rcp_f32_e32 v35, v37
	v_pk_add_f32 v[24:25], v[24:25], 1.0 op_sel_hi:[1,0]
	v_rcp_f32_e32 v34, v36
	v_lshlrev_b32_e32 v20, 16, v21
	v_and_b32_e32 v21, 0xffff0000, v21
	v_pk_fma_f32 v[14:15], v[14:15], v[34:35], v[20:21]
	v_rcp_f32_e32 v21, v25
	v_and_b32_e32 v27, 0xffff0000, v27
	v_mul_f32_e32 v26, 0xbfb8aa3b, v26
	v_mul_f32_e32 v27, 0xbfb8aa3b, v27
	v_exp_f32_e32 v26, v26
	v_exp_f32_e32 v27, v27
	v_rcp_f32_e32 v20, v24
	v_pk_add_f32 v[24:25], v[26:27], 1.0 op_sel_hi:[1,0]
	v_lshlrev_b32_e32 v26, 16, v22
	v_and_b32_e32 v27, 0xffff0000, v22
	v_pk_fma_f32 v[20:21], v[8:9], v[20:21], v[26:27]
	v_rcp_f32_e32 v9, v25
	s_nop 0
	v_rcp_f32_e32 v8, v24
	v_lshlrev_b32_e32 v22, 16, v23
	v_and_b32_e32 v23, 0xffff0000, v23
	v_pk_fma_f32 v[22:23], v[10:11], v[8:9], v[22:23]
	v_cvt_pk_bf16_f32 v8, v12, v13
	v_cvt_pk_bf16_f32 v9, v14, v15
	v_cvt_pk_bf16_f32 v10, v20, v21
	v_cvt_pk_bf16_f32 v11, v22, v23
	global_store_dwordx4 v[28:29], v[8:11], off sc1
	s_waitcnt vmcnt(2)
	v_lshlrev_b32_e32 v12, 16, v32
	v_and_b32_e32 v13, 0xffff0000, v32
	v_lshlrev_b32_e32 v8, 16, v30
	v_and_b32_e32 v9, 0xffff0000, v30
	v_mul_f32_e32 v8, 0xbfb8aa3b, v8
	v_mul_f32_e32 v9, 0xbfb8aa3b, v9
	v_exp_f32_e32 v8, v8
	v_exp_f32_e32 v9, v9
	v_lshlrev_b32_e32 v10, 16, v31
	v_and_b32_e32 v11, 0xffff0000, v31
	v_mul_f32_e32 v10, 0xbfb8aa3b, v10
	v_pk_add_f32 v[8:9], v[8:9], 1.0 op_sel_hi:[1,0]
	v_mul_f32_e32 v11, 0xbfb8aa3b, v11
	v_exp_f32_e32 v10, v10
	v_exp_f32_e32 v11, v11
	v_mul_f32_e32 v12, 0xbfb8aa3b, v12
	v_rcp_f32_e32 v9, v9
	v_pk_add_f32 v[10:11], v[10:11], 1.0 op_sel_hi:[1,0]
	v_rcp_f32_e32 v8, v8
	s_waitcnt vmcnt(1)
	v_lshlrev_b32_e32 v20, 16, v16
	v_and_b32_e32 v21, 0xffff0000, v16
	v_pk_fma_f32 v[4:5], v[4:5], v[8:9], v[20:21]
	v_rcp_f32_e32 v9, v11
	v_mul_f32_e32 v13, 0xbfb8aa3b, v13
	v_exp_f32_e32 v12, v12
	v_exp_f32_e32 v13, v13
	v_rcp_f32_e32 v8, v10
	v_pk_add_f32 v[10:11], v[12:13], 1.0 op_sel_hi:[1,0]
	v_lshlrev_b32_e32 v12, 16, v17
	v_and_b32_e32 v13, 0xffff0000, v17
	v_pk_fma_f32 v[6:7], v[6:7], v[8:9], v[12:13]
	v_lshlrev_b32_e32 v14, 16, v33
	v_rcp_f32_e32 v9, v11
	v_and_b32_e32 v15, 0xffff0000, v33
	v_mul_f32_e32 v14, 0xbfb8aa3b, v14
	v_mul_f32_e32 v15, 0xbfb8aa3b, v15
	v_exp_f32_e32 v14, v14
	v_exp_f32_e32 v15, v15
	v_rcp_f32_e32 v8, v10
	v_pk_add_f32 v[10:11], v[14:15], 1.0 op_sel_hi:[1,0]
	v_lshlrev_b32_e32 v12, 16, v18
	v_and_b32_e32 v13, 0xffff0000, v18
	v_pk_fma_f32 v[8:9], v[0:1], v[8:9], v[12:13]
	v_rcp_f32_e32 v1, v11
	s_nop 0
	v_rcp_f32_e32 v0, v10
	v_lshlrev_b32_e32 v10, 16, v19
	v_and_b32_e32 v11, 0xffff0000, v19
	v_pk_fma_f32 v[10:11], v[2:3], v[0:1], v[10:11]
	v_cvt_pk_bf16_f32 v0, v4, v5
	v_cvt_pk_bf16_f32 v1, v6, v7
	v_cvt_pk_bf16_f32 v2, v8, v9
	v_cvt_pk_bf16_f32 v3, v10, v11
	s_andn2_b64 vcc, exec, s[2:3]
	s_mov_b64 s[0:1], -1
	global_store_dwordx4 v[28:29], v[0:3], off offset:256 sc1
	s_cbranch_vccnz .LBB0_920
	s_andn2_b64 vcc, exec, s[10:11]
	s_cbranch_vccnz .LBB0_919
	s_barrier
	s_branch .LBB0_919

.LBB0_1012:
	s_ashr_i32 s17, s24, 4
	s_mul_hi_i32 s19, s17, 0x6000
	s_mulk_i32 s17, 0x6000
	s_add_u32 s17, s96, s17
	s_addc_u32 s19, s97, s19
	v_lshl_or_b32 v162, s26, 8, v181
	s_add_u32 s26, s17, 0x2000
	s_addc_u32 s27, s19, 0
	s_add_u32 s28, s17, 0x4000
	s_addc_u32 s29, s19, 0
	v_ashrrev_i32_e32 v163, 31, v162
	s_lshl_b32 s17, s24, 8
	v_lshlrev_b64 v[80:81], 2, v[162:163]
	v_add_u32_e32 v166, s17, v176
	v_lshl_add_u64 v[92:93], s[76:77], 0, v[80:81]
	v_lshl_add_u64 v[84:85], s[28:29], 0, v[80:81]
	v_ashrrev_i32_e32 v167, 31, v166
	global_load_dwordx4 v[188:191], v[92:93], off offset:16
	global_load_dwordx4 v[168:171], v[92:93], off
	global_load_dwordx4 v[172:175], v[84:85], off offset:16
	global_load_dwordx4 v[192:195], v[84:85], off
	v_lshlrev_b64 v[84:85], 12, v[166:167]
	v_lshl_add_u64 v[84:85], s[64:65], 0, v[84:85]
	v_lshl_add_u64 v[220:221], v[84:85], 0, v[80:81]
	v_lshl_add_u64 v[82:83], s[26:27], 0, v[80:81]
	global_load_dwordx4 v[196:199], v[220:221], off
	global_load_dwordx4 v[88:91], v[82:83], off
	global_load_dwordx4 v[84:87], v[82:83], off offset:16
	global_load_dwordx4 v[200:203], v[220:221], off offset:16
	v_or_b32_e32 v80, 0x80, v162
	v_or_b32_e32 v82, 0x84, v162
	v_ashrrev_i32_e32 v81, 31, v80
	v_lshlrev_b64 v[222:223], 11, v[166:167]
	v_ashrrev_i32_e32 v83, 31, v82
	v_lshlrev_b64 v[164:165], 1, v[162:163]
	v_lshlrev_b64 v[80:81], 2, v[80:81]
	v_lshl_add_u64 v[224:225], s[52:53], 0, v[222:223]
	global_load_dwordx4 v[204:207], v[92:93], off offset:528
	global_load_dwordx4 v[208:211], v[92:93], off offset:512
	v_lshl_add_u64 v[92:93], s[26:27], 0, v[80:81]
	v_lshl_add_u64 v[82:83], v[82:83], 2, s[26:27]
	v_lshl_add_u64 v[80:81], s[28:29], 0, v[80:81]
	v_lshl_add_u64 v[222:223], s[12:13], 0, v[222:223]
	v_lshl_add_u64 v[224:225], v[224:225], 0, v[164:165]
	global_load_dwordx4 v[92:95], v[92:93], off
	s_nop 0
	global_load_dwordx4 v[212:215], v[80:81], off
	global_load_dwordx4 v[216:219], v[80:81], off offset:16
	s_nop 0
	global_load_dwordx4 v[80:83], v[82:83], off
	v_lshl_add_u64 v[222:223], v[222:223], 0, v[164:165]
	s_waitcnt vmcnt(0)
	v_pk_add_f32 v[226:227], v[174:175], 1.0 op_sel_hi:[1,0]
	v_pk_add_f32 v[194:195], v[194:195], 1.0 op_sel_hi:[1,0]
	v_pk_add_f32 v[192:193], v[192:193], 1.0 op_sel_hi:[1,0]
	v_pk_add_f32 v[172:173], v[172:173], 1.0 op_sel_hi:[1,0]
	v_pk_mul_f32 v[170:171], v[170:171], v[194:195]
	v_pk_mul_f32 v[174:175], v[168:169], v[192:193]
	v_pk_mul_f32 v[168:169], v[190:191], v[226:227]
	v_pk_mul_f32 v[172:173], v[188:189], v[172:173]
	v_pk_fma_f32 v[198:199], v[142:143], v[90:91], v[198:199]
	v_pk_fma_f32 v[226:227], v[140:141], v[88:89], v[196:197]
	v_pk_fma_f32 v[202:203], v[138:139], v[86:87], v[202:203]
	v_pk_fma_f32 v[200:201], v[136:137], v[84:85], v[200:201]
	v_cvt_pk_bf16_f32 v136, v226, v227
	v_cvt_pk_bf16_f32 v137, v198, v199
	v_cvt_pk_bf16_f32 v138, v200, v201
	v_cvt_pk_bf16_f32 v139, v202, v203
	v_pk_mul_f32 v[140:141], v[170:171], v[198:199]
	v_pk_mul_f32 v[142:143], v[174:175], v[226:227]
	v_pk_mul_f32 v[188:189], v[168:169], v[202:203]
	v_pk_mul_f32 v[190:191], v[172:173], v[200:201]
	global_store_dwordx4 v[224:225], v[136:139], off sc1
	v_mul_f32_e32 v199, v199, v199
	v_mul_f32_e32 v201, v201, v201
	v_cvt_pk_bf16_f32 v136, v142, v143
	v_cvt_pk_bf16_f32 v137, v140, v141
	v_cvt_pk_bf16_f32 v138, v190, v191
	v_cvt_pk_bf16_f32 v139, v188, v189
	global_store_dwordx4 v[222:223], v[136:139], off sc1
	global_load_dwordx4 v[190:193], v[220:221], off offset:512
	global_load_dwordx4 v[194:197], v[220:221], off offset:528
	v_mul_f32_e32 v189, v227, v227
	v_and_b32_e32 v137, 64, v186
	v_fmac_f32_e32 v189, v226, v226
	v_fmac_f32_e32 v199, v198, v198
	v_xor_b32_e32 v136, 16, v186
	v_add_u32_e32 v137, 64, v137
	v_mul_f32_e32 v203, v203, v203
	v_fmac_f32_e32 v201, v200, v200
	v_add_f32_e32 v189, v189, v199
	v_cmp_lt_i32_e32 vcc, v136, v137
	v_fmac_f32_e32 v203, v202, v202
	v_add_f32_e32 v189, v189, v201
	v_cndmask_b32_e32 v136, v186, v136, vcc
	v_add_f32_e32 v189, v203, v189
	v_lshlrev_b32_e32 v188, 2, v136
	v_xor_b32_e32 v138, 32, v186
	v_cmp_lt_i32_e32 vcc, v138, v137
	s_waitcnt vmcnt(1)
	v_pk_fma_f32 v[134:135], v[134:135], v[94:95], v[192:193]
	v_pk_fma_f32 v[132:133], v[132:133], v[92:93], v[190:191]
	s_waitcnt vmcnt(0)
	v_pk_fma_f32 v[190:191], v[130:131], v[82:83], v[196:197]
	v_pk_fma_f32 v[192:193], v[128:129], v[80:81], v[194:195]
	v_mul_f32_e32 v194, v133, v133
	v_mul_f32_e32 v195, v135, v135
	v_cvt_pk_bf16_f32 v128, v132, v133
	v_cvt_pk_bf16_f32 v129, v134, v135
	v_cvt_pk_bf16_f32 v130, v192, v193
	v_cvt_pk_bf16_f32 v131, v190, v191
	v_mul_f32_e32 v196, v193, v193
	v_fmac_f32_e32 v194, v132, v132
	v_fmac_f32_e32 v195, v134, v134
	v_mul_f32_e32 v197, v191, v191
	global_store_dwordx4 v[224:225], v[128:131], off offset:256 sc1
	v_fmac_f32_e32 v196, v192, v192
	v_fmac_f32_e32 v197, v190, v190
	v_add_f32_e32 v128, v194, v195
	v_add_f32_e32 v128, v128, v196
	v_add_f32_e32 v128, v197, v128
	v_add_f32_e32 v131, v189, v128
	ds_bpermute_b32 v189, v188, v131
	v_cndmask_b32_e32 v137, v186, v138, vcc
	v_pk_add_f32 v[138:139], v[212:213], 1.0 op_sel_hi:[1,0]
	v_lshlrev_b32_e32 v187, 2, v137
	v_pk_mul_f32 v[140:141], v[208:209], v[138:139]
	v_pk_add_f32 v[136:137], v[214:215], 1.0 op_sel_hi:[1,0]
	v_pk_mul_f32 v[128:129], v[140:141], v[132:133]
	v_pk_add_f32 v[212:213], v[218:219], 1.0 op_sel_hi:[1,0]
	v_cvt_pk_bf16_f32 v130, v128, v129
	s_waitcnt lgkmcnt(0)
	v_add_f32_e32 v128, v131, v189
	ds_bpermute_b32 v129, v187, v128
	v_pk_add_f32 v[214:215], v[216:217], 1.0 op_sel_hi:[1,0]
	v_pk_mul_f32 v[142:143], v[210:211], v[136:137]
	v_pk_mul_f32 v[136:137], v[206:207], v[212:213]
	v_pk_mul_f32 v[138:139], v[204:205], v[214:215]
	v_pk_mul_f32 v[134:135], v[142:143], v[134:135]
	v_pk_mul_f32 v[190:191], v[136:137], v[190:191]
	v_pk_mul_f32 v[132:133], v[138:139], v[192:193]
	v_cvt_pk_bf16_f32 v131, v134, v135
	v_cvt_pk_bf16_f32 v132, v132, v133
	v_cvt_pk_bf16_f32 v133, v190, v191
	global_store_dwordx4 v[222:223], v[130:133], off offset:256 sc1
	s_and_saveexec_b64 s[24:25], s[2:3]
	s_cbranch_execz .LBB0_1014
	v_lshl_add_u64 v[130:131], v[166:167], 2, s[14:15]
	s_waitcnt lgkmcnt(0)
	v_add_f32_e32 v128, v128, v129
	global_atomic_add_f32 v[130:131], v128, off
.LBB0_1014:
	s_or_b64 exec, exec, s[24:25]
	v_add_u32_e32 v128, s17, v178
	s_waitcnt lgkmcnt(0)
	v_ashrrev_i32_e32 v129, 31, v128
	v_lshlrev_b64 v[130:131], 12, v[128:129]
	v_lshl_add_u64 v[130:131], s[64:65], 0, v[130:131]
	v_lshl_add_u64 v[134:135], v[162:163], 2, v[130:131]
	global_load_dwordx4 v[130:133], v[134:135], off
	global_load_dwordx4 v[190:193], v[134:135], off offset:16
	v_lshlrev_b64 v[194:195], 11, v[128:129]
	v_lshl_add_u64 v[196:197], s[52:53], 0, v[194:195]
	v_lshl_add_u64 v[194:195], s[12:13], 0, v[194:195]
	v_lshl_add_u64 v[196:197], v[196:197], 0, v[164:165]
	v_lshl_add_u64 v[194:195], v[194:195], 0, v[164:165]
	s_waitcnt vmcnt(1)
	v_pk_fma_f32 v[132:133], v[126:127], v[90:91], v[132:133]
	v_pk_fma_f32 v[130:131], v[124:125], v[88:89], v[130:131]
	s_waitcnt vmcnt(0)
	v_pk_fma_f32 v[192:193], v[122:123], v[86:87], v[192:193]
	v_pk_fma_f32 v[190:191], v[120:121], v[84:85], v[190:191]
	v_cvt_pk_bf16_f32 v120, v130, v131
	v_cvt_pk_bf16_f32 v121, v132, v133
	v_cvt_pk_bf16_f32 v122, v190, v191
	v_cvt_pk_bf16_f32 v123, v192, v193
	v_pk_mul_f32 v[124:125], v[170:171], v[132:133]
	v_pk_mul_f32 v[126:127], v[174:175], v[130:131]
	v_pk_mul_f32 v[198:199], v[168:169], v[192:193]
	v_pk_mul_f32 v[200:201], v[172:173], v[190:191]
	global_store_dwordx4 v[196:197], v[120:123], off sc1
	v_mul_f32_e32 v131, v131, v131
	v_mul_f32_e32 v133, v133, v133
	v_cvt_pk_bf16_f32 v120, v126, v127
	v_cvt_pk_bf16_f32 v121, v124, v125
	v_cvt_pk_bf16_f32 v122, v200, v201
	v_cvt_pk_bf16_f32 v123, v198, v199
	global_store_dwordx4 v[194:195], v[120:123], off sc1
	global_load_dwordx4 v[120:123], v[134:135], off offset:512
	s_nop 0
	global_load_dwordx4 v[124:127], v[134:135], off offset:528
	v_mul_f32_e32 v134, v191, v191
	v_fmac_f32_e32 v131, v130, v130
	v_fmac_f32_e32 v133, v132, v132
	v_mul_f32_e32 v135, v193, v193
	v_fmac_f32_e32 v134, v190, v190
	v_add_f32_e32 v130, v131, v133
	v_fmac_f32_e32 v135, v192, v192
	v_add_f32_e32 v130, v130, v134
	v_add_f32_e32 v130, v135, v130
	s_waitcnt vmcnt(1)
	v_pk_fma_f32 v[118:119], v[118:119], v[94:95], v[122:123]
	v_pk_fma_f32 v[116:117], v[116:117], v[92:93], v[120:121]
	s_waitcnt vmcnt(0)
	v_pk_fma_f32 v[120:121], v[114:115], v[82:83], v[126:127]
	v_pk_fma_f32 v[122:123], v[112:113], v[80:81], v[124:125]
	v_mul_f32_e32 v124, v117, v117
	v_mul_f32_e32 v125, v119, v119
	v_cvt_pk_bf16_f32 v112, v116, v117
	v_cvt_pk_bf16_f32 v113, v118, v119
	v_cvt_pk_bf16_f32 v114, v122, v123
	v_cvt_pk_bf16_f32 v115, v120, v121
	v_mul_f32_e32 v126, v123, v123
	v_fmac_f32_e32 v124, v116, v116
	v_fmac_f32_e32 v125, v118, v118
	v_mul_f32_e32 v127, v121, v121
	global_store_dwordx4 v[196:197], v[112:115], off offset:256 sc1
	v_fmac_f32_e32 v126, v122, v122
	v_fmac_f32_e32 v127, v120, v120
	v_add_f32_e32 v112, v124, v125
	v_add_f32_e32 v112, v112, v126
	v_add_f32_e32 v112, v127, v112
	v_add_f32_e32 v115, v130, v112
	ds_bpermute_b32 v124, v188, v115
	v_pk_mul_f32 v[112:113], v[140:141], v[116:117]
	v_pk_mul_f32 v[118:119], v[142:143], v[118:119]
	v_cvt_pk_bf16_f32 v114, v112, v113
	v_pk_mul_f32 v[120:121], v[136:137], v[120:121]
	s_waitcnt lgkmcnt(0)
	v_add_f32_e32 v112, v115, v124
	ds_bpermute_b32 v113, v187, v112
	v_pk_mul_f32 v[116:117], v[138:139], v[122:123]
	v_cvt_pk_bf16_f32 v115, v118, v119
	v_cvt_pk_bf16_f32 v116, v116, v117
	v_cvt_pk_bf16_f32 v117, v120, v121
	global_store_dwordx4 v[194:195], v[114:117], off offset:256 sc1
	s_and_saveexec_b64 s[24:25], s[2:3]
	s_cbranch_execz .LBB0_1016
	v_lshl_add_u64 v[114:115], v[128:129], 2, s[14:15]
	s_waitcnt lgkmcnt(0)
	v_add_f32_e32 v112, v112, v113
	global_atomic_add_f32 v[114:115], v112, off
.LBB0_1016:
	s_or_b64 exec, exec, s[24:25]
	v_add_u32_e32 v112, s17, v179
	s_waitcnt lgkmcnt(0)
	v_ashrrev_i32_e32 v113, 31, v112
	v_lshlrev_b64 v[114:115], 12, v[112:113]
	v_lshl_add_u64 v[114:115], s[64:65], 0, v[114:115]
	v_lshl_add_u64 v[122:123], v[162:163], 2, v[114:115]
	global_load_dwordx4 v[114:117], v[122:123], off
	global_load_dwordx4 v[118:121], v[122:123], off offset:16
	v_lshlrev_b64 v[124:125], 11, v[112:113]
	v_lshl_add_u64 v[126:127], s[52:53], 0, v[124:125]
	v_lshl_add_u64 v[124:125], s[12:13], 0, v[124:125]
	v_lshl_add_u64 v[126:127], v[126:127], 0, v[164:165]
	v_lshl_add_u64 v[124:125], v[124:125], 0, v[164:165]
	s_waitcnt vmcnt(1)
	v_pk_fma_f32 v[116:117], v[110:111], v[90:91], v[116:117]
	v_pk_fma_f32 v[114:115], v[108:109], v[88:89], v[114:115]
	s_waitcnt vmcnt(0)
	v_pk_fma_f32 v[120:121], v[106:107], v[86:87], v[120:121]
	v_pk_fma_f32 v[118:119], v[104:105], v[84:85], v[118:119]
	v_cvt_pk_bf16_f32 v104, v114, v115
	v_cvt_pk_bf16_f32 v105, v116, v117
	v_cvt_pk_bf16_f32 v106, v118, v119
	v_cvt_pk_bf16_f32 v107, v120, v121
	v_pk_mul_f32 v[108:109], v[170:171], v[116:117]
	v_pk_mul_f32 v[110:111], v[174:175], v[114:115]
	v_pk_mul_f32 v[128:129], v[168:169], v[120:121]
	v_pk_mul_f32 v[130:131], v[172:173], v[118:119]
	global_store_dwordx4 v[126:127], v[104:107], off sc1
	v_mul_f32_e32 v115, v115, v115
	v_mul_f32_e32 v117, v117, v117
	v_cvt_pk_bf16_f32 v104, v110, v111
	v_cvt_pk_bf16_f32 v105, v108, v109
	v_cvt_pk_bf16_f32 v106, v130, v131
	v_cvt_pk_bf16_f32 v107, v128, v129
	global_store_dwordx4 v[124:125], v[104:107], off sc1
	global_load_dwordx4 v[104:107], v[122:123], off offset:512
	s_nop 0
	global_load_dwordx4 v[108:111], v[122:123], off offset:528
	v_mul_f32_e32 v119, v119, v119
	v_fmac_f32_e32 v115, v114, v114
	v_fmac_f32_e32 v117, v116, v116
	v_mul_f32_e32 v121, v121, v121
	v_fmac_f32_e32 v119, v118, v118
	v_add_f32_e32 v114, v115, v117
	v_fmac_f32_e32 v121, v120, v120
	v_add_f32_e32 v114, v114, v119
	v_add_f32_e32 v114, v121, v114
	s_waitcnt vmcnt(1)
	v_pk_fma_f32 v[102:103], v[102:103], v[94:95], v[106:107]
	v_pk_fma_f32 v[100:101], v[100:101], v[92:93], v[104:105]
	s_waitcnt vmcnt(0)
	v_pk_fma_f32 v[104:105], v[98:99], v[82:83], v[110:111]
	v_pk_fma_f32 v[106:107], v[96:97], v[80:81], v[108:109]
	v_mul_f32_e32 v108, v101, v101
	v_mul_f32_e32 v109, v103, v103
	v_cvt_pk_bf16_f32 v96, v100, v101
	v_cvt_pk_bf16_f32 v97, v102, v103
	v_cvt_pk_bf16_f32 v98, v106, v107
	v_cvt_pk_bf16_f32 v99, v104, v105
	v_mul_f32_e32 v110, v107, v107
	v_fmac_f32_e32 v108, v100, v100
	v_fmac_f32_e32 v109, v102, v102
	v_mul_f32_e32 v111, v105, v105
	global_store_dwordx4 v[126:127], v[96:99], off offset:256 sc1
	v_fmac_f32_e32 v110, v106, v106
	v_fmac_f32_e32 v111, v104, v104
	v_add_f32_e32 v96, v108, v109
	v_add_f32_e32 v96, v96, v110
	v_add_f32_e32 v96, v111, v96
	v_add_f32_e32 v99, v114, v96
	ds_bpermute_b32 v108, v188, v99
	v_pk_mul_f32 v[96:97], v[140:141], v[100:101]
	v_pk_mul_f32 v[102:103], v[142:143], v[102:103]
	v_cvt_pk_bf16_f32 v98, v96, v97
	v_pk_mul_f32 v[104:105], v[136:137], v[104:105]
	s_waitcnt lgkmcnt(0)
	v_add_f32_e32 v96, v99, v108
	ds_bpermute_b32 v97, v187, v96
	v_pk_mul_f32 v[100:101], v[138:139], v[106:107]
	v_cvt_pk_bf16_f32 v99, v102, v103
	v_cvt_pk_bf16_f32 v100, v100, v101
	v_cvt_pk_bf16_f32 v101, v104, v105
	global_store_dwordx4 v[124:125], v[98:101], off offset:256 sc1
	s_and_saveexec_b64 s[24:25], s[2:3]
	s_cbranch_execz .LBB0_1018
	v_lshl_add_u64 v[98:99], v[112:113], 2, s[14:15]
	s_waitcnt lgkmcnt(0)
	v_add_f32_e32 v96, v96, v97
	global_atomic_add_f32 v[98:99], v96, off
.LBB0_1018:
	s_or_b64 exec, exec, s[24:25]
	v_add_u32_e32 v96, s17, v180
	s_waitcnt lgkmcnt(0)
	v_ashrrev_i32_e32 v97, 31, v96
	v_lshlrev_b64 v[98:99], 12, v[96:97]
	v_lshl_add_u64 v[98:99], s[64:65], 0, v[98:99]
	v_lshl_add_u64 v[106:107], v[162:163], 2, v[98:99]
	global_load_dwordx4 v[98:101], v[106:107], off
	global_load_dwordx4 v[102:105], v[106:107], off offset:16
	v_lshlrev_b64 v[108:109], 11, v[96:97]
	v_lshl_add_u64 v[110:111], s[52:53], 0, v[108:109]
	v_lshl_add_u64 v[108:109], s[12:13], 0, v[108:109]
	v_lshl_add_u64 v[110:111], v[110:111], 0, v[164:165]
	v_lshl_add_u64 v[108:109], v[108:109], 0, v[164:165]
	s_waitcnt vmcnt(1)
	v_pk_fma_f32 v[100:101], v[78:79], v[90:91], v[100:101]
	v_pk_fma_f32 v[98:99], v[76:77], v[88:89], v[98:99]
	s_waitcnt vmcnt(0)
	v_pk_fma_f32 v[104:105], v[74:75], v[86:87], v[104:105]
	v_pk_fma_f32 v[102:103], v[72:73], v[84:85], v[102:103]
	v_cvt_pk_bf16_f32 v72, v98, v99
	v_cvt_pk_bf16_f32 v73, v100, v101
	v_cvt_pk_bf16_f32 v74, v102, v103
	v_cvt_pk_bf16_f32 v75, v104, v105
	v_pk_mul_f32 v[76:77], v[170:171], v[100:101]
	v_pk_mul_f32 v[78:79], v[174:175], v[98:99]
	v_pk_mul_f32 v[112:113], v[168:169], v[104:105]
	v_pk_mul_f32 v[114:115], v[172:173], v[102:103]
	global_store_dwordx4 v[110:111], v[72:75], off sc1
	v_mul_f32_e32 v99, v99, v99
	v_mul_f32_e32 v101, v101, v101
	v_cvt_pk_bf16_f32 v72, v78, v79
	v_cvt_pk_bf16_f32 v73, v76, v77
	v_cvt_pk_bf16_f32 v74, v114, v115
	v_cvt_pk_bf16_f32 v75, v112, v113
	global_store_dwordx4 v[108:109], v[72:75], off sc1
	global_load_dwordx4 v[72:75], v[106:107], off offset:512
	s_nop 0
	global_load_dwordx4 v[76:79], v[106:107], off offset:528
	v_mul_f32_e32 v103, v103, v103
	v_fmac_f32_e32 v99, v98, v98
	v_fmac_f32_e32 v101, v100, v100
	v_mul_f32_e32 v105, v105, v105
	v_fmac_f32_e32 v103, v102, v102
	v_add_f32_e32 v98, v99, v101
	v_fmac_f32_e32 v105, v104, v104
	v_add_f32_e32 v98, v98, v103
	v_add_f32_e32 v98, v105, v98
	s_waitcnt vmcnt(1)
	v_pk_fma_f32 v[70:71], v[70:71], v[94:95], v[74:75]
	v_pk_fma_f32 v[68:69], v[68:69], v[92:93], v[72:73]
	s_waitcnt vmcnt(0)
	v_pk_fma_f32 v[72:73], v[66:67], v[82:83], v[78:79]
	v_pk_fma_f32 v[74:75], v[64:65], v[80:81], v[76:77]
	v_mul_f32_e32 v76, v69, v69
	v_mul_f32_e32 v77, v71, v71
	v_cvt_pk_bf16_f32 v64, v68, v69
	v_cvt_pk_bf16_f32 v65, v70, v71
	v_cvt_pk_bf16_f32 v66, v74, v75
	v_cvt_pk_bf16_f32 v67, v72, v73
	v_mul_f32_e32 v78, v75, v75
	v_fmac_f32_e32 v76, v68, v68
	v_fmac_f32_e32 v77, v70, v70
	v_mul_f32_e32 v79, v73, v73
	global_store_dwordx4 v[110:111], v[64:67], off offset:256 sc1
	v_fmac_f32_e32 v78, v74, v74
	v_fmac_f32_e32 v79, v72, v72
	v_add_f32_e32 v64, v76, v77
	v_add_f32_e32 v64, v64, v78
	v_add_f32_e32 v64, v79, v64
	v_add_f32_e32 v67, v98, v64
	ds_bpermute_b32 v76, v188, v67
	v_pk_mul_f32 v[64:65], v[140:141], v[68:69]
	v_pk_mul_f32 v[70:71], v[142:143], v[70:71]
	v_cvt_pk_bf16_f32 v66, v64, v65
	v_pk_mul_f32 v[72:73], v[136:137], v[72:73]
	s_waitcnt lgkmcnt(0)
	v_add_f32_e32 v64, v67, v76
	ds_bpermute_b32 v65, v187, v64
	v_pk_mul_f32 v[68:69], v[138:139], v[74:75]
	v_cvt_pk_bf16_f32 v67, v70, v71
	v_cvt_pk_bf16_f32 v68, v68, v69
	v_cvt_pk_bf16_f32 v69, v72, v73
	global_store_dwordx4 v[108:109], v[66:69], off offset:256 sc1
	s_and_saveexec_b64 s[24:25], s[2:3]
	s_cbranch_execz .LBB0_1020
	v_lshl_add_u64 v[66:67], v[96:97], 2, s[14:15]
	s_waitcnt lgkmcnt(0)
	v_add_f32_e32 v64, v64, v65
	global_atomic_add_f32 v[66:67], v64, off
.LBB0_1020:
	s_or_b64 exec, exec, s[24:25]
	v_add_u32_e32 v64, 0x80, v166
	s_waitcnt lgkmcnt(0)
	v_ashrrev_i32_e32 v65, 31, v64
	v_lshlrev_b64 v[66:67], 12, v[64:65]
	v_lshl_add_u64 v[66:67], s[64:65], 0, v[66:67]
	v_lshl_add_u64 v[74:75], v[162:163], 2, v[66:67]
	global_load_dwordx4 v[66:69], v[74:75], off
	global_load_dwordx4 v[70:73], v[74:75], off offset:16
	v_lshlrev_b64 v[76:77], 11, v[64:65]
	v_lshl_add_u64 v[78:79], s[52:53], 0, v[76:77]
	v_lshl_add_u64 v[76:77], s[12:13], 0, v[76:77]
	v_lshl_add_u64 v[78:79], v[78:79], 0, v[164:165]
	v_lshl_add_u64 v[76:77], v[76:77], 0, v[164:165]
	s_waitcnt vmcnt(1)
	v_pk_fma_f32 v[68:69], v[62:63], v[90:91], v[68:69]
	v_pk_fma_f32 v[66:67], v[60:61], v[88:89], v[66:67]
	s_waitcnt vmcnt(0)
	v_pk_fma_f32 v[72:73], v[58:59], v[86:87], v[72:73]
	v_pk_fma_f32 v[70:71], v[56:57], v[84:85], v[70:71]
	v_cvt_pk_bf16_f32 v56, v66, v67
	v_cvt_pk_bf16_f32 v57, v68, v69
	v_cvt_pk_bf16_f32 v58, v70, v71
	v_cvt_pk_bf16_f32 v59, v72, v73
	v_pk_mul_f32 v[60:61], v[170:171], v[68:69]
	v_pk_mul_f32 v[62:63], v[174:175], v[66:67]
	v_pk_mul_f32 v[96:97], v[168:169], v[72:73]
	v_pk_mul_f32 v[98:99], v[172:173], v[70:71]
	global_store_dwordx4 v[78:79], v[56:59], off sc1
	v_mul_f32_e32 v67, v67, v67
	v_mul_f32_e32 v69, v69, v69
	v_cvt_pk_bf16_f32 v56, v62, v63
	v_cvt_pk_bf16_f32 v57, v60, v61
	v_cvt_pk_bf16_f32 v58, v98, v99
	v_cvt_pk_bf16_f32 v59, v96, v97
	global_store_dwordx4 v[76:77], v[56:59], off sc1
	global_load_dwordx4 v[56:59], v[74:75], off offset:512
	s_nop 0
	global_load_dwordx4 v[60:63], v[74:75], off offset:528
	v_mul_f32_e32 v71, v71, v71
	v_fmac_f32_e32 v67, v66, v66
	v_fmac_f32_e32 v69, v68, v68
	v_mul_f32_e32 v73, v73, v73
	v_fmac_f32_e32 v71, v70, v70
	v_add_f32_e32 v66, v67, v69
	v_fmac_f32_e32 v73, v72, v72
	v_add_f32_e32 v66, v66, v71
	v_add_f32_e32 v66, v73, v66
	s_waitcnt vmcnt(1)
	v_pk_fma_f32 v[54:55], v[54:55], v[94:95], v[58:59]
	v_pk_fma_f32 v[52:53], v[52:53], v[92:93], v[56:57]
	s_waitcnt vmcnt(0)
	v_pk_fma_f32 v[56:57], v[50:51], v[82:83], v[62:63]
	v_pk_fma_f32 v[58:59], v[48:49], v[80:81], v[60:61]
	v_mul_f32_e32 v60, v53, v53
	v_mul_f32_e32 v61, v55, v55
	v_cvt_pk_bf16_f32 v48, v52, v53
	v_cvt_pk_bf16_f32 v49, v54, v55
	v_cvt_pk_bf16_f32 v50, v58, v59
	v_cvt_pk_bf16_f32 v51, v56, v57
	v_mul_f32_e32 v62, v59, v59
	v_fmac_f32_e32 v60, v52, v52
	v_fmac_f32_e32 v61, v54, v54
	v_mul_f32_e32 v63, v57, v57
	global_store_dwordx4 v[78:79], v[48:51], off offset:256 sc1
	v_fmac_f32_e32 v62, v58, v58
	v_fmac_f32_e32 v63, v56, v56
	v_add_f32_e32 v48, v60, v61
	v_add_f32_e32 v48, v48, v62
	v_add_f32_e32 v48, v63, v48
	v_add_f32_e32 v51, v66, v48
	ds_bpermute_b32 v60, v188, v51
	v_pk_mul_f32 v[48:49], v[140:141], v[52:53]
	v_pk_mul_f32 v[54:55], v[142:143], v[54:55]
	v_cvt_pk_bf16_f32 v50, v48, v49
	v_pk_mul_f32 v[56:57], v[136:137], v[56:57]
	s_waitcnt lgkmcnt(0)
	v_add_f32_e32 v48, v51, v60
	ds_bpermute_b32 v49, v187, v48
	v_pk_mul_f32 v[52:53], v[138:139], v[58:59]
	v_cvt_pk_bf16_f32 v51, v54, v55
	v_cvt_pk_bf16_f32 v52, v52, v53
	v_cvt_pk_bf16_f32 v53, v56, v57
	global_store_dwordx4 v[76:77], v[50:53], off offset:256 sc1
	s_and_saveexec_b64 s[24:25], s[2:3]
	s_cbranch_execz .LBB0_1022
	v_lshl_add_u64 v[50:51], v[64:65], 2, s[14:15]
	s_waitcnt lgkmcnt(0)
	v_add_f32_e32 v48, v48, v49
	global_atomic_add_f32 v[50:51], v48, off
.LBB0_1022:
	s_or_b64 exec, exec, s[24:25]
	v_add_u32_e32 v48, 0x90, v166
	s_waitcnt lgkmcnt(0)
	v_ashrrev_i32_e32 v49, 31, v48
	v_lshlrev_b64 v[50:51], 12, v[48:49]
	v_lshl_add_u64 v[50:51], s[64:65], 0, v[50:51]
	v_lshl_add_u64 v[58:59], v[162:163], 2, v[50:51]
	global_load_dwordx4 v[50:53], v[58:59], off
	global_load_dwordx4 v[54:57], v[58:59], off offset:16
	v_lshlrev_b64 v[60:61], 11, v[48:49]
	v_lshl_add_u64 v[62:63], s[52:53], 0, v[60:61]
	v_lshl_add_u64 v[60:61], s[12:13], 0, v[60:61]
	v_lshl_add_u64 v[62:63], v[62:63], 0, v[164:165]
	v_lshl_add_u64 v[60:61], v[60:61], 0, v[164:165]
	s_waitcnt vmcnt(1)
	v_pk_fma_f32 v[52:53], v[46:47], v[90:91], v[52:53]
	v_pk_fma_f32 v[50:51], v[44:45], v[88:89], v[50:51]
	s_waitcnt vmcnt(0)
	v_pk_fma_f32 v[56:57], v[42:43], v[86:87], v[56:57]
	v_pk_fma_f32 v[54:55], v[40:41], v[84:85], v[54:55]
	v_cvt_pk_bf16_f32 v40, v50, v51
	v_cvt_pk_bf16_f32 v41, v52, v53
	v_cvt_pk_bf16_f32 v42, v54, v55
	v_cvt_pk_bf16_f32 v43, v56, v57
	v_pk_mul_f32 v[44:45], v[170:171], v[52:53]
	v_pk_mul_f32 v[46:47], v[174:175], v[50:51]
	v_pk_mul_f32 v[64:65], v[168:169], v[56:57]
	v_pk_mul_f32 v[66:67], v[172:173], v[54:55]
	global_store_dwordx4 v[62:63], v[40:43], off sc1
	v_mul_f32_e32 v51, v51, v51
	v_mul_f32_e32 v53, v53, v53
	v_cvt_pk_bf16_f32 v40, v46, v47
	v_cvt_pk_bf16_f32 v41, v44, v45
	v_cvt_pk_bf16_f32 v42, v66, v67
	v_cvt_pk_bf16_f32 v43, v64, v65
	global_store_dwordx4 v[60:61], v[40:43], off sc1
	global_load_dwordx4 v[40:43], v[58:59], off offset:512
	s_nop 0
	global_load_dwordx4 v[44:47], v[58:59], off offset:528
	v_mul_f32_e32 v55, v55, v55
	v_fmac_f32_e32 v51, v50, v50
	v_fmac_f32_e32 v53, v52, v52
	v_mul_f32_e32 v57, v57, v57
	v_fmac_f32_e32 v55, v54, v54
	v_add_f32_e32 v50, v51, v53
	v_fmac_f32_e32 v57, v56, v56
	v_add_f32_e32 v50, v50, v55
	v_add_f32_e32 v50, v57, v50
	s_waitcnt vmcnt(1)
	v_pk_fma_f32 v[38:39], v[38:39], v[94:95], v[42:43]
	v_pk_fma_f32 v[36:37], v[36:37], v[92:93], v[40:41]
	s_waitcnt vmcnt(0)
	v_pk_fma_f32 v[40:41], v[34:35], v[82:83], v[46:47]
	v_pk_fma_f32 v[42:43], v[32:33], v[80:81], v[44:45]
	v_mul_f32_e32 v44, v37, v37
	v_mul_f32_e32 v45, v39, v39
	v_cvt_pk_bf16_f32 v32, v36, v37
	v_cvt_pk_bf16_f32 v33, v38, v39
	v_cvt_pk_bf16_f32 v34, v42, v43
	v_cvt_pk_bf16_f32 v35, v40, v41
	v_mul_f32_e32 v46, v43, v43
	v_fmac_f32_e32 v44, v36, v36
	v_fmac_f32_e32 v45, v38, v38
	v_mul_f32_e32 v47, v41, v41
	global_store_dwordx4 v[62:63], v[32:35], off offset:256 sc1
	v_fmac_f32_e32 v46, v42, v42
	v_fmac_f32_e32 v47, v40, v40
	v_add_f32_e32 v32, v44, v45
	v_add_f32_e32 v32, v32, v46
	v_add_f32_e32 v32, v47, v32
	v_add_f32_e32 v35, v50, v32
	ds_bpermute_b32 v44, v188, v35
	v_pk_mul_f32 v[32:33], v[140:141], v[36:37]
	v_pk_mul_f32 v[38:39], v[142:143], v[38:39]
	v_cvt_pk_bf16_f32 v34, v32, v33
	v_pk_mul_f32 v[40:41], v[136:137], v[40:41]
	s_waitcnt lgkmcnt(0)
	v_add_f32_e32 v32, v35, v44
	ds_bpermute_b32 v33, v187, v32
	v_pk_mul_f32 v[36:37], v[138:139], v[42:43]
	v_cvt_pk_bf16_f32 v35, v38, v39
	v_cvt_pk_bf16_f32 v36, v36, v37
	v_cvt_pk_bf16_f32 v37, v40, v41
	global_store_dwordx4 v[60:61], v[34:37], off offset:256 sc1
	s_and_saveexec_b64 s[24:25], s[2:3]
	s_cbranch_execz .LBB0_1024
	v_lshl_add_u64 v[34:35], v[48:49], 2, s[14:15]
	s_waitcnt lgkmcnt(0)
	v_add_f32_e32 v32, v32, v33
	global_atomic_add_f32 v[34:35], v32, off
.LBB0_1024:
	s_or_b64 exec, exec, s[24:25]
	v_add_u32_e32 v32, 0xa0, v166
	s_waitcnt lgkmcnt(0)
	v_ashrrev_i32_e32 v33, 31, v32
	v_lshlrev_b64 v[34:35], 12, v[32:33]
	v_lshl_add_u64 v[34:35], s[64:65], 0, v[34:35]
	v_lshl_add_u64 v[42:43], v[162:163], 2, v[34:35]
	global_load_dwordx4 v[34:37], v[42:43], off
	global_load_dwordx4 v[38:41], v[42:43], off offset:16
	v_lshlrev_b64 v[44:45], 11, v[32:33]
	v_lshl_add_u64 v[46:47], s[52:53], 0, v[44:45]
	v_lshl_add_u64 v[44:45], s[12:13], 0, v[44:45]
	v_lshl_add_u64 v[46:47], v[46:47], 0, v[164:165]
	v_lshl_add_u64 v[44:45], v[44:45], 0, v[164:165]
	s_waitcnt vmcnt(1)
	v_pk_fma_f32 v[36:37], v[30:31], v[90:91], v[36:37]
	v_pk_fma_f32 v[34:35], v[28:29], v[88:89], v[34:35]
	s_waitcnt vmcnt(0)
	v_pk_fma_f32 v[40:41], v[26:27], v[86:87], v[40:41]
	v_pk_fma_f32 v[38:39], v[24:25], v[84:85], v[38:39]
	v_cvt_pk_bf16_f32 v24, v34, v35
	v_cvt_pk_bf16_f32 v25, v36, v37
	v_cvt_pk_bf16_f32 v26, v38, v39
	v_cvt_pk_bf16_f32 v27, v40, v41
	v_pk_mul_f32 v[28:29], v[170:171], v[36:37]
	v_pk_mul_f32 v[30:31], v[174:175], v[34:35]
	v_pk_mul_f32 v[48:49], v[168:169], v[40:41]
	v_pk_mul_f32 v[50:51], v[172:173], v[38:39]
	global_store_dwordx4 v[46:47], v[24:27], off sc1
	v_mul_f32_e32 v35, v35, v35
	v_mul_f32_e32 v37, v37, v37
	v_cvt_pk_bf16_f32 v24, v30, v31
	v_cvt_pk_bf16_f32 v25, v28, v29
	v_cvt_pk_bf16_f32 v26, v50, v51
	v_cvt_pk_bf16_f32 v27, v48, v49
	global_store_dwordx4 v[44:45], v[24:27], off sc1
	global_load_dwordx4 v[24:27], v[42:43], off offset:512
	s_nop 0
	global_load_dwordx4 v[28:31], v[42:43], off offset:528
	v_mul_f32_e32 v39, v39, v39
	v_fmac_f32_e32 v35, v34, v34
	v_fmac_f32_e32 v37, v36, v36
	v_mul_f32_e32 v41, v41, v41
	v_fmac_f32_e32 v39, v38, v38
	v_add_f32_e32 v34, v35, v37
	v_fmac_f32_e32 v41, v40, v40
	v_add_f32_e32 v34, v34, v39
	v_add_f32_e32 v34, v41, v34
	s_waitcnt vmcnt(1)
	v_pk_fma_f32 v[22:23], v[22:23], v[94:95], v[26:27]
	v_pk_fma_f32 v[20:21], v[20:21], v[92:93], v[24:25]
	s_waitcnt vmcnt(0)
	v_pk_fma_f32 v[24:25], v[18:19], v[82:83], v[30:31]
	v_pk_fma_f32 v[26:27], v[16:17], v[80:81], v[28:29]
	v_mul_f32_e32 v28, v21, v21
	v_mul_f32_e32 v29, v23, v23
	v_cvt_pk_bf16_f32 v16, v20, v21
	v_cvt_pk_bf16_f32 v17, v22, v23
	v_cvt_pk_bf16_f32 v18, v26, v27
	v_cvt_pk_bf16_f32 v19, v24, v25
	v_mul_f32_e32 v30, v27, v27
	v_fmac_f32_e32 v28, v20, v20
	v_fmac_f32_e32 v29, v22, v22
	v_mul_f32_e32 v31, v25, v25
	global_store_dwordx4 v[46:47], v[16:19], off offset:256 sc1
	v_fmac_f32_e32 v30, v26, v26
	v_fmac_f32_e32 v31, v24, v24
	v_add_f32_e32 v16, v28, v29
	v_add_f32_e32 v16, v16, v30
	v_add_f32_e32 v16, v31, v16
	v_add_f32_e32 v19, v34, v16
	ds_bpermute_b32 v28, v188, v19
	v_pk_mul_f32 v[16:17], v[140:141], v[20:21]
	v_pk_mul_f32 v[22:23], v[142:143], v[22:23]
	v_cvt_pk_bf16_f32 v18, v16, v17
	v_pk_mul_f32 v[24:25], v[136:137], v[24:25]
	s_waitcnt lgkmcnt(0)
	v_add_f32_e32 v16, v19, v28
	ds_bpermute_b32 v17, v187, v16
	v_pk_mul_f32 v[20:21], v[138:139], v[26:27]
	v_cvt_pk_bf16_f32 v19, v22, v23
	v_cvt_pk_bf16_f32 v20, v20, v21
	v_cvt_pk_bf16_f32 v21, v24, v25
	global_store_dwordx4 v[44:45], v[18:21], off offset:256 sc1
	s_and_saveexec_b64 s[24:25], s[2:3]
	s_cbranch_execz .LBB0_1026
	v_lshl_add_u64 v[18:19], v[32:33], 2, s[14:15]
	s_waitcnt lgkmcnt(0)
	v_add_f32_e32 v16, v16, v17
	global_atomic_add_f32 v[18:19], v16, off
.LBB0_1026:
	s_or_b64 exec, exec, s[24:25]
	v_add_u32_e32 v16, 0xb0, v166
	s_waitcnt lgkmcnt(0)
	v_ashrrev_i32_e32 v17, 31, v16
	v_lshlrev_b64 v[18:19], 12, v[16:17]
	v_lshl_add_u64 v[18:19], s[64:65], 0, v[18:19]
	v_lshl_add_u64 v[26:27], v[162:163], 2, v[18:19]
	global_load_dwordx4 v[18:21], v[26:27], off
	global_load_dwordx4 v[22:25], v[26:27], off offset:16
	v_lshlrev_b64 v[28:29], 11, v[16:17]
	v_lshl_add_u64 v[30:31], s[52:53], 0, v[28:29]
	v_lshl_add_u64 v[28:29], s[12:13], 0, v[28:29]
	v_lshl_add_u64 v[30:31], v[30:31], 0, v[164:165]
	v_lshl_add_u64 v[28:29], v[28:29], 0, v[164:165]
	s_waitcnt vmcnt(1)
	v_pk_fma_f32 v[20:21], v[14:15], v[90:91], v[20:21]
	v_pk_fma_f32 v[18:19], v[12:13], v[88:89], v[18:19]
	s_waitcnt vmcnt(0)
	v_pk_fma_f32 v[24:25], v[10:11], v[86:87], v[24:25]
	v_pk_fma_f32 v[22:23], v[8:9], v[84:85], v[22:23]
	v_cvt_pk_bf16_f32 v8, v18, v19
	v_cvt_pk_bf16_f32 v9, v20, v21
	v_cvt_pk_bf16_f32 v10, v22, v23
	v_cvt_pk_bf16_f32 v11, v24, v25
	v_pk_mul_f32 v[12:13], v[170:171], v[20:21]
	v_pk_mul_f32 v[14:15], v[174:175], v[18:19]
	v_pk_mul_f32 v[32:33], v[168:169], v[24:25]
	v_pk_mul_f32 v[34:35], v[172:173], v[22:23]
	global_store_dwordx4 v[30:31], v[8:11], off sc1
	v_mul_f32_e32 v19, v19, v19
	v_mul_f32_e32 v21, v21, v21
	v_cvt_pk_bf16_f32 v8, v14, v15
	v_cvt_pk_bf16_f32 v9, v12, v13
	v_cvt_pk_bf16_f32 v10, v34, v35
	v_cvt_pk_bf16_f32 v11, v32, v33
	global_store_dwordx4 v[28:29], v[8:11], off sc1
	global_load_dwordx4 v[8:11], v[26:27], off offset:512
	s_nop 0
	global_load_dwordx4 v[12:15], v[26:27], off offset:528
	v_mul_f32_e32 v23, v23, v23
	v_fmac_f32_e32 v19, v18, v18
	v_fmac_f32_e32 v21, v20, v20
	v_mul_f32_e32 v25, v25, v25
	v_fmac_f32_e32 v23, v22, v22
	v_add_f32_e32 v18, v19, v21
	v_fmac_f32_e32 v25, v24, v24
	v_add_f32_e32 v18, v18, v23
	v_add_f32_e32 v18, v25, v18
	s_waitcnt vmcnt(1)
	v_pk_fma_f32 v[6:7], v[6:7], v[94:95], v[10:11]
	v_pk_fma_f32 v[4:5], v[4:5], v[92:93], v[8:9]
	s_waitcnt vmcnt(0)
	v_pk_fma_f32 v[8:9], v[2:3], v[82:83], v[14:15]
	v_pk_fma_f32 v[10:11], v[0:1], v[80:81], v[12:13]
	v_mul_f32_e32 v12, v5, v5
	v_mul_f32_e32 v13, v7, v7
	v_cvt_pk_bf16_f32 v0, v4, v5
	v_cvt_pk_bf16_f32 v1, v6, v7
	v_cvt_pk_bf16_f32 v2, v10, v11
	v_cvt_pk_bf16_f32 v3, v8, v9
	v_mul_f32_e32 v14, v11, v11
	v_fmac_f32_e32 v12, v4, v4
	v_fmac_f32_e32 v13, v6, v6
	v_mul_f32_e32 v15, v9, v9
	global_store_dwordx4 v[30:31], v[0:3], off offset:256 sc1
	v_fmac_f32_e32 v14, v10, v10
	v_fmac_f32_e32 v15, v8, v8
	v_add_f32_e32 v0, v12, v13
	v_add_f32_e32 v0, v0, v14
	v_add_f32_e32 v0, v15, v0
	v_add_f32_e32 v3, v18, v0
	ds_bpermute_b32 v12, v188, v3
	v_pk_mul_f32 v[0:1], v[140:141], v[4:5]
	v_pk_mul_f32 v[6:7], v[142:143], v[6:7]
	v_cvt_pk_bf16_f32 v2, v0, v1
	v_pk_mul_f32 v[8:9], v[136:137], v[8:9]
	s_waitcnt lgkmcnt(0)
	v_add_f32_e32 v0, v3, v12
	ds_bpermute_b32 v1, v187, v0
	v_pk_mul_f32 v[4:5], v[138:139], v[10:11]
	v_cvt_pk_bf16_f32 v3, v6, v7
	v_cvt_pk_bf16_f32 v4, v4, v5
	v_cvt_pk_bf16_f32 v5, v8, v9
	global_store_dwordx4 v[28:29], v[2:5], off offset:256 sc1
	s_and_saveexec_b64 s[24:25], s[2:3]
	s_cbranch_execz .LBB0_1028
	v_lshl_add_u64 v[2:3], v[16:17], 2, s[14:15]
	s_waitcnt lgkmcnt(0)
	v_add_f32_e32 v0, v0, v1
	global_atomic_add_f32 v[2:3], v0, off

.LBB0_1099:
	s_ashr_i32 s17, s4, 4
	s_mul_hi_i32 s19, s17, 0x5800
	s_mulk_i32 s17, 0x5800
	s_add_u32 s17, s48, s17
	s_addc_u32 s19, s49, s19
	s_lshl_b32 s24, s60, 8
	s_ashr_i32 s25, s24, 31
	s_lshl_b64 s[26:27], s[24:25], 2
	s_add_u32 s17, s17, s26
	s_addc_u32 s19, s19, s27
	s_lshl_b32 s26, s43, 2
	s_add_u32 s26, s17, s26
	s_addc_u32 s27, s19, 0
	s_lshl_b32 s17, s4, 8
	v_add_u32_e32 v168, s17, v157
	v_ashrrev_i32_e32 v169, 31, v168
	v_lshl_add_u64 v[128:129], v[168:169], 2, s[12:13]
	global_load_dword v169, v[128:129], off
	v_lshlrev_b32_e32 v128, 2, v156
	global_load_dwordx4 v[140:143], v128, s[26:27]
	global_load_dwordx4 v[136:139], v128, s[26:27] offset:16
	global_load_dwordx4 v[132:135], v128, s[26:27] offset:512
	s_nop 0
	global_load_dwordx4 v[128:131], v128, s[26:27] offset:528
	v_mov_b64_e32 v[166:167], s[14:15]
	s_lshl_b64 s[24:25], s[24:25], 1
	v_mad_i64_i32 v[180:181], s[26:27], v168, s64, v[166:167]
	s_lshl_b32 s4, s43, 1
	v_lshl_add_u64 v[180:181], v[180:181], 0, s[24:25]
	v_lshlrev_b32_e32 v154, 1, v156
	v_add_u32_e32 v178, s17, v171
	v_lshl_add_u64 v[180:181], v[180:181], 0, s[4:5]
	v_ashrrev_i32_e32 v179, 31, v178
	v_lshl_add_u64 v[180:181], v[180:181], 0, v[154:155]
	v_lshl_add_u64 v[186:187], v[178:179], 2, s[12:13]
	s_andn2_b64 vcc, exec, s[2:3]
	s_waitcnt vmcnt(0)
	v_fmamk_f32 v169, v169, 0x3a800000, v177
	v_rsq_f32_e32 v182, v169
	s_nop 0
	v_pk_fma_f32 v[126:127], v[126:127], v[182:183], v[142:143] op_sel_hi:[1,0,1]
	v_pk_fma_f32 v[124:125], v[124:125], v[182:183], v[140:141] op_sel_hi:[1,0,1]
	v_pk_fma_f32 v[122:123], v[122:123], v[182:183], v[138:139] op_sel_hi:[1,0,1]
	v_pk_fma_f32 v[120:121], v[120:121], v[182:183], v[136:137] op_sel_hi:[1,0,1]
	v_pk_fma_f32 v[118:119], v[118:119], v[182:183], v[134:135] op_sel_hi:[1,0,1]
	v_pk_fma_f32 v[116:117], v[116:117], v[182:183], v[132:133] op_sel_hi:[1,0,1]
	v_pk_fma_f32 v[188:189], v[114:115], v[182:183], v[130:131] op_sel_hi:[1,0,1]
	v_pk_fma_f32 v[182:183], v[112:113], v[182:183], v[128:129] op_sel_hi:[1,0,1]
	v_cvt_pk_bf16_f32 v112, v124, v125
	v_cvt_pk_bf16_f32 v113, v126, v127
	v_cvt_pk_bf16_f32 v114, v120, v121
	v_cvt_pk_bf16_f32 v115, v122, v123
	v_cvt_pk_bf16_f32 v116, v116, v117
	v_cvt_pk_bf16_f32 v117, v118, v119
	v_cvt_pk_bf16_f32 v118, v182, v183
	v_cvt_pk_bf16_f32 v119, v188, v189
	global_store_dwordx4 v[180:181], v[112:115], off sc1
	global_store_dwordx4 v[180:181], v[116:119], off offset:256 sc1
	global_load_dword v116, v[186:187], off
	v_mad_i64_i32 v[114:115], s[26:27], v178, s64, v[166:167]
	v_lshl_add_u64 v[114:115], v[114:115], 0, s[24:25]
	v_add_u32_e32 v112, s17, v172
	v_lshl_add_u64 v[114:115], v[114:115], 0, s[4:5]
	v_ashrrev_i32_e32 v113, 31, v112
	v_lshl_add_u64 v[114:115], v[114:115], 0, v[154:155]
	v_lshl_add_u64 v[118:119], v[112:113], 2, s[12:13]
	s_waitcnt vmcnt(0)
	v_fmamk_f32 v116, v116, 0x3a800000, v177
	v_rsq_f32_e32 v116, v116
	s_nop 0
	v_pk_fma_f32 v[110:111], v[110:111], v[116:117], v[142:143] op_sel_hi:[1,0,1]
	v_pk_fma_f32 v[108:109], v[108:109], v[116:117], v[140:141] op_sel_hi:[1,0,1]
	v_pk_fma_f32 v[106:107], v[106:107], v[116:117], v[138:139] op_sel_hi:[1,0,1]
	v_pk_fma_f32 v[104:105], v[104:105], v[116:117], v[136:137] op_sel_hi:[1,0,1]
	v_pk_fma_f32 v[102:103], v[102:103], v[116:117], v[134:135] op_sel_hi:[1,0,1]
	v_pk_fma_f32 v[100:101], v[100:101], v[116:117], v[132:133] op_sel_hi:[1,0,1]
	v_pk_fma_f32 v[120:121], v[98:99], v[116:117], v[130:131] op_sel_hi:[1,0,1]
	v_pk_fma_f32 v[116:117], v[96:97], v[116:117], v[128:129] op_sel_hi:[1,0,1]
	v_cvt_pk_bf16_f32 v96, v108, v109
	v_cvt_pk_bf16_f32 v97, v110, v111
	v_cvt_pk_bf16_f32 v98, v104, v105
	v_cvt_pk_bf16_f32 v99, v106, v107
	v_cvt_pk_bf16_f32 v100, v100, v101
	v_cvt_pk_bf16_f32 v101, v102, v103
	v_cvt_pk_bf16_f32 v102, v116, v117
	v_cvt_pk_bf16_f32 v103, v120, v121
	global_store_dwordx4 v[114:115], v[96:99], off sc1
	global_store_dwordx4 v[114:115], v[100:103], off offset:256 sc1
	global_load_dword v100, v[118:119], off
	v_mad_i64_i32 v[98:99], s[26:27], v112, s64, v[166:167]
	v_lshl_add_u64 v[98:99], v[98:99], 0, s[24:25]
	v_add_u32_e32 v96, s17, v173
	v_lshl_add_u64 v[98:99], v[98:99], 0, s[4:5]
	v_ashrrev_i32_e32 v97, 31, v96
	v_lshl_add_u64 v[98:99], v[98:99], 0, v[154:155]
	v_lshl_add_u64 v[102:103], v[96:97], 2, s[12:13]
	s_waitcnt vmcnt(0)
	v_fmamk_f32 v100, v100, 0x3a800000, v177
	v_rsq_f32_e32 v100, v100
	s_nop 0
	v_pk_fma_f32 v[94:95], v[94:95], v[100:101], v[142:143] op_sel_hi:[1,0,1]
	v_pk_fma_f32 v[92:93], v[92:93], v[100:101], v[140:141] op_sel_hi:[1,0,1]
	v_pk_fma_f32 v[90:91], v[90:91], v[100:101], v[138:139] op_sel_hi:[1,0,1]
	v_pk_fma_f32 v[88:89], v[88:89], v[100:101], v[136:137] op_sel_hi:[1,0,1]
	v_pk_fma_f32 v[86:87], v[86:87], v[100:101], v[134:135] op_sel_hi:[1,0,1]
	v_pk_fma_f32 v[84:85], v[84:85], v[100:101], v[132:133] op_sel_hi:[1,0,1]
	v_pk_fma_f32 v[104:105], v[82:83], v[100:101], v[130:131] op_sel_hi:[1,0,1]
	v_pk_fma_f32 v[100:101], v[80:81], v[100:101], v[128:129] op_sel_hi:[1,0,1]
	v_cvt_pk_bf16_f32 v80, v92, v93
	v_cvt_pk_bf16_f32 v81, v94, v95
	v_cvt_pk_bf16_f32 v82, v88, v89
	v_cvt_pk_bf16_f32 v83, v90, v91
	v_cvt_pk_bf16_f32 v84, v84, v85
	v_cvt_pk_bf16_f32 v85, v86, v87
	v_cvt_pk_bf16_f32 v86, v100, v101
	v_cvt_pk_bf16_f32 v87, v104, v105
	global_store_dwordx4 v[98:99], v[80:83], off sc1
	global_store_dwordx4 v[98:99], v[84:87], off offset:256 sc1
	global_load_dword v84, v[102:103], off
	v_mad_i64_i32 v[80:81], s[26:27], v96, s64, v[166:167]
	v_lshl_add_u64 v[80:81], v[80:81], 0, s[24:25]
	v_add_u32_e32 v82, 0x80, v168
	v_lshl_add_u64 v[80:81], v[80:81], 0, s[4:5]
	v_ashrrev_i32_e32 v83, 31, v82
	v_lshl_add_u64 v[80:81], v[80:81], 0, v[154:155]
	v_lshl_add_u64 v[86:87], v[82:83], 2, s[12:13]
	s_waitcnt vmcnt(0)
	v_fmamk_f32 v84, v84, 0x3a800000, v177
	v_rsq_f32_e32 v84, v84
	s_nop 0
	v_pk_fma_f32 v[78:79], v[78:79], v[84:85], v[142:143] op_sel_hi:[1,0,1]
	v_pk_fma_f32 v[76:77], v[76:77], v[84:85], v[140:141] op_sel_hi:[1,0,1]
	v_pk_fma_f32 v[74:75], v[74:75], v[84:85], v[138:139] op_sel_hi:[1,0,1]
	v_pk_fma_f32 v[72:73], v[72:73], v[84:85], v[136:137] op_sel_hi:[1,0,1]
	v_pk_fma_f32 v[70:71], v[70:71], v[84:85], v[134:135] op_sel_hi:[1,0,1]
	v_pk_fma_f32 v[68:69], v[68:69], v[84:85], v[132:133] op_sel_hi:[1,0,1]
	v_pk_fma_f32 v[88:89], v[66:67], v[84:85], v[130:131] op_sel_hi:[1,0,1]
	v_pk_fma_f32 v[84:85], v[64:65], v[84:85], v[128:129] op_sel_hi:[1,0,1]
	v_cvt_pk_bf16_f32 v64, v76, v77
	v_cvt_pk_bf16_f32 v65, v78, v79
	v_cvt_pk_bf16_f32 v66, v72, v73
	v_cvt_pk_bf16_f32 v67, v74, v75
	v_cvt_pk_bf16_f32 v68, v68, v69
	v_cvt_pk_bf16_f32 v69, v70, v71
	v_cvt_pk_bf16_f32 v70, v84, v85
	v_cvt_pk_bf16_f32 v71, v88, v89
	global_store_dwordx4 v[80:81], v[64:67], off sc1
	global_store_dwordx4 v[80:81], v[68:71], off offset:256 sc1
	global_load_dword v68, v[86:87], off
	v_mad_i64_i32 v[66:67], s[26:27], v82, s64, v[166:167]
	v_lshl_add_u64 v[66:67], v[66:67], 0, s[24:25]
	v_add_u32_e32 v64, 0x90, v168
	v_lshl_add_u64 v[66:67], v[66:67], 0, s[4:5]
	v_ashrrev_i32_e32 v65, 31, v64
	v_lshl_add_u64 v[66:67], v[66:67], 0, v[154:155]
	v_lshl_add_u64 v[70:71], v[64:65], 2, s[12:13]
	s_waitcnt vmcnt(0)
	v_fmamk_f32 v68, v68, 0x3a800000, v177
	v_rsq_f32_e32 v68, v68
	s_nop 0
	v_pk_fma_f32 v[62:63], v[62:63], v[68:69], v[142:143] op_sel_hi:[1,0,1]
	v_pk_fma_f32 v[60:61], v[60:61], v[68:69], v[140:141] op_sel_hi:[1,0,1]
	v_pk_fma_f32 v[58:59], v[58:59], v[68:69], v[138:139] op_sel_hi:[1,0,1]
	v_pk_fma_f32 v[56:57], v[56:57], v[68:69], v[136:137] op_sel_hi:[1,0,1]
	v_pk_fma_f32 v[54:55], v[54:55], v[68:69], v[134:135] op_sel_hi:[1,0,1]
	v_pk_fma_f32 v[52:53], v[52:53], v[68:69], v[132:133] op_sel_hi:[1,0,1]
	v_pk_fma_f32 v[72:73], v[50:51], v[68:69], v[130:131] op_sel_hi:[1,0,1]
	v_pk_fma_f32 v[68:69], v[48:49], v[68:69], v[128:129] op_sel_hi:[1,0,1]
	v_cvt_pk_bf16_f32 v48, v60, v61
	v_cvt_pk_bf16_f32 v49, v62, v63
	v_cvt_pk_bf16_f32 v50, v56, v57
	v_cvt_pk_bf16_f32 v51, v58, v59
	v_cvt_pk_bf16_f32 v52, v52, v53
	v_cvt_pk_bf16_f32 v53, v54, v55
	v_cvt_pk_bf16_f32 v54, v68, v69
	v_cvt_pk_bf16_f32 v55, v72, v73
	global_store_dwordx4 v[66:67], v[48:51], off sc1
	global_store_dwordx4 v[66:67], v[52:55], off offset:256 sc1
	global_load_dword v52, v[70:71], off
	v_mad_i64_i32 v[50:51], s[26:27], v64, s64, v[166:167]
	v_lshl_add_u64 v[50:51], v[50:51], 0, s[24:25]
	v_add_u32_e32 v48, 0xa0, v168
	v_lshl_add_u64 v[50:51], v[50:51], 0, s[4:5]
	v_ashrrev_i32_e32 v49, 31, v48
	v_lshl_add_u64 v[50:51], v[50:51], 0, v[154:155]
	v_lshl_add_u64 v[54:55], v[48:49], 2, s[12:13]
	s_waitcnt vmcnt(0)
	v_fmamk_f32 v52, v52, 0x3a800000, v177
	v_rsq_f32_e32 v52, v52
	s_nop 0
	v_pk_fma_f32 v[46:47], v[46:47], v[52:53], v[142:143] op_sel_hi:[1,0,1]
	v_pk_fma_f32 v[44:45], v[44:45], v[52:53], v[140:141] op_sel_hi:[1,0,1]
	v_pk_fma_f32 v[42:43], v[42:43], v[52:53], v[138:139] op_sel_hi:[1,0,1]
	v_pk_fma_f32 v[40:41], v[40:41], v[52:53], v[136:137] op_sel_hi:[1,0,1]
	v_pk_fma_f32 v[38:39], v[38:39], v[52:53], v[134:135] op_sel_hi:[1,0,1]
	v_pk_fma_f32 v[36:37], v[36:37], v[52:53], v[132:133] op_sel_hi:[1,0,1]
	v_pk_fma_f32 v[56:57], v[34:35], v[52:53], v[130:131] op_sel_hi:[1,0,1]
	v_pk_fma_f32 v[52:53], v[32:33], v[52:53], v[128:129] op_sel_hi:[1,0,1]
	v_cvt_pk_bf16_f32 v32, v44, v45
	v_cvt_pk_bf16_f32 v33, v46, v47
	v_cvt_pk_bf16_f32 v34, v40, v41
	v_cvt_pk_bf16_f32 v35, v42, v43
	v_cvt_pk_bf16_f32 v36, v36, v37
	v_cvt_pk_bf16_f32 v37, v38, v39
	v_cvt_pk_bf16_f32 v38, v52, v53
	v_cvt_pk_bf16_f32 v39, v56, v57
	global_store_dwordx4 v[50:51], v[32:35], off sc1
	global_store_dwordx4 v[50:51], v[36:39], off offset:256 sc1
	global_load_dword v36, v[54:55], off
	v_mad_i64_i32 v[34:35], s[26:27], v48, s64, v[166:167]
	v_lshl_add_u64 v[34:35], v[34:35], 0, s[24:25]
	v_add_u32_e32 v32, 0xb0, v168
	v_lshl_add_u64 v[34:35], v[34:35], 0, s[4:5]
	v_ashrrev_i32_e32 v33, 31, v32
	v_lshl_add_u64 v[34:35], v[34:35], 0, v[154:155]
	v_lshl_add_u64 v[38:39], v[32:33], 2, s[12:13]
	s_waitcnt vmcnt(0)
	v_fmamk_f32 v36, v36, 0x3a800000, v177
	v_rsq_f32_e32 v36, v36
	s_nop 0
	v_pk_fma_f32 v[30:31], v[30:31], v[36:37], v[142:143] op_sel_hi:[1,0,1]
	v_pk_fma_f32 v[28:29], v[28:29], v[36:37], v[140:141] op_sel_hi:[1,0,1]
	v_pk_fma_f32 v[26:27], v[26:27], v[36:37], v[138:139] op_sel_hi:[1,0,1]
	v_pk_fma_f32 v[24:25], v[24:25], v[36:37], v[136:137] op_sel_hi:[1,0,1]
	v_pk_fma_f32 v[22:23], v[22:23], v[36:37], v[134:135] op_sel_hi:[1,0,1]
	v_pk_fma_f32 v[20:21], v[20:21], v[36:37], v[132:133] op_sel_hi:[1,0,1]
	v_pk_fma_f32 v[40:41], v[18:19], v[36:37], v[130:131] op_sel_hi:[1,0,1]
	v_pk_fma_f32 v[36:37], v[16:17], v[36:37], v[128:129] op_sel_hi:[1,0,1]
	v_cvt_pk_bf16_f32 v16, v28, v29
	v_cvt_pk_bf16_f32 v17, v30, v31
	v_cvt_pk_bf16_f32 v18, v24, v25
	v_cvt_pk_bf16_f32 v19, v26, v27
	v_cvt_pk_bf16_f32 v20, v20, v21
	v_cvt_pk_bf16_f32 v21, v22, v23
	v_cvt_pk_bf16_f32 v22, v36, v37
	v_cvt_pk_bf16_f32 v23, v40, v41
	global_store_dwordx4 v[34:35], v[16:19], off sc1
	global_store_dwordx4 v[34:35], v[20:23], off offset:256 sc1
	global_load_dword v18, v[38:39], off
	v_mad_i64_i32 v[16:17], s[2:3], v32, s64, v[166:167]
	v_lshl_add_u64 v[16:17], v[16:17], 0, s[24:25]
	v_lshl_add_u64 v[16:17], v[16:17], 0, s[4:5]
	v_lshl_add_u64 v[16:17], v[16:17], 0, v[154:155]
	s_mov_b64 s[2:3], -1
	s_waitcnt vmcnt(0)
	v_fmamk_f32 v18, v18, 0x3a800000, v177
	v_rsq_f32_e32 v18, v18
	s_nop 0
	v_pk_fma_f32 v[14:15], v[14:15], v[18:19], v[142:143] op_sel_hi:[1,0,1]
	v_pk_fma_f32 v[12:13], v[12:13], v[18:19], v[140:141] op_sel_hi:[1,0,1]
	v_pk_fma_f32 v[10:11], v[10:11], v[18:19], v[138:139] op_sel_hi:[1,0,1]
	v_pk_fma_f32 v[8:9], v[8:9], v[18:19], v[136:137] op_sel_hi:[1,0,1]
	v_pk_fma_f32 v[6:7], v[6:7], v[18:19], v[134:135] op_sel_hi:[1,0,1]
	v_pk_fma_f32 v[4:5], v[4:5], v[18:19], v[132:133] op_sel_hi:[1,0,1]
	v_pk_fma_f32 v[20:21], v[2:3], v[18:19], v[130:131] op_sel_hi:[1,0,1]
	v_pk_fma_f32 v[18:19], v[0:1], v[18:19], v[128:129] op_sel_hi:[1,0,1]
	v_cvt_pk_bf16_f32 v0, v12, v13
	v_cvt_pk_bf16_f32 v1, v14, v15
	v_cvt_pk_bf16_f32 v2, v8, v9
	v_cvt_pk_bf16_f32 v3, v10, v11
	v_cvt_pk_bf16_f32 v4, v4, v5
	v_cvt_pk_bf16_f32 v5, v6, v7
	v_cvt_pk_bf16_f32 v6, v18, v19
	v_cvt_pk_bf16_f32 v7, v20, v21
	global_store_dwordx4 v[16:17], v[0:3], off sc1
	global_store_dwordx4 v[16:17], v[4:7], off offset:256 sc1
	s_cbranch_vccnz .LBB0_1092
	s_andn2_b64 vcc, exec, s[6:7]
	s_cbranch_vccnz .LBB0_1091
	s_barrier
	s_branch .LBB0_1091

.Lconv_item:
	s_mov_b32 s20, 0x2e8ba2e9
	v_mul_hi_i32 v232, v230, s20
	v_lshrrev_b32_e32 v233, 31, v232
	v_ashrrev_i32_e32 v232, 6, v232
	v_add_u32_e32 v232, v232, v233
	v_mul_i32_i24_e32 v233, 0x160, v232
	v_sub_u32_e32 v231, v230, v233
	v_lshlrev_b32_e32 v231, 4, v231
	v_mov_b32_e32 v233, v231
	global_load_dwordx4 v[146:149], v233, s[16:17]
	v_add_u32_e32 v233, 0x1600, v233
	global_load_dwordx4 v[150:153], v233, s[16:17]
	v_add_u32_e32 v233, 0x1600, v233
	global_load_dwordx4 v[154:157], v233, s[16:17]
	v_add_u32_e32 v233, 0x1600, v233
	global_load_dwordx4 v[158:161], v233, s[16:17]
	v_add_u32_e32 v233, 0x1600, v233
	global_load_dwordx4 v[162:165], v233, s[16:17]
	v_add_u32_e32 v233, 0x1600, v233
	global_load_dwordx4 v[166:169], v233, s[16:17]
	v_add_u32_e32 v233, 0x1600, v233
	global_load_dwordx4 v[170:173], v233, s[16:17]
	v_add_u32_e32 v233, 0x1600, v233
	global_load_dwordx4 v[174:177], v233, s[16:17]
	v_add_u32_e32 v233, 0x1600, v233
	global_load_dwordx4 v[178:181], v233, s[16:17]
	v_lshlrev_b32_e32 v234, 1, v231
	global_load_dwordx4 v[72:75], v234, s[18:19]
	global_load_dwordx4 v[76:79], v234, s[18:19] offset:16
	v_and_b32_e32 v233, 1, v232
	v_cmp_eq_u32_e64 s[4:5], 0, v233
	v_cmp_eq_u32_e64 s[6:7], 1, v233
	v_bfe_u32 v234, v232, 1, 6
	v_cmp_eq_u32_e64 s[0:1], 0, v234
	v_cmp_eq_u32_e64 s[2:3], 63, v234
	v_lshrrev_b32_e32 v234, 1, v232
	v_lshlrev_b32_e32 v234, 6, v234
	v_lshl_add_u32 v234, v233, 5, v234
	v_mul_u32_u24_e32 v234, 0x2c00, v234
	v_add_u32_e32 v139, v234, v231
	v_mov_b32_e32 v140, v139
	v_add_u32_e32 v137, 0x1600, v139
	v_subrev_u32_e32 v233, 0x2c00, v137
	v_cndmask_b32_e64 v137, v233, v137, s[4:5]
	v_mov_b32_e32 v233, 0xb0000
	v_sub_u32_e32 v136, v137, v233
	v_cndmask_b32_e64 v136, v136, v137, s[0:1]
	v_add_u32_e32 v138, v137, v233
	v_cndmask_b32_e64 v138, v138, v137, s[2:3]
	s_waitcnt vmcnt(10)
	v_lshlrev_b32_e32 v0, 16, v146
	v_and_b32_e32 v1, 0xffff0000, v146
	v_lshlrev_b32_e32 v2, 16, v147
	v_and_b32_e32 v3, 0xffff0000, v147
	v_lshlrev_b32_e32 v4, 16, v148
	v_and_b32_e32 v5, 0xffff0000, v148
	v_lshlrev_b32_e32 v6, 16, v149
	v_and_b32_e32 v7, 0xffff0000, v149
	s_waitcnt vmcnt(9)
	v_lshlrev_b32_e32 v8, 16, v150
	v_and_b32_e32 v9, 0xffff0000, v150
	v_lshlrev_b32_e32 v10, 16, v151
	v_and_b32_e32 v11, 0xffff0000, v151
	v_lshlrev_b32_e32 v12, 16, v152
	v_and_b32_e32 v13, 0xffff0000, v152
	v_lshlrev_b32_e32 v14, 16, v153
	v_and_b32_e32 v15, 0xffff0000, v153
	s_waitcnt vmcnt(8)
	v_lshlrev_b32_e32 v16, 16, v154
	v_and_b32_e32 v17, 0xffff0000, v154
	v_lshlrev_b32_e32 v18, 16, v155
	v_and_b32_e32 v19, 0xffff0000, v155
	v_lshlrev_b32_e32 v20, 16, v156
	v_and_b32_e32 v21, 0xffff0000, v156
	v_lshlrev_b32_e32 v22, 16, v157
	v_and_b32_e32 v23, 0xffff0000, v157
	s_waitcnt vmcnt(7)
	v_lshlrev_b32_e32 v24, 16, v158
	v_and_b32_e32 v25, 0xffff0000, v158
	v_lshlrev_b32_e32 v26, 16, v159
	v_and_b32_e32 v27, 0xffff0000, v159
	v_lshlrev_b32_e32 v28, 16, v160
	v_and_b32_e32 v29, 0xffff0000, v160
	v_lshlrev_b32_e32 v30, 16, v161
	v_and_b32_e32 v31, 0xffff0000, v161
	s_waitcnt vmcnt(6)
	v_lshlrev_b32_e32 v32, 16, v162
	v_and_b32_e32 v33, 0xffff0000, v162
	v_lshlrev_b32_e32 v34, 16, v163
	v_and_b32_e32 v35, 0xffff0000, v163
	v_lshlrev_b32_e32 v36, 16, v164
	v_and_b32_e32 v37, 0xffff0000, v164
	v_lshlrev_b32_e32 v38, 16, v165
	v_and_b32_e32 v39, 0xffff0000, v165
	s_waitcnt vmcnt(5)
	v_lshlrev_b32_e32 v40, 16, v166
	v_and_b32_e32 v41, 0xffff0000, v166
	v_lshlrev_b32_e32 v42, 16, v167
	v_and_b32_e32 v43, 0xffff0000, v167
	v_lshlrev_b32_e32 v44, 16, v168
	v_and_b32_e32 v45, 0xffff0000, v168
	v_lshlrev_b32_e32 v46, 16, v169
	v_and_b32_e32 v47, 0xffff0000, v169
	s_waitcnt vmcnt(4)
	v_lshlrev_b32_e32 v48, 16, v170
	v_and_b32_e32 v49, 0xffff0000, v170
	v_lshlrev_b32_e32 v50, 16, v171
	v_and_b32_e32 v51, 0xffff0000, v171
	v_lshlrev_b32_e32 v52, 16, v172
	v_and_b32_e32 v53, 0xffff0000, v172
	v_lshlrev_b32_e32 v54, 16, v173
	v_and_b32_e32 v55, 0xffff0000, v173
	s_waitcnt vmcnt(3)
	v_lshlrev_b32_e32 v56, 16, v174
	v_and_b32_e32 v57, 0xffff0000, v174
	v_lshlrev_b32_e32 v58, 16, v175
	v_and_b32_e32 v59, 0xffff0000, v175
	v_lshlrev_b32_e32 v60, 16, v176
	v_and_b32_e32 v61, 0xffff0000, v176
	v_lshlrev_b32_e32 v62, 16, v177
	v_and_b32_e32 v63, 0xffff0000, v177
	s_waitcnt vmcnt(2)
	v_lshlrev_b32_e32 v64, 16, v178
	v_and_b32_e32 v65, 0xffff0000, v178
	v_lshlrev_b32_e32 v66, 16, v179
	v_and_b32_e32 v67, 0xffff0000, v179
	v_lshlrev_b32_e32 v68, 16, v180
	v_and_b32_e32 v69, 0xffff0000, v180
	v_lshlrev_b32_e32 v70, 16, v181
	v_and_b32_e32 v71, 0xffff0000, v181
	v_cndmask_b32_e64 v0, v0, 0, s[0:1]
	v_cndmask_b32_e64 v1, v1, 0, s[0:1]
	v_cndmask_b32_e64 v2, v2, 0, s[0:1]
	v_cndmask_b32_e64 v3, v3, 0, s[0:1]
	v_cndmask_b32_e64 v4, v4, 0, s[0:1]
	v_cndmask_b32_e64 v5, v5, 0, s[0:1]
	v_cndmask_b32_e64 v6, v6, 0, s[0:1]
	v_cndmask_b32_e64 v7, v7, 0, s[0:1]
	v_cndmask_b32_e64 v8, v8, 0, s[0:1]
	v_cndmask_b32_e64 v9, v9, 0, s[0:1]
	v_cndmask_b32_e64 v10, v10, 0, s[0:1]
	v_cndmask_b32_e64 v11, v11, 0, s[0:1]
	v_cndmask_b32_e64 v12, v12, 0, s[0:1]
	v_cndmask_b32_e64 v13, v13, 0, s[0:1]
	v_cndmask_b32_e64 v14, v14, 0, s[0:1]
	v_cndmask_b32_e64 v15, v15, 0, s[0:1]
	v_cndmask_b32_e64 v16, v16, 0, s[0:1]
	v_cndmask_b32_e64 v17, v17, 0, s[0:1]
	v_cndmask_b32_e64 v18, v18, 0, s[0:1]
	v_cndmask_b32_e64 v19, v19, 0, s[0:1]
	v_cndmask_b32_e64 v20, v20, 0, s[0:1]
	v_cndmask_b32_e64 v21, v21, 0, s[0:1]
	v_cndmask_b32_e64 v22, v22, 0, s[0:1]
	v_cndmask_b32_e64 v23, v23, 0, s[0:1]
	v_cndmask_b32_e64 v48, v48, 0, s[2:3]
	v_cndmask_b32_e64 v49, v49, 0, s[2:3]
	v_cndmask_b32_e64 v50, v50, 0, s[2:3]
	v_cndmask_b32_e64 v51, v51, 0, s[2:3]
	v_cndmask_b32_e64 v52, v52, 0, s[2:3]
	v_cndmask_b32_e64 v53, v53, 0, s[2:3]
	v_cndmask_b32_e64 v54, v54, 0, s[2:3]
	v_cndmask_b32_e64 v55, v55, 0, s[2:3]
	v_cndmask_b32_e64 v56, v56, 0, s[2:3]
	v_cndmask_b32_e64 v57, v57, 0, s[2:3]
	v_cndmask_b32_e64 v58, v58, 0, s[2:3]
	v_cndmask_b32_e64 v59, v59, 0, s[2:3]
	v_cndmask_b32_e64 v60, v60, 0, s[2:3]
	v_cndmask_b32_e64 v61, v61, 0, s[2:3]
	v_cndmask_b32_e64 v62, v62, 0, s[2:3]
	v_cndmask_b32_e64 v63, v63, 0, s[2:3]
	v_cndmask_b32_e64 v64, v64, 0, s[2:3]
	v_cndmask_b32_e64 v65, v65, 0, s[2:3]
	v_cndmask_b32_e64 v66, v66, 0, s[2:3]
	v_cndmask_b32_e64 v67, v67, 0, s[2:3]
	v_cndmask_b32_e64 v68, v68, 0, s[2:3]
	v_cndmask_b32_e64 v69, v69, 0, s[2:3]
	v_cndmask_b32_e64 v70, v70, 0, s[2:3]
	v_cndmask_b32_e64 v71, v71, 0, s[2:3]
	s_waitcnt vmcnt(0)
	global_load_dwordx4 v[146:149], v136, s[14:15]
	global_load_dwordx4 v[150:153], v137, s[14:15]
	global_load_dwordx4 v[154:157], v138, s[14:15]
	v_add_u32_e32 v136, 0x2c00, v136
	v_add_u32_e32 v137, 0x2c00, v137
	v_add_u32_e32 v138, 0x2c00, v138
	v_subrev_u32_e32 v233, 0x2c00, v136
	v_cndmask_b32_e64 v136, v136, v233, s[4:5]
	v_subrev_u32_e32 v233, 0x2c00, v137
	v_cndmask_b32_e64 v137, v137, v233, s[4:5]
	v_subrev_u32_e32 v233, 0x2c00, v138
	v_cndmask_b32_e64 v138, v138, v233, s[4:5]
	global_load_dwordx4 v[158:161], v136, s[14:15]
	global_load_dwordx4 v[162:165], v137, s[14:15]
	global_load_dwordx4 v[166:169], v138, s[14:15]
	v_add_u32_e32 v136, 0x2c00, v136
	v_add_u32_e32 v137, 0x2c00, v137
	v_add_u32_e32 v138, 0x2c00, v138
	global_load_dwordx4 v[170:173], v136, s[14:15]
	global_load_dwordx4 v[174:177], v137, s[14:15]
	global_load_dwordx4 v[178:181], v138, s[14:15]
	v_add_u32_e32 v136, 0x2c00, v136
	v_add_u32_e32 v137, 0x2c00, v137
	v_add_u32_e32 v138, 0x2c00, v138
	global_load_dwordx4 v[182:185], v136, s[14:15]
	global_load_dwordx4 v[186:189], v137, s[14:15]
	global_load_dwordx4 v[190:193], v138, s[14:15]
	v_add_u32_e32 v136, 0x2c00, v136
	v_add_u32_e32 v137, 0x2c00, v137
	v_add_u32_e32 v138, 0x2c00, v138
	global_load_dwordx4 v[194:197], v136, s[14:15]
	global_load_dwordx4 v[198:201], v137, s[14:15]
	global_load_dwordx4 v[202:205], v138, s[14:15]
	v_add_u32_e32 v136, 0x2c00, v136
	v_add_u32_e32 v137, 0x2c00, v137
	v_add_u32_e32 v138, 0x2c00, v138
	global_load_dwordx4 v[80:83], v139, s[14:15]
	v_add_u32_e32 v139, 0x2c00, v139
	global_load_dwordx4 v[84:87], v139, s[14:15]
	v_add_u32_e32 v139, 0x2c00, v139
	global_load_dwordx4 v[88:91], v139, s[14:15]
	v_add_u32_e32 v139, 0x2c00, v139
	global_load_dwordx4 v[92:95], v139, s[14:15]
	v_add_u32_e32 v139, 0x2c00, v139
	s_waitcnt vmcnt(16)
	v_cndmask_b32_e64 v146, v146, 0, s[4:5]
	v_cndmask_b32_e64 v147, v147, 0, s[4:5]
	v_cndmask_b32_e64 v148, v148, 0, s[4:5]
	v_cndmask_b32_e64 v149, v149, 0, s[4:5]
	v_cndmask_b32_e64 v150, v150, 0, s[4:5]
	v_cndmask_b32_e64 v151, v151, 0, s[4:5]
	v_cndmask_b32_e64 v152, v152, 0, s[4:5]
	v_cndmask_b32_e64 v153, v153, 0, s[4:5]
	v_cndmask_b32_e64 v154, v154, 0, s[4:5]
	v_cndmask_b32_e64 v155, v155, 0, s[4:5]
	v_cndmask_b32_e64 v156, v156, 0, s[4:5]
	v_cndmask_b32_e64 v157, v157, 0, s[4:5]
	global_load_dwordx4 v[206:209], v136, s[14:15]
	global_load_dwordx4 v[210:213], v137, s[14:15]
	global_load_dwordx4 v[214:217], v138, s[14:15]
	v_add_u32_e32 v136, 0x2c00, v136
	v_add_u32_e32 v137, 0x2c00, v137
	v_add_u32_e32 v138, 0x2c00, v138
	global_load_dwordx4 v[96:99], v139, s[14:15]
	v_add_u32_e32 v139, 0x2c00, v139
	s_waitcnt vmcnt(14)
	s_waitcnt vmcnt(7)
	v_mov_b64_e32 v[104:105], v[72:73]
	v_mov_b64_e32 v[106:107], v[74:75]
	v_mov_b64_e32 v[108:109], v[76:77]
	v_mov_b64_e32 v[110:111], v[78:79]
	v_lshlrev_b32_e32 v112, 16, v146
	v_and_b32_e32 v113, 0xffff0000, v146
	v_pk_fma_f32 v[104:105], v[112:113], v[0:1], v[104:105]
	v_lshlrev_b32_e32 v114, 16, v147
	v_and_b32_e32 v115, 0xffff0000, v147
	v_pk_fma_f32 v[106:107], v[114:115], v[2:3], v[106:107]
	v_lshlrev_b32_e32 v112, 16, v148
	v_and_b32_e32 v113, 0xffff0000, v148
	v_pk_fma_f32 v[108:109], v[112:113], v[4:5], v[108:109]
	v_lshlrev_b32_e32 v114, 16, v149
	v_and_b32_e32 v115, 0xffff0000, v149
	v_pk_fma_f32 v[110:111], v[114:115], v[6:7], v[110:111]
	v_lshlrev_b32_e32 v112, 16, v158
	v_and_b32_e32 v113, 0xffff0000, v158
	v_pk_fma_f32 v[104:105], v[112:113], v[8:9], v[104:105]
	v_lshlrev_b32_e32 v114, 16, v159
	v_and_b32_e32 v115, 0xffff0000, v159
	v_pk_fma_f32 v[106:107], v[114:115], v[10:11], v[106:107]
	v_lshlrev_b32_e32 v112, 16, v160
	v_and_b32_e32 v113, 0xffff0000, v160
	v_pk_fma_f32 v[108:109], v[112:113], v[12:13], v[108:109]
	v_lshlrev_b32_e32 v114, 16, v161
	v_and_b32_e32 v115, 0xffff0000, v161
	v_pk_fma_f32 v[110:111], v[114:115], v[14:15], v[110:111]
	v_lshlrev_b32_e32 v112, 16, v170
	v_and_b32_e32 v113, 0xffff0000, v170
	v_pk_fma_f32 v[104:105], v[112:113], v[16:17], v[104:105]
	v_lshlrev_b32_e32 v114, 16, v171
	v_and_b32_e32 v115, 0xffff0000, v171
	v_pk_fma_f32 v[106:107], v[114:115], v[18:19], v[106:107]
	v_lshlrev_b32_e32 v112, 16, v172
	v_and_b32_e32 v113, 0xffff0000, v172
	v_pk_fma_f32 v[108:109], v[112:113], v[20:21], v[108:109]
	v_lshlrev_b32_e32 v114, 16, v173
	v_and_b32_e32 v115, 0xffff0000, v173
	v_pk_fma_f32 v[110:111], v[114:115], v[22:23], v[110:111]
	v_lshlrev_b32_e32 v112, 16, v150
	v_and_b32_e32 v113, 0xffff0000, v150
	v_pk_fma_f32 v[104:105], v[112:113], v[24:25], v[104:105]
	v_lshlrev_b32_e32 v114, 16, v151
	v_and_b32_e32 v115, 0xffff0000, v151
	v_pk_fma_f32 v[106:107], v[114:115], v[26:27], v[106:107]
	v_lshlrev_b32_e32 v112, 16, v152
	v_and_b32_e32 v113, 0xffff0000, v152
	v_pk_fma_f32 v[108:109], v[112:113], v[28:29], v[108:109]
	v_lshlrev_b32_e32 v114, 16, v153
	v_and_b32_e32 v115, 0xffff0000, v153
	v_pk_fma_f32 v[110:111], v[114:115], v[30:31], v[110:111]
	v_lshlrev_b32_e32 v112, 16, v162
	v_and_b32_e32 v113, 0xffff0000, v162
	v_pk_fma_f32 v[104:105], v[112:113], v[32:33], v[104:105]
	v_lshlrev_b32_e32 v114, 16, v163
	v_and_b32_e32 v115, 0xffff0000, v163
	v_pk_fma_f32 v[106:107], v[114:115], v[34:35], v[106:107]
	v_lshlrev_b32_e32 v112, 16, v164
	v_and_b32_e32 v113, 0xffff0000, v164
	v_pk_fma_f32 v[108:109], v[112:113], v[36:37], v[108:109]
	v_lshlrev_b32_e32 v114, 16, v165
	v_and_b32_e32 v115, 0xffff0000, v165
	v_pk_fma_f32 v[110:111], v[114:115], v[38:39], v[110:111]
	v_lshlrev_b32_e32 v112, 16, v174
	v_and_b32_e32 v113, 0xffff0000, v174
	v_pk_fma_f32 v[104:105], v[112:113], v[40:41], v[104:105]
	v_lshlrev_b32_e32 v114, 16, v175
	v_and_b32_e32 v115, 0xffff0000, v175
	v_pk_fma_f32 v[106:107], v[114:115], v[42:43], v[106:107]
	v_lshlrev_b32_e32 v112, 16, v176
	v_and_b32_e32 v113, 0xffff0000, v176
	v_pk_fma_f32 v[108:109], v[112:113], v[44:45], v[108:109]
	v_lshlrev_b32_e32 v114, 16, v177
	v_and_b32_e32 v115, 0xffff0000, v177
	v_pk_fma_f32 v[110:111], v[114:115], v[46:47], v[110:111]
	v_lshlrev_b32_e32 v112, 16, v154
	v_and_b32_e32 v113, 0xffff0000, v154
	v_pk_fma_f32 v[104:105], v[112:113], v[48:49], v[104:105]
	v_lshlrev_b32_e32 v114, 16, v155
	v_and_b32_e32 v115, 0xffff0000, v155
	v_pk_fma_f32 v[106:107], v[114:115], v[50:51], v[106:107]
	v_lshlrev_b32_e32 v112, 16, v156
	v_and_b32_e32 v113, 0xffff0000, v156
	v_pk_fma_f32 v[108:109], v[112:113], v[52:53], v[108:109]
	v_lshlrev_b32_e32 v114, 16, v157
	v_and_b32_e32 v115, 0xffff0000, v157
	v_pk_fma_f32 v[110:111], v[114:115], v[54:55], v[110:111]
	v_lshlrev_b32_e32 v112, 16, v166
	v_and_b32_e32 v113, 0xffff0000, v166
	v_pk_fma_f32 v[104:105], v[112:113], v[56:57], v[104:105]
	v_lshlrev_b32_e32 v114, 16, v167
	v_and_b32_e32 v115, 0xffff0000, v167
	v_pk_fma_f32 v[106:107], v[114:115], v[58:59], v[106:107]
	v_lshlrev_b32_e32 v112, 16, v168
	v_and_b32_e32 v113, 0xffff0000, v168
	v_pk_fma_f32 v[108:109], v[112:113], v[60:61], v[108:109]
	v_lshlrev_b32_e32 v114, 16, v169
	v_and_b32_e32 v115, 0xffff0000, v169
	v_pk_fma_f32 v[110:111], v[114:115], v[62:63], v[110:111]
	v_lshlrev_b32_e32 v112, 16, v178
	v_and_b32_e32 v113, 0xffff0000, v178
	v_pk_fma_f32 v[104:105], v[112:113], v[64:65], v[104:105]
	v_lshlrev_b32_e32 v114, 16, v179
	v_and_b32_e32 v115, 0xffff0000, v179
	v_pk_fma_f32 v[106:107], v[114:115], v[66:67], v[106:107]
	v_lshlrev_b32_e32 v112, 16, v180
	v_and_b32_e32 v113, 0xffff0000, v180
	v_pk_fma_f32 v[108:109], v[112:113], v[68:69], v[108:109]
	v_lshlrev_b32_e32 v114, 16, v181
	v_and_b32_e32 v115, 0xffff0000, v181
	v_pk_fma_f32 v[110:111], v[114:115], v[70:71], v[110:111]
	v_mov_b64_e32 v[132:133], s[28:29]
	v_and_b32_e32 v116, 0x7fffffff, v104
	v_and_b32_e32 v117, 0x7fffffff, v105
	v_pk_fma_f32 v[116:117], v[116:117], s[24:25], 1.0 op_sel_hi:[1,0,0]
	v_pk_mul_f32 v[218:219], v[104:105], v[104:105]
	v_rcp_f32_e32 v116, v116
	v_rcp_f32_e32 v117, v117
	v_pk_mul_f32 v[218:219], v[218:219], s[38:39] op_sel_hi:[1,0]
	v_and_b32_e32 v118, 0x7fffffff, v106
	v_and_b32_e32 v119, 0x7fffffff, v107
	v_pk_fma_f32 v[118:119], v[118:119], s[24:25], 1.0 op_sel_hi:[1,0,0]
	v_pk_mul_f32 v[220:221], v[106:107], v[106:107]
	v_rcp_f32_e32 v118, v118
	v_rcp_f32_e32 v119, v119
	v_pk_mul_f32 v[220:221], v[220:221], s[38:39] op_sel_hi:[1,0]
	v_and_b32_e32 v120, 0x7fffffff, v108
	v_and_b32_e32 v121, 0x7fffffff, v109
	v_pk_fma_f32 v[120:121], v[120:121], s[24:25], 1.0 op_sel_hi:[1,0,0]
	v_pk_mul_f32 v[222:223], v[108:109], v[108:109]
	v_rcp_f32_e32 v120, v120
	v_rcp_f32_e32 v121, v121
	v_pk_mul_f32 v[222:223], v[222:223], s[38:39] op_sel_hi:[1,0]
	v_and_b32_e32 v122, 0x7fffffff, v110
	v_and_b32_e32 v123, 0x7fffffff, v111
	v_pk_fma_f32 v[122:123], v[122:123], s[24:25], 1.0 op_sel_hi:[1,0,0]
	v_pk_mul_f32 v[224:225], v[110:111], v[110:111]
	v_rcp_f32_e32 v122, v122
	v_rcp_f32_e32 v123, v123
	v_pk_mul_f32 v[224:225], v[224:225], s[38:39] op_sel_hi:[1,0]
	v_pk_fma_f32 v[124:125], v[116:117], s[26:27], v[132:133] op_sel_hi:[1,0,0]
	v_exp_f32_e32 v218, v218
	v_pk_fma_f32 v[124:125], v[116:117], v[124:125], s[30:31] op_sel_hi:[1,1,0]
	v_exp_f32_e32 v219, v219
	v_pk_fma_f32 v[124:125], v[116:117], v[124:125], s[34:35] op_sel_hi:[1,1,0]
	v_pk_fma_f32 v[124:125], v[116:117], v[124:125], s[36:37] op_sel_hi:[1,1,0]
	v_pk_mul_f32 v[124:125], v[116:117], v[124:125]
	v_pk_fma_f32 v[126:127], v[118:119], s[26:27], v[132:133] op_sel_hi:[1,0,0]
	v_exp_f32_e32 v220, v220
	v_pk_fma_f32 v[126:127], v[118:119], v[126:127], s[30:31] op_sel_hi:[1,1,0]
	v_exp_f32_e32 v221, v221
	v_pk_fma_f32 v[126:127], v[118:119], v[126:127], s[34:35] op_sel_hi:[1,1,0]
	v_pk_fma_f32 v[126:127], v[118:119], v[126:127], s[36:37] op_sel_hi:[1,1,0]
	v_pk_mul_f32 v[126:127], v[118:119], v[126:127]
	v_pk_fma_f32 v[128:129], v[120:121], s[26:27], v[132:133] op_sel_hi:[1,0,0]
	v_exp_f32_e32 v222, v222
	v_pk_fma_f32 v[128:129], v[120:121], v[128:129], s[30:31] op_sel_hi:[1,1,0]
	v_exp_f32_e32 v223, v223
	v_pk_fma_f32 v[128:129], v[120:121], v[128:129], s[34:35] op_sel_hi:[1,1,0]
	v_pk_fma_f32 v[128:129], v[120:121], v[128:129], s[36:37] op_sel_hi:[1,1,0]
	v_pk_mul_f32 v[128:129], v[120:121], v[128:129]
	v_pk_fma_f32 v[130:131], v[122:123], s[26:27], v[132:133] op_sel_hi:[1,0,0]
	v_exp_f32_e32 v224, v224
	v_pk_fma_f32 v[130:131], v[122:123], v[130:131], s[30:31] op_sel_hi:[1,1,0]
	v_exp_f32_e32 v225, v225
	v_pk_fma_f32 v[130:131], v[122:123], v[130:131], s[34:35] op_sel_hi:[1,1,0]
	v_pk_fma_f32 v[130:131], v[122:123], v[130:131], s[36:37] op_sel_hi:[1,1,0]
	v_pk_mul_f32 v[130:131], v[122:123], v[130:131]
	v_pk_mul_f32 v[124:125], v[218:219], v[124:125]
	v_pk_mul_f32 v[218:219], v[104:105], v[124:125]
	v_pk_fma_f32 v[124:125], v[104:105], v[124:125], v[104:105] neg_lo:[1,0,0] neg_hi:[1,0,0]
	v_cmp_gt_f32_e64 s[8:9], 0, v104
	v_cmp_gt_f32_e64 s[22:23], 0, v105
	v_lshlrev_b32_e32 v112, 16, v80
	v_and_b32_e32 v113, 0xffff0000, v80
	v_cndmask_b32_e64 v104, v124, v218, s[8:9]
	v_cndmask_b32_e64 v105, v125, v219, s[22:23]
	v_pk_mul_f32 v[104:105], v[104:105], v[112:113]
	v_cvt_pk_bf16_f32 v226, v104, v105
	v_pk_mul_f32 v[126:127], v[220:221], v[126:127]
	v_pk_mul_f32 v[220:221], v[106:107], v[126:127]
	v_pk_fma_f32 v[126:127], v[106:107], v[126:127], v[106:107] neg_lo:[1,0,0] neg_hi:[1,0,0]
	v_cmp_gt_f32_e64 s[8:9], 0, v106
	v_cmp_gt_f32_e64 s[22:23], 0, v107
	v_lshlrev_b32_e32 v112, 16, v81
	v_and_b32_e32 v113, 0xffff0000, v81
	v_cndmask_b32_e64 v106, v126, v220, s[8:9]
	v_cndmask_b32_e64 v107, v127, v221, s[22:23]
	v_pk_mul_f32 v[106:107], v[106:107], v[112:113]
	v_cvt_pk_bf16_f32 v227, v106, v107
	v_pk_mul_f32 v[128:129], v[222:223], v[128:129]
	v_pk_mul_f32 v[222:223], v[108:109], v[128:129]
	v_pk_fma_f32 v[128:129], v[108:109], v[128:129], v[108:109] neg_lo:[1,0,0] neg_hi:[1,0,0]
	v_cmp_gt_f32_e64 s[8:9], 0, v108
	v_cmp_gt_f32_e64 s[22:23], 0, v109
	v_lshlrev_b32_e32 v112, 16, v82
	v_and_b32_e32 v113, 0xffff0000, v82
	v_cndmask_b32_e64 v108, v128, v222, s[8:9]
	v_cndmask_b32_e64 v109, v129, v223, s[22:23]
	v_pk_mul_f32 v[108:109], v[108:109], v[112:113]
	v_cvt_pk_bf16_f32 v228, v108, v109
	v_pk_mul_f32 v[130:131], v[224:225], v[130:131]
	v_pk_mul_f32 v[224:225], v[110:111], v[130:131]
	v_pk_fma_f32 v[130:131], v[110:111], v[130:131], v[110:111] neg_lo:[1,0,0] neg_hi:[1,0,0]
	v_cmp_gt_f32_e64 s[8:9], 0, v110
	v_cmp_gt_f32_e64 s[22:23], 0, v111
	v_lshlrev_b32_e32 v112, 16, v83
	v_and_b32_e32 v113, 0xffff0000, v83
	v_cndmask_b32_e64 v110, v130, v224, s[8:9]
	v_cndmask_b32_e64 v111, v131, v225, s[22:23]
	v_pk_mul_f32 v[110:111], v[110:111], v[112:113]
	v_cvt_pk_bf16_f32 v229, v110, v111
	global_store_dwordx4 v140, v[226:229], s[14:15] sc1
	v_add_u32_e32 v140, 0x2c00, v140
	global_load_dwordx4 v[146:149], v136, s[14:15]
	global_load_dwordx4 v[150:153], v137, s[14:15]
	global_load_dwordx4 v[154:157], v138, s[14:15]
	v_add_u32_e32 v136, 0x2c00, v136
	v_add_u32_e32 v137, 0x2c00, v137
	v_add_u32_e32 v138, 0x2c00, v138
	global_load_dwordx4 v[100:103], v139, s[14:15]
	v_add_u32_e32 v139, 0x2c00, v139
	s_waitcnt vmcnt(11)
	v_mov_b64_e32 v[104:105], v[72:73]
	v_mov_b64_e32 v[106:107], v[74:75]
	v_mov_b64_e32 v[108:109], v[76:77]
	v_mov_b64_e32 v[110:111], v[78:79]
	v_lshlrev_b32_e32 v112, 16, v158
	v_and_b32_e32 v113, 0xffff0000, v158
	v_pk_fma_f32 v[104:105], v[112:113], v[0:1], v[104:105]
	v_lshlrev_b32_e32 v114, 16, v159
	v_and_b32_e32 v115, 0xffff0000, v159
	v_pk_fma_f32 v[106:107], v[114:115], v[2:3], v[106:107]
	v_lshlrev_b32_e32 v112, 16, v160
	v_and_b32_e32 v113, 0xffff0000, v160
	v_pk_fma_f32 v[108:109], v[112:113], v[4:5], v[108:109]
	v_lshlrev_b32_e32 v114, 16, v161
	v_and_b32_e32 v115, 0xffff0000, v161
	v_pk_fma_f32 v[110:111], v[114:115], v[6:7], v[110:111]
	v_lshlrev_b32_e32 v112, 16, v170
	v_and_b32_e32 v113, 0xffff0000, v170
	v_pk_fma_f32 v[104:105], v[112:113], v[8:9], v[104:105]
	v_lshlrev_b32_e32 v114, 16, v171
	v_and_b32_e32 v115, 0xffff0000, v171
	v_pk_fma_f32 v[106:107], v[114:115], v[10:11], v[106:107]
	v_lshlrev_b32_e32 v112, 16, v172
	v_and_b32_e32 v113, 0xffff0000, v172
	v_pk_fma_f32 v[108:109], v[112:113], v[12:13], v[108:109]
	v_lshlrev_b32_e32 v114, 16, v173
	v_and_b32_e32 v115, 0xffff0000, v173
	v_pk_fma_f32 v[110:111], v[114:115], v[14:15], v[110:111]
	v_lshlrev_b32_e32 v112, 16, v182
	v_and_b32_e32 v113, 0xffff0000, v182
	v_pk_fma_f32 v[104:105], v[112:113], v[16:17], v[104:105]
	v_lshlrev_b32_e32 v114, 16, v183
	v_and_b32_e32 v115, 0xffff0000, v183
	v_pk_fma_f32 v[106:107], v[114:115], v[18:19], v[106:107]
	v_lshlrev_b32_e32 v112, 16, v184
	v_and_b32_e32 v113, 0xffff0000, v184
	v_pk_fma_f32 v[108:109], v[112:113], v[20:21], v[108:109]
	v_lshlrev_b32_e32 v114, 16, v185
	v_and_b32_e32 v115, 0xffff0000, v185
	v_pk_fma_f32 v[110:111], v[114:115], v[22:23], v[110:111]
	v_lshlrev_b32_e32 v112, 16, v162
	v_and_b32_e32 v113, 0xffff0000, v162
	v_pk_fma_f32 v[104:105], v[112:113], v[24:25], v[104:105]
	v_lshlrev_b32_e32 v114, 16, v163
	v_and_b32_e32 v115, 0xffff0000, v163
	v_pk_fma_f32 v[106:107], v[114:115], v[26:27], v[106:107]
	v_lshlrev_b32_e32 v112, 16, v164
	v_and_b32_e32 v113, 0xffff0000, v164
	v_pk_fma_f32 v[108:109], v[112:113], v[28:29], v[108:109]
	v_lshlrev_b32_e32 v114, 16, v165
	v_and_b32_e32 v115, 0xffff0000, v165
	v_pk_fma_f32 v[110:111], v[114:115], v[30:31], v[110:111]
	v_lshlrev_b32_e32 v112, 16, v174
	v_and_b32_e32 v113, 0xffff0000, v174
	v_pk_fma_f32 v[104:105], v[112:113], v[32:33], v[104:105]
	v_lshlrev_b32_e32 v114, 16, v175
	v_and_b32_e32 v115, 0xffff0000, v175
	v_pk_fma_f32 v[106:107], v[114:115], v[34:35], v[106:107]
	v_lshlrev_b32_e32 v112, 16, v176
	v_and_b32_e32 v113, 0xffff0000, v176
	v_pk_fma_f32 v[108:109], v[112:113], v[36:37], v[108:109]
	v_lshlrev_b32_e32 v114, 16, v177
	v_and_b32_e32 v115, 0xffff0000, v177
	v_pk_fma_f32 v[110:111], v[114:115], v[38:39], v[110:111]
	v_lshlrev_b32_e32 v112, 16, v186
	v_and_b32_e32 v113, 0xffff0000, v186
	v_pk_fma_f32 v[104:105], v[112:113], v[40:41], v[104:105]
	v_lshlrev_b32_e32 v114, 16, v187
	v_and_b32_e32 v115, 0xffff0000, v187
	v_pk_fma_f32 v[106:107], v[114:115], v[42:43], v[106:107]
	v_lshlrev_b32_e32 v112, 16, v188
	v_and_b32_e32 v113, 0xffff0000, v188
	v_pk_fma_f32 v[108:109], v[112:113], v[44:45], v[108:109]
	v_lshlrev_b32_e32 v114, 16, v189
	v_and_b32_e32 v115, 0xffff0000, v189
	v_pk_fma_f32 v[110:111], v[114:115], v[46:47], v[110:111]
	v_lshlrev_b32_e32 v112, 16, v166
	v_and_b32_e32 v113, 0xffff0000, v166
	v_pk_fma_f32 v[104:105], v[112:113], v[48:49], v[104:105]
	v_lshlrev_b32_e32 v114, 16, v167
	v_and_b32_e32 v115, 0xffff0000, v167
	v_pk_fma_f32 v[106:107], v[114:115], v[50:51], v[106:107]
	v_lshlrev_b32_e32 v112, 16, v168
	v_and_b32_e32 v113, 0xffff0000, v168
	v_pk_fma_f32 v[108:109], v[112:113], v[52:53], v[108:109]
	v_lshlrev_b32_e32 v114, 16, v169
	v_and_b32_e32 v115, 0xffff0000, v169
	v_pk_fma_f32 v[110:111], v[114:115], v[54:55], v[110:111]
	v_lshlrev_b32_e32 v112, 16, v178
	v_and_b32_e32 v113, 0xffff0000, v178
	v_pk_fma_f32 v[104:105], v[112:113], v[56:57], v[104:105]
	v_lshlrev_b32_e32 v114, 16, v179
	v_and_b32_e32 v115, 0xffff0000, v179
	v_pk_fma_f32 v[106:107], v[114:115], v[58:59], v[106:107]
	v_lshlrev_b32_e32 v112, 16, v180
	v_and_b32_e32 v113, 0xffff0000, v180
	v_pk_fma_f32 v[108:109], v[112:113], v[60:61], v[108:109]
	v_lshlrev_b32_e32 v114, 16, v181
	v_and_b32_e32 v115, 0xffff0000, v181
	v_pk_fma_f32 v[110:111], v[114:115], v[62:63], v[110:111]
	v_lshlrev_b32_e32 v112, 16, v190
	v_and_b32_e32 v113, 0xffff0000, v190
	v_pk_fma_f32 v[104:105], v[112:113], v[64:65], v[104:105]
	v_lshlrev_b32_e32 v114, 16, v191
	v_and_b32_e32 v115, 0xffff0000, v191
	v_pk_fma_f32 v[106:107], v[114:115], v[66:67], v[106:107]
	v_lshlrev_b32_e32 v112, 16, v192
	v_and_b32_e32 v113, 0xffff0000, v192
	v_pk_fma_f32 v[108:109], v[112:113], v[68:69], v[108:109]
	v_lshlrev_b32_e32 v114, 16, v193
	v_and_b32_e32 v115, 0xffff0000, v193
	v_pk_fma_f32 v[110:111], v[114:115], v[70:71], v[110:111]
	v_mov_b64_e32 v[132:133], s[28:29]
	v_and_b32_e32 v116, 0x7fffffff, v104
	v_and_b32_e32 v117, 0x7fffffff, v105
	v_pk_fma_f32 v[116:117], v[116:117], s[24:25], 1.0 op_sel_hi:[1,0,0]
	v_pk_mul_f32 v[218:219], v[104:105], v[104:105]
	v_rcp_f32_e32 v116, v116
	v_rcp_f32_e32 v117, v117
	v_pk_mul_f32 v[218:219], v[218:219], s[38:39] op_sel_hi:[1,0]
	v_and_b32_e32 v118, 0x7fffffff, v106
	v_and_b32_e32 v119, 0x7fffffff, v107
	v_pk_fma_f32 v[118:119], v[118:119], s[24:25], 1.0 op_sel_hi:[1,0,0]
	v_pk_mul_f32 v[220:221], v[106:107], v[106:107]
	v_rcp_f32_e32 v118, v118
	v_rcp_f32_e32 v119, v119
	v_pk_mul_f32 v[220:221], v[220:221], s[38:39] op_sel_hi:[1,0]
	v_and_b32_e32 v120, 0x7fffffff, v108
	v_and_b32_e32 v121, 0x7fffffff, v109
	v_pk_fma_f32 v[120:121], v[120:121], s[24:25], 1.0 op_sel_hi:[1,0,0]
	v_pk_mul_f32 v[222:223], v[108:109], v[108:109]
	v_rcp_f32_e32 v120, v120
	v_rcp_f32_e32 v121, v121
	v_pk_mul_f32 v[222:223], v[222:223], s[38:39] op_sel_hi:[1,0]
	v_and_b32_e32 v122, 0x7fffffff, v110
	v_and_b32_e32 v123, 0x7fffffff, v111
	v_pk_fma_f32 v[122:123], v[122:123], s[24:25], 1.0 op_sel_hi:[1,0,0]
	v_pk_mul_f32 v[224:225], v[110:111], v[110:111]
	v_rcp_f32_e32 v122, v122
	v_rcp_f32_e32 v123, v123
	v_pk_mul_f32 v[224:225], v[224:225], s[38:39] op_sel_hi:[1,0]
	v_pk_fma_f32 v[124:125], v[116:117], s[26:27], v[132:133] op_sel_hi:[1,0,0]
	v_exp_f32_e32 v218, v218
	v_pk_fma_f32 v[124:125], v[116:117], v[124:125], s[30:31] op_sel_hi:[1,1,0]
	v_exp_f32_e32 v219, v219
	v_pk_fma_f32 v[124:125], v[116:117], v[124:125], s[34:35] op_sel_hi:[1,1,0]
	v_pk_fma_f32 v[124:125], v[116:117], v[124:125], s[36:37] op_sel_hi:[1,1,0]
	v_pk_mul_f32 v[124:125], v[116:117], v[124:125]
	v_pk_fma_f32 v[126:127], v[118:119], s[26:27], v[132:133] op_sel_hi:[1,0,0]
	v_exp_f32_e32 v220, v220
	v_pk_fma_f32 v[126:127], v[118:119], v[126:127], s[30:31] op_sel_hi:[1,1,0]
	v_exp_f32_e32 v221, v221
	v_pk_fma_f32 v[126:127], v[118:119], v[126:127], s[34:35] op_sel_hi:[1,1,0]
	v_pk_fma_f32 v[126:127], v[118:119], v[126:127], s[36:37] op_sel_hi:[1,1,0]
	v_pk_mul_f32 v[126:127], v[118:119], v[126:127]
	v_pk_fma_f32 v[128:129], v[120:121], s[26:27], v[132:133] op_sel_hi:[1,0,0]
	v_exp_f32_e32 v222, v222
	v_pk_fma_f32 v[128:129], v[120:121], v[128:129], s[30:31] op_sel_hi:[1,1,0]
	v_exp_f32_e32 v223, v223
	v_pk_fma_f32 v[128:129], v[120:121], v[128:129], s[34:35] op_sel_hi:[1,1,0]
	v_pk_fma_f32 v[128:129], v[120:121], v[128:129], s[36:37] op_sel_hi:[1,1,0]
	v_pk_mul_f32 v[128:129], v[120:121], v[128:129]
	v_pk_fma_f32 v[130:131], v[122:123], s[26:27], v[132:133] op_sel_hi:[1,0,0]
	v_exp_f32_e32 v224, v224
	v_pk_fma_f32 v[130:131], v[122:123], v[130:131], s[30:31] op_sel_hi:[1,1,0]
	v_exp_f32_e32 v225, v225
	v_pk_fma_f32 v[130:131], v[122:123], v[130:131], s[34:35] op_sel_hi:[1,1,0]
	v_pk_fma_f32 v[130:131], v[122:123], v[130:131], s[36:37] op_sel_hi:[1,1,0]
	v_pk_mul_f32 v[130:131], v[122:123], v[130:131]
	v_pk_mul_f32 v[124:125], v[218:219], v[124:125]
	v_pk_mul_f32 v[218:219], v[104:105], v[124:125]
	v_pk_fma_f32 v[124:125], v[104:105], v[124:125], v[104:105] neg_lo:[1,0,0] neg_hi:[1,0,0]
	v_cmp_gt_f32_e64 s[8:9], 0, v104
	v_cmp_gt_f32_e64 s[22:23], 0, v105
	v_lshlrev_b32_e32 v112, 16, v84
	v_and_b32_e32 v113, 0xffff0000, v84
	v_cndmask_b32_e64 v104, v124, v218, s[8:9]
	v_cndmask_b32_e64 v105, v125, v219, s[22:23]
	v_pk_mul_f32 v[104:105], v[104:105], v[112:113]
	v_cvt_pk_bf16_f32 v226, v104, v105
	v_pk_mul_f32 v[126:127], v[220:221], v[126:127]
	v_pk_mul_f32 v[220:221], v[106:107], v[126:127]
	v_pk_fma_f32 v[126:127], v[106:107], v[126:127], v[106:107] neg_lo:[1,0,0] neg_hi:[1,0,0]
	v_cmp_gt_f32_e64 s[8:9], 0, v106
	v_cmp_gt_f32_e64 s[22:23], 0, v107
	v_lshlrev_b32_e32 v112, 16, v85
	v_and_b32_e32 v113, 0xffff0000, v85
	v_cndmask_b32_e64 v106, v126, v220, s[8:9]
	v_cndmask_b32_e64 v107, v127, v221, s[22:23]
	v_pk_mul_f32 v[106:107], v[106:107], v[112:113]
	v_cvt_pk_bf16_f32 v227, v106, v107
	v_pk_mul_f32 v[128:129], v[222:223], v[128:129]
	v_pk_mul_f32 v[222:223], v[108:109], v[128:129]
	v_pk_fma_f32 v[128:129], v[108:109], v[128:129], v[108:109] neg_lo:[1,0,0] neg_hi:[1,0,0]
	v_cmp_gt_f32_e64 s[8:9], 0, v108
	v_cmp_gt_f32_e64 s[22:23], 0, v109
	v_lshlrev_b32_e32 v112, 16, v86
	v_and_b32_e32 v113, 0xffff0000, v86
	v_cndmask_b32_e64 v108, v128, v222, s[8:9]
	v_cndmask_b32_e64 v109, v129, v223, s[22:23]
	v_pk_mul_f32 v[108:109], v[108:109], v[112:113]
	v_cvt_pk_bf16_f32 v228, v108, v109
	v_pk_mul_f32 v[130:131], v[224:225], v[130:131]
	v_pk_mul_f32 v[224:225], v[110:111], v[130:131]
	v_pk_fma_f32 v[130:131], v[110:111], v[130:131], v[110:111] neg_lo:[1,0,0] neg_hi:[1,0,0]
	v_cmp_gt_f32_e64 s[8:9], 0, v110
	v_cmp_gt_f32_e64 s[22:23], 0, v111
	v_lshlrev_b32_e32 v112, 16, v87
	v_and_b32_e32 v113, 0xffff0000, v87
	v_cndmask_b32_e64 v110, v130, v224, s[8:9]
	v_cndmask_b32_e64 v111, v131, v225, s[22:23]
	v_pk_mul_f32 v[110:111], v[110:111], v[112:113]
	v_cvt_pk_bf16_f32 v229, v110, v111
	global_store_dwordx4 v140, v[226:229], s[14:15] sc1
	v_add_u32_e32 v140, 0x2c00, v140
	global_load_dwordx4 v[158:161], v136, s[14:15]
	global_load_dwordx4 v[162:165], v137, s[14:15]
	global_load_dwordx4 v[166:169], v138, s[14:15]
	v_add_u32_e32 v136, 0x2c00, v136
	v_add_u32_e32 v137, 0x2c00, v137
	v_add_u32_e32 v138, 0x2c00, v138
	global_load_dwordx4 v[80:83], v139, s[14:15]
	v_add_u32_e32 v139, 0x2c00, v139
	s_waitcnt vmcnt(15)
	v_mov_b64_e32 v[104:105], v[72:73]
	v_mov_b64_e32 v[106:107], v[74:75]
	v_mov_b64_e32 v[108:109], v[76:77]
	v_mov_b64_e32 v[110:111], v[78:79]
	v_lshlrev_b32_e32 v112, 16, v170
	v_and_b32_e32 v113, 0xffff0000, v170
	v_pk_fma_f32 v[104:105], v[112:113], v[0:1], v[104:105]
	v_lshlrev_b32_e32 v114, 16, v171
	v_and_b32_e32 v115, 0xffff0000, v171
	v_pk_fma_f32 v[106:107], v[114:115], v[2:3], v[106:107]
	v_lshlrev_b32_e32 v112, 16, v172
	v_and_b32_e32 v113, 0xffff0000, v172
	v_pk_fma_f32 v[108:109], v[112:113], v[4:5], v[108:109]
	v_lshlrev_b32_e32 v114, 16, v173
	v_and_b32_e32 v115, 0xffff0000, v173
	v_pk_fma_f32 v[110:111], v[114:115], v[6:7], v[110:111]
	v_lshlrev_b32_e32 v112, 16, v182
	v_and_b32_e32 v113, 0xffff0000, v182
	v_pk_fma_f32 v[104:105], v[112:113], v[8:9], v[104:105]
	v_lshlrev_b32_e32 v114, 16, v183
	v_and_b32_e32 v115, 0xffff0000, v183
	v_pk_fma_f32 v[106:107], v[114:115], v[10:11], v[106:107]
	v_lshlrev_b32_e32 v112, 16, v184
	v_and_b32_e32 v113, 0xffff0000, v184
	v_pk_fma_f32 v[108:109], v[112:113], v[12:13], v[108:109]
	v_lshlrev_b32_e32 v114, 16, v185
	v_and_b32_e32 v115, 0xffff0000, v185
	v_pk_fma_f32 v[110:111], v[114:115], v[14:15], v[110:111]
	v_lshlrev_b32_e32 v112, 16, v194
	v_and_b32_e32 v113, 0xffff0000, v194
	v_pk_fma_f32 v[104:105], v[112:113], v[16:17], v[104:105]
	v_lshlrev_b32_e32 v114, 16, v195
	v_and_b32_e32 v115, 0xffff0000, v195
	v_pk_fma_f32 v[106:107], v[114:115], v[18:19], v[106:107]
	v_lshlrev_b32_e32 v112, 16, v196
	v_and_b32_e32 v113, 0xffff0000, v196
	v_pk_fma_f32 v[108:109], v[112:113], v[20:21], v[108:109]
	v_lshlrev_b32_e32 v114, 16, v197
	v_and_b32_e32 v115, 0xffff0000, v197
	v_pk_fma_f32 v[110:111], v[114:115], v[22:23], v[110:111]
	v_lshlrev_b32_e32 v112, 16, v174
	v_and_b32_e32 v113, 0xffff0000, v174
	v_pk_fma_f32 v[104:105], v[112:113], v[24:25], v[104:105]
	v_lshlrev_b32_e32 v114, 16, v175
	v_and_b32_e32 v115, 0xffff0000, v175
	v_pk_fma_f32 v[106:107], v[114:115], v[26:27], v[106:107]
	v_lshlrev_b32_e32 v112, 16, v176
	v_and_b32_e32 v113, 0xffff0000, v176
	v_pk_fma_f32 v[108:109], v[112:113], v[28:29], v[108:109]
	v_lshlrev_b32_e32 v114, 16, v177
	v_and_b32_e32 v115, 0xffff0000, v177
	v_pk_fma_f32 v[110:111], v[114:115], v[30:31], v[110:111]
	v_lshlrev_b32_e32 v112, 16, v186
	v_and_b32_e32 v113, 0xffff0000, v186
	v_pk_fma_f32 v[104:105], v[112:113], v[32:33], v[104:105]
	v_lshlrev_b32_e32 v114, 16, v187
	v_and_b32_e32 v115, 0xffff0000, v187
	v_pk_fma_f32 v[106:107], v[114:115], v[34:35], v[106:107]
	v_lshlrev_b32_e32 v112, 16, v188
	v_and_b32_e32 v113, 0xffff0000, v188
	v_pk_fma_f32 v[108:109], v[112:113], v[36:37], v[108:109]
	v_lshlrev_b32_e32 v114, 16, v189
	v_and_b32_e32 v115, 0xffff0000, v189
	v_pk_fma_f32 v[110:111], v[114:115], v[38:39], v[110:111]
	v_lshlrev_b32_e32 v112, 16, v198
	v_and_b32_e32 v113, 0xffff0000, v198
	v_pk_fma_f32 v[104:105], v[112:113], v[40:41], v[104:105]
	v_lshlrev_b32_e32 v114, 16, v199
	v_and_b32_e32 v115, 0xffff0000, v199
	v_pk_fma_f32 v[106:107], v[114:115], v[42:43], v[106:107]
	v_lshlrev_b32_e32 v112, 16, v200
	v_and_b32_e32 v113, 0xffff0000, v200
	v_pk_fma_f32 v[108:109], v[112:113], v[44:45], v[108:109]
	v_lshlrev_b32_e32 v114, 16, v201
	v_and_b32_e32 v115, 0xffff0000, v201
	v_pk_fma_f32 v[110:111], v[114:115], v[46:47], v[110:111]
	v_lshlrev_b32_e32 v112, 16, v178
	v_and_b32_e32 v113, 0xffff0000, v178
	v_pk_fma_f32 v[104:105], v[112:113], v[48:49], v[104:105]
	v_lshlrev_b32_e32 v114, 16, v179
	v_and_b32_e32 v115, 0xffff0000, v179
	v_pk_fma_f32 v[106:107], v[114:115], v[50:51], v[106:107]
	v_lshlrev_b32_e32 v112, 16, v180
	v_and_b32_e32 v113, 0xffff0000, v180
	v_pk_fma_f32 v[108:109], v[112:113], v[52:53], v[108:109]
	v_lshlrev_b32_e32 v114, 16, v181
	v_and_b32_e32 v115, 0xffff0000, v181
	v_pk_fma_f32 v[110:111], v[114:115], v[54:55], v[110:111]
	v_lshlrev_b32_e32 v112, 16, v190
	v_and_b32_e32 v113, 0xffff0000, v190
	v_pk_fma_f32 v[104:105], v[112:113], v[56:57], v[104:105]
	v_lshlrev_b32_e32 v114, 16, v191
	v_and_b32_e32 v115, 0xffff0000, v191
	v_pk_fma_f32 v[106:107], v[114:115], v[58:59], v[106:107]
	v_lshlrev_b32_e32 v112, 16, v192
	v_and_b32_e32 v113, 0xffff0000, v192
	v_pk_fma_f32 v[108:109], v[112:113], v[60:61], v[108:109]
	v_lshlrev_b32_e32 v114, 16, v193
	v_and_b32_e32 v115, 0xffff0000, v193
	v_pk_fma_f32 v[110:111], v[114:115], v[62:63], v[110:111]
	v_lshlrev_b32_e32 v112, 16, v202
	v_and_b32_e32 v113, 0xffff0000, v202
	v_pk_fma_f32 v[104:105], v[112:113], v[64:65], v[104:105]
	v_lshlrev_b32_e32 v114, 16, v203
	v_and_b32_e32 v115, 0xffff0000, v203
	v_pk_fma_f32 v[106:107], v[114:115], v[66:67], v[106:107]
	v_lshlrev_b32_e32 v112, 16, v204
	v_and_b32_e32 v113, 0xffff0000, v204
	v_pk_fma_f32 v[108:109], v[112:113], v[68:69], v[108:109]
	v_lshlrev_b32_e32 v114, 16, v205
	v_and_b32_e32 v115, 0xffff0000, v205
	v_pk_fma_f32 v[110:111], v[114:115], v[70:71], v[110:111]
	v_mov_b64_e32 v[132:133], s[28:29]
	v_and_b32_e32 v116, 0x7fffffff, v104
	v_and_b32_e32 v117, 0x7fffffff, v105
	v_pk_fma_f32 v[116:117], v[116:117], s[24:25], 1.0 op_sel_hi:[1,0,0]
	v_pk_mul_f32 v[218:219], v[104:105], v[104:105]
	v_rcp_f32_e32 v116, v116
	v_rcp_f32_e32 v117, v117
	v_pk_mul_f32 v[218:219], v[218:219], s[38:39] op_sel_hi:[1,0]
	v_and_b32_e32 v118, 0x7fffffff, v106
	v_and_b32_e32 v119, 0x7fffffff, v107
	v_pk_fma_f32 v[118:119], v[118:119], s[24:25], 1.0 op_sel_hi:[1,0,0]
	v_pk_mul_f32 v[220:221], v[106:107], v[106:107]
	v_rcp_f32_e32 v118, v118
	v_rcp_f32_e32 v119, v119
	v_pk_mul_f32 v[220:221], v[220:221], s[38:39] op_sel_hi:[1,0]
	v_and_b32_e32 v120, 0x7fffffff, v108
	v_and_b32_e32 v121, 0x7fffffff, v109
	v_pk_fma_f32 v[120:121], v[120:121], s[24:25], 1.0 op_sel_hi:[1,0,0]
	v_pk_mul_f32 v[222:223], v[108:109], v[108:109]
	v_rcp_f32_e32 v120, v120
	v_rcp_f32_e32 v121, v121
	v_pk_mul_f32 v[222:223], v[222:223], s[38:39] op_sel_hi:[1,0]
	v_and_b32_e32 v122, 0x7fffffff, v110
	v_and_b32_e32 v123, 0x7fffffff, v111
	v_pk_fma_f32 v[122:123], v[122:123], s[24:25], 1.0 op_sel_hi:[1,0,0]
	v_pk_mul_f32 v[224:225], v[110:111], v[110:111]
	v_rcp_f32_e32 v122, v122
	v_rcp_f32_e32 v123, v123
	v_pk_mul_f32 v[224:225], v[224:225], s[38:39] op_sel_hi:[1,0]
	v_pk_fma_f32 v[124:125], v[116:117], s[26:27], v[132:133] op_sel_hi:[1,0,0]
	v_exp_f32_e32 v218, v218
	v_pk_fma_f32 v[124:125], v[116:117], v[124:125], s[30:31] op_sel_hi:[1,1,0]
	v_exp_f32_e32 v219, v219
	v_pk_fma_f32 v[124:125], v[116:117], v[124:125], s[34:35] op_sel_hi:[1,1,0]
	v_pk_fma_f32 v[124:125], v[116:117], v[124:125], s[36:37] op_sel_hi:[1,1,0]
	v_pk_mul_f32 v[124:125], v[116:117], v[124:125]
	v_pk_fma_f32 v[126:127], v[118:119], s[26:27], v[132:133] op_sel_hi:[1,0,0]
	v_exp_f32_e32 v220, v220
	v_pk_fma_f32 v[126:127], v[118:119], v[126:127], s[30:31] op_sel_hi:[1,1,0]
	v_exp_f32_e32 v221, v221
	v_pk_fma_f32 v[126:127], v[118:119], v[126:127], s[34:35] op_sel_hi:[1,1,0]
	v_pk_fma_f32 v[126:127], v[118:119], v[126:127], s[36:37] op_sel_hi:[1,1,0]
	v_pk_mul_f32 v[126:127], v[118:119], v[126:127]
	v_pk_fma_f32 v[128:129], v[120:121], s[26:27], v[132:133] op_sel_hi:[1,0,0]
	v_exp_f32_e32 v222, v222
	v_pk_fma_f32 v[128:129], v[120:121], v[128:129], s[30:31] op_sel_hi:[1,1,0]
	v_exp_f32_e32 v223, v223
	v_pk_fma_f32 v[128:129], v[120:121], v[128:129], s[34:35] op_sel_hi:[1,1,0]
	v_pk_fma_f32 v[128:129], v[120:121], v[128:129], s[36:37] op_sel_hi:[1,1,0]
	v_pk_mul_f32 v[128:129], v[120:121], v[128:129]
	v_pk_fma_f32 v[130:131], v[122:123], s[26:27], v[132:133] op_sel_hi:[1,0,0]
	v_exp_f32_e32 v224, v224
	v_pk_fma_f32 v[130:131], v[122:123], v[130:131], s[30:31] op_sel_hi:[1,1,0]
	v_exp_f32_e32 v225, v225
	v_pk_fma_f32 v[130:131], v[122:123], v[130:131], s[34:35] op_sel_hi:[1,1,0]
	v_pk_fma_f32 v[130:131], v[122:123], v[130:131], s[36:37] op_sel_hi:[1,1,0]
	v_pk_mul_f32 v[130:131], v[122:123], v[130:131]
	v_pk_mul_f32 v[124:125], v[218:219], v[124:125]
	v_pk_mul_f32 v[218:219], v[104:105], v[124:125]
	v_pk_fma_f32 v[124:125], v[104:105], v[124:125], v[104:105] neg_lo:[1,0,0] neg_hi:[1,0,0]
	v_cmp_gt_f32_e64 s[8:9], 0, v104
	v_cmp_gt_f32_e64 s[22:23], 0, v105
	v_lshlrev_b32_e32 v112, 16, v88
	v_and_b32_e32 v113, 0xffff0000, v88
	v_cndmask_b32_e64 v104, v124, v218, s[8:9]
	v_cndmask_b32_e64 v105, v125, v219, s[22:23]
	v_pk_mul_f32 v[104:105], v[104:105], v[112:113]
	v_cvt_pk_bf16_f32 v226, v104, v105
	v_pk_mul_f32 v[126:127], v[220:221], v[126:127]
	v_pk_mul_f32 v[220:221], v[106:107], v[126:127]
	v_pk_fma_f32 v[126:127], v[106:107], v[126:127], v[106:107] neg_lo:[1,0,0] neg_hi:[1,0,0]
	v_cmp_gt_f32_e64 s[8:9], 0, v106
	v_cmp_gt_f32_e64 s[22:23], 0, v107
	v_lshlrev_b32_e32 v112, 16, v89
	v_and_b32_e32 v113, 0xffff0000, v89
	v_cndmask_b32_e64 v106, v126, v220, s[8:9]
	v_cndmask_b32_e64 v107, v127, v221, s[22:23]
	v_pk_mul_f32 v[106:107], v[106:107], v[112:113]
	v_cvt_pk_bf16_f32 v227, v106, v107
	v_pk_mul_f32 v[128:129], v[222:223], v[128:129]
	v_pk_mul_f32 v[222:223], v[108:109], v[128:129]
	v_pk_fma_f32 v[128:129], v[108:109], v[128:129], v[108:109] neg_lo:[1,0,0] neg_hi:[1,0,0]
	v_cmp_gt_f32_e64 s[8:9], 0, v108
	v_cmp_gt_f32_e64 s[22:23], 0, v109
	v_lshlrev_b32_e32 v112, 16, v90
	v_and_b32_e32 v113, 0xffff0000, v90
	v_cndmask_b32_e64 v108, v128, v222, s[8:9]
	v_cndmask_b32_e64 v109, v129, v223, s[22:23]
	v_pk_mul_f32 v[108:109], v[108:109], v[112:113]
	v_cvt_pk_bf16_f32 v228, v108, v109
	v_pk_mul_f32 v[130:131], v[224:225], v[130:131]
	v_pk_mul_f32 v[224:225], v[110:111], v[130:131]
	v_pk_fma_f32 v[130:131], v[110:111], v[130:131], v[110:111] neg_lo:[1,0,0] neg_hi:[1,0,0]
	v_cmp_gt_f32_e64 s[8:9], 0, v110
	v_cmp_gt_f32_e64 s[22:23], 0, v111
	v_lshlrev_b32_e32 v112, 16, v91
	v_and_b32_e32 v113, 0xffff0000, v91
	v_cndmask_b32_e64 v110, v130, v224, s[8:9]
	v_cndmask_b32_e64 v111, v131, v225, s[22:23]
	v_pk_mul_f32 v[110:111], v[110:111], v[112:113]
	v_cvt_pk_bf16_f32 v229, v110, v111
	global_store_dwordx4 v140, v[226:229], s[14:15] sc1
	v_add_u32_e32 v140, 0x2c00, v140
	global_load_dwordx4 v[170:173], v136, s[14:15]
	global_load_dwordx4 v[174:177], v137, s[14:15]
	global_load_dwordx4 v[178:181], v138, s[14:15]
	v_add_u32_e32 v136, 0x2c00, v136
	v_add_u32_e32 v137, 0x2c00, v137
	v_add_u32_e32 v138, 0x2c00, v138
	global_load_dwordx4 v[84:87], v139, s[14:15]
	v_add_u32_e32 v139, 0x2c00, v139
	s_waitcnt vmcnt(16)
	v_mov_b64_e32 v[104:105], v[72:73]
	v_mov_b64_e32 v[106:107], v[74:75]
	v_mov_b64_e32 v[108:109], v[76:77]
	v_mov_b64_e32 v[110:111], v[78:79]
	v_lshlrev_b32_e32 v112, 16, v182
	v_and_b32_e32 v113, 0xffff0000, v182
	v_pk_fma_f32 v[104:105], v[112:113], v[0:1], v[104:105]
	v_lshlrev_b32_e32 v114, 16, v183
	v_and_b32_e32 v115, 0xffff0000, v183
	v_pk_fma_f32 v[106:107], v[114:115], v[2:3], v[106:107]
	v_lshlrev_b32_e32 v112, 16, v184
	v_and_b32_e32 v113, 0xffff0000, v184
	v_pk_fma_f32 v[108:109], v[112:113], v[4:5], v[108:109]
	v_lshlrev_b32_e32 v114, 16, v185
	v_and_b32_e32 v115, 0xffff0000, v185
	v_pk_fma_f32 v[110:111], v[114:115], v[6:7], v[110:111]
	v_lshlrev_b32_e32 v112, 16, v194
	v_and_b32_e32 v113, 0xffff0000, v194
	v_pk_fma_f32 v[104:105], v[112:113], v[8:9], v[104:105]
	v_lshlrev_b32_e32 v114, 16, v195
	v_and_b32_e32 v115, 0xffff0000, v195
	v_pk_fma_f32 v[106:107], v[114:115], v[10:11], v[106:107]
	v_lshlrev_b32_e32 v112, 16, v196
	v_and_b32_e32 v113, 0xffff0000, v196
	v_pk_fma_f32 v[108:109], v[112:113], v[12:13], v[108:109]
	v_lshlrev_b32_e32 v114, 16, v197
	v_and_b32_e32 v115, 0xffff0000, v197
	v_pk_fma_f32 v[110:111], v[114:115], v[14:15], v[110:111]
	v_lshlrev_b32_e32 v112, 16, v206
	v_and_b32_e32 v113, 0xffff0000, v206
	v_pk_fma_f32 v[104:105], v[112:113], v[16:17], v[104:105]
	v_lshlrev_b32_e32 v114, 16, v207
	v_and_b32_e32 v115, 0xffff0000, v207
	v_pk_fma_f32 v[106:107], v[114:115], v[18:19], v[106:107]
	v_lshlrev_b32_e32 v112, 16, v208
	v_and_b32_e32 v113, 0xffff0000, v208
	v_pk_fma_f32 v[108:109], v[112:113], v[20:21], v[108:109]
	v_lshlrev_b32_e32 v114, 16, v209
	v_and_b32_e32 v115, 0xffff0000, v209
	v_pk_fma_f32 v[110:111], v[114:115], v[22:23], v[110:111]
	v_lshlrev_b32_e32 v112, 16, v186
	v_and_b32_e32 v113, 0xffff0000, v186
	v_pk_fma_f32 v[104:105], v[112:113], v[24:25], v[104:105]
	v_lshlrev_b32_e32 v114, 16, v187
	v_and_b32_e32 v115, 0xffff0000, v187
	v_pk_fma_f32 v[106:107], v[114:115], v[26:27], v[106:107]
	v_lshlrev_b32_e32 v112, 16, v188
	v_and_b32_e32 v113, 0xffff0000, v188
	v_pk_fma_f32 v[108:109], v[112:113], v[28:29], v[108:109]
	v_lshlrev_b32_e32 v114, 16, v189
	v_and_b32_e32 v115, 0xffff0000, v189
	v_pk_fma_f32 v[110:111], v[114:115], v[30:31], v[110:111]
	v_lshlrev_b32_e32 v112, 16, v198
	v_and_b32_e32 v113, 0xffff0000, v198
	v_pk_fma_f32 v[104:105], v[112:113], v[32:33], v[104:105]
	v_lshlrev_b32_e32 v114, 16, v199
	v_and_b32_e32 v115, 0xffff0000, v199
	v_pk_fma_f32 v[106:107], v[114:115], v[34:35], v[106:107]
	v_lshlrev_b32_e32 v112, 16, v200
	v_and_b32_e32 v113, 0xffff0000, v200
	v_pk_fma_f32 v[108:109], v[112:113], v[36:37], v[108:109]
	v_lshlrev_b32_e32 v114, 16, v201
	v_and_b32_e32 v115, 0xffff0000, v201
	v_pk_fma_f32 v[110:111], v[114:115], v[38:39], v[110:111]
	v_lshlrev_b32_e32 v112, 16, v210
	v_and_b32_e32 v113, 0xffff0000, v210
	v_pk_fma_f32 v[104:105], v[112:113], v[40:41], v[104:105]
	v_lshlrev_b32_e32 v114, 16, v211
	v_and_b32_e32 v115, 0xffff0000, v211
	v_pk_fma_f32 v[106:107], v[114:115], v[42:43], v[106:107]
	v_lshlrev_b32_e32 v112, 16, v212
	v_and_b32_e32 v113, 0xffff0000, v212
	v_pk_fma_f32 v[108:109], v[112:113], v[44:45], v[108:109]
	v_lshlrev_b32_e32 v114, 16, v213
	v_and_b32_e32 v115, 0xffff0000, v213
	v_pk_fma_f32 v[110:111], v[114:115], v[46:47], v[110:111]
	v_lshlrev_b32_e32 v112, 16, v190
	v_and_b32_e32 v113, 0xffff0000, v190
	v_pk_fma_f32 v[104:105], v[112:113], v[48:49], v[104:105]
	v_lshlrev_b32_e32 v114, 16, v191
	v_and_b32_e32 v115, 0xffff0000, v191
	v_pk_fma_f32 v[106:107], v[114:115], v[50:51], v[106:107]
	v_lshlrev_b32_e32 v112, 16, v192
	v_and_b32_e32 v113, 0xffff0000, v192
	v_pk_fma_f32 v[108:109], v[112:113], v[52:53], v[108:109]
	v_lshlrev_b32_e32 v114, 16, v193
	v_and_b32_e32 v115, 0xffff0000, v193
	v_pk_fma_f32 v[110:111], v[114:115], v[54:55], v[110:111]
	v_lshlrev_b32_e32 v112, 16, v202
	v_and_b32_e32 v113, 0xffff0000, v202
	v_pk_fma_f32 v[104:105], v[112:113], v[56:57], v[104:105]
	v_lshlrev_b32_e32 v114, 16, v203
	v_and_b32_e32 v115, 0xffff0000, v203
	v_pk_fma_f32 v[106:107], v[114:115], v[58:59], v[106:107]
	v_lshlrev_b32_e32 v112, 16, v204
	v_and_b32_e32 v113, 0xffff0000, v204
	v_pk_fma_f32 v[108:109], v[112:113], v[60:61], v[108:109]
	v_lshlrev_b32_e32 v114, 16, v205
	v_and_b32_e32 v115, 0xffff0000, v205
	v_pk_fma_f32 v[110:111], v[114:115], v[62:63], v[110:111]
	v_lshlrev_b32_e32 v112, 16, v214
	v_and_b32_e32 v113, 0xffff0000, v214
	v_pk_fma_f32 v[104:105], v[112:113], v[64:65], v[104:105]
	v_lshlrev_b32_e32 v114, 16, v215
	v_and_b32_e32 v115, 0xffff0000, v215
	v_pk_fma_f32 v[106:107], v[114:115], v[66:67], v[106:107]
	v_lshlrev_b32_e32 v112, 16, v216
	v_and_b32_e32 v113, 0xffff0000, v216
	v_pk_fma_f32 v[108:109], v[112:113], v[68:69], v[108:109]
	v_lshlrev_b32_e32 v114, 16, v217
	v_and_b32_e32 v115, 0xffff0000, v217
	v_pk_fma_f32 v[110:111], v[114:115], v[70:71], v[110:111]
	v_mov_b64_e32 v[132:133], s[28:29]
	v_and_b32_e32 v116, 0x7fffffff, v104
	v_and_b32_e32 v117, 0x7fffffff, v105
	v_pk_fma_f32 v[116:117], v[116:117], s[24:25], 1.0 op_sel_hi:[1,0,0]
	v_pk_mul_f32 v[218:219], v[104:105], v[104:105]
	v_rcp_f32_e32 v116, v116
	v_rcp_f32_e32 v117, v117
	v_pk_mul_f32 v[218:219], v[218:219], s[38:39] op_sel_hi:[1,0]
	v_and_b32_e32 v118, 0x7fffffff, v106
	v_and_b32_e32 v119, 0x7fffffff, v107
	v_pk_fma_f32 v[118:119], v[118:119], s[24:25], 1.0 op_sel_hi:[1,0,0]
	v_pk_mul_f32 v[220:221], v[106:107], v[106:107]
	v_rcp_f32_e32 v118, v118
	v_rcp_f32_e32 v119, v119
	v_pk_mul_f32 v[220:221], v[220:221], s[38:39] op_sel_hi:[1,0]
	v_and_b32_e32 v120, 0x7fffffff, v108
	v_and_b32_e32 v121, 0x7fffffff, v109
	v_pk_fma_f32 v[120:121], v[120:121], s[24:25], 1.0 op_sel_hi:[1,0,0]
	v_pk_mul_f32 v[222:223], v[108:109], v[108:109]
	v_rcp_f32_e32 v120, v120
	v_rcp_f32_e32 v121, v121
	v_pk_mul_f32 v[222:223], v[222:223], s[38:39] op_sel_hi:[1,0]
	v_and_b32_e32 v122, 0x7fffffff, v110
	v_and_b32_e32 v123, 0x7fffffff, v111
	v_pk_fma_f32 v[122:123], v[122:123], s[24:25], 1.0 op_sel_hi:[1,0,0]
	v_pk_mul_f32 v[224:225], v[110:111], v[110:111]
	v_rcp_f32_e32 v122, v122
	v_rcp_f32_e32 v123, v123
	v_pk_mul_f32 v[224:225], v[224:225], s[38:39] op_sel_hi:[1,0]
	v_pk_fma_f32 v[124:125], v[116:117], s[26:27], v[132:133] op_sel_hi:[1,0,0]
	v_exp_f32_e32 v218, v218
	v_pk_fma_f32 v[124:125], v[116:117], v[124:125], s[30:31] op_sel_hi:[1,1,0]
	v_exp_f32_e32 v219, v219
	v_pk_fma_f32 v[124:125], v[116:117], v[124:125], s[34:35] op_sel_hi:[1,1,0]
	v_pk_fma_f32 v[124:125], v[116:117], v[124:125], s[36:37] op_sel_hi:[1,1,0]
	v_pk_mul_f32 v[124:125], v[116:117], v[124:125]
	v_pk_fma_f32 v[126:127], v[118:119], s[26:27], v[132:133] op_sel_hi:[1,0,0]
	v_exp_f32_e32 v220, v220
	v_pk_fma_f32 v[126:127], v[118:119], v[126:127], s[30:31] op_sel_hi:[1,1,0]
	v_exp_f32_e32 v221, v221
	v_pk_fma_f32 v[126:127], v[118:119], v[126:127], s[34:35] op_sel_hi:[1,1,0]
	v_pk_fma_f32 v[126:127], v[118:119], v[126:127], s[36:37] op_sel_hi:[1,1,0]
	v_pk_mul_f32 v[126:127], v[118:119], v[126:127]
	v_pk_fma_f32 v[128:129], v[120:121], s[26:27], v[132:133] op_sel_hi:[1,0,0]
	v_exp_f32_e32 v222, v222
	v_pk_fma_f32 v[128:129], v[120:121], v[128:129], s[30:31] op_sel_hi:[1,1,0]
	v_exp_f32_e32 v223, v223
	v_pk_fma_f32 v[128:129], v[120:121], v[128:129], s[34:35] op_sel_hi:[1,1,0]
	v_pk_fma_f32 v[128:129], v[120:121], v[128:129], s[36:37] op_sel_hi:[1,1,0]
	v_pk_mul_f32 v[128:129], v[120:121], v[128:129]
	v_pk_fma_f32 v[130:131], v[122:123], s[26:27], v[132:133] op_sel_hi:[1,0,0]
	v_exp_f32_e32 v224, v224
	v_pk_fma_f32 v[130:131], v[122:123], v[130:131], s[30:31] op_sel_hi:[1,1,0]
	v_exp_f32_e32 v225, v225
	v_pk_fma_f32 v[130:131], v[122:123], v[130:131], s[34:35] op_sel_hi:[1,1,0]
	v_pk_fma_f32 v[130:131], v[122:123], v[130:131], s[36:37] op_sel_hi:[1,1,0]
	v_pk_mul_f32 v[130:131], v[122:123], v[130:131]
	v_pk_mul_f32 v[124:125], v[218:219], v[124:125]
	v_pk_mul_f32 v[218:219], v[104:105], v[124:125]
	v_pk_fma_f32 v[124:125], v[104:105], v[124:125], v[104:105] neg_lo:[1,0,0] neg_hi:[1,0,0]
	v_cmp_gt_f32_e64 s[8:9], 0, v104
	v_cmp_gt_f32_e64 s[22:23], 0, v105
	v_lshlrev_b32_e32 v112, 16, v92
	v_and_b32_e32 v113, 0xffff0000, v92
	v_cndmask_b32_e64 v104, v124, v218, s[8:9]
	v_cndmask_b32_e64 v105, v125, v219, s[22:23]
	v_pk_mul_f32 v[104:105], v[104:105], v[112:113]
	v_cvt_pk_bf16_f32 v226, v104, v105
	v_pk_mul_f32 v[126:127], v[220:221], v[126:127]
	v_pk_mul_f32 v[220:221], v[106:107], v[126:127]
	v_pk_fma_f32 v[126:127], v[106:107], v[126:127], v[106:107] neg_lo:[1,0,0] neg_hi:[1,0,0]
	v_cmp_gt_f32_e64 s[8:9], 0, v106
	v_cmp_gt_f32_e64 s[22:23], 0, v107
	v_lshlrev_b32_e32 v112, 16, v93
	v_and_b32_e32 v113, 0xffff0000, v93
	v_cndmask_b32_e64 v106, v126, v220, s[8:9]
	v_cndmask_b32_e64 v107, v127, v221, s[22:23]
	v_pk_mul_f32 v[106:107], v[106:107], v[112:113]
	v_cvt_pk_bf16_f32 v227, v106, v107
	v_pk_mul_f32 v[128:129], v[222:223], v[128:129]
	v_pk_mul_f32 v[222:223], v[108:109], v[128:129]
	v_pk_fma_f32 v[128:129], v[108:109], v[128:129], v[108:109] neg_lo:[1,0,0] neg_hi:[1,0,0]
	v_cmp_gt_f32_e64 s[8:9], 0, v108
	v_cmp_gt_f32_e64 s[22:23], 0, v109
	v_lshlrev_b32_e32 v112, 16, v94
	v_and_b32_e32 v113, 0xffff0000, v94
	v_cndmask_b32_e64 v108, v128, v222, s[8:9]
	v_cndmask_b32_e64 v109, v129, v223, s[22:23]
	v_pk_mul_f32 v[108:109], v[108:109], v[112:113]
	v_cvt_pk_bf16_f32 v228, v108, v109
	v_pk_mul_f32 v[130:131], v[224:225], v[130:131]
	v_pk_mul_f32 v[224:225], v[110:111], v[130:131]
	v_pk_fma_f32 v[130:131], v[110:111], v[130:131], v[110:111] neg_lo:[1,0,0] neg_hi:[1,0,0]
	v_cmp_gt_f32_e64 s[8:9], 0, v110
	v_cmp_gt_f32_e64 s[22:23], 0, v111
	v_lshlrev_b32_e32 v112, 16, v95
	v_and_b32_e32 v113, 0xffff0000, v95
	v_cndmask_b32_e64 v110, v130, v224, s[8:9]
	v_cndmask_b32_e64 v111, v131, v225, s[22:23]
	v_pk_mul_f32 v[110:111], v[110:111], v[112:113]
	v_cvt_pk_bf16_f32 v229, v110, v111
	global_store_dwordx4 v140, v[226:229], s[14:15] sc1
	v_add_u32_e32 v140, 0x2c00, v140
	global_load_dwordx4 v[182:185], v136, s[14:15]
	global_load_dwordx4 v[186:189], v137, s[14:15]
	global_load_dwordx4 v[190:193], v138, s[14:15]
	v_add_u32_e32 v136, 0x2c00, v136
	v_add_u32_e32 v137, 0x2c00, v137
	v_add_u32_e32 v138, 0x2c00, v138
	global_load_dwordx4 v[88:91], v139, s[14:15]
	v_add_u32_e32 v139, 0x2c00, v139
	s_waitcnt vmcnt(16)
	v_mov_b64_e32 v[104:105], v[72:73]
	v_mov_b64_e32 v[106:107], v[74:75]
	v_mov_b64_e32 v[108:109], v[76:77]
	v_mov_b64_e32 v[110:111], v[78:79]
	v_lshlrev_b32_e32 v112, 16, v194
	v_and_b32_e32 v113, 0xffff0000, v194
	v_pk_fma_f32 v[104:105], v[112:113], v[0:1], v[104:105]
	v_lshlrev_b32_e32 v114, 16, v195
	v_and_b32_e32 v115, 0xffff0000, v195
	v_pk_fma_f32 v[106:107], v[114:115], v[2:3], v[106:107]
	v_lshlrev_b32_e32 v112, 16, v196
	v_and_b32_e32 v113, 0xffff0000, v196
	v_pk_fma_f32 v[108:109], v[112:113], v[4:5], v[108:109]
	v_lshlrev_b32_e32 v114, 16, v197
	v_and_b32_e32 v115, 0xffff0000, v197
	v_pk_fma_f32 v[110:111], v[114:115], v[6:7], v[110:111]
	v_lshlrev_b32_e32 v112, 16, v206
	v_and_b32_e32 v113, 0xffff0000, v206
	v_pk_fma_f32 v[104:105], v[112:113], v[8:9], v[104:105]
	v_lshlrev_b32_e32 v114, 16, v207
	v_and_b32_e32 v115, 0xffff0000, v207
	v_pk_fma_f32 v[106:107], v[114:115], v[10:11], v[106:107]
	v_lshlrev_b32_e32 v112, 16, v208
	v_and_b32_e32 v113, 0xffff0000, v208
	v_pk_fma_f32 v[108:109], v[112:113], v[12:13], v[108:109]
	v_lshlrev_b32_e32 v114, 16, v209
	v_and_b32_e32 v115, 0xffff0000, v209
	v_pk_fma_f32 v[110:111], v[114:115], v[14:15], v[110:111]
	v_lshlrev_b32_e32 v112, 16, v146
	v_and_b32_e32 v113, 0xffff0000, v146
	v_pk_fma_f32 v[104:105], v[112:113], v[16:17], v[104:105]
	v_lshlrev_b32_e32 v114, 16, v147
	v_and_b32_e32 v115, 0xffff0000, v147
	v_pk_fma_f32 v[106:107], v[114:115], v[18:19], v[106:107]
	v_lshlrev_b32_e32 v112, 16, v148
	v_and_b32_e32 v113, 0xffff0000, v148
	v_pk_fma_f32 v[108:109], v[112:113], v[20:21], v[108:109]
	v_lshlrev_b32_e32 v114, 16, v149
	v_and_b32_e32 v115, 0xffff0000, v149
	v_pk_fma_f32 v[110:111], v[114:115], v[22:23], v[110:111]
	v_lshlrev_b32_e32 v112, 16, v198
	v_and_b32_e32 v113, 0xffff0000, v198
	v_pk_fma_f32 v[104:105], v[112:113], v[24:25], v[104:105]
	v_lshlrev_b32_e32 v114, 16, v199
	v_and_b32_e32 v115, 0xffff0000, v199
	v_pk_fma_f32 v[106:107], v[114:115], v[26:27], v[106:107]
	v_lshlrev_b32_e32 v112, 16, v200
	v_and_b32_e32 v113, 0xffff0000, v200
	v_pk_fma_f32 v[108:109], v[112:113], v[28:29], v[108:109]
	v_lshlrev_b32_e32 v114, 16, v201
	v_and_b32_e32 v115, 0xffff0000, v201
	v_pk_fma_f32 v[110:111], v[114:115], v[30:31], v[110:111]
	v_lshlrev_b32_e32 v112, 16, v210
	v_and_b32_e32 v113, 0xffff0000, v210
	v_pk_fma_f32 v[104:105], v[112:113], v[32:33], v[104:105]
	v_lshlrev_b32_e32 v114, 16, v211
	v_and_b32_e32 v115, 0xffff0000, v211
	v_pk_fma_f32 v[106:107], v[114:115], v[34:35], v[106:107]
	v_lshlrev_b32_e32 v112, 16, v212
	v_and_b32_e32 v113, 0xffff0000, v212
	v_pk_fma_f32 v[108:109], v[112:113], v[36:37], v[108:109]
	v_lshlrev_b32_e32 v114, 16, v213
	v_and_b32_e32 v115, 0xffff0000, v213
	v_pk_fma_f32 v[110:111], v[114:115], v[38:39], v[110:111]
	v_lshlrev_b32_e32 v112, 16, v150
	v_and_b32_e32 v113, 0xffff0000, v150
	v_pk_fma_f32 v[104:105], v[112:113], v[40:41], v[104:105]
	v_lshlrev_b32_e32 v114, 16, v151
	v_and_b32_e32 v115, 0xffff0000, v151
	v_pk_fma_f32 v[106:107], v[114:115], v[42:43], v[106:107]
	v_lshlrev_b32_e32 v112, 16, v152
	v_and_b32_e32 v113, 0xffff0000, v152
	v_pk_fma_f32 v[108:109], v[112:113], v[44:45], v[108:109]
	v_lshlrev_b32_e32 v114, 16, v153
	v_and_b32_e32 v115, 0xffff0000, v153
	v_pk_fma_f32 v[110:111], v[114:115], v[46:47], v[110:111]
	v_lshlrev_b32_e32 v112, 16, v202
	v_and_b32_e32 v113, 0xffff0000, v202
	v_pk_fma_f32 v[104:105], v[112:113], v[48:49], v[104:105]
	v_lshlrev_b32_e32 v114, 16, v203
	v_and_b32_e32 v115, 0xffff0000, v203
	v_pk_fma_f32 v[106:107], v[114:115], v[50:51], v[106:107]
	v_lshlrev_b32_e32 v112, 16, v204
	v_and_b32_e32 v113, 0xffff0000, v204
	v_pk_fma_f32 v[108:109], v[112:113], v[52:53], v[108:109]
	v_lshlrev_b32_e32 v114, 16, v205
	v_and_b32_e32 v115, 0xffff0000, v205
	v_pk_fma_f32 v[110:111], v[114:115], v[54:55], v[110:111]
	v_lshlrev_b32_e32 v112, 16, v214
	v_and_b32_e32 v113, 0xffff0000, v214
	v_pk_fma_f32 v[104:105], v[112:113], v[56:57], v[104:105]
	v_lshlrev_b32_e32 v114, 16, v215
	v_and_b32_e32 v115, 0xffff0000, v215
	v_pk_fma_f32 v[106:107], v[114:115], v[58:59], v[106:107]
	v_lshlrev_b32_e32 v112, 16, v216
	v_and_b32_e32 v113, 0xffff0000, v216
	v_pk_fma_f32 v[108:109], v[112:113], v[60:61], v[108:109]
	v_lshlrev_b32_e32 v114, 16, v217
	v_and_b32_e32 v115, 0xffff0000, v217
	v_pk_fma_f32 v[110:111], v[114:115], v[62:63], v[110:111]
	v_lshlrev_b32_e32 v112, 16, v154
	v_and_b32_e32 v113, 0xffff0000, v154
	v_pk_fma_f32 v[104:105], v[112:113], v[64:65], v[104:105]
	v_lshlrev_b32_e32 v114, 16, v155
	v_and_b32_e32 v115, 0xffff0000, v155
	v_pk_fma_f32 v[106:107], v[114:115], v[66:67], v[106:107]
	v_lshlrev_b32_e32 v112, 16, v156
	v_and_b32_e32 v113, 0xffff0000, v156
	v_pk_fma_f32 v[108:109], v[112:113], v[68:69], v[108:109]
	v_lshlrev_b32_e32 v114, 16, v157
	v_and_b32_e32 v115, 0xffff0000, v157
	v_pk_fma_f32 v[110:111], v[114:115], v[70:71], v[110:111]
	v_mov_b64_e32 v[132:133], s[28:29]
	v_and_b32_e32 v116, 0x7fffffff, v104
	v_and_b32_e32 v117, 0x7fffffff, v105
	v_pk_fma_f32 v[116:117], v[116:117], s[24:25], 1.0 op_sel_hi:[1,0,0]
	v_pk_mul_f32 v[218:219], v[104:105], v[104:105]
	v_rcp_f32_e32 v116, v116
	v_rcp_f32_e32 v117, v117
	v_pk_mul_f32 v[218:219], v[218:219], s[38:39] op_sel_hi:[1,0]
	v_and_b32_e32 v118, 0x7fffffff, v106
	v_and_b32_e32 v119, 0x7fffffff, v107
	v_pk_fma_f32 v[118:119], v[118:119], s[24:25], 1.0 op_sel_hi:[1,0,0]
	v_pk_mul_f32 v[220:221], v[106:107], v[106:107]
	v_rcp_f32_e32 v118, v118
	v_rcp_f32_e32 v119, v119
	v_pk_mul_f32 v[220:221], v[220:221], s[38:39] op_sel_hi:[1,0]
	v_and_b32_e32 v120, 0x7fffffff, v108
	v_and_b32_e32 v121, 0x7fffffff, v109
	v_pk_fma_f32 v[120:121], v[120:121], s[24:25], 1.0 op_sel_hi:[1,0,0]
	v_pk_mul_f32 v[222:223], v[108:109], v[108:109]
	v_rcp_f32_e32 v120, v120
	v_rcp_f32_e32 v121, v121
	v_pk_mul_f32 v[222:223], v[222:223], s[38:39] op_sel_hi:[1,0]
	v_and_b32_e32 v122, 0x7fffffff, v110
	v_and_b32_e32 v123, 0x7fffffff, v111
	v_pk_fma_f32 v[122:123], v[122:123], s[24:25], 1.0 op_sel_hi:[1,0,0]
	v_pk_mul_f32 v[224:225], v[110:111], v[110:111]
	v_rcp_f32_e32 v122, v122
	v_rcp_f32_e32 v123, v123
	v_pk_mul_f32 v[224:225], v[224:225], s[38:39] op_sel_hi:[1,0]
	v_pk_fma_f32 v[124:125], v[116:117], s[26:27], v[132:133] op_sel_hi:[1,0,0]
	v_exp_f32_e32 v218, v218
	v_pk_fma_f32 v[124:125], v[116:117], v[124:125], s[30:31] op_sel_hi:[1,1,0]
	v_exp_f32_e32 v219, v219
	v_pk_fma_f32 v[124:125], v[116:117], v[124:125], s[34:35] op_sel_hi:[1,1,0]
	v_pk_fma_f32 v[124:125], v[116:117], v[124:125], s[36:37] op_sel_hi:[1,1,0]
	v_pk_mul_f32 v[124:125], v[116:117], v[124:125]
	v_pk_fma_f32 v[126:127], v[118:119], s[26:27], v[132:133] op_sel_hi:[1,0,0]
	v_exp_f32_e32 v220, v220
	v_pk_fma_f32 v[126:127], v[118:119], v[126:127], s[30:31] op_sel_hi:[1,1,0]
	v_exp_f32_e32 v221, v221
	v_pk_fma_f32 v[126:127], v[118:119], v[126:127], s[34:35] op_sel_hi:[1,1,0]
	v_pk_fma_f32 v[126:127], v[118:119], v[126:127], s[36:37] op_sel_hi:[1,1,0]
	v_pk_mul_f32 v[126:127], v[118:119], v[126:127]
	v_pk_fma_f32 v[128:129], v[120:121], s[26:27], v[132:133] op_sel_hi:[1,0,0]
	v_exp_f32_e32 v222, v222
	v_pk_fma_f32 v[128:129], v[120:121], v[128:129], s[30:31] op_sel_hi:[1,1,0]
	v_exp_f32_e32 v223, v223
	v_pk_fma_f32 v[128:129], v[120:121], v[128:129], s[34:35] op_sel_hi:[1,1,0]
	v_pk_fma_f32 v[128:129], v[120:121], v[128:129], s[36:37] op_sel_hi:[1,1,0]
	v_pk_mul_f32 v[128:129], v[120:121], v[128:129]
	v_pk_fma_f32 v[130:131], v[122:123], s[26:27], v[132:133] op_sel_hi:[1,0,0]
	v_exp_f32_e32 v224, v224
	v_pk_fma_f32 v[130:131], v[122:123], v[130:131], s[30:31] op_sel_hi:[1,1,0]
	v_exp_f32_e32 v225, v225
	v_pk_fma_f32 v[130:131], v[122:123], v[130:131], s[34:35] op_sel_hi:[1,1,0]
	v_pk_fma_f32 v[130:131], v[122:123], v[130:131], s[36:37] op_sel_hi:[1,1,0]
	v_pk_mul_f32 v[130:131], v[122:123], v[130:131]
	v_pk_mul_f32 v[124:125], v[218:219], v[124:125]
	v_pk_mul_f32 v[218:219], v[104:105], v[124:125]
	v_pk_fma_f32 v[124:125], v[104:105], v[124:125], v[104:105] neg_lo:[1,0,0] neg_hi:[1,0,0]
	v_cmp_gt_f32_e64 s[8:9], 0, v104
	v_cmp_gt_f32_e64 s[22:23], 0, v105
	v_lshlrev_b32_e32 v112, 16, v96
	v_and_b32_e32 v113, 0xffff0000, v96
	v_cndmask_b32_e64 v104, v124, v218, s[8:9]
	v_cndmask_b32_e64 v105, v125, v219, s[22:23]
	v_pk_mul_f32 v[104:105], v[104:105], v[112:113]
	v_cvt_pk_bf16_f32 v226, v104, v105
	v_pk_mul_f32 v[126:127], v[220:221], v[126:127]
	v_pk_mul_f32 v[220:221], v[106:107], v[126:127]
	v_pk_fma_f32 v[126:127], v[106:107], v[126:127], v[106:107] neg_lo:[1,0,0] neg_hi:[1,0,0]
	v_cmp_gt_f32_e64 s[8:9], 0, v106
	v_cmp_gt_f32_e64 s[22:23], 0, v107
	v_lshlrev_b32_e32 v112, 16, v97
	v_and_b32_e32 v113, 0xffff0000, v97
	v_cndmask_b32_e64 v106, v126, v220, s[8:9]
	v_cndmask_b32_e64 v107, v127, v221, s[22:23]
	v_pk_mul_f32 v[106:107], v[106:107], v[112:113]
	v_cvt_pk_bf16_f32 v227, v106, v107
	v_pk_mul_f32 v[128:129], v[222:223], v[128:129]
	v_pk_mul_f32 v[222:223], v[108:109], v[128:129]
	v_pk_fma_f32 v[128:129], v[108:109], v[128:129], v[108:109] neg_lo:[1,0,0] neg_hi:[1,0,0]
	v_cmp_gt_f32_e64 s[8:9], 0, v108
	v_cmp_gt_f32_e64 s[22:23], 0, v109
	v_lshlrev_b32_e32 v112, 16, v98
	v_and_b32_e32 v113, 0xffff0000, v98
	v_cndmask_b32_e64 v108, v128, v222, s[8:9]
	v_cndmask_b32_e64 v109, v129, v223, s[22:23]
	v_pk_mul_f32 v[108:109], v[108:109], v[112:113]
	v_cvt_pk_bf16_f32 v228, v108, v109
	v_pk_mul_f32 v[130:131], v[224:225], v[130:131]
	v_pk_mul_f32 v[224:225], v[110:111], v[130:131]
	v_pk_fma_f32 v[130:131], v[110:111], v[130:131], v[110:111] neg_lo:[1,0,0] neg_hi:[1,0,0]
	v_cmp_gt_f32_e64 s[8:9], 0, v110
	v_cmp_gt_f32_e64 s[22:23], 0, v111
	v_lshlrev_b32_e32 v112, 16, v99
	v_and_b32_e32 v113, 0xffff0000, v99
	v_cndmask_b32_e64 v110, v130, v224, s[8:9]
	v_cndmask_b32_e64 v111, v131, v225, s[22:23]
	v_pk_mul_f32 v[110:111], v[110:111], v[112:113]
	v_cvt_pk_bf16_f32 v229, v110, v111
	global_store_dwordx4 v140, v[226:229], s[14:15] sc1
	v_add_u32_e32 v140, 0x2c00, v140
	global_load_dwordx4 v[194:197], v136, s[14:15]
	global_load_dwordx4 v[198:201], v137, s[14:15]
	global_load_dwordx4 v[202:205], v138, s[14:15]
	v_add_u32_e32 v136, 0x2c00, v136
	v_add_u32_e32 v137, 0x2c00, v137
	v_add_u32_e32 v138, 0x2c00, v138
	global_load_dwordx4 v[92:95], v139, s[14:15]
	v_add_u32_e32 v139, 0x2c00, v139
	s_waitcnt vmcnt(16)
	v_mov_b64_e32 v[104:105], v[72:73]
	v_mov_b64_e32 v[106:107], v[74:75]
	v_mov_b64_e32 v[108:109], v[76:77]
	v_mov_b64_e32 v[110:111], v[78:79]
	v_lshlrev_b32_e32 v112, 16, v206
	v_and_b32_e32 v113, 0xffff0000, v206
	v_pk_fma_f32 v[104:105], v[112:113], v[0:1], v[104:105]
	v_lshlrev_b32_e32 v114, 16, v207
	v_and_b32_e32 v115, 0xffff0000, v207
	v_pk_fma_f32 v[106:107], v[114:115], v[2:3], v[106:107]
	v_lshlrev_b32_e32 v112, 16, v208
	v_and_b32_e32 v113, 0xffff0000, v208
	v_pk_fma_f32 v[108:109], v[112:113], v[4:5], v[108:109]
	v_lshlrev_b32_e32 v114, 16, v209
	v_and_b32_e32 v115, 0xffff0000, v209
	v_pk_fma_f32 v[110:111], v[114:115], v[6:7], v[110:111]
	v_lshlrev_b32_e32 v112, 16, v146
	v_and_b32_e32 v113, 0xffff0000, v146
	v_pk_fma_f32 v[104:105], v[112:113], v[8:9], v[104:105]
	v_lshlrev_b32_e32 v114, 16, v147
	v_and_b32_e32 v115, 0xffff0000, v147
	v_pk_fma_f32 v[106:107], v[114:115], v[10:11], v[106:107]
	v_lshlrev_b32_e32 v112, 16, v148
	v_and_b32_e32 v113, 0xffff0000, v148
	v_pk_fma_f32 v[108:109], v[112:113], v[12:13], v[108:109]
	v_lshlrev_b32_e32 v114, 16, v149
	v_and_b32_e32 v115, 0xffff0000, v149
	v_pk_fma_f32 v[110:111], v[114:115], v[14:15], v[110:111]
	v_lshlrev_b32_e32 v112, 16, v158
	v_and_b32_e32 v113, 0xffff0000, v158
	v_pk_fma_f32 v[104:105], v[112:113], v[16:17], v[104:105]
	v_lshlrev_b32_e32 v114, 16, v159
	v_and_b32_e32 v115, 0xffff0000, v159
	v_pk_fma_f32 v[106:107], v[114:115], v[18:19], v[106:107]
	v_lshlrev_b32_e32 v112, 16, v160
	v_and_b32_e32 v113, 0xffff0000, v160
	v_pk_fma_f32 v[108:109], v[112:113], v[20:21], v[108:109]
	v_lshlrev_b32_e32 v114, 16, v161
	v_and_b32_e32 v115, 0xffff0000, v161
	v_pk_fma_f32 v[110:111], v[114:115], v[22:23], v[110:111]
	v_lshlrev_b32_e32 v112, 16, v210
	v_and_b32_e32 v113, 0xffff0000, v210
	v_pk_fma_f32 v[104:105], v[112:113], v[24:25], v[104:105]
	v_lshlrev_b32_e32 v114, 16, v211
	v_and_b32_e32 v115, 0xffff0000, v211
	v_pk_fma_f32 v[106:107], v[114:115], v[26:27], v[106:107]
	v_lshlrev_b32_e32 v112, 16, v212
	v_and_b32_e32 v113, 0xffff0000, v212
	v_pk_fma_f32 v[108:109], v[112:113], v[28:29], v[108:109]
	v_lshlrev_b32_e32 v114, 16, v213
	v_and_b32_e32 v115, 0xffff0000, v213
	v_pk_fma_f32 v[110:111], v[114:115], v[30:31], v[110:111]
	v_lshlrev_b32_e32 v112, 16, v150
	v_and_b32_e32 v113, 0xffff0000, v150
	v_pk_fma_f32 v[104:105], v[112:113], v[32:33], v[104:105]
	v_lshlrev_b32_e32 v114, 16, v151
	v_and_b32_e32 v115, 0xffff0000, v151
	v_pk_fma_f32 v[106:107], v[114:115], v[34:35], v[106:107]
	v_lshlrev_b32_e32 v112, 16, v152
	v_and_b32_e32 v113, 0xffff0000, v152
	v_pk_fma_f32 v[108:109], v[112:113], v[36:37], v[108:109]
	v_lshlrev_b32_e32 v114, 16, v153
	v_and_b32_e32 v115, 0xffff0000, v153
	v_pk_fma_f32 v[110:111], v[114:115], v[38:39], v[110:111]
	v_lshlrev_b32_e32 v112, 16, v162
	v_and_b32_e32 v113, 0xffff0000, v162
	v_pk_fma_f32 v[104:105], v[112:113], v[40:41], v[104:105]
	v_lshlrev_b32_e32 v114, 16, v163
	v_and_b32_e32 v115, 0xffff0000, v163
	v_pk_fma_f32 v[106:107], v[114:115], v[42:43], v[106:107]
	v_lshlrev_b32_e32 v112, 16, v164
	v_and_b32_e32 v113, 0xffff0000, v164
	v_pk_fma_f32 v[108:109], v[112:113], v[44:45], v[108:109]
	v_lshlrev_b32_e32 v114, 16, v165
	v_and_b32_e32 v115, 0xffff0000, v165
	v_pk_fma_f32 v[110:111], v[114:115], v[46:47], v[110:111]
	v_lshlrev_b32_e32 v112, 16, v214
	v_and_b32_e32 v113, 0xffff0000, v214
	v_pk_fma_f32 v[104:105], v[112:113], v[48:49], v[104:105]
	v_lshlrev_b32_e32 v114, 16, v215
	v_and_b32_e32 v115, 0xffff0000, v215
	v_pk_fma_f32 v[106:107], v[114:115], v[50:51], v[106:107]
	v_lshlrev_b32_e32 v112, 16, v216
	v_and_b32_e32 v113, 0xffff0000, v216
	v_pk_fma_f32 v[108:109], v[112:113], v[52:53], v[108:109]
	v_lshlrev_b32_e32 v114, 16, v217
	v_and_b32_e32 v115, 0xffff0000, v217
	v_pk_fma_f32 v[110:111], v[114:115], v[54:55], v[110:111]
	v_lshlrev_b32_e32 v112, 16, v154
	v_and_b32_e32 v113, 0xffff0000, v154
	v_pk_fma_f32 v[104:105], v[112:113], v[56:57], v[104:105]
	v_lshlrev_b32_e32 v114, 16, v155
	v_and_b32_e32 v115, 0xffff0000, v155
	v_pk_fma_f32 v[106:107], v[114:115], v[58:59], v[106:107]
	v_lshlrev_b32_e32 v112, 16, v156
	v_and_b32_e32 v113, 0xffff0000, v156
	v_pk_fma_f32 v[108:109], v[112:113], v[60:61], v[108:109]
	v_lshlrev_b32_e32 v114, 16, v157
	v_and_b32_e32 v115, 0xffff0000, v157
	v_pk_fma_f32 v[110:111], v[114:115], v[62:63], v[110:111]
	v_lshlrev_b32_e32 v112, 16, v166
	v_and_b32_e32 v113, 0xffff0000, v166
	v_pk_fma_f32 v[104:105], v[112:113], v[64:65], v[104:105]
	v_lshlrev_b32_e32 v114, 16, v167
	v_and_b32_e32 v115, 0xffff0000, v167
	v_pk_fma_f32 v[106:107], v[114:115], v[66:67], v[106:107]
	v_lshlrev_b32_e32 v112, 16, v168
	v_and_b32_e32 v113, 0xffff0000, v168
	v_pk_fma_f32 v[108:109], v[112:113], v[68:69], v[108:109]
	v_lshlrev_b32_e32 v114, 16, v169
	v_and_b32_e32 v115, 0xffff0000, v169
	v_pk_fma_f32 v[110:111], v[114:115], v[70:71], v[110:111]
	v_mov_b64_e32 v[132:133], s[28:29]
	v_and_b32_e32 v116, 0x7fffffff, v104
	v_and_b32_e32 v117, 0x7fffffff, v105
	v_pk_fma_f32 v[116:117], v[116:117], s[24:25], 1.0 op_sel_hi:[1,0,0]
	v_pk_mul_f32 v[218:219], v[104:105], v[104:105]
	v_rcp_f32_e32 v116, v116
	v_rcp_f32_e32 v117, v117
	v_pk_mul_f32 v[218:219], v[218:219], s[38:39] op_sel_hi:[1,0]
	v_and_b32_e32 v118, 0x7fffffff, v106
	v_and_b32_e32 v119, 0x7fffffff, v107
	v_pk_fma_f32 v[118:119], v[118:119], s[24:25], 1.0 op_sel_hi:[1,0,0]
	v_pk_mul_f32 v[220:221], v[106:107], v[106:107]
	v_rcp_f32_e32 v118, v118
	v_rcp_f32_e32 v119, v119
	v_pk_mul_f32 v[220:221], v[220:221], s[38:39] op_sel_hi:[1,0]
	v_and_b32_e32 v120, 0x7fffffff, v108
	v_and_b32_e32 v121, 0x7fffffff, v109
	v_pk_fma_f32 v[120:121], v[120:121], s[24:25], 1.0 op_sel_hi:[1,0,0]
	v_pk_mul_f32 v[222:223], v[108:109], v[108:109]
	v_rcp_f32_e32 v120, v120
	v_rcp_f32_e32 v121, v121
	v_pk_mul_f32 v[222:223], v[222:223], s[38:39] op_sel_hi:[1,0]
	v_and_b32_e32 v122, 0x7fffffff, v110
	v_and_b32_e32 v123, 0x7fffffff, v111
	v_pk_fma_f32 v[122:123], v[122:123], s[24:25], 1.0 op_sel_hi:[1,0,0]
	v_pk_mul_f32 v[224:225], v[110:111], v[110:111]
	v_rcp_f32_e32 v122, v122
	v_rcp_f32_e32 v123, v123
	v_pk_mul_f32 v[224:225], v[224:225], s[38:39] op_sel_hi:[1,0]
	v_pk_fma_f32 v[124:125], v[116:117], s[26:27], v[132:133] op_sel_hi:[1,0,0]
	v_exp_f32_e32 v218, v218
	v_pk_fma_f32 v[124:125], v[116:117], v[124:125], s[30:31] op_sel_hi:[1,1,0]
	v_exp_f32_e32 v219, v219
	v_pk_fma_f32 v[124:125], v[116:117], v[124:125], s[34:35] op_sel_hi:[1,1,0]
	v_pk_fma_f32 v[124:125], v[116:117], v[124:125], s[36:37] op_sel_hi:[1,1,0]
	v_pk_mul_f32 v[124:125], v[116:117], v[124:125]
	v_pk_fma_f32 v[126:127], v[118:119], s[26:27], v[132:133] op_sel_hi:[1,0,0]
	v_exp_f32_e32 v220, v220
	v_pk_fma_f32 v[126:127], v[118:119], v[126:127], s[30:31] op_sel_hi:[1,1,0]
	v_exp_f32_e32 v221, v221
	v_pk_fma_f32 v[126:127], v[118:119], v[126:127], s[34:35] op_sel_hi:[1,1,0]
	v_pk_fma_f32 v[126:127], v[118:119], v[126:127], s[36:37] op_sel_hi:[1,1,0]
	v_pk_mul_f32 v[126:127], v[118:119], v[126:127]
	v_pk_fma_f32 v[128:129], v[120:121], s[26:27], v[132:133] op_sel_hi:[1,0,0]
	v_exp_f32_e32 v222, v222
	v_pk_fma_f32 v[128:129], v[120:121], v[128:129], s[30:31] op_sel_hi:[1,1,0]
	v_exp_f32_e32 v223, v223
	v_pk_fma_f32 v[128:129], v[120:121], v[128:129], s[34:35] op_sel_hi:[1,1,0]
	v_pk_fma_f32 v[128:129], v[120:121], v[128:129], s[36:37] op_sel_hi:[1,1,0]
	v_pk_mul_f32 v[128:129], v[120:121], v[128:129]
	v_pk_fma_f32 v[130:131], v[122:123], s[26:27], v[132:133] op_sel_hi:[1,0,0]
	v_exp_f32_e32 v224, v224
	v_pk_fma_f32 v[130:131], v[122:123], v[130:131], s[30:31] op_sel_hi:[1,1,0]
	v_exp_f32_e32 v225, v225
	v_pk_fma_f32 v[130:131], v[122:123], v[130:131], s[34:35] op_sel_hi:[1,1,0]
	v_pk_fma_f32 v[130:131], v[122:123], v[130:131], s[36:37] op_sel_hi:[1,1,0]
	v_pk_mul_f32 v[130:131], v[122:123], v[130:131]
	v_pk_mul_f32 v[124:125], v[218:219], v[124:125]
	v_pk_mul_f32 v[218:219], v[104:105], v[124:125]
	v_pk_fma_f32 v[124:125], v[104:105], v[124:125], v[104:105] neg_lo:[1,0,0] neg_hi:[1,0,0]
	v_cmp_gt_f32_e64 s[8:9], 0, v104
	v_cmp_gt_f32_e64 s[22:23], 0, v105
	v_lshlrev_b32_e32 v112, 16, v100
	v_and_b32_e32 v113, 0xffff0000, v100
	v_cndmask_b32_e64 v104, v124, v218, s[8:9]
	v_cndmask_b32_e64 v105, v125, v219, s[22:23]
	v_pk_mul_f32 v[104:105], v[104:105], v[112:113]
	v_cvt_pk_bf16_f32 v226, v104, v105
	v_pk_mul_f32 v[126:127], v[220:221], v[126:127]
	v_pk_mul_f32 v[220:221], v[106:107], v[126:127]
	v_pk_fma_f32 v[126:127], v[106:107], v[126:127], v[106:107] neg_lo:[1,0,0] neg_hi:[1,0,0]
	v_cmp_gt_f32_e64 s[8:9], 0, v106
	v_cmp_gt_f32_e64 s[22:23], 0, v107
	v_lshlrev_b32_e32 v112, 16, v101
	v_and_b32_e32 v113, 0xffff0000, v101
	v_cndmask_b32_e64 v106, v126, v220, s[8:9]
	v_cndmask_b32_e64 v107, v127, v221, s[22:23]
	v_pk_mul_f32 v[106:107], v[106:107], v[112:113]
	v_cvt_pk_bf16_f32 v227, v106, v107
	v_pk_mul_f32 v[128:129], v[222:223], v[128:129]
	v_pk_mul_f32 v[222:223], v[108:109], v[128:129]
	v_pk_fma_f32 v[128:129], v[108:109], v[128:129], v[108:109] neg_lo:[1,0,0] neg_hi:[1,0,0]
	v_cmp_gt_f32_e64 s[8:9], 0, v108
	v_cmp_gt_f32_e64 s[22:23], 0, v109
	v_lshlrev_b32_e32 v112, 16, v102
	v_and_b32_e32 v113, 0xffff0000, v102
	v_cndmask_b32_e64 v108, v128, v222, s[8:9]
	v_cndmask_b32_e64 v109, v129, v223, s[22:23]
	v_pk_mul_f32 v[108:109], v[108:109], v[112:113]
	v_cvt_pk_bf16_f32 v228, v108, v109
	v_pk_mul_f32 v[130:131], v[224:225], v[130:131]
	v_pk_mul_f32 v[224:225], v[110:111], v[130:131]
	v_pk_fma_f32 v[130:131], v[110:111], v[130:131], v[110:111] neg_lo:[1,0,0] neg_hi:[1,0,0]
	v_cmp_gt_f32_e64 s[8:9], 0, v110
	v_cmp_gt_f32_e64 s[22:23], 0, v111
	v_lshlrev_b32_e32 v112, 16, v103
	v_and_b32_e32 v113, 0xffff0000, v103
	v_cndmask_b32_e64 v110, v130, v224, s[8:9]
	v_cndmask_b32_e64 v111, v131, v225, s[22:23]
	v_pk_mul_f32 v[110:111], v[110:111], v[112:113]
	v_cvt_pk_bf16_f32 v229, v110, v111
	global_store_dwordx4 v140, v[226:229], s[14:15] sc1
	v_add_u32_e32 v140, 0x2c00, v140
	s_mov_b32 s21, 4
.Lconv_cols:
	global_load_dwordx4 v[206:209], v136, s[14:15]
	global_load_dwordx4 v[210:213], v137, s[14:15]
	global_load_dwordx4 v[214:217], v138, s[14:15]
	v_add_u32_e32 v136, 0x2c00, v136
	v_add_u32_e32 v137, 0x2c00, v137
	v_add_u32_e32 v138, 0x2c00, v138
	global_load_dwordx4 v[96:99], v139, s[14:15]
	v_add_u32_e32 v139, 0x2c00, v139
	s_waitcnt vmcnt(16)
	v_mov_b64_e32 v[104:105], v[72:73]
	v_mov_b64_e32 v[106:107], v[74:75]
	v_mov_b64_e32 v[108:109], v[76:77]
	v_mov_b64_e32 v[110:111], v[78:79]
	v_lshlrev_b32_e32 v112, 16, v146
	v_and_b32_e32 v113, 0xffff0000, v146
	v_pk_fma_f32 v[104:105], v[112:113], v[0:1], v[104:105]
	v_lshlrev_b32_e32 v114, 16, v147
	v_and_b32_e32 v115, 0xffff0000, v147
	v_pk_fma_f32 v[106:107], v[114:115], v[2:3], v[106:107]
	v_lshlrev_b32_e32 v112, 16, v148
	v_and_b32_e32 v113, 0xffff0000, v148
	v_pk_fma_f32 v[108:109], v[112:113], v[4:5], v[108:109]
	v_lshlrev_b32_e32 v114, 16, v149
	v_and_b32_e32 v115, 0xffff0000, v149
	v_pk_fma_f32 v[110:111], v[114:115], v[6:7], v[110:111]
	v_lshlrev_b32_e32 v112, 16, v158
	v_and_b32_e32 v113, 0xffff0000, v158
	v_pk_fma_f32 v[104:105], v[112:113], v[8:9], v[104:105]
	v_lshlrev_b32_e32 v114, 16, v159
	v_and_b32_e32 v115, 0xffff0000, v159
	v_pk_fma_f32 v[106:107], v[114:115], v[10:11], v[106:107]
	v_lshlrev_b32_e32 v112, 16, v160
	v_and_b32_e32 v113, 0xffff0000, v160
	v_pk_fma_f32 v[108:109], v[112:113], v[12:13], v[108:109]
	v_lshlrev_b32_e32 v114, 16, v161
	v_and_b32_e32 v115, 0xffff0000, v161
	v_pk_fma_f32 v[110:111], v[114:115], v[14:15], v[110:111]
	v_lshlrev_b32_e32 v112, 16, v170
	v_and_b32_e32 v113, 0xffff0000, v170
	v_pk_fma_f32 v[104:105], v[112:113], v[16:17], v[104:105]
	v_lshlrev_b32_e32 v114, 16, v171
	v_and_b32_e32 v115, 0xffff0000, v171
	v_pk_fma_f32 v[106:107], v[114:115], v[18:19], v[106:107]
	v_lshlrev_b32_e32 v112, 16, v172
	v_and_b32_e32 v113, 0xffff0000, v172
	v_pk_fma_f32 v[108:109], v[112:113], v[20:21], v[108:109]
	v_lshlrev_b32_e32 v114, 16, v173
	v_and_b32_e32 v115, 0xffff0000, v173
	v_pk_fma_f32 v[110:111], v[114:115], v[22:23], v[110:111]
	v_lshlrev_b32_e32 v112, 16, v150
	v_and_b32_e32 v113, 0xffff0000, v150
	v_pk_fma_f32 v[104:105], v[112:113], v[24:25], v[104:105]
	v_lshlrev_b32_e32 v114, 16, v151
	v_and_b32_e32 v115, 0xffff0000, v151
	v_pk_fma_f32 v[106:107], v[114:115], v[26:27], v[106:107]
	v_lshlrev_b32_e32 v112, 16, v152
	v_and_b32_e32 v113, 0xffff0000, v152
	v_pk_fma_f32 v[108:109], v[112:113], v[28:29], v[108:109]
	v_lshlrev_b32_e32 v114, 16, v153
	v_and_b32_e32 v115, 0xffff0000, v153
	v_pk_fma_f32 v[110:111], v[114:115], v[30:31], v[110:111]
	v_lshlrev_b32_e32 v112, 16, v162
	v_and_b32_e32 v113, 0xffff0000, v162
	v_pk_fma_f32 v[104:105], v[112:113], v[32:33], v[104:105]
	v_lshlrev_b32_e32 v114, 16, v163
	v_and_b32_e32 v115, 0xffff0000, v163
	v_pk_fma_f32 v[106:107], v[114:115], v[34:35], v[106:107]
	v_lshlrev_b32_e32 v112, 16, v164
	v_and_b32_e32 v113, 0xffff0000, v164
	v_pk_fma_f32 v[108:109], v[112:113], v[36:37], v[108:109]
	v_lshlrev_b32_e32 v114, 16, v165
	v_and_b32_e32 v115, 0xffff0000, v165
	v_pk_fma_f32 v[110:111], v[114:115], v[38:39], v[110:111]
	v_lshlrev_b32_e32 v112, 16, v174
	v_and_b32_e32 v113, 0xffff0000, v174
	v_pk_fma_f32 v[104:105], v[112:113], v[40:41], v[104:105]
	v_lshlrev_b32_e32 v114, 16, v175
	v_and_b32_e32 v115, 0xffff0000, v175
	v_pk_fma_f32 v[106:107], v[114:115], v[42:43], v[106:107]
	v_lshlrev_b32_e32 v112, 16, v176
	v_and_b32_e32 v113, 0xffff0000, v176
	v_pk_fma_f32 v[108:109], v[112:113], v[44:45], v[108:109]
	v_lshlrev_b32_e32 v114, 16, v177
	v_and_b32_e32 v115, 0xffff0000, v177
	v_pk_fma_f32 v[110:111], v[114:115], v[46:47], v[110:111]
	v_lshlrev_b32_e32 v112, 16, v154
	v_and_b32_e32 v113, 0xffff0000, v154
	v_pk_fma_f32 v[104:105], v[112:113], v[48:49], v[104:105]
	v_lshlrev_b32_e32 v114, 16, v155
	v_and_b32_e32 v115, 0xffff0000, v155
	v_pk_fma_f32 v[106:107], v[114:115], v[50:51], v[106:107]
	v_lshlrev_b32_e32 v112, 16, v156
	v_and_b32_e32 v113, 0xffff0000, v156
	v_pk_fma_f32 v[108:109], v[112:113], v[52:53], v[108:109]
	v_lshlrev_b32_e32 v114, 16, v157
	v_and_b32_e32 v115, 0xffff0000, v157
	v_pk_fma_f32 v[110:111], v[114:115], v[54:55], v[110:111]
	v_lshlrev_b32_e32 v112, 16, v166
	v_and_b32_e32 v113, 0xffff0000, v166
	v_pk_fma_f32 v[104:105], v[112:113], v[56:57], v[104:105]
	v_lshlrev_b32_e32 v114, 16, v167
	v_and_b32_e32 v115, 0xffff0000, v167
	v_pk_fma_f32 v[106:107], v[114:115], v[58:59], v[106:107]
	v_lshlrev_b32_e32 v112, 16, v168
	v_and_b32_e32 v113, 0xffff0000, v168
	v_pk_fma_f32 v[108:109], v[112:113], v[60:61], v[108:109]
	v_lshlrev_b32_e32 v114, 16, v169
	v_and_b32_e32 v115, 0xffff0000, v169
	v_pk_fma_f32 v[110:111], v[114:115], v[62:63], v[110:111]
	v_lshlrev_b32_e32 v112, 16, v178
	v_and_b32_e32 v113, 0xffff0000, v178
	v_pk_fma_f32 v[104:105], v[112:113], v[64:65], v[104:105]
	v_lshlrev_b32_e32 v114, 16, v179
	v_and_b32_e32 v115, 0xffff0000, v179
	v_pk_fma_f32 v[106:107], v[114:115], v[66:67], v[106:107]
	v_lshlrev_b32_e32 v112, 16, v180
	v_and_b32_e32 v113, 0xffff0000, v180
	v_pk_fma_f32 v[108:109], v[112:113], v[68:69], v[108:109]
	v_lshlrev_b32_e32 v114, 16, v181
	v_and_b32_e32 v115, 0xffff0000, v181
	v_pk_fma_f32 v[110:111], v[114:115], v[70:71], v[110:111]
	v_mov_b64_e32 v[132:133], s[28:29]
	v_and_b32_e32 v116, 0x7fffffff, v104
	v_and_b32_e32 v117, 0x7fffffff, v105
	v_pk_fma_f32 v[116:117], v[116:117], s[24:25], 1.0 op_sel_hi:[1,0,0]
	v_pk_mul_f32 v[218:219], v[104:105], v[104:105]
	v_rcp_f32_e32 v116, v116
	v_rcp_f32_e32 v117, v117
	v_pk_mul_f32 v[218:219], v[218:219], s[38:39] op_sel_hi:[1,0]
	v_and_b32_e32 v118, 0x7fffffff, v106
	v_and_b32_e32 v119, 0x7fffffff, v107
	v_pk_fma_f32 v[118:119], v[118:119], s[24:25], 1.0 op_sel_hi:[1,0,0]
	v_pk_mul_f32 v[220:221], v[106:107], v[106:107]
	v_rcp_f32_e32 v118, v118
	v_rcp_f32_e32 v119, v119
	v_pk_mul_f32 v[220:221], v[220:221], s[38:39] op_sel_hi:[1,0]
	v_and_b32_e32 v120, 0x7fffffff, v108
	v_and_b32_e32 v121, 0x7fffffff, v109
	v_pk_fma_f32 v[120:121], v[120:121], s[24:25], 1.0 op_sel_hi:[1,0,0]
	v_pk_mul_f32 v[222:223], v[108:109], v[108:109]
	v_rcp_f32_e32 v120, v120
	v_rcp_f32_e32 v121, v121
	v_pk_mul_f32 v[222:223], v[222:223], s[38:39] op_sel_hi:[1,0]
	v_and_b32_e32 v122, 0x7fffffff, v110
	v_and_b32_e32 v123, 0x7fffffff, v111
	v_pk_fma_f32 v[122:123], v[122:123], s[24:25], 1.0 op_sel_hi:[1,0,0]
	v_pk_mul_f32 v[224:225], v[110:111], v[110:111]
	v_rcp_f32_e32 v122, v122
	v_rcp_f32_e32 v123, v123
	v_pk_mul_f32 v[224:225], v[224:225], s[38:39] op_sel_hi:[1,0]
	v_pk_fma_f32 v[124:125], v[116:117], s[26:27], v[132:133] op_sel_hi:[1,0,0]
	v_exp_f32_e32 v218, v218
	v_pk_fma_f32 v[124:125], v[116:117], v[124:125], s[30:31] op_sel_hi:[1,1,0]
	v_exp_f32_e32 v219, v219
	v_pk_fma_f32 v[124:125], v[116:117], v[124:125], s[34:35] op_sel_hi:[1,1,0]
	v_pk_fma_f32 v[124:125], v[116:117], v[124:125], s[36:37] op_sel_hi:[1,1,0]
	v_pk_mul_f32 v[124:125], v[116:117], v[124:125]
	v_pk_fma_f32 v[126:127], v[118:119], s[26:27], v[132:133] op_sel_hi:[1,0,0]
	v_exp_f32_e32 v220, v220
	v_pk_fma_f32 v[126:127], v[118:119], v[126:127], s[30:31] op_sel_hi:[1,1,0]
	v_exp_f32_e32 v221, v221
	v_pk_fma_f32 v[126:127], v[118:119], v[126:127], s[34:35] op_sel_hi:[1,1,0]
	v_pk_fma_f32 v[126:127], v[118:119], v[126:127], s[36:37] op_sel_hi:[1,1,0]
	v_pk_mul_f32 v[126:127], v[118:119], v[126:127]
	v_pk_fma_f32 v[128:129], v[120:121], s[26:27], v[132:133] op_sel_hi:[1,0,0]
	v_exp_f32_e32 v222, v222
	v_pk_fma_f32 v[128:129], v[120:121], v[128:129], s[30:31] op_sel_hi:[1,1,0]
	v_exp_f32_e32 v223, v223
	v_pk_fma_f32 v[128:129], v[120:121], v[128:129], s[34:35] op_sel_hi:[1,1,0]
	v_pk_fma_f32 v[128:129], v[120:121], v[128:129], s[36:37] op_sel_hi:[1,1,0]
	v_pk_mul_f32 v[128:129], v[120:121], v[128:129]
	v_pk_fma_f32 v[130:131], v[122:123], s[26:27], v[132:133] op_sel_hi:[1,0,0]
	v_exp_f32_e32 v224, v224
	v_pk_fma_f32 v[130:131], v[122:123], v[130:131], s[30:31] op_sel_hi:[1,1,0]
	v_exp_f32_e32 v225, v225
	v_pk_fma_f32 v[130:131], v[122:123], v[130:131], s[34:35] op_sel_hi:[1,1,0]
	v_pk_fma_f32 v[130:131], v[122:123], v[130:131], s[36:37] op_sel_hi:[1,1,0]
	v_pk_mul_f32 v[130:131], v[122:123], v[130:131]
	v_pk_mul_f32 v[124:125], v[218:219], v[124:125]
	v_pk_mul_f32 v[218:219], v[104:105], v[124:125]
	v_pk_fma_f32 v[124:125], v[104:105], v[124:125], v[104:105] neg_lo:[1,0,0] neg_hi:[1,0,0]
	v_cmp_gt_f32_e64 s[8:9], 0, v104
	v_cmp_gt_f32_e64 s[22:23], 0, v105
	v_lshlrev_b32_e32 v112, 16, v80
	v_and_b32_e32 v113, 0xffff0000, v80
	v_cndmask_b32_e64 v104, v124, v218, s[8:9]
	v_cndmask_b32_e64 v105, v125, v219, s[22:23]
	v_pk_mul_f32 v[104:105], v[104:105], v[112:113]
	v_cvt_pk_bf16_f32 v226, v104, v105
	v_pk_mul_f32 v[126:127], v[220:221], v[126:127]
	v_pk_mul_f32 v[220:221], v[106:107], v[126:127]
	v_pk_fma_f32 v[126:127], v[106:107], v[126:127], v[106:107] neg_lo:[1,0,0] neg_hi:[1,0,0]
	v_cmp_gt_f32_e64 s[8:9], 0, v106
	v_cmp_gt_f32_e64 s[22:23], 0, v107
	v_lshlrev_b32_e32 v112, 16, v81
	v_and_b32_e32 v113, 0xffff0000, v81
	v_cndmask_b32_e64 v106, v126, v220, s[8:9]
	v_cndmask_b32_e64 v107, v127, v221, s[22:23]
	v_pk_mul_f32 v[106:107], v[106:107], v[112:113]
	v_cvt_pk_bf16_f32 v227, v106, v107
	v_pk_mul_f32 v[128:129], v[222:223], v[128:129]
	v_pk_mul_f32 v[222:223], v[108:109], v[128:129]
	v_pk_fma_f32 v[128:129], v[108:109], v[128:129], v[108:109] neg_lo:[1,0,0] neg_hi:[1,0,0]
	v_cmp_gt_f32_e64 s[8:9], 0, v108
	v_cmp_gt_f32_e64 s[22:23], 0, v109
	v_lshlrev_b32_e32 v112, 16, v82
	v_and_b32_e32 v113, 0xffff0000, v82
	v_cndmask_b32_e64 v108, v128, v222, s[8:9]
	v_cndmask_b32_e64 v109, v129, v223, s[22:23]
	v_pk_mul_f32 v[108:109], v[108:109], v[112:113]
	v_cvt_pk_bf16_f32 v228, v108, v109
	v_pk_mul_f32 v[130:131], v[224:225], v[130:131]
	v_pk_mul_f32 v[224:225], v[110:111], v[130:131]
	v_pk_fma_f32 v[130:131], v[110:111], v[130:131], v[110:111] neg_lo:[1,0,0] neg_hi:[1,0,0]
	v_cmp_gt_f32_e64 s[8:9], 0, v110
	v_cmp_gt_f32_e64 s[22:23], 0, v111
	v_lshlrev_b32_e32 v112, 16, v83
	v_and_b32_e32 v113, 0xffff0000, v83
	v_cndmask_b32_e64 v110, v130, v224, s[8:9]
	v_cndmask_b32_e64 v111, v131, v225, s[22:23]
	v_pk_mul_f32 v[110:111], v[110:111], v[112:113]
	v_cvt_pk_bf16_f32 v229, v110, v111
	global_store_dwordx4 v140, v[226:229], s[14:15] sc1
	v_add_u32_e32 v140, 0x2c00, v140
	global_load_dwordx4 v[146:149], v136, s[14:15]
	global_load_dwordx4 v[150:153], v137, s[14:15]
	global_load_dwordx4 v[154:157], v138, s[14:15]
	v_add_u32_e32 v136, 0x2c00, v136
	v_add_u32_e32 v137, 0x2c00, v137
	v_add_u32_e32 v138, 0x2c00, v138
	global_load_dwordx4 v[100:103], v139, s[14:15]
	v_add_u32_e32 v139, 0x2c00, v139
	s_waitcnt vmcnt(16)
	v_mov_b64_e32 v[104:105], v[72:73]
	v_mov_b64_e32 v[106:107], v[74:75]
	v_mov_b64_e32 v[108:109], v[76:77]
	v_mov_b64_e32 v[110:111], v[78:79]
	v_lshlrev_b32_e32 v112, 16, v158
	v_and_b32_e32 v113, 0xffff0000, v158
	v_pk_fma_f32 v[104:105], v[112:113], v[0:1], v[104:105]
	v_lshlrev_b32_e32 v114, 16, v159
	v_and_b32_e32 v115, 0xffff0000, v159
	v_pk_fma_f32 v[106:107], v[114:115], v[2:3], v[106:107]
	v_lshlrev_b32_e32 v112, 16, v160
	v_and_b32_e32 v113, 0xffff0000, v160
	v_pk_fma_f32 v[108:109], v[112:113], v[4:5], v[108:109]
	v_lshlrev_b32_e32 v114, 16, v161
	v_and_b32_e32 v115, 0xffff0000, v161
	v_pk_fma_f32 v[110:111], v[114:115], v[6:7], v[110:111]
	v_lshlrev_b32_e32 v112, 16, v170
	v_and_b32_e32 v113, 0xffff0000, v170
	v_pk_fma_f32 v[104:105], v[112:113], v[8:9], v[104:105]
	v_lshlrev_b32_e32 v114, 16, v171
	v_and_b32_e32 v115, 0xffff0000, v171
	v_pk_fma_f32 v[106:107], v[114:115], v[10:11], v[106:107]
	v_lshlrev_b32_e32 v112, 16, v172
	v_and_b32_e32 v113, 0xffff0000, v172
	v_pk_fma_f32 v[108:109], v[112:113], v[12:13], v[108:109]
	v_lshlrev_b32_e32 v114, 16, v173
	v_and_b32_e32 v115, 0xffff0000, v173
	v_pk_fma_f32 v[110:111], v[114:115], v[14:15], v[110:111]
	v_lshlrev_b32_e32 v112, 16, v182
	v_and_b32_e32 v113, 0xffff0000, v182
	v_pk_fma_f32 v[104:105], v[112:113], v[16:17], v[104:105]
	v_lshlrev_b32_e32 v114, 16, v183
	v_and_b32_e32 v115, 0xffff0000, v183
	v_pk_fma_f32 v[106:107], v[114:115], v[18:19], v[106:107]
	v_lshlrev_b32_e32 v112, 16, v184
	v_and_b32_e32 v113, 0xffff0000, v184
	v_pk_fma_f32 v[108:109], v[112:113], v[20:21], v[108:109]
	v_lshlrev_b32_e32 v114, 16, v185
	v_and_b32_e32 v115, 0xffff0000, v185
	v_pk_fma_f32 v[110:111], v[114:115], v[22:23], v[110:111]
	v_lshlrev_b32_e32 v112, 16, v162
	v_and_b32_e32 v113, 0xffff0000, v162
	v_pk_fma_f32 v[104:105], v[112:113], v[24:25], v[104:105]
	v_lshlrev_b32_e32 v114, 16, v163
	v_and_b32_e32 v115, 0xffff0000, v163
	v_pk_fma_f32 v[106:107], v[114:115], v[26:27], v[106:107]
	v_lshlrev_b32_e32 v112, 16, v164
	v_and_b32_e32 v113, 0xffff0000, v164
	v_pk_fma_f32 v[108:109], v[112:113], v[28:29], v[108:109]
	v_lshlrev_b32_e32 v114, 16, v165
	v_and_b32_e32 v115, 0xffff0000, v165
	v_pk_fma_f32 v[110:111], v[114:115], v[30:31], v[110:111]
	v_lshlrev_b32_e32 v112, 16, v174
	v_and_b32_e32 v113, 0xffff0000, v174
	v_pk_fma_f32 v[104:105], v[112:113], v[32:33], v[104:105]
	v_lshlrev_b32_e32 v114, 16, v175
	v_and_b32_e32 v115, 0xffff0000, v175
	v_pk_fma_f32 v[106:107], v[114:115], v[34:35], v[106:107]
	v_lshlrev_b32_e32 v112, 16, v176
	v_and_b32_e32 v113, 0xffff0000, v176
	v_pk_fma_f32 v[108:109], v[112:113], v[36:37], v[108:109]
	v_lshlrev_b32_e32 v114, 16, v177
	v_and_b32_e32 v115, 0xffff0000, v177
	v_pk_fma_f32 v[110:111], v[114:115], v[38:39], v[110:111]
	v_lshlrev_b32_e32 v112, 16, v186
	v_and_b32_e32 v113, 0xffff0000, v186
	v_pk_fma_f32 v[104:105], v[112:113], v[40:41], v[104:105]
	v_lshlrev_b32_e32 v114, 16, v187
	v_and_b32_e32 v115, 0xffff0000, v187
	v_pk_fma_f32 v[106:107], v[114:115], v[42:43], v[106:107]
	v_lshlrev_b32_e32 v112, 16, v188
	v_and_b32_e32 v113, 0xffff0000, v188
	v_pk_fma_f32 v[108:109], v[112:113], v[44:45], v[108:109]
	v_lshlrev_b32_e32 v114, 16, v189
	v_and_b32_e32 v115, 0xffff0000, v189
	v_pk_fma_f32 v[110:111], v[114:115], v[46:47], v[110:111]
	v_lshlrev_b32_e32 v112, 16, v166
	v_and_b32_e32 v113, 0xffff0000, v166
	v_pk_fma_f32 v[104:105], v[112:113], v[48:49], v[104:105]
	v_lshlrev_b32_e32 v114, 16, v167
	v_and_b32_e32 v115, 0xffff0000, v167
	v_pk_fma_f32 v[106:107], v[114:115], v[50:51], v[106:107]
	v_lshlrev_b32_e32 v112, 16, v168
	v_and_b32_e32 v113, 0xffff0000, v168
	v_pk_fma_f32 v[108:109], v[112:113], v[52:53], v[108:109]
	v_lshlrev_b32_e32 v114, 16, v169
	v_and_b32_e32 v115, 0xffff0000, v169
	v_pk_fma_f32 v[110:111], v[114:115], v[54:55], v[110:111]
	v_lshlrev_b32_e32 v112, 16, v178
	v_and_b32_e32 v113, 0xffff0000, v178
	v_pk_fma_f32 v[104:105], v[112:113], v[56:57], v[104:105]
	v_lshlrev_b32_e32 v114, 16, v179
	v_and_b32_e32 v115, 0xffff0000, v179
	v_pk_fma_f32 v[106:107], v[114:115], v[58:59], v[106:107]
	v_lshlrev_b32_e32 v112, 16, v180
	v_and_b32_e32 v113, 0xffff0000, v180
	v_pk_fma_f32 v[108:109], v[112:113], v[60:61], v[108:109]
	v_lshlrev_b32_e32 v114, 16, v181
	v_and_b32_e32 v115, 0xffff0000, v181
	v_pk_fma_f32 v[110:111], v[114:115], v[62:63], v[110:111]
	v_lshlrev_b32_e32 v112, 16, v190
	v_and_b32_e32 v113, 0xffff0000, v190
	v_pk_fma_f32 v[104:105], v[112:113], v[64:65], v[104:105]
	v_lshlrev_b32_e32 v114, 16, v191
	v_and_b32_e32 v115, 0xffff0000, v191
	v_pk_fma_f32 v[106:107], v[114:115], v[66:67], v[106:107]
	v_lshlrev_b32_e32 v112, 16, v192
	v_and_b32_e32 v113, 0xffff0000, v192
	v_pk_fma_f32 v[108:109], v[112:113], v[68:69], v[108:109]
	v_lshlrev_b32_e32 v114, 16, v193
	v_and_b32_e32 v115, 0xffff0000, v193
	v_pk_fma_f32 v[110:111], v[114:115], v[70:71], v[110:111]
	v_mov_b64_e32 v[132:133], s[28:29]
	v_and_b32_e32 v116, 0x7fffffff, v104
	v_and_b32_e32 v117, 0x7fffffff, v105
	v_pk_fma_f32 v[116:117], v[116:117], s[24:25], 1.0 op_sel_hi:[1,0,0]
	v_pk_mul_f32 v[218:219], v[104:105], v[104:105]
	v_rcp_f32_e32 v116, v116
	v_rcp_f32_e32 v117, v117
	v_pk_mul_f32 v[218:219], v[218:219], s[38:39] op_sel_hi:[1,0]
	v_and_b32_e32 v118, 0x7fffffff, v106
	v_and_b32_e32 v119, 0x7fffffff, v107
	v_pk_fma_f32 v[118:119], v[118:119], s[24:25], 1.0 op_sel_hi:[1,0,0]
	v_pk_mul_f32 v[220:221], v[106:107], v[106:107]
	v_rcp_f32_e32 v118, v118
	v_rcp_f32_e32 v119, v119
	v_pk_mul_f32 v[220:221], v[220:221], s[38:39] op_sel_hi:[1,0]
	v_and_b32_e32 v120, 0x7fffffff, v108
	v_and_b32_e32 v121, 0x7fffffff, v109
	v_pk_fma_f32 v[120:121], v[120:121], s[24:25], 1.0 op_sel_hi:[1,0,0]
	v_pk_mul_f32 v[222:223], v[108:109], v[108:109]
	v_rcp_f32_e32 v120, v120
	v_rcp_f32_e32 v121, v121
	v_pk_mul_f32 v[222:223], v[222:223], s[38:39] op_sel_hi:[1,0]
	v_and_b32_e32 v122, 0x7fffffff, v110
	v_and_b32_e32 v123, 0x7fffffff, v111
	v_pk_fma_f32 v[122:123], v[122:123], s[24:25], 1.0 op_sel_hi:[1,0,0]
	v_pk_mul_f32 v[224:225], v[110:111], v[110:111]
	v_rcp_f32_e32 v122, v122
	v_rcp_f32_e32 v123, v123
	v_pk_mul_f32 v[224:225], v[224:225], s[38:39] op_sel_hi:[1,0]
	v_pk_fma_f32 v[124:125], v[116:117], s[26:27], v[132:133] op_sel_hi:[1,0,0]
	v_exp_f32_e32 v218, v218
	v_pk_fma_f32 v[124:125], v[116:117], v[124:125], s[30:31] op_sel_hi:[1,1,0]
	v_exp_f32_e32 v219, v219
	v_pk_fma_f32 v[124:125], v[116:117], v[124:125], s[34:35] op_sel_hi:[1,1,0]
	v_pk_fma_f32 v[124:125], v[116:117], v[124:125], s[36:37] op_sel_hi:[1,1,0]
	v_pk_mul_f32 v[124:125], v[116:117], v[124:125]
	v_pk_fma_f32 v[126:127], v[118:119], s[26:27], v[132:133] op_sel_hi:[1,0,0]
	v_exp_f32_e32 v220, v220
	v_pk_fma_f32 v[126:127], v[118:119], v[126:127], s[30:31] op_sel_hi:[1,1,0]
	v_exp_f32_e32 v221, v221
	v_pk_fma_f32 v[126:127], v[118:119], v[126:127], s[34:35] op_sel_hi:[1,1,0]
	v_pk_fma_f32 v[126:127], v[118:119], v[126:127], s[36:37] op_sel_hi:[1,1,0]
	v_pk_mul_f32 v[126:127], v[118:119], v[126:127]
	v_pk_fma_f32 v[128:129], v[120:121], s[26:27], v[132:133] op_sel_hi:[1,0,0]
	v_exp_f32_e32 v222, v222
	v_pk_fma_f32 v[128:129], v[120:121], v[128:129], s[30:31] op_sel_hi:[1,1,0]
	v_exp_f32_e32 v223, v223
	v_pk_fma_f32 v[128:129], v[120:121], v[128:129], s[34:35] op_sel_hi:[1,1,0]
	v_pk_fma_f32 v[128:129], v[120:121], v[128:129], s[36:37] op_sel_hi:[1,1,0]
	v_pk_mul_f32 v[128:129], v[120:121], v[128:129]
	v_pk_fma_f32 v[130:131], v[122:123], s[26:27], v[132:133] op_sel_hi:[1,0,0]
	v_exp_f32_e32 v224, v224
	v_pk_fma_f32 v[130:131], v[122:123], v[130:131], s[30:31] op_sel_hi:[1,1,0]
	v_exp_f32_e32 v225, v225
	v_pk_fma_f32 v[130:131], v[122:123], v[130:131], s[34:35] op_sel_hi:[1,1,0]
	v_pk_fma_f32 v[130:131], v[122:123], v[130:131], s[36:37] op_sel_hi:[1,1,0]
	v_pk_mul_f32 v[130:131], v[122:123], v[130:131]
	v_pk_mul_f32 v[124:125], v[218:219], v[124:125]
	v_pk_mul_f32 v[218:219], v[104:105], v[124:125]
	v_pk_fma_f32 v[124:125], v[104:105], v[124:125], v[104:105] neg_lo:[1,0,0] neg_hi:[1,0,0]
	v_cmp_gt_f32_e64 s[8:9], 0, v104
	v_cmp_gt_f32_e64 s[22:23], 0, v105
	v_lshlrev_b32_e32 v112, 16, v84
	v_and_b32_e32 v113, 0xffff0000, v84
	v_cndmask_b32_e64 v104, v124, v218, s[8:9]
	v_cndmask_b32_e64 v105, v125, v219, s[22:23]
	v_pk_mul_f32 v[104:105], v[104:105], v[112:113]
	v_cvt_pk_bf16_f32 v226, v104, v105
	v_pk_mul_f32 v[126:127], v[220:221], v[126:127]
	v_pk_mul_f32 v[220:221], v[106:107], v[126:127]
	v_pk_fma_f32 v[126:127], v[106:107], v[126:127], v[106:107] neg_lo:[1,0,0] neg_hi:[1,0,0]
	v_cmp_gt_f32_e64 s[8:9], 0, v106
	v_cmp_gt_f32_e64 s[22:23], 0, v107
	v_lshlrev_b32_e32 v112, 16, v85
	v_and_b32_e32 v113, 0xffff0000, v85
	v_cndmask_b32_e64 v106, v126, v220, s[8:9]
	v_cndmask_b32_e64 v107, v127, v221, s[22:23]
	v_pk_mul_f32 v[106:107], v[106:107], v[112:113]
	v_cvt_pk_bf16_f32 v227, v106, v107
	v_pk_mul_f32 v[128:129], v[222:223], v[128:129]
	v_pk_mul_f32 v[222:223], v[108:109], v[128:129]
	v_pk_fma_f32 v[128:129], v[108:109], v[128:129], v[108:109] neg_lo:[1,0,0] neg_hi:[1,0,0]
	v_cmp_gt_f32_e64 s[8:9], 0, v108
	v_cmp_gt_f32_e64 s[22:23], 0, v109
	v_lshlrev_b32_e32 v112, 16, v86
	v_and_b32_e32 v113, 0xffff0000, v86
	v_cndmask_b32_e64 v108, v128, v222, s[8:9]
	v_cndmask_b32_e64 v109, v129, v223, s[22:23]
	v_pk_mul_f32 v[108:109], v[108:109], v[112:113]
	v_cvt_pk_bf16_f32 v228, v108, v109
	v_pk_mul_f32 v[130:131], v[224:225], v[130:131]
	v_pk_mul_f32 v[224:225], v[110:111], v[130:131]
	v_pk_fma_f32 v[130:131], v[110:111], v[130:131], v[110:111] neg_lo:[1,0,0] neg_hi:[1,0,0]
	v_cmp_gt_f32_e64 s[8:9], 0, v110
	v_cmp_gt_f32_e64 s[22:23], 0, v111
	v_lshlrev_b32_e32 v112, 16, v87
	v_and_b32_e32 v113, 0xffff0000, v87
	v_cndmask_b32_e64 v110, v130, v224, s[8:9]
	v_cndmask_b32_e64 v111, v131, v225, s[22:23]
	v_pk_mul_f32 v[110:111], v[110:111], v[112:113]
	v_cvt_pk_bf16_f32 v229, v110, v111
	global_store_dwordx4 v140, v[226:229], s[14:15] sc1
	v_add_u32_e32 v140, 0x2c00, v140
	global_load_dwordx4 v[158:161], v136, s[14:15]
	global_load_dwordx4 v[162:165], v137, s[14:15]
	global_load_dwordx4 v[166:169], v138, s[14:15]
	v_add_u32_e32 v136, 0x2c00, v136
	v_add_u32_e32 v137, 0x2c00, v137
	v_add_u32_e32 v138, 0x2c00, v138
	global_load_dwordx4 v[80:83], v139, s[14:15]
	v_add_u32_e32 v139, 0x2c00, v139
	s_waitcnt vmcnt(16)
	v_mov_b64_e32 v[104:105], v[72:73]
	v_mov_b64_e32 v[106:107], v[74:75]
	v_mov_b64_e32 v[108:109], v[76:77]
	v_mov_b64_e32 v[110:111], v[78:79]
	v_lshlrev_b32_e32 v112, 16, v170
	v_and_b32_e32 v113, 0xffff0000, v170
	v_pk_fma_f32 v[104:105], v[112:113], v[0:1], v[104:105]
	v_lshlrev_b32_e32 v114, 16, v171
	v_and_b32_e32 v115, 0xffff0000, v171
	v_pk_fma_f32 v[106:107], v[114:115], v[2:3], v[106:107]
	v_lshlrev_b32_e32 v112, 16, v172
	v_and_b32_e32 v113, 0xffff0000, v172
	v_pk_fma_f32 v[108:109], v[112:113], v[4:5], v[108:109]
	v_lshlrev_b32_e32 v114, 16, v173
	v_and_b32_e32 v115, 0xffff0000, v173
	v_pk_fma_f32 v[110:111], v[114:115], v[6:7], v[110:111]
	v_lshlrev_b32_e32 v112, 16, v182
	v_and_b32_e32 v113, 0xffff0000, v182
	v_pk_fma_f32 v[104:105], v[112:113], v[8:9], v[104:105]
	v_lshlrev_b32_e32 v114, 16, v183
	v_and_b32_e32 v115, 0xffff0000, v183
	v_pk_fma_f32 v[106:107], v[114:115], v[10:11], v[106:107]
	v_lshlrev_b32_e32 v112, 16, v184
	v_and_b32_e32 v113, 0xffff0000, v184
	v_pk_fma_f32 v[108:109], v[112:113], v[12:13], v[108:109]
	v_lshlrev_b32_e32 v114, 16, v185
	v_and_b32_e32 v115, 0xffff0000, v185
	v_pk_fma_f32 v[110:111], v[114:115], v[14:15], v[110:111]
	v_lshlrev_b32_e32 v112, 16, v194
	v_and_b32_e32 v113, 0xffff0000, v194
	v_pk_fma_f32 v[104:105], v[112:113], v[16:17], v[104:105]
	v_lshlrev_b32_e32 v114, 16, v195
	v_and_b32_e32 v115, 0xffff0000, v195
	v_pk_fma_f32 v[106:107], v[114:115], v[18:19], v[106:107]
	v_lshlrev_b32_e32 v112, 16, v196
	v_and_b32_e32 v113, 0xffff0000, v196
	v_pk_fma_f32 v[108:109], v[112:113], v[20:21], v[108:109]
	v_lshlrev_b32_e32 v114, 16, v197
	v_and_b32_e32 v115, 0xffff0000, v197
	v_pk_fma_f32 v[110:111], v[114:115], v[22:23], v[110:111]
	v_lshlrev_b32_e32 v112, 16, v174
	v_and_b32_e32 v113, 0xffff0000, v174
	v_pk_fma_f32 v[104:105], v[112:113], v[24:25], v[104:105]
	v_lshlrev_b32_e32 v114, 16, v175
	v_and_b32_e32 v115, 0xffff0000, v175
	v_pk_fma_f32 v[106:107], v[114:115], v[26:27], v[106:107]
	v_lshlrev_b32_e32 v112, 16, v176
	v_and_b32_e32 v113, 0xffff0000, v176
	v_pk_fma_f32 v[108:109], v[112:113], v[28:29], v[108:109]
	v_lshlrev_b32_e32 v114, 16, v177
	v_and_b32_e32 v115, 0xffff0000, v177
	v_pk_fma_f32 v[110:111], v[114:115], v[30:31], v[110:111]
	v_lshlrev_b32_e32 v112, 16, v186
	v_and_b32_e32 v113, 0xffff0000, v186
	v_pk_fma_f32 v[104:105], v[112:113], v[32:33], v[104:105]
	v_lshlrev_b32_e32 v114, 16, v187
	v_and_b32_e32 v115, 0xffff0000, v187
	v_pk_fma_f32 v[106:107], v[114:115], v[34:35], v[106:107]
	v_lshlrev_b32_e32 v112, 16, v188
	v_and_b32_e32 v113, 0xffff0000, v188
	v_pk_fma_f32 v[108:109], v[112:113], v[36:37], v[108:109]
	v_lshlrev_b32_e32 v114, 16, v189
	v_and_b32_e32 v115, 0xffff0000, v189
	v_pk_fma_f32 v[110:111], v[114:115], v[38:39], v[110:111]
	v_lshlrev_b32_e32 v112, 16, v198
	v_and_b32_e32 v113, 0xffff0000, v198
	v_pk_fma_f32 v[104:105], v[112:113], v[40:41], v[104:105]
	v_lshlrev_b32_e32 v114, 16, v199
	v_and_b32_e32 v115, 0xffff0000, v199
	v_pk_fma_f32 v[106:107], v[114:115], v[42:43], v[106:107]
	v_lshlrev_b32_e32 v112, 16, v200
	v_and_b32_e32 v113, 0xffff0000, v200
	v_pk_fma_f32 v[108:109], v[112:113], v[44:45], v[108:109]
	v_lshlrev_b32_e32 v114, 16, v201
	v_and_b32_e32 v115, 0xffff0000, v201
	v_pk_fma_f32 v[110:111], v[114:115], v[46:47], v[110:111]
	v_lshlrev_b32_e32 v112, 16, v178
	v_and_b32_e32 v113, 0xffff0000, v178
	v_pk_fma_f32 v[104:105], v[112:113], v[48:49], v[104:105]
	v_lshlrev_b32_e32 v114, 16, v179
	v_and_b32_e32 v115, 0xffff0000, v179
	v_pk_fma_f32 v[106:107], v[114:115], v[50:51], v[106:107]
	v_lshlrev_b32_e32 v112, 16, v180
	v_and_b32_e32 v113, 0xffff0000, v180
	v_pk_fma_f32 v[108:109], v[112:113], v[52:53], v[108:109]
	v_lshlrev_b32_e32 v114, 16, v181
	v_and_b32_e32 v115, 0xffff0000, v181
	v_pk_fma_f32 v[110:111], v[114:115], v[54:55], v[110:111]
	v_lshlrev_b32_e32 v112, 16, v190
	v_and_b32_e32 v113, 0xffff0000, v190
	v_pk_fma_f32 v[104:105], v[112:113], v[56:57], v[104:105]
	v_lshlrev_b32_e32 v114, 16, v191
	v_and_b32_e32 v115, 0xffff0000, v191
	v_pk_fma_f32 v[106:107], v[114:115], v[58:59], v[106:107]
	v_lshlrev_b32_e32 v112, 16, v192
	v_and_b32_e32 v113, 0xffff0000, v192
	v_pk_fma_f32 v[108:109], v[112:113], v[60:61], v[108:109]
	v_lshlrev_b32_e32 v114, 16, v193
	v_and_b32_e32 v115, 0xffff0000, v193
	v_pk_fma_f32 v[110:111], v[114:115], v[62:63], v[110:111]
	v_lshlrev_b32_e32 v112, 16, v202
	v_and_b32_e32 v113, 0xffff0000, v202
	v_pk_fma_f32 v[104:105], v[112:113], v[64:65], v[104:105]
	v_lshlrev_b32_e32 v114, 16, v203
	v_and_b32_e32 v115, 0xffff0000, v203
	v_pk_fma_f32 v[106:107], v[114:115], v[66:67], v[106:107]
	v_lshlrev_b32_e32 v112, 16, v204
	v_and_b32_e32 v113, 0xffff0000, v204
	v_pk_fma_f32 v[108:109], v[112:113], v[68:69], v[108:109]
	v_lshlrev_b32_e32 v114, 16, v205
	v_and_b32_e32 v115, 0xffff0000, v205
	v_pk_fma_f32 v[110:111], v[114:115], v[70:71], v[110:111]
	v_mov_b64_e32 v[132:133], s[28:29]
	v_and_b32_e32 v116, 0x7fffffff, v104
	v_and_b32_e32 v117, 0x7fffffff, v105
	v_pk_fma_f32 v[116:117], v[116:117], s[24:25], 1.0 op_sel_hi:[1,0,0]
	v_pk_mul_f32 v[218:219], v[104:105], v[104:105]
	v_rcp_f32_e32 v116, v116
	v_rcp_f32_e32 v117, v117
	v_pk_mul_f32 v[218:219], v[218:219], s[38:39] op_sel_hi:[1,0]
	v_and_b32_e32 v118, 0x7fffffff, v106
	v_and_b32_e32 v119, 0x7fffffff, v107
	v_pk_fma_f32 v[118:119], v[118:119], s[24:25], 1.0 op_sel_hi:[1,0,0]
	v_pk_mul_f32 v[220:221], v[106:107], v[106:107]
	v_rcp_f32_e32 v118, v118
	v_rcp_f32_e32 v119, v119
	v_pk_mul_f32 v[220:221], v[220:221], s[38:39] op_sel_hi:[1,0]
	v_and_b32_e32 v120, 0x7fffffff, v108
	v_and_b32_e32 v121, 0x7fffffff, v109
	v_pk_fma_f32 v[120:121], v[120:121], s[24:25], 1.0 op_sel_hi:[1,0,0]
	v_pk_mul_f32 v[222:223], v[108:109], v[108:109]
	v_rcp_f32_e32 v120, v120
	v_rcp_f32_e32 v121, v121
	v_pk_mul_f32 v[222:223], v[222:223], s[38:39] op_sel_hi:[1,0]
	v_and_b32_e32 v122, 0x7fffffff, v110
	v_and_b32_e32 v123, 0x7fffffff, v111
	v_pk_fma_f32 v[122:123], v[122:123], s[24:25], 1.0 op_sel_hi:[1,0,0]
	v_pk_mul_f32 v[224:225], v[110:111], v[110:111]
	v_rcp_f32_e32 v122, v122
	v_rcp_f32_e32 v123, v123
	v_pk_mul_f32 v[224:225], v[224:225], s[38:39] op_sel_hi:[1,0]
	v_pk_fma_f32 v[124:125], v[116:117], s[26:27], v[132:133] op_sel_hi:[1,0,0]
	v_exp_f32_e32 v218, v218
	v_pk_fma_f32 v[124:125], v[116:117], v[124:125], s[30:31] op_sel_hi:[1,1,0]
	v_exp_f32_e32 v219, v219
	v_pk_fma_f32 v[124:125], v[116:117], v[124:125], s[34:35] op_sel_hi:[1,1,0]
	v_pk_fma_f32 v[124:125], v[116:117], v[124:125], s[36:37] op_sel_hi:[1,1,0]
	v_pk_mul_f32 v[124:125], v[116:117], v[124:125]
	v_pk_fma_f32 v[126:127], v[118:119], s[26:27], v[132:133] op_sel_hi:[1,0,0]
	v_exp_f32_e32 v220, v220
	v_pk_fma_f32 v[126:127], v[118:119], v[126:127], s[30:31] op_sel_hi:[1,1,0]
	v_exp_f32_e32 v221, v221
	v_pk_fma_f32 v[126:127], v[118:119], v[126:127], s[34:35] op_sel_hi:[1,1,0]
	v_pk_fma_f32 v[126:127], v[118:119], v[126:127], s[36:37] op_sel_hi:[1,1,0]
	v_pk_mul_f32 v[126:127], v[118:119], v[126:127]
	v_pk_fma_f32 v[128:129], v[120:121], s[26:27], v[132:133] op_sel_hi:[1,0,0]
	v_exp_f32_e32 v222, v222
	v_pk_fma_f32 v[128:129], v[120:121], v[128:129], s[30:31] op_sel_hi:[1,1,0]
	v_exp_f32_e32 v223, v223
	v_pk_fma_f32 v[128:129], v[120:121], v[128:129], s[34:35] op_sel_hi:[1,1,0]
	v_pk_fma_f32 v[128:129], v[120:121], v[128:129], s[36:37] op_sel_hi:[1,1,0]
	v_pk_mul_f32 v[128:129], v[120:121], v[128:129]
	v_pk_fma_f32 v[130:131], v[122:123], s[26:27], v[132:133] op_sel_hi:[1,0,0]
	v_exp_f32_e32 v224, v224
	v_pk_fma_f32 v[130:131], v[122:123], v[130:131], s[30:31] op_sel_hi:[1,1,0]
	v_exp_f32_e32 v225, v225
	v_pk_fma_f32 v[130:131], v[122:123], v[130:131], s[34:35] op_sel_hi:[1,1,0]
	v_pk_fma_f32 v[130:131], v[122:123], v[130:131], s[36:37] op_sel_hi:[1,1,0]
	v_pk_mul_f32 v[130:131], v[122:123], v[130:131]
	v_pk_mul_f32 v[124:125], v[218:219], v[124:125]
	v_pk_mul_f32 v[218:219], v[104:105], v[124:125]
	v_pk_fma_f32 v[124:125], v[104:105], v[124:125], v[104:105] neg_lo:[1,0,0] neg_hi:[1,0,0]
	v_cmp_gt_f32_e64 s[8:9], 0, v104
	v_cmp_gt_f32_e64 s[22:23], 0, v105
	v_lshlrev_b32_e32 v112, 16, v88
	v_and_b32_e32 v113, 0xffff0000, v88
	v_cndmask_b32_e64 v104, v124, v218, s[8:9]
	v_cndmask_b32_e64 v105, v125, v219, s[22:23]
	v_pk_mul_f32 v[104:105], v[104:105], v[112:113]
	v_cvt_pk_bf16_f32 v226, v104, v105
	v_pk_mul_f32 v[126:127], v[220:221], v[126:127]
	v_pk_mul_f32 v[220:221], v[106:107], v[126:127]
	v_pk_fma_f32 v[126:127], v[106:107], v[126:127], v[106:107] neg_lo:[1,0,0] neg_hi:[1,0,0]
	v_cmp_gt_f32_e64 s[8:9], 0, v106
	v_cmp_gt_f32_e64 s[22:23], 0, v107
	v_lshlrev_b32_e32 v112, 16, v89
	v_and_b32_e32 v113, 0xffff0000, v89
	v_cndmask_b32_e64 v106, v126, v220, s[8:9]
	v_cndmask_b32_e64 v107, v127, v221, s[22:23]
	v_pk_mul_f32 v[106:107], v[106:107], v[112:113]
	v_cvt_pk_bf16_f32 v227, v106, v107
	v_pk_mul_f32 v[128:129], v[222:223], v[128:129]
	v_pk_mul_f32 v[222:223], v[108:109], v[128:129]
	v_pk_fma_f32 v[128:129], v[108:109], v[128:129], v[108:109] neg_lo:[1,0,0] neg_hi:[1,0,0]
	v_cmp_gt_f32_e64 s[8:9], 0, v108
	v_cmp_gt_f32_e64 s[22:23], 0, v109
	v_lshlrev_b32_e32 v112, 16, v90
	v_and_b32_e32 v113, 0xffff0000, v90
	v_cndmask_b32_e64 v108, v128, v222, s[8:9]
	v_cndmask_b32_e64 v109, v129, v223, s[22:23]
	v_pk_mul_f32 v[108:109], v[108:109], v[112:113]
	v_cvt_pk_bf16_f32 v228, v108, v109
	v_pk_mul_f32 v[130:131], v[224:225], v[130:131]
	v_pk_mul_f32 v[224:225], v[110:111], v[130:131]
	v_pk_fma_f32 v[130:131], v[110:111], v[130:131], v[110:111] neg_lo:[1,0,0] neg_hi:[1,0,0]
	v_cmp_gt_f32_e64 s[8:9], 0, v110
	v_cmp_gt_f32_e64 s[22:23], 0, v111
	v_lshlrev_b32_e32 v112, 16, v91
	v_and_b32_e32 v113, 0xffff0000, v91
	v_cndmask_b32_e64 v110, v130, v224, s[8:9]
	v_cndmask_b32_e64 v111, v131, v225, s[22:23]
	v_pk_mul_f32 v[110:111], v[110:111], v[112:113]
	v_cvt_pk_bf16_f32 v229, v110, v111
	global_store_dwordx4 v140, v[226:229], s[14:15] sc1
	v_add_u32_e32 v140, 0x2c00, v140
	global_load_dwordx4 v[170:173], v136, s[14:15]
	global_load_dwordx4 v[174:177], v137, s[14:15]
	global_load_dwordx4 v[178:181], v138, s[14:15]
	v_add_u32_e32 v136, 0x2c00, v136
	v_add_u32_e32 v137, 0x2c00, v137
	v_add_u32_e32 v138, 0x2c00, v138
	global_load_dwordx4 v[84:87], v139, s[14:15]
	v_add_u32_e32 v139, 0x2c00, v139
	s_waitcnt vmcnt(16)
	v_mov_b64_e32 v[104:105], v[72:73]
	v_mov_b64_e32 v[106:107], v[74:75]
	v_mov_b64_e32 v[108:109], v[76:77]
	v_mov_b64_e32 v[110:111], v[78:79]
	v_lshlrev_b32_e32 v112, 16, v182
	v_and_b32_e32 v113, 0xffff0000, v182
	v_pk_fma_f32 v[104:105], v[112:113], v[0:1], v[104:105]
	v_lshlrev_b32_e32 v114, 16, v183
	v_and_b32_e32 v115, 0xffff0000, v183
	v_pk_fma_f32 v[106:107], v[114:115], v[2:3], v[106:107]
	v_lshlrev_b32_e32 v112, 16, v184
	v_and_b32_e32 v113, 0xffff0000, v184
	v_pk_fma_f32 v[108:109], v[112:113], v[4:5], v[108:109]
	v_lshlrev_b32_e32 v114, 16, v185
	v_and_b32_e32 v115, 0xffff0000, v185
	v_pk_fma_f32 v[110:111], v[114:115], v[6:7], v[110:111]
	v_lshlrev_b32_e32 v112, 16, v194
	v_and_b32_e32 v113, 0xffff0000, v194
	v_pk_fma_f32 v[104:105], v[112:113], v[8:9], v[104:105]
	v_lshlrev_b32_e32 v114, 16, v195
	v_and_b32_e32 v115, 0xffff0000, v195
	v_pk_fma_f32 v[106:107], v[114:115], v[10:11], v[106:107]
	v_lshlrev_b32_e32 v112, 16, v196
	v_and_b32_e32 v113, 0xffff0000, v196
	v_pk_fma_f32 v[108:109], v[112:113], v[12:13], v[108:109]
	v_lshlrev_b32_e32 v114, 16, v197
	v_and_b32_e32 v115, 0xffff0000, v197
	v_pk_fma_f32 v[110:111], v[114:115], v[14:15], v[110:111]
	v_lshlrev_b32_e32 v112, 16, v206
	v_and_b32_e32 v113, 0xffff0000, v206
	v_pk_fma_f32 v[104:105], v[112:113], v[16:17], v[104:105]
	v_lshlrev_b32_e32 v114, 16, v207
	v_and_b32_e32 v115, 0xffff0000, v207
	v_pk_fma_f32 v[106:107], v[114:115], v[18:19], v[106:107]
	v_lshlrev_b32_e32 v112, 16, v208
	v_and_b32_e32 v113, 0xffff0000, v208
	v_pk_fma_f32 v[108:109], v[112:113], v[20:21], v[108:109]
	v_lshlrev_b32_e32 v114, 16, v209
	v_and_b32_e32 v115, 0xffff0000, v209
	v_pk_fma_f32 v[110:111], v[114:115], v[22:23], v[110:111]
	v_lshlrev_b32_e32 v112, 16, v186
	v_and_b32_e32 v113, 0xffff0000, v186
	v_pk_fma_f32 v[104:105], v[112:113], v[24:25], v[104:105]
	v_lshlrev_b32_e32 v114, 16, v187
	v_and_b32_e32 v115, 0xffff0000, v187
	v_pk_fma_f32 v[106:107], v[114:115], v[26:27], v[106:107]
	v_lshlrev_b32_e32 v112, 16, v188
	v_and_b32_e32 v113, 0xffff0000, v188
	v_pk_fma_f32 v[108:109], v[112:113], v[28:29], v[108:109]
	v_lshlrev_b32_e32 v114, 16, v189
	v_and_b32_e32 v115, 0xffff0000, v189
	v_pk_fma_f32 v[110:111], v[114:115], v[30:31], v[110:111]
	v_lshlrev_b32_e32 v112, 16, v198
	v_and_b32_e32 v113, 0xffff0000, v198
	v_pk_fma_f32 v[104:105], v[112:113], v[32:33], v[104:105]
	v_lshlrev_b32_e32 v114, 16, v199
	v_and_b32_e32 v115, 0xffff0000, v199
	v_pk_fma_f32 v[106:107], v[114:115], v[34:35], v[106:107]
	v_lshlrev_b32_e32 v112, 16, v200
	v_and_b32_e32 v113, 0xffff0000, v200
	v_pk_fma_f32 v[108:109], v[112:113], v[36:37], v[108:109]
	v_lshlrev_b32_e32 v114, 16, v201
	v_and_b32_e32 v115, 0xffff0000, v201
	v_pk_fma_f32 v[110:111], v[114:115], v[38:39], v[110:111]
	v_lshlrev_b32_e32 v112, 16, v210
	v_and_b32_e32 v113, 0xffff0000, v210
	v_pk_fma_f32 v[104:105], v[112:113], v[40:41], v[104:105]
	v_lshlrev_b32_e32 v114, 16, v211
	v_and_b32_e32 v115, 0xffff0000, v211
	v_pk_fma_f32 v[106:107], v[114:115], v[42:43], v[106:107]
	v_lshlrev_b32_e32 v112, 16, v212
	v_and_b32_e32 v113, 0xffff0000, v212
	v_pk_fma_f32 v[108:109], v[112:113], v[44:45], v[108:109]
	v_lshlrev_b32_e32 v114, 16, v213
	v_and_b32_e32 v115, 0xffff0000, v213
	v_pk_fma_f32 v[110:111], v[114:115], v[46:47], v[110:111]
	v_lshlrev_b32_e32 v112, 16, v190
	v_and_b32_e32 v113, 0xffff0000, v190
	v_pk_fma_f32 v[104:105], v[112:113], v[48:49], v[104:105]
	v_lshlrev_b32_e32 v114, 16, v191
	v_and_b32_e32 v115, 0xffff0000, v191
	v_pk_fma_f32 v[106:107], v[114:115], v[50:51], v[106:107]
	v_lshlrev_b32_e32 v112, 16, v192
	v_and_b32_e32 v113, 0xffff0000, v192
	v_pk_fma_f32 v[108:109], v[112:113], v[52:53], v[108:109]
	v_lshlrev_b32_e32 v114, 16, v193
	v_and_b32_e32 v115, 0xffff0000, v193
	v_pk_fma_f32 v[110:111], v[114:115], v[54:55], v[110:111]
	v_lshlrev_b32_e32 v112, 16, v202
	v_and_b32_e32 v113, 0xffff0000, v202
	v_pk_fma_f32 v[104:105], v[112:113], v[56:57], v[104:105]
	v_lshlrev_b32_e32 v114, 16, v203
	v_and_b32_e32 v115, 0xffff0000, v203
	v_pk_fma_f32 v[106:107], v[114:115], v[58:59], v[106:107]
	v_lshlrev_b32_e32 v112, 16, v204
	v_and_b32_e32 v113, 0xffff0000, v204
	v_pk_fma_f32 v[108:109], v[112:113], v[60:61], v[108:109]
	v_lshlrev_b32_e32 v114, 16, v205
	v_and_b32_e32 v115, 0xffff0000, v205
	v_pk_fma_f32 v[110:111], v[114:115], v[62:63], v[110:111]
	v_lshlrev_b32_e32 v112, 16, v214
	v_and_b32_e32 v113, 0xffff0000, v214
	v_pk_fma_f32 v[104:105], v[112:113], v[64:65], v[104:105]
	v_lshlrev_b32_e32 v114, 16, v215
	v_and_b32_e32 v115, 0xffff0000, v215
	v_pk_fma_f32 v[106:107], v[114:115], v[66:67], v[106:107]
	v_lshlrev_b32_e32 v112, 16, v216
	v_and_b32_e32 v113, 0xffff0000, v216
	v_pk_fma_f32 v[108:109], v[112:113], v[68:69], v[108:109]
	v_lshlrev_b32_e32 v114, 16, v217
	v_and_b32_e32 v115, 0xffff0000, v217
	v_pk_fma_f32 v[110:111], v[114:115], v[70:71], v[110:111]
	v_mov_b64_e32 v[132:133], s[28:29]
	v_and_b32_e32 v116, 0x7fffffff, v104
	v_and_b32_e32 v117, 0x7fffffff, v105
	v_pk_fma_f32 v[116:117], v[116:117], s[24:25], 1.0 op_sel_hi:[1,0,0]
	v_pk_mul_f32 v[218:219], v[104:105], v[104:105]
	v_rcp_f32_e32 v116, v116
	v_rcp_f32_e32 v117, v117
	v_pk_mul_f32 v[218:219], v[218:219], s[38:39] op_sel_hi:[1,0]
	v_and_b32_e32 v118, 0x7fffffff, v106
	v_and_b32_e32 v119, 0x7fffffff, v107
	v_pk_fma_f32 v[118:119], v[118:119], s[24:25], 1.0 op_sel_hi:[1,0,0]
	v_pk_mul_f32 v[220:221], v[106:107], v[106:107]
	v_rcp_f32_e32 v118, v118
	v_rcp_f32_e32 v119, v119
	v_pk_mul_f32 v[220:221], v[220:221], s[38:39] op_sel_hi:[1,0]
	v_and_b32_e32 v120, 0x7fffffff, v108
	v_and_b32_e32 v121, 0x7fffffff, v109
	v_pk_fma_f32 v[120:121], v[120:121], s[24:25], 1.0 op_sel_hi:[1,0,0]
	v_pk_mul_f32 v[222:223], v[108:109], v[108:109]
	v_rcp_f32_e32 v120, v120
	v_rcp_f32_e32 v121, v121
	v_pk_mul_f32 v[222:223], v[222:223], s[38:39] op_sel_hi:[1,0]
	v_and_b32_e32 v122, 0x7fffffff, v110
	v_and_b32_e32 v123, 0x7fffffff, v111
	v_pk_fma_f32 v[122:123], v[122:123], s[24:25], 1.0 op_sel_hi:[1,0,0]
	v_pk_mul_f32 v[224:225], v[110:111], v[110:111]
	v_rcp_f32_e32 v122, v122
	v_rcp_f32_e32 v123, v123
	v_pk_mul_f32 v[224:225], v[224:225], s[38:39] op_sel_hi:[1,0]
	v_pk_fma_f32 v[124:125], v[116:117], s[26:27], v[132:133] op_sel_hi:[1,0,0]
	v_exp_f32_e32 v218, v218
	v_pk_fma_f32 v[124:125], v[116:117], v[124:125], s[30:31] op_sel_hi:[1,1,0]
	v_exp_f32_e32 v219, v219
	v_pk_fma_f32 v[124:125], v[116:117], v[124:125], s[34:35] op_sel_hi:[1,1,0]
	v_pk_fma_f32 v[124:125], v[116:117], v[124:125], s[36:37] op_sel_hi:[1,1,0]
	v_pk_mul_f32 v[124:125], v[116:117], v[124:125]
	v_pk_fma_f32 v[126:127], v[118:119], s[26:27], v[132:133] op_sel_hi:[1,0,0]
	v_exp_f32_e32 v220, v220
	v_pk_fma_f32 v[126:127], v[118:119], v[126:127], s[30:31] op_sel_hi:[1,1,0]
	v_exp_f32_e32 v221, v221
	v_pk_fma_f32 v[126:127], v[118:119], v[126:127], s[34:35] op_sel_hi:[1,1,0]
	v_pk_fma_f32 v[126:127], v[118:119], v[126:127], s[36:37] op_sel_hi:[1,1,0]
	v_pk_mul_f32 v[126:127], v[118:119], v[126:127]
	v_pk_fma_f32 v[128:129], v[120:121], s[26:27], v[132:133] op_sel_hi:[1,0,0]
	v_exp_f32_e32 v222, v222
	v_pk_fma_f32 v[128:129], v[120:121], v[128:129], s[30:31] op_sel_hi:[1,1,0]
	v_exp_f32_e32 v223, v223
	v_pk_fma_f32 v[128:129], v[120:121], v[128:129], s[34:35] op_sel_hi:[1,1,0]
	v_pk_fma_f32 v[128:129], v[120:121], v[128:129], s[36:37] op_sel_hi:[1,1,0]
	v_pk_mul_f32 v[128:129], v[120:121], v[128:129]
	v_pk_fma_f32 v[130:131], v[122:123], s[26:27], v[132:133] op_sel_hi:[1,0,0]
	v_exp_f32_e32 v224, v224
	v_pk_fma_f32 v[130:131], v[122:123], v[130:131], s[30:31] op_sel_hi:[1,1,0]
	v_exp_f32_e32 v225, v225
	v_pk_fma_f32 v[130:131], v[122:123], v[130:131], s[34:35] op_sel_hi:[1,1,0]
	v_pk_fma_f32 v[130:131], v[122:123], v[130:131], s[36:37] op_sel_hi:[1,1,0]
	v_pk_mul_f32 v[130:131], v[122:123], v[130:131]
	v_pk_mul_f32 v[124:125], v[218:219], v[124:125]
	v_pk_mul_f32 v[218:219], v[104:105], v[124:125]
	v_pk_fma_f32 v[124:125], v[104:105], v[124:125], v[104:105] neg_lo:[1,0,0] neg_hi:[1,0,0]
	v_cmp_gt_f32_e64 s[8:9], 0, v104
	v_cmp_gt_f32_e64 s[22:23], 0, v105
	v_lshlrev_b32_e32 v112, 16, v92
	v_and_b32_e32 v113, 0xffff0000, v92
	v_cndmask_b32_e64 v104, v124, v218, s[8:9]
	v_cndmask_b32_e64 v105, v125, v219, s[22:23]
	v_pk_mul_f32 v[104:105], v[104:105], v[112:113]
	v_cvt_pk_bf16_f32 v226, v104, v105
	v_pk_mul_f32 v[126:127], v[220:221], v[126:127]
	v_pk_mul_f32 v[220:221], v[106:107], v[126:127]
	v_pk_fma_f32 v[126:127], v[106:107], v[126:127], v[106:107] neg_lo:[1,0,0] neg_hi:[1,0,0]
	v_cmp_gt_f32_e64 s[8:9], 0, v106
	v_cmp_gt_f32_e64 s[22:23], 0, v107
	v_lshlrev_b32_e32 v112, 16, v93
	v_and_b32_e32 v113, 0xffff0000, v93
	v_cndmask_b32_e64 v106, v126, v220, s[8:9]
	v_cndmask_b32_e64 v107, v127, v221, s[22:23]
	v_pk_mul_f32 v[106:107], v[106:107], v[112:113]
	v_cvt_pk_bf16_f32 v227, v106, v107
	v_pk_mul_f32 v[128:129], v[222:223], v[128:129]
	v_pk_mul_f32 v[222:223], v[108:109], v[128:129]
	v_pk_fma_f32 v[128:129], v[108:109], v[128:129], v[108:109] neg_lo:[1,0,0] neg_hi:[1,0,0]
	v_cmp_gt_f32_e64 s[8:9], 0, v108
	v_cmp_gt_f32_e64 s[22:23], 0, v109
	v_lshlrev_b32_e32 v112, 16, v94
	v_and_b32_e32 v113, 0xffff0000, v94
	v_cndmask_b32_e64 v108, v128, v222, s[8:9]
	v_cndmask_b32_e64 v109, v129, v223, s[22:23]
	v_pk_mul_f32 v[108:109], v[108:109], v[112:113]
	v_cvt_pk_bf16_f32 v228, v108, v109
	v_pk_mul_f32 v[130:131], v[224:225], v[130:131]
	v_pk_mul_f32 v[224:225], v[110:111], v[130:131]
	v_pk_fma_f32 v[130:131], v[110:111], v[130:131], v[110:111] neg_lo:[1,0,0] neg_hi:[1,0,0]
	v_cmp_gt_f32_e64 s[8:9], 0, v110
	v_cmp_gt_f32_e64 s[22:23], 0, v111
	v_lshlrev_b32_e32 v112, 16, v95
	v_and_b32_e32 v113, 0xffff0000, v95
	v_cndmask_b32_e64 v110, v130, v224, s[8:9]
	v_cndmask_b32_e64 v111, v131, v225, s[22:23]
	v_pk_mul_f32 v[110:111], v[110:111], v[112:113]
	v_cvt_pk_bf16_f32 v229, v110, v111
	global_store_dwordx4 v140, v[226:229], s[14:15] sc1
	v_add_u32_e32 v140, 0x2c00, v140
	global_load_dwordx4 v[182:185], v136, s[14:15]
	global_load_dwordx4 v[186:189], v137, s[14:15]
	global_load_dwordx4 v[190:193], v138, s[14:15]
	v_add_u32_e32 v136, 0x2c00, v136
	v_add_u32_e32 v137, 0x2c00, v137
	v_add_u32_e32 v138, 0x2c00, v138
	global_load_dwordx4 v[88:91], v139, s[14:15]
	v_add_u32_e32 v139, 0x2c00, v139
	s_waitcnt vmcnt(16)
	v_mov_b64_e32 v[104:105], v[72:73]
	v_mov_b64_e32 v[106:107], v[74:75]
	v_mov_b64_e32 v[108:109], v[76:77]
	v_mov_b64_e32 v[110:111], v[78:79]
	v_lshlrev_b32_e32 v112, 16, v194
	v_and_b32_e32 v113, 0xffff0000, v194
	v_pk_fma_f32 v[104:105], v[112:113], v[0:1], v[104:105]
	v_lshlrev_b32_e32 v114, 16, v195
	v_and_b32_e32 v115, 0xffff0000, v195
	v_pk_fma_f32 v[106:107], v[114:115], v[2:3], v[106:107]
	v_lshlrev_b32_e32 v112, 16, v196
	v_and_b32_e32 v113, 0xffff0000, v196
	v_pk_fma_f32 v[108:109], v[112:113], v[4:5], v[108:109]
	v_lshlrev_b32_e32 v114, 16, v197
	v_and_b32_e32 v115, 0xffff0000, v197
	v_pk_fma_f32 v[110:111], v[114:115], v[6:7], v[110:111]
	v_lshlrev_b32_e32 v112, 16, v206
	v_and_b32_e32 v113, 0xffff0000, v206
	v_pk_fma_f32 v[104:105], v[112:113], v[8:9], v[104:105]
	v_lshlrev_b32_e32 v114, 16, v207
	v_and_b32_e32 v115, 0xffff0000, v207
	v_pk_fma_f32 v[106:107], v[114:115], v[10:11], v[106:107]
	v_lshlrev_b32_e32 v112, 16, v208
	v_and_b32_e32 v113, 0xffff0000, v208
	v_pk_fma_f32 v[108:109], v[112:113], v[12:13], v[108:109]
	v_lshlrev_b32_e32 v114, 16, v209
	v_and_b32_e32 v115, 0xffff0000, v209
	v_pk_fma_f32 v[110:111], v[114:115], v[14:15], v[110:111]
	v_lshlrev_b32_e32 v112, 16, v146
	v_and_b32_e32 v113, 0xffff0000, v146
	v_pk_fma_f32 v[104:105], v[112:113], v[16:17], v[104:105]
	v_lshlrev_b32_e32 v114, 16, v147
	v_and_b32_e32 v115, 0xffff0000, v147
	v_pk_fma_f32 v[106:107], v[114:115], v[18:19], v[106:107]
	v_lshlrev_b32_e32 v112, 16, v148
	v_and_b32_e32 v113, 0xffff0000, v148
	v_pk_fma_f32 v[108:109], v[112:113], v[20:21], v[108:109]
	v_lshlrev_b32_e32 v114, 16, v149
	v_and_b32_e32 v115, 0xffff0000, v149
	v_pk_fma_f32 v[110:111], v[114:115], v[22:23], v[110:111]
	v_lshlrev_b32_e32 v112, 16, v198
	v_and_b32_e32 v113, 0xffff0000, v198
	v_pk_fma_f32 v[104:105], v[112:113], v[24:25], v[104:105]
	v_lshlrev_b32_e32 v114, 16, v199
	v_and_b32_e32 v115, 0xffff0000, v199
	v_pk_fma_f32 v[106:107], v[114:115], v[26:27], v[106:107]
	v_lshlrev_b32_e32 v112, 16, v200
	v_and_b32_e32 v113, 0xffff0000, v200
	v_pk_fma_f32 v[108:109], v[112:113], v[28:29], v[108:109]
	v_lshlrev_b32_e32 v114, 16, v201
	v_and_b32_e32 v115, 0xffff0000, v201
	v_pk_fma_f32 v[110:111], v[114:115], v[30:31], v[110:111]
	v_lshlrev_b32_e32 v112, 16, v210
	v_and_b32_e32 v113, 0xffff0000, v210
	v_pk_fma_f32 v[104:105], v[112:113], v[32:33], v[104:105]
	v_lshlrev_b32_e32 v114, 16, v211
	v_and_b32_e32 v115, 0xffff0000, v211
	v_pk_fma_f32 v[106:107], v[114:115], v[34:35], v[106:107]
	v_lshlrev_b32_e32 v112, 16, v212
	v_and_b32_e32 v113, 0xffff0000, v212
	v_pk_fma_f32 v[108:109], v[112:113], v[36:37], v[108:109]
	v_lshlrev_b32_e32 v114, 16, v213
	v_and_b32_e32 v115, 0xffff0000, v213
	v_pk_fma_f32 v[110:111], v[114:115], v[38:39], v[110:111]
	v_lshlrev_b32_e32 v112, 16, v150
	v_and_b32_e32 v113, 0xffff0000, v150
	v_pk_fma_f32 v[104:105], v[112:113], v[40:41], v[104:105]
	v_lshlrev_b32_e32 v114, 16, v151
	v_and_b32_e32 v115, 0xffff0000, v151
	v_pk_fma_f32 v[106:107], v[114:115], v[42:43], v[106:107]
	v_lshlrev_b32_e32 v112, 16, v152
	v_and_b32_e32 v113, 0xffff0000, v152
	v_pk_fma_f32 v[108:109], v[112:113], v[44:45], v[108:109]
	v_lshlrev_b32_e32 v114, 16, v153
	v_and_b32_e32 v115, 0xffff0000, v153
	v_pk_fma_f32 v[110:111], v[114:115], v[46:47], v[110:111]
	v_lshlrev_b32_e32 v112, 16, v202
	v_and_b32_e32 v113, 0xffff0000, v202
	v_pk_fma_f32 v[104:105], v[112:113], v[48:49], v[104:105]
	v_lshlrev_b32_e32 v114, 16, v203
	v_and_b32_e32 v115, 0xffff0000, v203
	v_pk_fma_f32 v[106:107], v[114:115], v[50:51], v[106:107]
	v_lshlrev_b32_e32 v112, 16, v204
	v_and_b32_e32 v113, 0xffff0000, v204
	v_pk_fma_f32 v[108:109], v[112:113], v[52:53], v[108:109]
	v_lshlrev_b32_e32 v114, 16, v205
	v_and_b32_e32 v115, 0xffff0000, v205
	v_pk_fma_f32 v[110:111], v[114:115], v[54:55], v[110:111]
	v_lshlrev_b32_e32 v112, 16, v214
	v_and_b32_e32 v113, 0xffff0000, v214
	v_pk_fma_f32 v[104:105], v[112:113], v[56:57], v[104:105]
	v_lshlrev_b32_e32 v114, 16, v215
	v_and_b32_e32 v115, 0xffff0000, v215
	v_pk_fma_f32 v[106:107], v[114:115], v[58:59], v[106:107]
	v_lshlrev_b32_e32 v112, 16, v216
	v_and_b32_e32 v113, 0xffff0000, v216
	v_pk_fma_f32 v[108:109], v[112:113], v[60:61], v[108:109]
	v_lshlrev_b32_e32 v114, 16, v217
	v_and_b32_e32 v115, 0xffff0000, v217
	v_pk_fma_f32 v[110:111], v[114:115], v[62:63], v[110:111]
	v_lshlrev_b32_e32 v112, 16, v154
	v_and_b32_e32 v113, 0xffff0000, v154
	v_pk_fma_f32 v[104:105], v[112:113], v[64:65], v[104:105]
	v_lshlrev_b32_e32 v114, 16, v155
	v_and_b32_e32 v115, 0xffff0000, v155
	v_pk_fma_f32 v[106:107], v[114:115], v[66:67], v[106:107]
	v_lshlrev_b32_e32 v112, 16, v156
	v_and_b32_e32 v113, 0xffff0000, v156
	v_pk_fma_f32 v[108:109], v[112:113], v[68:69], v[108:109]
	v_lshlrev_b32_e32 v114, 16, v157
	v_and_b32_e32 v115, 0xffff0000, v157
	v_pk_fma_f32 v[110:111], v[114:115], v[70:71], v[110:111]
	v_mov_b64_e32 v[132:133], s[28:29]
	v_and_b32_e32 v116, 0x7fffffff, v104
	v_and_b32_e32 v117, 0x7fffffff, v105
	v_pk_fma_f32 v[116:117], v[116:117], s[24:25], 1.0 op_sel_hi:[1,0,0]
	v_pk_mul_f32 v[218:219], v[104:105], v[104:105]
	v_rcp_f32_e32 v116, v116
	v_rcp_f32_e32 v117, v117
	v_pk_mul_f32 v[218:219], v[218:219], s[38:39] op_sel_hi:[1,0]
	v_and_b32_e32 v118, 0x7fffffff, v106
	v_and_b32_e32 v119, 0x7fffffff, v107
	v_pk_fma_f32 v[118:119], v[118:119], s[24:25], 1.0 op_sel_hi:[1,0,0]
	v_pk_mul_f32 v[220:221], v[106:107], v[106:107]
	v_rcp_f32_e32 v118, v118
	v_rcp_f32_e32 v119, v119
	v_pk_mul_f32 v[220:221], v[220:221], s[38:39] op_sel_hi:[1,0]
	v_and_b32_e32 v120, 0x7fffffff, v108
	v_and_b32_e32 v121, 0x7fffffff, v109
	v_pk_fma_f32 v[120:121], v[120:121], s[24:25], 1.0 op_sel_hi:[1,0,0]
	v_pk_mul_f32 v[222:223], v[108:109], v[108:109]
	v_rcp_f32_e32 v120, v120
	v_rcp_f32_e32 v121, v121
	v_pk_mul_f32 v[222:223], v[222:223], s[38:39] op_sel_hi:[1,0]
	v_and_b32_e32 v122, 0x7fffffff, v110
	v_and_b32_e32 v123, 0x7fffffff, v111
	v_pk_fma_f32 v[122:123], v[122:123], s[24:25], 1.0 op_sel_hi:[1,0,0]
	v_pk_mul_f32 v[224:225], v[110:111], v[110:111]
	v_rcp_f32_e32 v122, v122
	v_rcp_f32_e32 v123, v123
	v_pk_mul_f32 v[224:225], v[224:225], s[38:39] op_sel_hi:[1,0]
	v_pk_fma_f32 v[124:125], v[116:117], s[26:27], v[132:133] op_sel_hi:[1,0,0]
	v_exp_f32_e32 v218, v218
	v_pk_fma_f32 v[124:125], v[116:117], v[124:125], s[30:31] op_sel_hi:[1,1,0]
	v_exp_f32_e32 v219, v219
	v_pk_fma_f32 v[124:125], v[116:117], v[124:125], s[34:35] op_sel_hi:[1,1,0]
	v_pk_fma_f32 v[124:125], v[116:117], v[124:125], s[36:37] op_sel_hi:[1,1,0]
	v_pk_mul_f32 v[124:125], v[116:117], v[124:125]
	v_pk_fma_f32 v[126:127], v[118:119], s[26:27], v[132:133] op_sel_hi:[1,0,0]
	v_exp_f32_e32 v220, v220
	v_pk_fma_f32 v[126:127], v[118:119], v[126:127], s[30:31] op_sel_hi:[1,1,0]
	v_exp_f32_e32 v221, v221
	v_pk_fma_f32 v[126:127], v[118:119], v[126:127], s[34:35] op_sel_hi:[1,1,0]
	v_pk_fma_f32 v[126:127], v[118:119], v[126:127], s[36:37] op_sel_hi:[1,1,0]
	v_pk_mul_f32 v[126:127], v[118:119], v[126:127]
	v_pk_fma_f32 v[128:129], v[120:121], s[26:27], v[132:133] op_sel_hi:[1,0,0]
	v_exp_f32_e32 v222, v222
	v_pk_fma_f32 v[128:129], v[120:121], v[128:129], s[30:31] op_sel_hi:[1,1,0]
	v_exp_f32_e32 v223, v223
	v_pk_fma_f32 v[128:129], v[120:121], v[128:129], s[34:35] op_sel_hi:[1,1,0]
	v_pk_fma_f32 v[128:129], v[120:121], v[128:129], s[36:37] op_sel_hi:[1,1,0]
	v_pk_mul_f32 v[128:129], v[120:121], v[128:129]
	v_pk_fma_f32 v[130:131], v[122:123], s[26:27], v[132:133] op_sel_hi:[1,0,0]
	v_exp_f32_e32 v224, v224
	v_pk_fma_f32 v[130:131], v[122:123], v[130:131], s[30:31] op_sel_hi:[1,1,0]
	v_exp_f32_e32 v225, v225
	v_pk_fma_f32 v[130:131], v[122:123], v[130:131], s[34:35] op_sel_hi:[1,1,0]
	v_pk_fma_f32 v[130:131], v[122:123], v[130:131], s[36:37] op_sel_hi:[1,1,0]
	v_pk_mul_f32 v[130:131], v[122:123], v[130:131]
	v_pk_mul_f32 v[124:125], v[218:219], v[124:125]
	v_pk_mul_f32 v[218:219], v[104:105], v[124:125]
	v_pk_fma_f32 v[124:125], v[104:105], v[124:125], v[104:105] neg_lo:[1,0,0] neg_hi:[1,0,0]
	v_cmp_gt_f32_e64 s[8:9], 0, v104
	v_cmp_gt_f32_e64 s[22:23], 0, v105
	v_lshlrev_b32_e32 v112, 16, v96
	v_and_b32_e32 v113, 0xffff0000, v96
	v_cndmask_b32_e64 v104, v124, v218, s[8:9]
	v_cndmask_b32_e64 v105, v125, v219, s[22:23]
	v_pk_mul_f32 v[104:105], v[104:105], v[112:113]
	v_cvt_pk_bf16_f32 v226, v104, v105
	v_pk_mul_f32 v[126:127], v[220:221], v[126:127]
	v_pk_mul_f32 v[220:221], v[106:107], v[126:127]
	v_pk_fma_f32 v[126:127], v[106:107], v[126:127], v[106:107] neg_lo:[1,0,0] neg_hi:[1,0,0]
	v_cmp_gt_f32_e64 s[8:9], 0, v106
	v_cmp_gt_f32_e64 s[22:23], 0, v107
	v_lshlrev_b32_e32 v112, 16, v97
	v_and_b32_e32 v113, 0xffff0000, v97
	v_cndmask_b32_e64 v106, v126, v220, s[8:9]
	v_cndmask_b32_e64 v107, v127, v221, s[22:23]
	v_pk_mul_f32 v[106:107], v[106:107], v[112:113]
	v_cvt_pk_bf16_f32 v227, v106, v107
	v_pk_mul_f32 v[128:129], v[222:223], v[128:129]
	v_pk_mul_f32 v[222:223], v[108:109], v[128:129]
	v_pk_fma_f32 v[128:129], v[108:109], v[128:129], v[108:109] neg_lo:[1,0,0] neg_hi:[1,0,0]
	v_cmp_gt_f32_e64 s[8:9], 0, v108
	v_cmp_gt_f32_e64 s[22:23], 0, v109
	v_lshlrev_b32_e32 v112, 16, v98
	v_and_b32_e32 v113, 0xffff0000, v98
	v_cndmask_b32_e64 v108, v128, v222, s[8:9]
	v_cndmask_b32_e64 v109, v129, v223, s[22:23]
	v_pk_mul_f32 v[108:109], v[108:109], v[112:113]
	v_cvt_pk_bf16_f32 v228, v108, v109
	v_pk_mul_f32 v[130:131], v[224:225], v[130:131]
	v_pk_mul_f32 v[224:225], v[110:111], v[130:131]
	v_pk_fma_f32 v[130:131], v[110:111], v[130:131], v[110:111] neg_lo:[1,0,0] neg_hi:[1,0,0]
	v_cmp_gt_f32_e64 s[8:9], 0, v110
	v_cmp_gt_f32_e64 s[22:23], 0, v111
	v_lshlrev_b32_e32 v112, 16, v99
	v_and_b32_e32 v113, 0xffff0000, v99
	v_cndmask_b32_e64 v110, v130, v224, s[8:9]
	v_cndmask_b32_e64 v111, v131, v225, s[22:23]
	v_pk_mul_f32 v[110:111], v[110:111], v[112:113]
	v_cvt_pk_bf16_f32 v229, v110, v111
	global_store_dwordx4 v140, v[226:229], s[14:15] sc1
	v_add_u32_e32 v140, 0x2c00, v140
	global_load_dwordx4 v[194:197], v136, s[14:15]
	global_load_dwordx4 v[198:201], v137, s[14:15]
	global_load_dwordx4 v[202:205], v138, s[14:15]
	v_add_u32_e32 v136, 0x2c00, v136
	v_add_u32_e32 v137, 0x2c00, v137
	v_add_u32_e32 v138, 0x2c00, v138
	global_load_dwordx4 v[92:95], v139, s[14:15]
	v_add_u32_e32 v139, 0x2c00, v139
	s_waitcnt vmcnt(16)
	v_mov_b64_e32 v[104:105], v[72:73]
	v_mov_b64_e32 v[106:107], v[74:75]
	v_mov_b64_e32 v[108:109], v[76:77]
	v_mov_b64_e32 v[110:111], v[78:79]
	v_lshlrev_b32_e32 v112, 16, v206
	v_and_b32_e32 v113, 0xffff0000, v206
	v_pk_fma_f32 v[104:105], v[112:113], v[0:1], v[104:105]
	v_lshlrev_b32_e32 v114, 16, v207
	v_and_b32_e32 v115, 0xffff0000, v207
	v_pk_fma_f32 v[106:107], v[114:115], v[2:3], v[106:107]
	v_lshlrev_b32_e32 v112, 16, v208
	v_and_b32_e32 v113, 0xffff0000, v208
	v_pk_fma_f32 v[108:109], v[112:113], v[4:5], v[108:109]
	v_lshlrev_b32_e32 v114, 16, v209
	v_and_b32_e32 v115, 0xffff0000, v209
	v_pk_fma_f32 v[110:111], v[114:115], v[6:7], v[110:111]
	v_lshlrev_b32_e32 v112, 16, v146
	v_and_b32_e32 v113, 0xffff0000, v146
	v_pk_fma_f32 v[104:105], v[112:113], v[8:9], v[104:105]
	v_lshlrev_b32_e32 v114, 16, v147
	v_and_b32_e32 v115, 0xffff0000, v147
	v_pk_fma_f32 v[106:107], v[114:115], v[10:11], v[106:107]
	v_lshlrev_b32_e32 v112, 16, v148
	v_and_b32_e32 v113, 0xffff0000, v148
	v_pk_fma_f32 v[108:109], v[112:113], v[12:13], v[108:109]
	v_lshlrev_b32_e32 v114, 16, v149
	v_and_b32_e32 v115, 0xffff0000, v149
	v_pk_fma_f32 v[110:111], v[114:115], v[14:15], v[110:111]
	v_lshlrev_b32_e32 v112, 16, v158
	v_and_b32_e32 v113, 0xffff0000, v158
	v_pk_fma_f32 v[104:105], v[112:113], v[16:17], v[104:105]
	v_lshlrev_b32_e32 v114, 16, v159
	v_and_b32_e32 v115, 0xffff0000, v159
	v_pk_fma_f32 v[106:107], v[114:115], v[18:19], v[106:107]
	v_lshlrev_b32_e32 v112, 16, v160
	v_and_b32_e32 v113, 0xffff0000, v160
	v_pk_fma_f32 v[108:109], v[112:113], v[20:21], v[108:109]
	v_lshlrev_b32_e32 v114, 16, v161
	v_and_b32_e32 v115, 0xffff0000, v161
	v_pk_fma_f32 v[110:111], v[114:115], v[22:23], v[110:111]
	v_lshlrev_b32_e32 v112, 16, v210
	v_and_b32_e32 v113, 0xffff0000, v210
	v_pk_fma_f32 v[104:105], v[112:113], v[24:25], v[104:105]
	v_lshlrev_b32_e32 v114, 16, v211
	v_and_b32_e32 v115, 0xffff0000, v211
	v_pk_fma_f32 v[106:107], v[114:115], v[26:27], v[106:107]
	v_lshlrev_b32_e32 v112, 16, v212
	v_and_b32_e32 v113, 0xffff0000, v212
	v_pk_fma_f32 v[108:109], v[112:113], v[28:29], v[108:109]
	v_lshlrev_b32_e32 v114, 16, v213
	v_and_b32_e32 v115, 0xffff0000, v213
	v_pk_fma_f32 v[110:111], v[114:115], v[30:31], v[110:111]
	v_lshlrev_b32_e32 v112, 16, v150
	v_and_b32_e32 v113, 0xffff0000, v150
	v_pk_fma_f32 v[104:105], v[112:113], v[32:33], v[104:105]
	v_lshlrev_b32_e32 v114, 16, v151
	v_and_b32_e32 v115, 0xffff0000, v151
	v_pk_fma_f32 v[106:107], v[114:115], v[34:35], v[106:107]
	v_lshlrev_b32_e32 v112, 16, v152
	v_and_b32_e32 v113, 0xffff0000, v152
	v_pk_fma_f32 v[108:109], v[112:113], v[36:37], v[108:109]
	v_lshlrev_b32_e32 v114, 16, v153
	v_and_b32_e32 v115, 0xffff0000, v153
	v_pk_fma_f32 v[110:111], v[114:115], v[38:39], v[110:111]
	v_lshlrev_b32_e32 v112, 16, v162
	v_and_b32_e32 v113, 0xffff0000, v162
	v_pk_fma_f32 v[104:105], v[112:113], v[40:41], v[104:105]
	v_lshlrev_b32_e32 v114, 16, v163
	v_and_b32_e32 v115, 0xffff0000, v163
	v_pk_fma_f32 v[106:107], v[114:115], v[42:43], v[106:107]
	v_lshlrev_b32_e32 v112, 16, v164
	v_and_b32_e32 v113, 0xffff0000, v164
	v_pk_fma_f32 v[108:109], v[112:113], v[44:45], v[108:109]
	v_lshlrev_b32_e32 v114, 16, v165
	v_and_b32_e32 v115, 0xffff0000, v165
	v_pk_fma_f32 v[110:111], v[114:115], v[46:47], v[110:111]
	v_lshlrev_b32_e32 v112, 16, v214
	v_and_b32_e32 v113, 0xffff0000, v214
	v_pk_fma_f32 v[104:105], v[112:113], v[48:49], v[104:105]
	v_lshlrev_b32_e32 v114, 16, v215
	v_and_b32_e32 v115, 0xffff0000, v215
	v_pk_fma_f32 v[106:107], v[114:115], v[50:51], v[106:107]
	v_lshlrev_b32_e32 v112, 16, v216
	v_and_b32_e32 v113, 0xffff0000, v216
	v_pk_fma_f32 v[108:109], v[112:113], v[52:53], v[108:109]
	v_lshlrev_b32_e32 v114, 16, v217
	v_and_b32_e32 v115, 0xffff0000, v217
	v_pk_fma_f32 v[110:111], v[114:115], v[54:55], v[110:111]
	v_lshlrev_b32_e32 v112, 16, v154
	v_and_b32_e32 v113, 0xffff0000, v154
	v_pk_fma_f32 v[104:105], v[112:113], v[56:57], v[104:105]
	v_lshlrev_b32_e32 v114, 16, v155
	v_and_b32_e32 v115, 0xffff0000, v155
	v_pk_fma_f32 v[106:107], v[114:115], v[58:59], v[106:107]
	v_lshlrev_b32_e32 v112, 16, v156
	v_and_b32_e32 v113, 0xffff0000, v156
	v_pk_fma_f32 v[108:109], v[112:113], v[60:61], v[108:109]
	v_lshlrev_b32_e32 v114, 16, v157
	v_and_b32_e32 v115, 0xffff0000, v157
	v_pk_fma_f32 v[110:111], v[114:115], v[62:63], v[110:111]
	v_lshlrev_b32_e32 v112, 16, v166
	v_and_b32_e32 v113, 0xffff0000, v166
	v_pk_fma_f32 v[104:105], v[112:113], v[64:65], v[104:105]
	v_lshlrev_b32_e32 v114, 16, v167
	v_and_b32_e32 v115, 0xffff0000, v167
	v_pk_fma_f32 v[106:107], v[114:115], v[66:67], v[106:107]
	v_lshlrev_b32_e32 v112, 16, v168
	v_and_b32_e32 v113, 0xffff0000, v168
	v_pk_fma_f32 v[108:109], v[112:113], v[68:69], v[108:109]
	v_lshlrev_b32_e32 v114, 16, v169
	v_and_b32_e32 v115, 0xffff0000, v169
	v_pk_fma_f32 v[110:111], v[114:115], v[70:71], v[110:111]
	v_mov_b64_e32 v[132:133], s[28:29]
	v_and_b32_e32 v116, 0x7fffffff, v104
	v_and_b32_e32 v117, 0x7fffffff, v105
	v_pk_fma_f32 v[116:117], v[116:117], s[24:25], 1.0 op_sel_hi:[1,0,0]
	v_pk_mul_f32 v[218:219], v[104:105], v[104:105]
	v_rcp_f32_e32 v116, v116
	v_rcp_f32_e32 v117, v117
	v_pk_mul_f32 v[218:219], v[218:219], s[38:39] op_sel_hi:[1,0]
	v_and_b32_e32 v118, 0x7fffffff, v106
	v_and_b32_e32 v119, 0x7fffffff, v107
	v_pk_fma_f32 v[118:119], v[118:119], s[24:25], 1.0 op_sel_hi:[1,0,0]
	v_pk_mul_f32 v[220:221], v[106:107], v[106:107]
	v_rcp_f32_e32 v118, v118
	v_rcp_f32_e32 v119, v119
	v_pk_mul_f32 v[220:221], v[220:221], s[38:39] op_sel_hi:[1,0]
	v_and_b32_e32 v120, 0x7fffffff, v108
	v_and_b32_e32 v121, 0x7fffffff, v109
	v_pk_fma_f32 v[120:121], v[120:121], s[24:25], 1.0 op_sel_hi:[1,0,0]
	v_pk_mul_f32 v[222:223], v[108:109], v[108:109]
	v_rcp_f32_e32 v120, v120
	v_rcp_f32_e32 v121, v121
	v_pk_mul_f32 v[222:223], v[222:223], s[38:39] op_sel_hi:[1,0]
	v_and_b32_e32 v122, 0x7fffffff, v110
	v_and_b32_e32 v123, 0x7fffffff, v111
	v_pk_fma_f32 v[122:123], v[122:123], s[24:25], 1.0 op_sel_hi:[1,0,0]
	v_pk_mul_f32 v[224:225], v[110:111], v[110:111]
	v_rcp_f32_e32 v122, v122
	v_rcp_f32_e32 v123, v123
	v_pk_mul_f32 v[224:225], v[224:225], s[38:39] op_sel_hi:[1,0]
	v_pk_fma_f32 v[124:125], v[116:117], s[26:27], v[132:133] op_sel_hi:[1,0,0]
	v_exp_f32_e32 v218, v218
	v_pk_fma_f32 v[124:125], v[116:117], v[124:125], s[30:31] op_sel_hi:[1,1,0]
	v_exp_f32_e32 v219, v219
	v_pk_fma_f32 v[124:125], v[116:117], v[124:125], s[34:35] op_sel_hi:[1,1,0]
	v_pk_fma_f32 v[124:125], v[116:117], v[124:125], s[36:37] op_sel_hi:[1,1,0]
	v_pk_mul_f32 v[124:125], v[116:117], v[124:125]
	v_pk_fma_f32 v[126:127], v[118:119], s[26:27], v[132:133] op_sel_hi:[1,0,0]
	v_exp_f32_e32 v220, v220
	v_pk_fma_f32 v[126:127], v[118:119], v[126:127], s[30:31] op_sel_hi:[1,1,0]
	v_exp_f32_e32 v221, v221
	v_pk_fma_f32 v[126:127], v[118:119], v[126:127], s[34:35] op_sel_hi:[1,1,0]
	v_pk_fma_f32 v[126:127], v[118:119], v[126:127], s[36:37] op_sel_hi:[1,1,0]
	v_pk_mul_f32 v[126:127], v[118:119], v[126:127]
	v_pk_fma_f32 v[128:129], v[120:121], s[26:27], v[132:133] op_sel_hi:[1,0,0]
	v_exp_f32_e32 v222, v222
	v_pk_fma_f32 v[128:129], v[120:121], v[128:129], s[30:31] op_sel_hi:[1,1,0]
	v_exp_f32_e32 v223, v223
	v_pk_fma_f32 v[128:129], v[120:121], v[128:129], s[34:35] op_sel_hi:[1,1,0]
	v_pk_fma_f32 v[128:129], v[120:121], v[128:129], s[36:37] op_sel_hi:[1,1,0]
	v_pk_mul_f32 v[128:129], v[120:121], v[128:129]
	v_pk_fma_f32 v[130:131], v[122:123], s[26:27], v[132:133] op_sel_hi:[1,0,0]
	v_exp_f32_e32 v224, v224
	v_pk_fma_f32 v[130:131], v[122:123], v[130:131], s[30:31] op_sel_hi:[1,1,0]
	v_exp_f32_e32 v225, v225
	v_pk_fma_f32 v[130:131], v[122:123], v[130:131], s[34:35] op_sel_hi:[1,1,0]
	v_pk_fma_f32 v[130:131], v[122:123], v[130:131], s[36:37] op_sel_hi:[1,1,0]
	v_pk_mul_f32 v[130:131], v[122:123], v[130:131]
	v_pk_mul_f32 v[124:125], v[218:219], v[124:125]
	v_pk_mul_f32 v[218:219], v[104:105], v[124:125]
	v_pk_fma_f32 v[124:125], v[104:105], v[124:125], v[104:105] neg_lo:[1,0,0] neg_hi:[1,0,0]
	v_cmp_gt_f32_e64 s[8:9], 0, v104
	v_cmp_gt_f32_e64 s[22:23], 0, v105
	v_lshlrev_b32_e32 v112, 16, v100
	v_and_b32_e32 v113, 0xffff0000, v100
	v_cndmask_b32_e64 v104, v124, v218, s[8:9]
	v_cndmask_b32_e64 v105, v125, v219, s[22:23]
	v_pk_mul_f32 v[104:105], v[104:105], v[112:113]
	v_cvt_pk_bf16_f32 v226, v104, v105
	v_pk_mul_f32 v[126:127], v[220:221], v[126:127]
	v_pk_mul_f32 v[220:221], v[106:107], v[126:127]
	v_pk_fma_f32 v[126:127], v[106:107], v[126:127], v[106:107] neg_lo:[1,0,0] neg_hi:[1,0,0]
	v_cmp_gt_f32_e64 s[8:9], 0, v106
	v_cmp_gt_f32_e64 s[22:23], 0, v107
	v_lshlrev_b32_e32 v112, 16, v101
	v_and_b32_e32 v113, 0xffff0000, v101
	v_cndmask_b32_e64 v106, v126, v220, s[8:9]
	v_cndmask_b32_e64 v107, v127, v221, s[22:23]
	v_pk_mul_f32 v[106:107], v[106:107], v[112:113]
	v_cvt_pk_bf16_f32 v227, v106, v107
	v_pk_mul_f32 v[128:129], v[222:223], v[128:129]
	v_pk_mul_f32 v[222:223], v[108:109], v[128:129]
	v_pk_fma_f32 v[128:129], v[108:109], v[128:129], v[108:109] neg_lo:[1,0,0] neg_hi:[1,0,0]
	v_cmp_gt_f32_e64 s[8:9], 0, v108
	v_cmp_gt_f32_e64 s[22:23], 0, v109
	v_lshlrev_b32_e32 v112, 16, v102
	v_and_b32_e32 v113, 0xffff0000, v102
	v_cndmask_b32_e64 v108, v128, v222, s[8:9]
	v_cndmask_b32_e64 v109, v129, v223, s[22:23]
	v_pk_mul_f32 v[108:109], v[108:109], v[112:113]
	v_cvt_pk_bf16_f32 v228, v108, v109
	v_pk_mul_f32 v[130:131], v[224:225], v[130:131]
	v_pk_mul_f32 v[224:225], v[110:111], v[130:131]
	v_pk_fma_f32 v[130:131], v[110:111], v[130:131], v[110:111] neg_lo:[1,0,0] neg_hi:[1,0,0]
	v_cmp_gt_f32_e64 s[8:9], 0, v110
	v_cmp_gt_f32_e64 s[22:23], 0, v111
	v_lshlrev_b32_e32 v112, 16, v103
	v_and_b32_e32 v113, 0xffff0000, v103
	v_cndmask_b32_e64 v110, v130, v224, s[8:9]
	v_cndmask_b32_e64 v111, v131, v225, s[22:23]
	v_pk_mul_f32 v[110:111], v[110:111], v[112:113]
	v_cvt_pk_bf16_f32 v229, v110, v111
	global_store_dwordx4 v140, v[226:229], s[14:15] sc1
	v_add_u32_e32 v140, 0x2c00, v140
	s_add_i32 s21, s21, -1
	s_cmp_lg_u32 s21, 0
	s_cbranch_scc1 .Lconv_cols
	s_waitcnt vmcnt(12)
	v_mov_b64_e32 v[104:105], v[72:73]
	v_mov_b64_e32 v[106:107], v[74:75]
	v_mov_b64_e32 v[108:109], v[76:77]
	v_mov_b64_e32 v[110:111], v[78:79]
	v_lshlrev_b32_e32 v112, 16, v146
	v_and_b32_e32 v113, 0xffff0000, v146
	v_pk_fma_f32 v[104:105], v[112:113], v[0:1], v[104:105]
	v_lshlrev_b32_e32 v114, 16, v147
	v_and_b32_e32 v115, 0xffff0000, v147
	v_pk_fma_f32 v[106:107], v[114:115], v[2:3], v[106:107]
	v_lshlrev_b32_e32 v112, 16, v148
	v_and_b32_e32 v113, 0xffff0000, v148
	v_pk_fma_f32 v[108:109], v[112:113], v[4:5], v[108:109]
	v_lshlrev_b32_e32 v114, 16, v149
	v_and_b32_e32 v115, 0xffff0000, v149
	v_pk_fma_f32 v[110:111], v[114:115], v[6:7], v[110:111]
	v_lshlrev_b32_e32 v112, 16, v158
	v_and_b32_e32 v113, 0xffff0000, v158
	v_pk_fma_f32 v[104:105], v[112:113], v[8:9], v[104:105]
	v_lshlrev_b32_e32 v114, 16, v159
	v_and_b32_e32 v115, 0xffff0000, v159
	v_pk_fma_f32 v[106:107], v[114:115], v[10:11], v[106:107]
	v_lshlrev_b32_e32 v112, 16, v160
	v_and_b32_e32 v113, 0xffff0000, v160
	v_pk_fma_f32 v[108:109], v[112:113], v[12:13], v[108:109]
	v_lshlrev_b32_e32 v114, 16, v161
	v_and_b32_e32 v115, 0xffff0000, v161
	v_pk_fma_f32 v[110:111], v[114:115], v[14:15], v[110:111]
	v_lshlrev_b32_e32 v112, 16, v170
	v_and_b32_e32 v113, 0xffff0000, v170
	v_pk_fma_f32 v[104:105], v[112:113], v[16:17], v[104:105]
	v_lshlrev_b32_e32 v114, 16, v171
	v_and_b32_e32 v115, 0xffff0000, v171
	v_pk_fma_f32 v[106:107], v[114:115], v[18:19], v[106:107]
	v_lshlrev_b32_e32 v112, 16, v172
	v_and_b32_e32 v113, 0xffff0000, v172
	v_pk_fma_f32 v[108:109], v[112:113], v[20:21], v[108:109]
	v_lshlrev_b32_e32 v114, 16, v173
	v_and_b32_e32 v115, 0xffff0000, v173
	v_pk_fma_f32 v[110:111], v[114:115], v[22:23], v[110:111]
	v_lshlrev_b32_e32 v112, 16, v150
	v_and_b32_e32 v113, 0xffff0000, v150
	v_pk_fma_f32 v[104:105], v[112:113], v[24:25], v[104:105]
	v_lshlrev_b32_e32 v114, 16, v151
	v_and_b32_e32 v115, 0xffff0000, v151
	v_pk_fma_f32 v[106:107], v[114:115], v[26:27], v[106:107]
	v_lshlrev_b32_e32 v112, 16, v152
	v_and_b32_e32 v113, 0xffff0000, v152
	v_pk_fma_f32 v[108:109], v[112:113], v[28:29], v[108:109]
	v_lshlrev_b32_e32 v114, 16, v153
	v_and_b32_e32 v115, 0xffff0000, v153
	v_pk_fma_f32 v[110:111], v[114:115], v[30:31], v[110:111]
	v_lshlrev_b32_e32 v112, 16, v162
	v_and_b32_e32 v113, 0xffff0000, v162
	v_pk_fma_f32 v[104:105], v[112:113], v[32:33], v[104:105]
	v_lshlrev_b32_e32 v114, 16, v163
	v_and_b32_e32 v115, 0xffff0000, v163
	v_pk_fma_f32 v[106:107], v[114:115], v[34:35], v[106:107]
	v_lshlrev_b32_e32 v112, 16, v164
	v_and_b32_e32 v113, 0xffff0000, v164
	v_pk_fma_f32 v[108:109], v[112:113], v[36:37], v[108:109]
	v_lshlrev_b32_e32 v114, 16, v165
	v_and_b32_e32 v115, 0xffff0000, v165
	v_pk_fma_f32 v[110:111], v[114:115], v[38:39], v[110:111]
	v_lshlrev_b32_e32 v112, 16, v174
	v_and_b32_e32 v113, 0xffff0000, v174
	v_pk_fma_f32 v[104:105], v[112:113], v[40:41], v[104:105]
	v_lshlrev_b32_e32 v114, 16, v175
	v_and_b32_e32 v115, 0xffff0000, v175
	v_pk_fma_f32 v[106:107], v[114:115], v[42:43], v[106:107]
	v_lshlrev_b32_e32 v112, 16, v176
	v_and_b32_e32 v113, 0xffff0000, v176
	v_pk_fma_f32 v[108:109], v[112:113], v[44:45], v[108:109]
	v_lshlrev_b32_e32 v114, 16, v177
	v_and_b32_e32 v115, 0xffff0000, v177
	v_pk_fma_f32 v[110:111], v[114:115], v[46:47], v[110:111]
	v_lshlrev_b32_e32 v112, 16, v154
	v_and_b32_e32 v113, 0xffff0000, v154
	v_pk_fma_f32 v[104:105], v[112:113], v[48:49], v[104:105]
	v_lshlrev_b32_e32 v114, 16, v155
	v_and_b32_e32 v115, 0xffff0000, v155
	v_pk_fma_f32 v[106:107], v[114:115], v[50:51], v[106:107]
	v_lshlrev_b32_e32 v112, 16, v156
	v_and_b32_e32 v113, 0xffff0000, v156
	v_pk_fma_f32 v[108:109], v[112:113], v[52:53], v[108:109]
	v_lshlrev_b32_e32 v114, 16, v157
	v_and_b32_e32 v115, 0xffff0000, v157
	v_pk_fma_f32 v[110:111], v[114:115], v[54:55], v[110:111]
	v_lshlrev_b32_e32 v112, 16, v166
	v_and_b32_e32 v113, 0xffff0000, v166
	v_pk_fma_f32 v[104:105], v[112:113], v[56:57], v[104:105]
	v_lshlrev_b32_e32 v114, 16, v167
	v_and_b32_e32 v115, 0xffff0000, v167
	v_pk_fma_f32 v[106:107], v[114:115], v[58:59], v[106:107]
	v_lshlrev_b32_e32 v112, 16, v168
	v_and_b32_e32 v113, 0xffff0000, v168
	v_pk_fma_f32 v[108:109], v[112:113], v[60:61], v[108:109]
	v_lshlrev_b32_e32 v114, 16, v169
	v_and_b32_e32 v115, 0xffff0000, v169
	v_pk_fma_f32 v[110:111], v[114:115], v[62:63], v[110:111]
	v_lshlrev_b32_e32 v112, 16, v178
	v_and_b32_e32 v113, 0xffff0000, v178
	v_pk_fma_f32 v[104:105], v[112:113], v[64:65], v[104:105]
	v_lshlrev_b32_e32 v114, 16, v179
	v_and_b32_e32 v115, 0xffff0000, v179
	v_pk_fma_f32 v[106:107], v[114:115], v[66:67], v[106:107]
	v_lshlrev_b32_e32 v112, 16, v180
	v_and_b32_e32 v113, 0xffff0000, v180
	v_pk_fma_f32 v[108:109], v[112:113], v[68:69], v[108:109]
	v_lshlrev_b32_e32 v114, 16, v181
	v_and_b32_e32 v115, 0xffff0000, v181
	v_pk_fma_f32 v[110:111], v[114:115], v[70:71], v[110:111]
	v_mov_b64_e32 v[132:133], s[28:29]
	v_and_b32_e32 v116, 0x7fffffff, v104
	v_and_b32_e32 v117, 0x7fffffff, v105
	v_pk_fma_f32 v[116:117], v[116:117], s[24:25], 1.0 op_sel_hi:[1,0,0]
	v_pk_mul_f32 v[218:219], v[104:105], v[104:105]
	v_rcp_f32_e32 v116, v116
	v_rcp_f32_e32 v117, v117
	v_pk_mul_f32 v[218:219], v[218:219], s[38:39] op_sel_hi:[1,0]
	v_and_b32_e32 v118, 0x7fffffff, v106
	v_and_b32_e32 v119, 0x7fffffff, v107
	v_pk_fma_f32 v[118:119], v[118:119], s[24:25], 1.0 op_sel_hi:[1,0,0]
	v_pk_mul_f32 v[220:221], v[106:107], v[106:107]
	v_rcp_f32_e32 v118, v118
	v_rcp_f32_e32 v119, v119
	v_pk_mul_f32 v[220:221], v[220:221], s[38:39] op_sel_hi:[1,0]
	v_and_b32_e32 v120, 0x7fffffff, v108
	v_and_b32_e32 v121, 0x7fffffff, v109
	v_pk_fma_f32 v[120:121], v[120:121], s[24:25], 1.0 op_sel_hi:[1,0,0]
	v_pk_mul_f32 v[222:223], v[108:109], v[108:109]
	v_rcp_f32_e32 v120, v120
	v_rcp_f32_e32 v121, v121
	v_pk_mul_f32 v[222:223], v[222:223], s[38:39] op_sel_hi:[1,0]
	v_and_b32_e32 v122, 0x7fffffff, v110
	v_and_b32_e32 v123, 0x7fffffff, v111
	v_pk_fma_f32 v[122:123], v[122:123], s[24:25], 1.0 op_sel_hi:[1,0,0]
	v_pk_mul_f32 v[224:225], v[110:111], v[110:111]
	v_rcp_f32_e32 v122, v122
	v_rcp_f32_e32 v123, v123
	v_pk_mul_f32 v[224:225], v[224:225], s[38:39] op_sel_hi:[1,0]
	v_pk_fma_f32 v[124:125], v[116:117], s[26:27], v[132:133] op_sel_hi:[1,0,0]
	v_exp_f32_e32 v218, v218
	v_pk_fma_f32 v[124:125], v[116:117], v[124:125], s[30:31] op_sel_hi:[1,1,0]
	v_exp_f32_e32 v219, v219
	v_pk_fma_f32 v[124:125], v[116:117], v[124:125], s[34:35] op_sel_hi:[1,1,0]
	v_pk_fma_f32 v[124:125], v[116:117], v[124:125], s[36:37] op_sel_hi:[1,1,0]
	v_pk_mul_f32 v[124:125], v[116:117], v[124:125]
	v_pk_fma_f32 v[126:127], v[118:119], s[26:27], v[132:133] op_sel_hi:[1,0,0]
	v_exp_f32_e32 v220, v220
	v_pk_fma_f32 v[126:127], v[118:119], v[126:127], s[30:31] op_sel_hi:[1,1,0]
	v_exp_f32_e32 v221, v221
	v_pk_fma_f32 v[126:127], v[118:119], v[126:127], s[34:35] op_sel_hi:[1,1,0]
	v_pk_fma_f32 v[126:127], v[118:119], v[126:127], s[36:37] op_sel_hi:[1,1,0]
	v_pk_mul_f32 v[126:127], v[118:119], v[126:127]
	v_pk_fma_f32 v[128:129], v[120:121], s[26:27], v[132:133] op_sel_hi:[1,0,0]
	v_exp_f32_e32 v222, v222
	v_pk_fma_f32 v[128:129], v[120:121], v[128:129], s[30:31] op_sel_hi:[1,1,0]
	v_exp_f32_e32 v223, v223
	v_pk_fma_f32 v[128:129], v[120:121], v[128:129], s[34:35] op_sel_hi:[1,1,0]
	v_pk_fma_f32 v[128:129], v[120:121], v[128:129], s[36:37] op_sel_hi:[1,1,0]
	v_pk_mul_f32 v[128:129], v[120:121], v[128:129]
	v_pk_fma_f32 v[130:131], v[122:123], s[26:27], v[132:133] op_sel_hi:[1,0,0]
	v_exp_f32_e32 v224, v224
	v_pk_fma_f32 v[130:131], v[122:123], v[130:131], s[30:31] op_sel_hi:[1,1,0]
	v_exp_f32_e32 v225, v225
	v_pk_fma_f32 v[130:131], v[122:123], v[130:131], s[34:35] op_sel_hi:[1,1,0]
	v_pk_fma_f32 v[130:131], v[122:123], v[130:131], s[36:37] op_sel_hi:[1,1,0]
	v_pk_mul_f32 v[130:131], v[122:123], v[130:131]
	v_pk_mul_f32 v[124:125], v[218:219], v[124:125]
	v_pk_mul_f32 v[218:219], v[104:105], v[124:125]
	v_pk_fma_f32 v[124:125], v[104:105], v[124:125], v[104:105] neg_lo:[1,0,0] neg_hi:[1,0,0]
	v_cmp_gt_f32_e64 s[8:9], 0, v104
	v_cmp_gt_f32_e64 s[22:23], 0, v105
	v_lshlrev_b32_e32 v112, 16, v80
	v_and_b32_e32 v113, 0xffff0000, v80
	v_cndmask_b32_e64 v104, v124, v218, s[8:9]
	v_cndmask_b32_e64 v105, v125, v219, s[22:23]
	v_pk_mul_f32 v[104:105], v[104:105], v[112:113]
	v_cvt_pk_bf16_f32 v226, v104, v105
	v_pk_mul_f32 v[126:127], v[220:221], v[126:127]
	v_pk_mul_f32 v[220:221], v[106:107], v[126:127]
	v_pk_fma_f32 v[126:127], v[106:107], v[126:127], v[106:107] neg_lo:[1,0,0] neg_hi:[1,0,0]
	v_cmp_gt_f32_e64 s[8:9], 0, v106
	v_cmp_gt_f32_e64 s[22:23], 0, v107
	v_lshlrev_b32_e32 v112, 16, v81
	v_and_b32_e32 v113, 0xffff0000, v81
	v_cndmask_b32_e64 v106, v126, v220, s[8:9]
	v_cndmask_b32_e64 v107, v127, v221, s[22:23]
	v_pk_mul_f32 v[106:107], v[106:107], v[112:113]
	v_cvt_pk_bf16_f32 v227, v106, v107
	v_pk_mul_f32 v[128:129], v[222:223], v[128:129]
	v_pk_mul_f32 v[222:223], v[108:109], v[128:129]
	v_pk_fma_f32 v[128:129], v[108:109], v[128:129], v[108:109] neg_lo:[1,0,0] neg_hi:[1,0,0]
	v_cmp_gt_f32_e64 s[8:9], 0, v108
	v_cmp_gt_f32_e64 s[22:23], 0, v109
	v_lshlrev_b32_e32 v112, 16, v82
	v_and_b32_e32 v113, 0xffff0000, v82
	v_cndmask_b32_e64 v108, v128, v222, s[8:9]
	v_cndmask_b32_e64 v109, v129, v223, s[22:23]
	v_pk_mul_f32 v[108:109], v[108:109], v[112:113]
	v_cvt_pk_bf16_f32 v228, v108, v109
	v_pk_mul_f32 v[130:131], v[224:225], v[130:131]
	v_pk_mul_f32 v[224:225], v[110:111], v[130:131]
	v_pk_fma_f32 v[130:131], v[110:111], v[130:131], v[110:111] neg_lo:[1,0,0] neg_hi:[1,0,0]
	v_cmp_gt_f32_e64 s[8:9], 0, v110
	v_cmp_gt_f32_e64 s[22:23], 0, v111
	v_lshlrev_b32_e32 v112, 16, v83
	v_and_b32_e32 v113, 0xffff0000, v83
	v_cndmask_b32_e64 v110, v130, v224, s[8:9]
	v_cndmask_b32_e64 v111, v131, v225, s[22:23]
	v_pk_mul_f32 v[110:111], v[110:111], v[112:113]
	v_cvt_pk_bf16_f32 v229, v110, v111
	global_store_dwordx4 v140, v[226:229], s[14:15] sc1
	v_add_u32_e32 v140, 0x2c00, v140
	s_waitcnt vmcnt(8)
	v_cndmask_b32_e64 v182, v182, 0, s[6:7]
	v_cndmask_b32_e64 v183, v183, 0, s[6:7]
	v_cndmask_b32_e64 v184, v184, 0, s[6:7]
	v_cndmask_b32_e64 v185, v185, 0, s[6:7]
	v_cndmask_b32_e64 v186, v186, 0, s[6:7]
	v_cndmask_b32_e64 v187, v187, 0, s[6:7]
	v_cndmask_b32_e64 v188, v188, 0, s[6:7]
	v_cndmask_b32_e64 v189, v189, 0, s[6:7]
	v_cndmask_b32_e64 v190, v190, 0, s[6:7]
	v_cndmask_b32_e64 v191, v191, 0, s[6:7]
	v_cndmask_b32_e64 v192, v192, 0, s[6:7]
	v_cndmask_b32_e64 v193, v193, 0, s[6:7]
	v_mov_b64_e32 v[104:105], v[72:73]
	v_mov_b64_e32 v[106:107], v[74:75]
	v_mov_b64_e32 v[108:109], v[76:77]
	v_mov_b64_e32 v[110:111], v[78:79]
	v_lshlrev_b32_e32 v112, 16, v158
	v_and_b32_e32 v113, 0xffff0000, v158
	v_pk_fma_f32 v[104:105], v[112:113], v[0:1], v[104:105]
	v_lshlrev_b32_e32 v114, 16, v159
	v_and_b32_e32 v115, 0xffff0000, v159
	v_pk_fma_f32 v[106:107], v[114:115], v[2:3], v[106:107]
	v_lshlrev_b32_e32 v112, 16, v160
	v_and_b32_e32 v113, 0xffff0000, v160
	v_pk_fma_f32 v[108:109], v[112:113], v[4:5], v[108:109]
	v_lshlrev_b32_e32 v114, 16, v161
	v_and_b32_e32 v115, 0xffff0000, v161
	v_pk_fma_f32 v[110:111], v[114:115], v[6:7], v[110:111]
	v_lshlrev_b32_e32 v112, 16, v170
	v_and_b32_e32 v113, 0xffff0000, v170
	v_pk_fma_f32 v[104:105], v[112:113], v[8:9], v[104:105]
	v_lshlrev_b32_e32 v114, 16, v171
	v_and_b32_e32 v115, 0xffff0000, v171
	v_pk_fma_f32 v[106:107], v[114:115], v[10:11], v[106:107]
	v_lshlrev_b32_e32 v112, 16, v172
	v_and_b32_e32 v113, 0xffff0000, v172
	v_pk_fma_f32 v[108:109], v[112:113], v[12:13], v[108:109]
	v_lshlrev_b32_e32 v114, 16, v173
	v_and_b32_e32 v115, 0xffff0000, v173
	v_pk_fma_f32 v[110:111], v[114:115], v[14:15], v[110:111]
	v_lshlrev_b32_e32 v112, 16, v182
	v_and_b32_e32 v113, 0xffff0000, v182
	v_pk_fma_f32 v[104:105], v[112:113], v[16:17], v[104:105]
	v_lshlrev_b32_e32 v114, 16, v183
	v_and_b32_e32 v115, 0xffff0000, v183
	v_pk_fma_f32 v[106:107], v[114:115], v[18:19], v[106:107]
	v_lshlrev_b32_e32 v112, 16, v184
	v_and_b32_e32 v113, 0xffff0000, v184
	v_pk_fma_f32 v[108:109], v[112:113], v[20:21], v[108:109]
	v_lshlrev_b32_e32 v114, 16, v185
	v_and_b32_e32 v115, 0xffff0000, v185
	v_pk_fma_f32 v[110:111], v[114:115], v[22:23], v[110:111]
	v_lshlrev_b32_e32 v112, 16, v162
	v_and_b32_e32 v113, 0xffff0000, v162
	v_pk_fma_f32 v[104:105], v[112:113], v[24:25], v[104:105]
	v_lshlrev_b32_e32 v114, 16, v163
	v_and_b32_e32 v115, 0xffff0000, v163
	v_pk_fma_f32 v[106:107], v[114:115], v[26:27], v[106:107]
	v_lshlrev_b32_e32 v112, 16, v164
	v_and_b32_e32 v113, 0xffff0000, v164
	v_pk_fma_f32 v[108:109], v[112:113], v[28:29], v[108:109]
	v_lshlrev_b32_e32 v114, 16, v165
	v_and_b32_e32 v115, 0xffff0000, v165
	v_pk_fma_f32 v[110:111], v[114:115], v[30:31], v[110:111]
	v_lshlrev_b32_e32 v112, 16, v174
	v_and_b32_e32 v113, 0xffff0000, v174
	v_pk_fma_f32 v[104:105], v[112:113], v[32:33], v[104:105]
	v_lshlrev_b32_e32 v114, 16, v175
	v_and_b32_e32 v115, 0xffff0000, v175
	v_pk_fma_f32 v[106:107], v[114:115], v[34:35], v[106:107]
	v_lshlrev_b32_e32 v112, 16, v176
	v_and_b32_e32 v113, 0xffff0000, v176
	v_pk_fma_f32 v[108:109], v[112:113], v[36:37], v[108:109]
	v_lshlrev_b32_e32 v114, 16, v177
	v_and_b32_e32 v115, 0xffff0000, v177
	v_pk_fma_f32 v[110:111], v[114:115], v[38:39], v[110:111]
	v_lshlrev_b32_e32 v112, 16, v186
	v_and_b32_e32 v113, 0xffff0000, v186
	v_pk_fma_f32 v[104:105], v[112:113], v[40:41], v[104:105]
	v_lshlrev_b32_e32 v114, 16, v187
	v_and_b32_e32 v115, 0xffff0000, v187
	v_pk_fma_f32 v[106:107], v[114:115], v[42:43], v[106:107]
	v_lshlrev_b32_e32 v112, 16, v188
	v_and_b32_e32 v113, 0xffff0000, v188
	v_pk_fma_f32 v[108:109], v[112:113], v[44:45], v[108:109]
	v_lshlrev_b32_e32 v114, 16, v189
	v_and_b32_e32 v115, 0xffff0000, v189
	v_pk_fma_f32 v[110:111], v[114:115], v[46:47], v[110:111]
	v_lshlrev_b32_e32 v112, 16, v166
	v_and_b32_e32 v113, 0xffff0000, v166
	v_pk_fma_f32 v[104:105], v[112:113], v[48:49], v[104:105]
	v_lshlrev_b32_e32 v114, 16, v167
	v_and_b32_e32 v115, 0xffff0000, v167
	v_pk_fma_f32 v[106:107], v[114:115], v[50:51], v[106:107]
	v_lshlrev_b32_e32 v112, 16, v168
	v_and_b32_e32 v113, 0xffff0000, v168
	v_pk_fma_f32 v[108:109], v[112:113], v[52:53], v[108:109]
	v_lshlrev_b32_e32 v114, 16, v169
	v_and_b32_e32 v115, 0xffff0000, v169
	v_pk_fma_f32 v[110:111], v[114:115], v[54:55], v[110:111]
	v_lshlrev_b32_e32 v112, 16, v178
	v_and_b32_e32 v113, 0xffff0000, v178
	v_pk_fma_f32 v[104:105], v[112:113], v[56:57], v[104:105]
	v_lshlrev_b32_e32 v114, 16, v179
	v_and_b32_e32 v115, 0xffff0000, v179
	v_pk_fma_f32 v[106:107], v[114:115], v[58:59], v[106:107]
	v_lshlrev_b32_e32 v112, 16, v180
	v_and_b32_e32 v113, 0xffff0000, v180
	v_pk_fma_f32 v[108:109], v[112:113], v[60:61], v[108:109]
	v_lshlrev_b32_e32 v114, 16, v181
	v_and_b32_e32 v115, 0xffff0000, v181
	v_pk_fma_f32 v[110:111], v[114:115], v[62:63], v[110:111]
	v_lshlrev_b32_e32 v112, 16, v190
	v_and_b32_e32 v113, 0xffff0000, v190
	v_pk_fma_f32 v[104:105], v[112:113], v[64:65], v[104:105]
	v_lshlrev_b32_e32 v114, 16, v191
	v_and_b32_e32 v115, 0xffff0000, v191
	v_pk_fma_f32 v[106:107], v[114:115], v[66:67], v[106:107]
	v_lshlrev_b32_e32 v112, 16, v192
	v_and_b32_e32 v113, 0xffff0000, v192
	v_pk_fma_f32 v[108:109], v[112:113], v[68:69], v[108:109]
	v_lshlrev_b32_e32 v114, 16, v193
	v_and_b32_e32 v115, 0xffff0000, v193
	v_pk_fma_f32 v[110:111], v[114:115], v[70:71], v[110:111]
	v_mov_b64_e32 v[132:133], s[28:29]
	v_and_b32_e32 v116, 0x7fffffff, v104
	v_and_b32_e32 v117, 0x7fffffff, v105
	v_pk_fma_f32 v[116:117], v[116:117], s[24:25], 1.0 op_sel_hi:[1,0,0]
	v_pk_mul_f32 v[218:219], v[104:105], v[104:105]
	v_rcp_f32_e32 v116, v116
	v_rcp_f32_e32 v117, v117
	v_pk_mul_f32 v[218:219], v[218:219], s[38:39] op_sel_hi:[1,0]
	v_and_b32_e32 v118, 0x7fffffff, v106
	v_and_b32_e32 v119, 0x7fffffff, v107
	v_pk_fma_f32 v[118:119], v[118:119], s[24:25], 1.0 op_sel_hi:[1,0,0]
	v_pk_mul_f32 v[220:221], v[106:107], v[106:107]
	v_rcp_f32_e32 v118, v118
	v_rcp_f32_e32 v119, v119
	v_pk_mul_f32 v[220:221], v[220:221], s[38:39] op_sel_hi:[1,0]
	v_and_b32_e32 v120, 0x7fffffff, v108
	v_and_b32_e32 v121, 0x7fffffff, v109
	v_pk_fma_f32 v[120:121], v[120:121], s[24:25], 1.0 op_sel_hi:[1,0,0]
	v_pk_mul_f32 v[222:223], v[108:109], v[108:109]
	v_rcp_f32_e32 v120, v120
	v_rcp_f32_e32 v121, v121
	v_pk_mul_f32 v[222:223], v[222:223], s[38:39] op_sel_hi:[1,0]
	v_and_b32_e32 v122, 0x7fffffff, v110
	v_and_b32_e32 v123, 0x7fffffff, v111
	v_pk_fma_f32 v[122:123], v[122:123], s[24:25], 1.0 op_sel_hi:[1,0,0]
	v_pk_mul_f32 v[224:225], v[110:111], v[110:111]
	v_rcp_f32_e32 v122, v122
	v_rcp_f32_e32 v123, v123
	v_pk_mul_f32 v[224:225], v[224:225], s[38:39] op_sel_hi:[1,0]
	v_pk_fma_f32 v[124:125], v[116:117], s[26:27], v[132:133] op_sel_hi:[1,0,0]
	v_exp_f32_e32 v218, v218
	v_pk_fma_f32 v[124:125], v[116:117], v[124:125], s[30:31] op_sel_hi:[1,1,0]
	v_exp_f32_e32 v219, v219
	v_pk_fma_f32 v[124:125], v[116:117], v[124:125], s[34:35] op_sel_hi:[1,1,0]
	v_pk_fma_f32 v[124:125], v[116:117], v[124:125], s[36:37] op_sel_hi:[1,1,0]
	v_pk_mul_f32 v[124:125], v[116:117], v[124:125]
	v_pk_fma_f32 v[126:127], v[118:119], s[26:27], v[132:133] op_sel_hi:[1,0,0]
	v_exp_f32_e32 v220, v220
	v_pk_fma_f32 v[126:127], v[118:119], v[126:127], s[30:31] op_sel_hi:[1,1,0]
	v_exp_f32_e32 v221, v221
	v_pk_fma_f32 v[126:127], v[118:119], v[126:127], s[34:35] op_sel_hi:[1,1,0]
	v_pk_fma_f32 v[126:127], v[118:119], v[126:127], s[36:37] op_sel_hi:[1,1,0]
	v_pk_mul_f32 v[126:127], v[118:119], v[126:127]
	v_pk_fma_f32 v[128:129], v[120:121], s[26:27], v[132:133] op_sel_hi:[1,0,0]
	v_exp_f32_e32 v222, v222
	v_pk_fma_f32 v[128:129], v[120:121], v[128:129], s[30:31] op_sel_hi:[1,1,0]
	v_exp_f32_e32 v223, v223
	v_pk_fma_f32 v[128:129], v[120:121], v[128:129], s[34:35] op_sel_hi:[1,1,0]
	v_pk_fma_f32 v[128:129], v[120:121], v[128:129], s[36:37] op_sel_hi:[1,1,0]
	v_pk_mul_f32 v[128:129], v[120:121], v[128:129]
	v_pk_fma_f32 v[130:131], v[122:123], s[26:27], v[132:133] op_sel_hi:[1,0,0]
	v_exp_f32_e32 v224, v224
	v_pk_fma_f32 v[130:131], v[122:123], v[130:131], s[30:31] op_sel_hi:[1,1,0]
	v_exp_f32_e32 v225, v225
	v_pk_fma_f32 v[130:131], v[122:123], v[130:131], s[34:35] op_sel_hi:[1,1,0]
	v_pk_fma_f32 v[130:131], v[122:123], v[130:131], s[36:37] op_sel_hi:[1,1,0]
	v_pk_mul_f32 v[130:131], v[122:123], v[130:131]
	v_pk_mul_f32 v[124:125], v[218:219], v[124:125]
	v_pk_mul_f32 v[218:219], v[104:105], v[124:125]
	v_pk_fma_f32 v[124:125], v[104:105], v[124:125], v[104:105] neg_lo:[1,0,0] neg_hi:[1,0,0]
	v_cmp_gt_f32_e64 s[8:9], 0, v104
	v_cmp_gt_f32_e64 s[22:23], 0, v105
	v_lshlrev_b32_e32 v112, 16, v84
	v_and_b32_e32 v113, 0xffff0000, v84
	v_cndmask_b32_e64 v104, v124, v218, s[8:9]
	v_cndmask_b32_e64 v105, v125, v219, s[22:23]
	v_pk_mul_f32 v[104:105], v[104:105], v[112:113]
	v_cvt_pk_bf16_f32 v226, v104, v105
	v_pk_mul_f32 v[126:127], v[220:221], v[126:127]
	v_pk_mul_f32 v[220:221], v[106:107], v[126:127]
	v_pk_fma_f32 v[126:127], v[106:107], v[126:127], v[106:107] neg_lo:[1,0,0] neg_hi:[1,0,0]
	v_cmp_gt_f32_e64 s[8:9], 0, v106
	v_cmp_gt_f32_e64 s[22:23], 0, v107
	v_lshlrev_b32_e32 v112, 16, v85
	v_and_b32_e32 v113, 0xffff0000, v85
	v_cndmask_b32_e64 v106, v126, v220, s[8:9]
	v_cndmask_b32_e64 v107, v127, v221, s[22:23]
	v_pk_mul_f32 v[106:107], v[106:107], v[112:113]
	v_cvt_pk_bf16_f32 v227, v106, v107
	v_pk_mul_f32 v[128:129], v[222:223], v[128:129]
	v_pk_mul_f32 v[222:223], v[108:109], v[128:129]
	v_pk_fma_f32 v[128:129], v[108:109], v[128:129], v[108:109] neg_lo:[1,0,0] neg_hi:[1,0,0]
	v_cmp_gt_f32_e64 s[8:9], 0, v108
	v_cmp_gt_f32_e64 s[22:23], 0, v109
	v_lshlrev_b32_e32 v112, 16, v86
	v_and_b32_e32 v113, 0xffff0000, v86
	v_cndmask_b32_e64 v108, v128, v222, s[8:9]
	v_cndmask_b32_e64 v109, v129, v223, s[22:23]
	v_pk_mul_f32 v[108:109], v[108:109], v[112:113]
	v_cvt_pk_bf16_f32 v228, v108, v109
	v_pk_mul_f32 v[130:131], v[224:225], v[130:131]
	v_pk_mul_f32 v[224:225], v[110:111], v[130:131]
	v_pk_fma_f32 v[130:131], v[110:111], v[130:131], v[110:111] neg_lo:[1,0,0] neg_hi:[1,0,0]
	v_cmp_gt_f32_e64 s[8:9], 0, v110
	v_cmp_gt_f32_e64 s[22:23], 0, v111
	v_lshlrev_b32_e32 v112, 16, v87
	v_and_b32_e32 v113, 0xffff0000, v87
	v_cndmask_b32_e64 v110, v130, v224, s[8:9]
	v_cndmask_b32_e64 v111, v131, v225, s[22:23]
	v_pk_mul_f32 v[110:111], v[110:111], v[112:113]
	v_cvt_pk_bf16_f32 v229, v110, v111
	global_store_dwordx4 v140, v[226:229], s[14:15] sc1
	v_add_u32_e32 v140, 0x2c00, v140
	v_add_u32_e32 v230, s27, v230
	s_nop 1
	v_readfirstlane_b32 s22, v230
	s_cmp_lt_u32 s22, 0x58000
	s_cbranch_scc1 .Lconv_item

.LBB0_1277:
	s_lshl_b32 s16, s46, 8
	s_add_i32 s16, s16, s35
	v_or_b32_e32 v146, s16, v152
	v_ashrrev_i32_e32 v147, 31, v146
	v_lshl_or_b32 v150, s47, 8, v156
	s_ashr_i32 s17, s16, 12
	v_lshlrev_b64 v[172:173], 11, v[146:147]
	v_ashrrev_i32_e32 v151, 31, v150
	s_mul_hi_i32 s19, s17, 0x6000
	s_mulk_i32 s17, 0x6000
	v_lshl_add_u64 v[148:149], s[52:53], 0, v[172:173]
	v_lshlrev_b64 v[146:147], 1, v[150:151]
	s_add_u32 s18, s40, s17
	v_lshl_add_u64 v[174:175], v[148:149], 0, v[146:147]
	s_addc_u32 s19, s41, s19
	v_lshlrev_b64 v[148:149], 2, v[150:151]
	global_load_dwordx4 v[160:163], v[174:175], off
	v_lshl_add_u64 v[150:151], s[18:19], 0, v[148:149]
	global_load_dwordx4 v[164:167], v[150:151], off
	global_load_dwordx4 v[168:171], v[150:151], off offset:16
	v_lshl_add_u64 v[172:173], s[12:13], 0, v[172:173]
	v_lshl_add_u64 v[172:173], v[172:173], 0, v[146:147]
	s_waitcnt vmcnt(0)
	v_lshlrev_b32_e32 v176, 16, v160
	v_and_b32_e32 v177, 0xffff0000, v160
	v_lshlrev_b32_e32 v160, 16, v161
	v_and_b32_e32 v161, 0xffff0000, v161
	v_lshlrev_b32_e32 v178, 16, v162
	v_and_b32_e32 v179, 0xffff0000, v162
	v_lshlrev_b32_e32 v162, 16, v163
	v_and_b32_e32 v163, 0xffff0000, v163
	v_pk_fma_f32 v[126:127], v[126:127], v[166:167], v[160:161]
	v_pk_fma_f32 v[124:125], v[124:125], v[164:165], v[176:177]
	v_pk_fma_f32 v[160:161], v[122:123], v[170:171], v[162:163]
	v_pk_fma_f32 v[122:123], v[120:121], v[168:169], v[178:179]
	v_cvt_pk_bf16_f32 v120, v124, v125
	v_cvt_pk_bf16_f32 v121, v126, v127
	v_cvt_pk_bf16_f32 v122, v122, v123
	v_cvt_pk_bf16_f32 v123, v160, v161
	global_store_dwordx4 v[172:173], v[120:123], off sc1
	global_load_dwordx4 v[120:123], v[174:175], off offset:256
	s_nop 0
	global_load_dwordx4 v[124:127], v[150:151], off offset:512
	global_load_dwordx4 v[160:163], v[150:151], off offset:528
	v_or_b32_e32 v164, s16, v153
	v_ashrrev_i32_e32 v165, 31, v164
	v_lshlrev_b64 v[164:165], 11, v[164:165]
	v_lshl_add_u64 v[166:167], s[52:53], 0, v[164:165]
	v_lshl_add_u64 v[166:167], v[166:167], 0, v[146:147]
	s_waitcnt vmcnt(2)
	v_lshlrev_b32_e32 v168, 16, v120
	v_and_b32_e32 v169, 0xffff0000, v120
	v_lshlrev_b32_e32 v120, 16, v121
	v_and_b32_e32 v121, 0xffff0000, v121
	v_lshlrev_b32_e32 v170, 16, v122
	v_and_b32_e32 v171, 0xffff0000, v122
	v_lshlrev_b32_e32 v122, 16, v123
	v_and_b32_e32 v123, 0xffff0000, v123
	s_waitcnt vmcnt(1)
	v_pk_fma_f32 v[118:119], v[118:119], v[126:127], v[120:121]
	v_pk_fma_f32 v[116:117], v[116:117], v[124:125], v[168:169]
	s_waitcnt vmcnt(0)
	v_pk_fma_f32 v[120:121], v[114:115], v[162:163], v[122:123]
	v_pk_fma_f32 v[114:115], v[112:113], v[160:161], v[170:171]
	v_cvt_pk_bf16_f32 v112, v116, v117
	v_cvt_pk_bf16_f32 v113, v118, v119
	v_cvt_pk_bf16_f32 v114, v114, v115
	v_cvt_pk_bf16_f32 v115, v120, v121
	global_store_dwordx4 v[172:173], v[112:115], off offset:256 sc1
	global_load_dwordx4 v[112:115], v[166:167], off
	s_nop 0
	global_load_dwordx4 v[116:119], v[150:151], off
	global_load_dwordx4 v[120:123], v[150:151], off offset:16
	v_lshl_add_u64 v[124:125], s[12:13], 0, v[164:165]
	v_lshl_add_u64 v[124:125], v[124:125], 0, v[146:147]
	s_waitcnt vmcnt(2)
	v_lshlrev_b32_e32 v126, 16, v112
	v_and_b32_e32 v127, 0xffff0000, v112
	v_lshlrev_b32_e32 v112, 16, v113
	v_and_b32_e32 v113, 0xffff0000, v113
	v_lshlrev_b32_e32 v160, 16, v114
	v_and_b32_e32 v161, 0xffff0000, v114
	v_lshlrev_b32_e32 v114, 16, v115
	v_and_b32_e32 v115, 0xffff0000, v115
	s_waitcnt vmcnt(1)
	v_pk_fma_f32 v[110:111], v[110:111], v[118:119], v[112:113]
	v_pk_fma_f32 v[108:109], v[108:109], v[116:117], v[126:127]
	s_waitcnt vmcnt(0)
	v_pk_fma_f32 v[112:113], v[106:107], v[122:123], v[114:115]
	v_pk_fma_f32 v[106:107], v[104:105], v[120:121], v[160:161]
	v_cvt_pk_bf16_f32 v104, v108, v109
	v_cvt_pk_bf16_f32 v105, v110, v111
	v_cvt_pk_bf16_f32 v106, v106, v107
	v_cvt_pk_bf16_f32 v107, v112, v113
	global_store_dwordx4 v[124:125], v[104:107], off sc1
	global_load_dwordx4 v[104:107], v[166:167], off offset:256
	s_nop 0
	global_load_dwordx4 v[108:111], v[150:151], off offset:512
	global_load_dwordx4 v[112:115], v[150:151], off offset:528
	v_or_b32_e32 v116, s16, v154
	v_ashrrev_i32_e32 v117, 31, v116
	v_lshlrev_b64 v[116:117], 11, v[116:117]
	v_lshl_add_u64 v[118:119], s[52:53], 0, v[116:117]
	v_lshl_add_u64 v[118:119], v[118:119], 0, v[146:147]
	s_waitcnt vmcnt(2)
	v_lshlrev_b32_e32 v120, 16, v104
	v_and_b32_e32 v121, 0xffff0000, v104
	v_lshlrev_b32_e32 v104, 16, v105
	v_and_b32_e32 v105, 0xffff0000, v105
	v_lshlrev_b32_e32 v122, 16, v106
	v_and_b32_e32 v123, 0xffff0000, v106
	v_lshlrev_b32_e32 v106, 16, v107
	v_and_b32_e32 v107, 0xffff0000, v107
	s_waitcnt vmcnt(1)
	v_pk_fma_f32 v[102:103], v[102:103], v[110:111], v[104:105]
	v_pk_fma_f32 v[100:101], v[100:101], v[108:109], v[120:121]
	s_waitcnt vmcnt(0)
	v_pk_fma_f32 v[104:105], v[98:99], v[114:115], v[106:107]
	v_pk_fma_f32 v[98:99], v[96:97], v[112:113], v[122:123]
	v_cvt_pk_bf16_f32 v96, v100, v101
	v_cvt_pk_bf16_f32 v97, v102, v103
	v_cvt_pk_bf16_f32 v98, v98, v99
	v_cvt_pk_bf16_f32 v99, v104, v105
	global_store_dwordx4 v[124:125], v[96:99], off offset:256 sc1
	global_load_dwordx4 v[96:99], v[118:119], off
	s_nop 0
	global_load_dwordx4 v[100:103], v[150:151], off
	global_load_dwordx4 v[104:107], v[150:151], off offset:16
	v_lshl_add_u64 v[108:109], s[12:13], 0, v[116:117]
	v_lshl_add_u64 v[108:109], v[108:109], 0, v[146:147]
	s_waitcnt vmcnt(2)
	v_lshlrev_b32_e32 v110, 16, v96
	v_and_b32_e32 v111, 0xffff0000, v96
	v_lshlrev_b32_e32 v96, 16, v97
	v_and_b32_e32 v97, 0xffff0000, v97
	v_lshlrev_b32_e32 v112, 16, v98
	v_and_b32_e32 v113, 0xffff0000, v98
	v_lshlrev_b32_e32 v98, 16, v99
	v_and_b32_e32 v99, 0xffff0000, v99
	s_waitcnt vmcnt(1)
	v_pk_fma_f32 v[94:95], v[94:95], v[102:103], v[96:97]
	v_pk_fma_f32 v[92:93], v[92:93], v[100:101], v[110:111]
	s_waitcnt vmcnt(0)
	v_pk_fma_f32 v[96:97], v[90:91], v[106:107], v[98:99]
	v_pk_fma_f32 v[90:91], v[88:89], v[104:105], v[112:113]
	v_cvt_pk_bf16_f32 v88, v92, v93
	v_cvt_pk_bf16_f32 v89, v94, v95
	v_cvt_pk_bf16_f32 v90, v90, v91
	v_cvt_pk_bf16_f32 v91, v96, v97
	global_store_dwordx4 v[108:109], v[88:91], off sc1
	global_load_dwordx4 v[88:91], v[118:119], off offset:256
	s_nop 0
	global_load_dwordx4 v[92:95], v[150:151], off offset:512
	global_load_dwordx4 v[96:99], v[150:151], off offset:528
	v_or_b32_e32 v100, s16, v155
	v_ashrrev_i32_e32 v101, 31, v100
	v_lshlrev_b64 v[100:101], 11, v[100:101]
	v_lshl_add_u64 v[102:103], s[52:53], 0, v[100:101]
	v_lshl_add_u64 v[102:103], v[102:103], 0, v[146:147]
	s_addk_i32 s16, 0x80
	s_ashr_i32 s17, s16, 12
	s_mul_hi_i32 s19, s17, 0x6000
	s_mulk_i32 s17, 0x6000
	s_add_u32 s18, s40, s17
	s_addc_u32 s19, s41, s19
	s_and_b64 vcc, exec, s[2:3]
	s_mov_b64 s[2:3], -1
	s_waitcnt vmcnt(2)
	v_lshlrev_b32_e32 v104, 16, v88
	v_and_b32_e32 v105, 0xffff0000, v88
	v_lshlrev_b32_e32 v88, 16, v89
	v_and_b32_e32 v89, 0xffff0000, v89
	v_lshlrev_b32_e32 v106, 16, v90
	v_and_b32_e32 v107, 0xffff0000, v90
	v_lshlrev_b32_e32 v90, 16, v91
	v_and_b32_e32 v91, 0xffff0000, v91
	s_waitcnt vmcnt(1)
	v_pk_fma_f32 v[86:87], v[86:87], v[94:95], v[88:89]
	v_pk_fma_f32 v[84:85], v[84:85], v[92:93], v[104:105]
	s_waitcnt vmcnt(0)
	v_pk_fma_f32 v[88:89], v[82:83], v[98:99], v[90:91]
	v_pk_fma_f32 v[82:83], v[80:81], v[96:97], v[106:107]
	v_cvt_pk_bf16_f32 v80, v84, v85
	v_cvt_pk_bf16_f32 v81, v86, v87
	v_cvt_pk_bf16_f32 v82, v82, v83
	v_cvt_pk_bf16_f32 v83, v88, v89
	global_store_dwordx4 v[108:109], v[80:83], off offset:256 sc1
	global_load_dwordx4 v[80:83], v[102:103], off
	s_nop 0
	global_load_dwordx4 v[84:87], v[150:151], off
	global_load_dwordx4 v[88:91], v[150:151], off offset:16
	v_lshl_add_u64 v[92:93], s[12:13], 0, v[100:101]
	v_lshl_add_u64 v[92:93], v[92:93], 0, v[146:147]
	s_waitcnt vmcnt(2)
	v_lshlrev_b32_e32 v94, 16, v80
	v_and_b32_e32 v95, 0xffff0000, v80
	v_lshlrev_b32_e32 v80, 16, v81
	v_and_b32_e32 v81, 0xffff0000, v81
	v_lshlrev_b32_e32 v96, 16, v82
	v_and_b32_e32 v97, 0xffff0000, v82
	v_lshlrev_b32_e32 v82, 16, v83
	v_and_b32_e32 v83, 0xffff0000, v83
	s_waitcnt vmcnt(1)
	v_pk_fma_f32 v[78:79], v[78:79], v[86:87], v[80:81]
	v_pk_fma_f32 v[76:77], v[76:77], v[84:85], v[94:95]
	s_waitcnt vmcnt(0)
	v_pk_fma_f32 v[80:81], v[74:75], v[90:91], v[82:83]
	v_pk_fma_f32 v[74:75], v[72:73], v[88:89], v[96:97]
	v_cvt_pk_bf16_f32 v72, v76, v77
	v_cvt_pk_bf16_f32 v73, v78, v79
	v_cvt_pk_bf16_f32 v74, v74, v75
	v_cvt_pk_bf16_f32 v75, v80, v81
	global_store_dwordx4 v[92:93], v[72:75], off sc1
	global_load_dwordx4 v[72:75], v[102:103], off offset:256
	s_nop 0
	global_load_dwordx4 v[76:79], v[150:151], off offset:512
	global_load_dwordx4 v[80:83], v[150:151], off offset:528
	v_or_b32_e32 v84, s16, v152
	v_ashrrev_i32_e32 v85, 31, v84
	v_lshlrev_b64 v[84:85], 11, v[84:85]
	v_lshl_add_u64 v[86:87], s[52:53], 0, v[84:85]
	v_lshl_add_u64 v[86:87], v[86:87], 0, v[146:147]
	s_waitcnt vmcnt(2)
	v_lshlrev_b32_e32 v88, 16, v72
	v_and_b32_e32 v89, 0xffff0000, v72
	v_lshlrev_b32_e32 v72, 16, v73
	v_and_b32_e32 v73, 0xffff0000, v73
	v_lshlrev_b32_e32 v90, 16, v74
	v_and_b32_e32 v91, 0xffff0000, v74
	v_lshlrev_b32_e32 v74, 16, v75
	v_and_b32_e32 v75, 0xffff0000, v75
	s_waitcnt vmcnt(1)
	v_pk_fma_f32 v[70:71], v[70:71], v[78:79], v[72:73]
	v_pk_fma_f32 v[68:69], v[68:69], v[76:77], v[88:89]
	s_waitcnt vmcnt(0)
	v_pk_fma_f32 v[72:73], v[66:67], v[82:83], v[74:75]
	v_pk_fma_f32 v[66:67], v[64:65], v[80:81], v[90:91]
	v_cvt_pk_bf16_f32 v64, v68, v69
	v_cvt_pk_bf16_f32 v65, v70, v71
	v_cvt_pk_bf16_f32 v66, v66, v67
	v_cvt_pk_bf16_f32 v67, v72, v73
	global_store_dwordx4 v[92:93], v[64:67], off offset:256 sc1
	global_load_dwordx4 v[66:69], v[86:87], off
	v_lshl_add_u64 v[78:79], s[12:13], 0, v[84:85]
	v_lshl_add_u64 v[64:65], s[18:19], 0, v[148:149]
	global_load_dwordx4 v[70:73], v[64:65], off
	global_load_dwordx4 v[74:77], v[64:65], off offset:16
	v_lshl_add_u64 v[78:79], v[78:79], 0, v[146:147]
	s_waitcnt vmcnt(2)
	v_lshlrev_b32_e32 v80, 16, v66
	v_and_b32_e32 v81, 0xffff0000, v66
	v_lshlrev_b32_e32 v66, 16, v67
	v_and_b32_e32 v67, 0xffff0000, v67
	v_lshlrev_b32_e32 v82, 16, v68
	v_and_b32_e32 v83, 0xffff0000, v68
	v_lshlrev_b32_e32 v68, 16, v69
	v_and_b32_e32 v69, 0xffff0000, v69
	s_waitcnt vmcnt(1)
	v_pk_fma_f32 v[62:63], v[62:63], v[72:73], v[66:67]
	v_pk_fma_f32 v[60:61], v[60:61], v[70:71], v[80:81]
	s_waitcnt vmcnt(0)
	v_pk_fma_f32 v[66:67], v[58:59], v[76:77], v[68:69]
	v_pk_fma_f32 v[58:59], v[56:57], v[74:75], v[82:83]
	v_cvt_pk_bf16_f32 v56, v60, v61
	v_cvt_pk_bf16_f32 v57, v62, v63
	v_cvt_pk_bf16_f32 v58, v58, v59
	v_cvt_pk_bf16_f32 v59, v66, v67
	global_store_dwordx4 v[78:79], v[56:59], off sc1
	global_load_dwordx4 v[56:59], v[86:87], off offset:256
	s_nop 0
	global_load_dwordx4 v[60:63], v[64:65], off offset:512
	global_load_dwordx4 v[66:69], v[64:65], off offset:528
	v_or_b32_e32 v70, s16, v153
	v_ashrrev_i32_e32 v71, 31, v70
	v_lshlrev_b64 v[70:71], 11, v[70:71]
	v_lshl_add_u64 v[72:73], s[52:53], 0, v[70:71]
	v_lshl_add_u64 v[72:73], v[72:73], 0, v[146:147]
	s_waitcnt vmcnt(2)
	v_lshlrev_b32_e32 v74, 16, v56
	v_and_b32_e32 v75, 0xffff0000, v56
	v_lshlrev_b32_e32 v56, 16, v57
	v_and_b32_e32 v57, 0xffff0000, v57
	v_lshlrev_b32_e32 v76, 16, v58
	v_and_b32_e32 v77, 0xffff0000, v58
	v_lshlrev_b32_e32 v58, 16, v59
	v_and_b32_e32 v59, 0xffff0000, v59
	s_waitcnt vmcnt(1)
	v_pk_fma_f32 v[54:55], v[54:55], v[62:63], v[56:57]
	v_pk_fma_f32 v[52:53], v[52:53], v[60:61], v[74:75]
	s_waitcnt vmcnt(0)
	v_pk_fma_f32 v[56:57], v[50:51], v[68:69], v[58:59]
	v_pk_fma_f32 v[50:51], v[48:49], v[66:67], v[76:77]
	v_cvt_pk_bf16_f32 v48, v52, v53
	v_cvt_pk_bf16_f32 v49, v54, v55
	v_cvt_pk_bf16_f32 v50, v50, v51
	v_cvt_pk_bf16_f32 v51, v56, v57
	global_store_dwordx4 v[78:79], v[48:51], off offset:256 sc1
	global_load_dwordx4 v[48:51], v[72:73], off
	s_nop 0
	global_load_dwordx4 v[52:55], v[64:65], off
	global_load_dwordx4 v[56:59], v[64:65], off offset:16
	v_lshl_add_u64 v[60:61], s[12:13], 0, v[70:71]
	v_lshl_add_u64 v[60:61], v[60:61], 0, v[146:147]
	s_waitcnt vmcnt(2)
	v_lshlrev_b32_e32 v62, 16, v48
	v_and_b32_e32 v63, 0xffff0000, v48
	v_lshlrev_b32_e32 v48, 16, v49
	v_and_b32_e32 v49, 0xffff0000, v49
	v_lshlrev_b32_e32 v66, 16, v50
	v_and_b32_e32 v67, 0xffff0000, v50
	v_lshlrev_b32_e32 v50, 16, v51
	v_and_b32_e32 v51, 0xffff0000, v51
	s_waitcnt vmcnt(1)
	v_pk_fma_f32 v[46:47], v[46:47], v[54:55], v[48:49]
	v_pk_fma_f32 v[44:45], v[44:45], v[52:53], v[62:63]
	s_waitcnt vmcnt(0)
	v_pk_fma_f32 v[48:49], v[42:43], v[58:59], v[50:51]
	v_pk_fma_f32 v[42:43], v[40:41], v[56:57], v[66:67]
	v_cvt_pk_bf16_f32 v40, v44, v45
	v_cvt_pk_bf16_f32 v41, v46, v47
	v_cvt_pk_bf16_f32 v42, v42, v43
	v_cvt_pk_bf16_f32 v43, v48, v49
	global_store_dwordx4 v[60:61], v[40:43], off sc1
	global_load_dwordx4 v[40:43], v[72:73], off offset:256
	s_nop 0
	global_load_dwordx4 v[44:47], v[64:65], off offset:512
	global_load_dwordx4 v[48:51], v[64:65], off offset:528
	v_or_b32_e32 v52, s16, v154
	v_ashrrev_i32_e32 v53, 31, v52
	v_lshlrev_b64 v[52:53], 11, v[52:53]
	v_lshl_add_u64 v[54:55], s[52:53], 0, v[52:53]
	v_lshl_add_u64 v[54:55], v[54:55], 0, v[146:147]
	s_waitcnt vmcnt(2)
	v_lshlrev_b32_e32 v56, 16, v40
	v_and_b32_e32 v57, 0xffff0000, v40
	v_lshlrev_b32_e32 v40, 16, v41
	v_and_b32_e32 v41, 0xffff0000, v41
	v_lshlrev_b32_e32 v58, 16, v42
	v_and_b32_e32 v59, 0xffff0000, v42
	v_lshlrev_b32_e32 v42, 16, v43
	v_and_b32_e32 v43, 0xffff0000, v43
	s_waitcnt vmcnt(1)
	v_pk_fma_f32 v[38:39], v[38:39], v[46:47], v[40:41]
	v_pk_fma_f32 v[36:37], v[36:37], v[44:45], v[56:57]
	s_waitcnt vmcnt(0)
	v_pk_fma_f32 v[40:41], v[34:35], v[50:51], v[42:43]
	v_pk_fma_f32 v[34:35], v[32:33], v[48:49], v[58:59]
	v_cvt_pk_bf16_f32 v32, v36, v37
	v_cvt_pk_bf16_f32 v33, v38, v39
	v_cvt_pk_bf16_f32 v34, v34, v35
	v_cvt_pk_bf16_f32 v35, v40, v41
	global_store_dwordx4 v[60:61], v[32:35], off offset:256 sc1
	global_load_dwordx4 v[32:35], v[54:55], off
	s_nop 0
	global_load_dwordx4 v[36:39], v[64:65], off
	global_load_dwordx4 v[40:43], v[64:65], off offset:16
	v_lshl_add_u64 v[44:45], s[12:13], 0, v[52:53]
	v_lshl_add_u64 v[44:45], v[44:45], 0, v[146:147]
	s_waitcnt vmcnt(2)
	v_lshlrev_b32_e32 v46, 16, v32
	v_and_b32_e32 v47, 0xffff0000, v32
	v_lshlrev_b32_e32 v32, 16, v33
	v_and_b32_e32 v33, 0xffff0000, v33
	v_lshlrev_b32_e32 v48, 16, v34
	v_and_b32_e32 v49, 0xffff0000, v34
	v_lshlrev_b32_e32 v34, 16, v35
	v_and_b32_e32 v35, 0xffff0000, v35
	s_waitcnt vmcnt(1)
	v_pk_fma_f32 v[30:31], v[30:31], v[38:39], v[32:33]
	v_pk_fma_f32 v[28:29], v[28:29], v[36:37], v[46:47]
	s_waitcnt vmcnt(0)
	v_pk_fma_f32 v[32:33], v[26:27], v[42:43], v[34:35]
	v_pk_fma_f32 v[26:27], v[24:25], v[40:41], v[48:49]
	v_cvt_pk_bf16_f32 v24, v28, v29
	v_cvt_pk_bf16_f32 v25, v30, v31
	v_cvt_pk_bf16_f32 v26, v26, v27
	v_cvt_pk_bf16_f32 v27, v32, v33
	global_store_dwordx4 v[44:45], v[24:27], off sc1
	global_load_dwordx4 v[24:27], v[54:55], off offset:256
	s_nop 0
	global_load_dwordx4 v[28:31], v[64:65], off offset:512
	global_load_dwordx4 v[32:35], v[64:65], off offset:528
	v_or_b32_e32 v36, s16, v155
	v_ashrrev_i32_e32 v37, 31, v36
	v_lshlrev_b64 v[36:37], 11, v[36:37]
	v_lshl_add_u64 v[38:39], s[52:53], 0, v[36:37]
	v_lshl_add_u64 v[38:39], v[38:39], 0, v[146:147]
	s_waitcnt vmcnt(2)
	v_lshlrev_b32_e32 v40, 16, v24
	v_and_b32_e32 v41, 0xffff0000, v24
	v_lshlrev_b32_e32 v24, 16, v25
	v_and_b32_e32 v25, 0xffff0000, v25
	v_lshlrev_b32_e32 v42, 16, v26
	v_and_b32_e32 v43, 0xffff0000, v26
	v_lshlrev_b32_e32 v26, 16, v27
	v_and_b32_e32 v27, 0xffff0000, v27
	s_waitcnt vmcnt(1)
	v_pk_fma_f32 v[22:23], v[22:23], v[30:31], v[24:25]
	v_pk_fma_f32 v[20:21], v[20:21], v[28:29], v[40:41]
	s_waitcnt vmcnt(0)
	v_pk_fma_f32 v[24:25], v[18:19], v[34:35], v[26:27]
	v_pk_fma_f32 v[18:19], v[16:17], v[32:33], v[42:43]
	v_cvt_pk_bf16_f32 v16, v20, v21
	v_cvt_pk_bf16_f32 v17, v22, v23
	v_cvt_pk_bf16_f32 v18, v18, v19
	v_cvt_pk_bf16_f32 v19, v24, v25
	global_store_dwordx4 v[44:45], v[16:19], off offset:256 sc1
	global_load_dwordx4 v[16:19], v[38:39], off
	s_nop 0
	global_load_dwordx4 v[20:23], v[64:65], off
	global_load_dwordx4 v[24:27], v[64:65], off offset:16
	v_lshl_add_u64 v[28:29], s[12:13], 0, v[36:37]
	v_lshl_add_u64 v[28:29], v[28:29], 0, v[146:147]
	s_waitcnt vmcnt(2)
	v_lshlrev_b32_e32 v30, 16, v16
	v_and_b32_e32 v31, 0xffff0000, v16
	v_lshlrev_b32_e32 v16, 16, v17
	v_and_b32_e32 v17, 0xffff0000, v17
	v_lshlrev_b32_e32 v32, 16, v18
	v_and_b32_e32 v33, 0xffff0000, v18
	v_lshlrev_b32_e32 v18, 16, v19
	v_and_b32_e32 v19, 0xffff0000, v19
	s_waitcnt vmcnt(1)
	v_pk_fma_f32 v[14:15], v[14:15], v[22:23], v[16:17]
	v_pk_fma_f32 v[12:13], v[12:13], v[20:21], v[30:31]
	s_waitcnt vmcnt(0)
	v_pk_fma_f32 v[16:17], v[10:11], v[26:27], v[18:19]
	v_pk_fma_f32 v[10:11], v[8:9], v[24:25], v[32:33]
	v_cvt_pk_bf16_f32 v8, v12, v13
	v_cvt_pk_bf16_f32 v9, v14, v15
	v_cvt_pk_bf16_f32 v10, v10, v11
	v_cvt_pk_bf16_f32 v11, v16, v17
	global_store_dwordx4 v[28:29], v[8:11], off sc1
	global_load_dwordx4 v[8:11], v[38:39], off offset:256
	s_nop 0
	global_load_dwordx4 v[12:15], v[64:65], off offset:512
	global_load_dwordx4 v[16:19], v[64:65], off offset:528
	s_waitcnt vmcnt(2)
	v_lshlrev_b32_e32 v20, 16, v8
	v_and_b32_e32 v21, 0xffff0000, v8
	v_lshlrev_b32_e32 v8, 16, v9
	v_and_b32_e32 v9, 0xffff0000, v9
	v_lshlrev_b32_e32 v22, 16, v10
	v_and_b32_e32 v23, 0xffff0000, v10
	v_lshlrev_b32_e32 v10, 16, v11
	v_and_b32_e32 v11, 0xffff0000, v11
	s_waitcnt vmcnt(1)
	v_pk_fma_f32 v[6:7], v[6:7], v[14:15], v[8:9]
	v_pk_fma_f32 v[4:5], v[4:5], v[12:13], v[20:21]
	s_waitcnt vmcnt(0)
	v_pk_fma_f32 v[8:9], v[2:3], v[18:19], v[10:11]
	v_pk_fma_f32 v[2:3], v[0:1], v[16:17], v[22:23]
	v_cvt_pk_bf16_f32 v0, v4, v5
	v_cvt_pk_bf16_f32 v1, v6, v7
	v_cvt_pk_bf16_f32 v2, v2, v3
	v_cvt_pk_bf16_f32 v3, v8, v9
	global_store_dwordx4 v[28:29], v[0:3], off offset:256 sc1
	s_cbranch_vccnz .LBB0_1262
	s_andn2_b64 vcc, exec, s[6:7]
	s_cbranch_vccnz .LBB0_1261
	s_barrier
	s_branch .LBB0_1261

.Lp12_nonext:
	v_mul_f32_e32 v80, v48, v48
	v_mul_f32_e32 v82, v64, v64
	v_mul_f32_e32 v81, v49, v49
	v_mul_f32_e32 v83, v65, v65
	v_fmac_f32_e32 v80, v50, v50
	v_fmac_f32_e32 v82, v66, v66
	v_fmac_f32_e32 v81, v51, v51
	v_fmac_f32_e32 v83, v67, v67
	v_fmac_f32_e32 v80, v52, v52
	v_fmac_f32_e32 v82, v68, v68
	v_fmac_f32_e32 v81, v53, v53
	v_fmac_f32_e32 v83, v69, v69
	v_fmac_f32_e32 v80, v54, v54
	v_fmac_f32_e32 v82, v70, v70
	v_fmac_f32_e32 v81, v55, v55
	v_fmac_f32_e32 v83, v71, v71
	v_fmac_f32_e32 v80, v56, v56
	v_fmac_f32_e32 v82, v72, v72
	v_fmac_f32_e32 v81, v57, v57
	v_fmac_f32_e32 v83, v73, v73
	v_fmac_f32_e32 v80, v58, v58
	v_fmac_f32_e32 v82, v74, v74
	v_fmac_f32_e32 v81, v59, v59
	v_fmac_f32_e32 v83, v75, v75
	v_fmac_f32_e32 v80, v60, v60
	v_fmac_f32_e32 v82, v76, v76
	v_fmac_f32_e32 v81, v61, v61
	v_fmac_f32_e32 v83, v77, v77
	v_fmac_f32_e32 v80, v62, v62
	v_fmac_f32_e32 v82, v78, v78
	v_fmac_f32_e32 v81, v63, v63
	v_fmac_f32_e32 v83, v79, v79
	v_add_f32_e32 v80, v80, v81
	v_add_f32_e32 v82, v82, v83
	ds_bpermute_b32 v84, v40, v80
	ds_bpermute_b32 v85, v40, v82
	s_waitcnt lgkmcnt(1)
	v_add_f32_e32 v80, v80, v84
	s_waitcnt lgkmcnt(0)
	v_add_f32_e32 v82, v82, v85
	ds_bpermute_b32 v84, v41, v80
	ds_bpermute_b32 v85, v41, v82
	s_waitcnt lgkmcnt(1)
	v_add_f32_e32 v80, v80, v84
	s_waitcnt lgkmcnt(0)
	v_add_f32_e32 v82, v82, v85
	ds_bpermute_b32 v84, v42, v80
	ds_bpermute_b32 v85, v42, v82
	s_waitcnt lgkmcnt(1)
	v_add_f32_e32 v80, v80, v84
	s_waitcnt lgkmcnt(0)
	v_add_f32_e32 v82, v82, v85
	ds_bpermute_b32 v84, v43, v80
	ds_bpermute_b32 v85, v43, v82
	s_waitcnt lgkmcnt(1)
	v_add_f32_e32 v80, v80, v84
	s_waitcnt lgkmcnt(0)
	v_add_f32_e32 v82, v82, v85
	ds_bpermute_b32 v84, v44, v80
	ds_bpermute_b32 v85, v44, v82
	s_waitcnt lgkmcnt(1)
	v_add_f32_e32 v80, v80, v84
	s_waitcnt lgkmcnt(0)
	v_add_f32_e32 v82, v82, v85
	ds_bpermute_b32 v84, v45, v80
	ds_bpermute_b32 v85, v45, v82
	s_waitcnt lgkmcnt(1)
	v_add_f32_e32 v80, v80, v84
	s_waitcnt lgkmcnt(0)
	v_add_f32_e32 v82, v82, v85
	v_fmamk_f32 v80, v80, 0x3a800000, v86
	v_fmamk_f32 v82, v82, 0x3a800000, v86
	v_rsq_f32_e32 v80, v80
	v_rsq_f32_e32 v82, v82
	s_nop 0
	v_mul_f32_e32 v48, v48, v80
	v_mul_f32_e32 v64, v64, v82
	v_mul_f32_e32 v49, v49, v80
	v_mul_f32_e32 v65, v65, v82
	v_mul_f32_e32 v50, v50, v80
	v_mul_f32_e32 v66, v66, v82
	v_mul_f32_e32 v51, v51, v80
	v_mul_f32_e32 v67, v67, v82
	v_mul_f32_e32 v52, v52, v80
	v_mul_f32_e32 v68, v68, v82
	v_mul_f32_e32 v53, v53, v80
	v_mul_f32_e32 v69, v69, v82
	v_mul_f32_e32 v54, v54, v80
	v_mul_f32_e32 v70, v70, v82
	v_mul_f32_e32 v55, v55, v80
	v_mul_f32_e32 v71, v71, v82
	v_mul_f32_e32 v56, v56, v80
	v_mul_f32_e32 v72, v72, v82
	v_mul_f32_e32 v57, v57, v80
	v_mul_f32_e32 v73, v73, v82
	v_mul_f32_e32 v58, v58, v80
	v_mul_f32_e32 v74, v74, v82
	v_mul_f32_e32 v59, v59, v80
	v_mul_f32_e32 v75, v75, v82
	v_mul_f32_e32 v60, v60, v80
	v_mul_f32_e32 v76, v76, v82
	v_mul_f32_e32 v61, v61, v80
	v_mul_f32_e32 v77, v77, v82
	v_mul_f32_e32 v62, v62, v80
	v_mul_f32_e32 v78, v78, v82
	v_mul_f32_e32 v63, v63, v80
	v_mul_f32_e32 v79, v79, v82
	v_mul_f32_e32 v48, v48, v100
	v_mul_f32_e32 v64, v64, v100
	v_mul_f32_e32 v49, v49, v101
	v_mul_f32_e32 v65, v65, v101
	v_mul_f32_e32 v50, v50, v102
	v_mul_f32_e32 v66, v66, v102
	v_mul_f32_e32 v51, v51, v103
	v_mul_f32_e32 v67, v67, v103
	v_mul_f32_e32 v52, v52, v104
	v_mul_f32_e32 v68, v68, v104
	v_mul_f32_e32 v53, v53, v105
	v_mul_f32_e32 v69, v69, v105
	v_mul_f32_e32 v54, v54, v106
	v_mul_f32_e32 v70, v70, v106
	v_mul_f32_e32 v55, v55, v107
	v_mul_f32_e32 v71, v71, v107
	v_mul_f32_e32 v56, v56, v108
	v_mul_f32_e32 v72, v72, v108
	v_mul_f32_e32 v57, v57, v109
	v_mul_f32_e32 v73, v73, v109
	v_mul_f32_e32 v58, v58, v110
	v_mul_f32_e32 v74, v74, v110
	v_mul_f32_e32 v59, v59, v111
	v_mul_f32_e32 v75, v75, v111
	v_mul_f32_e32 v60, v60, v112
	v_mul_f32_e32 v76, v76, v112
	v_mul_f32_e32 v61, v61, v113
	v_mul_f32_e32 v77, v77, v113
	v_mul_f32_e32 v62, v62, v114
	v_mul_f32_e32 v78, v78, v114
	v_mul_f32_e32 v63, v63, v115
	v_mul_f32_e32 v79, v79, v115
	global_store_dwordx4 v2, v[48:51], s[14:15] sc1
	global_store_dwordx4 v2, v[52:55], s[14:15] offset:1024 sc1
	global_store_dwordx4 v2, v[56:59], s[14:15] offset:2048 sc1
	global_store_dwordx4 v2, v[60:63], s[14:15] offset:3072 sc1
	global_store_dwordx4 v2, v[64:67], s[16:17] sc1
	global_store_dwordx4 v2, v[68:71], s[16:17] offset:1024 sc1
	global_store_dwordx4 v2, v[72:75], s[16:17] offset:2048 sc1
	global_store_dwordx4 v2, v[76:79], s[16:17] offset:3072 sc1
	s_cmp_lg_u32 s18, 0
	s_cbranch_scc0 .LBB0_1347
	s_waitcnt vmcnt(8)
	s_branch .Lp12_loop
